# v44 with the second 16-MFMA block of each segment walked in mirrored m order (src1 shared across the block boundary)
# speedup vs baseline: 1.0003x; 1.0003x over previous
; #define PG8_STAGE(bufoff, gbase, voff) do { _Pragma("unroll") for (int _i = 0; _i < 2; ++_i) \
;         __builtin_amdgcn_global_load_lds((const unsigned*)((const char*)(gbase) + (voff)[_i]), (PG8_LAS unsigned*)(lds + (bufoff) + ldsw + _i * 8192), 16, 0, 0); } while (0)
; #define PG8_LDA(dst, b, h) do { _Pragma("unroll") for (int m = 0; m < 4; ++m) _Pragma("unroll") for (int k = 0; k < 2; ++k) dst[m][k] = *(const PG8_LAS bf16x8*)(lds + PG8_SA(b, h) + aoff + m * 2048 + k * 1024); } while (0)
; #define PG8_LDB(dst, b, h) do { _Pragma("unroll") for (int n = 0; n < 2; ++n) _Pragma("unroll") for (int k = 0; k < 2; ++k) dst[n][k] = *(const PG8_LAS bf16x8*)(lds + PG8_SB(b, h) + boff + n * 2048 + k * 1024); } while (0)
; #define PG8_MMA(ai, bj, At, Bt) do { __builtin_amdgcn_s_setprio(1); _Pragma("unroll") for (int m = 0; m < 4; ++m) _Pragma("unroll") for (int n = 0; n < 2; ++n) _Pragma("unroll") for (int k = 0; k < 2; ++k) \
;         acc[ai][bj][m][n] = mma16(Bt[n][k], At[m][k], acc[ai][bj][m][n]); __builtin_amdgcn_s_setprio(0); } while (0)
; #define PG8_WAIT_V(n) asm volatile("s_waitcnt vmcnt(" #n ")" ::: "memory")
; #define PG8_WAIT_L(n) asm volatile("s_waitcnt lgkmcnt(" #n ")" ::: "memory")
; template <class Epi, class Sched, bool ALIGN_EPI = false, bool SP2 = false>
; __device__ __forceinline__ void gemm_phase(PG8_LAS unsigned char* lds, const Gemm g, const Sched& S, const Epi& E) {
;     ...
;         for (int t = 0; t < nt; t += 2) {
;             const bool last = (t == nt - 2);
;             const char* a1 = cA + (size_t)(t + 1) * kstep;
;             const char* a2 = last ? nA : cA + (size_t)(t + 2) * kstep; const char* b2 = last ? nB : cB + (size_t)(t + 2) * kstep;
;             const char* a3 = a2 + kstep; const char* b3 = b2 + kstep;
;             if (last && has_next) S.a_ready(nxt);
;             if constexpr (SP2) {
;             PG8_LDB(B0, 0, 0); PG8_LDB(B1, 0, 1); PG8_SCHED; PG8_LDA(At, 0, 0); PG8_STAGE(PG8_SA(1, 1), a1 + hstepA, voffA);
;             PG8_WAIT_V(8); PG8_WAIT_L(0); PG8_BAR; PG8_MMA(0, 0, At, B0); PG8_MMA(0, 1, At, B1); PG8_BAR; PG8_SCHED;
;             PG8_LDA(At, 0, 1); PG8_STAGE(PG8_SB(0, 0), b2, voffB); PG8_STAGE(PG8_SB(0, 1), b2 + hstepB, voffB); PG8_STAGE(PG8_SA(0, 0), a2, voffA);
;             PG8_WAIT_V(8); PG8_WAIT_L(0); PG8_BAR; PG8_MMA(1, 0, At, B0); PG8_MMA(1, 1, At, B1); PG8_BAR; PG8_SCHED;
.LBB0_230:
	s_ashr_i32 s45, s44, 31
	s_lshl_b64 s[36:37], s[44:45], 21
	s_add_u32 s58, s8, s36
	s_addc_u32 s59, s11, s37
	s_and_b64 s[0:1], s[0:1], exec
	s_cselect_b32 s29, s59, s65
	s_cselect_b32 s33, s58, s64
	s_add_u32 s0, s66, 0x100080
	s_addc_u32 s1, s67, 0
	s_add_u32 s35, s64, 0x100
	s_addc_u32 s36, s65, 0
	s_mov_b32 s37, -2
	ds_read_b128 v[146:149], v158
	ds_read_b128 v[162:165], v158 offset:1024
	ds_read_b128 v[182:185], v158 offset:2048
	ds_read_b128 v[186:189], v158 offset:3072
	ds_read_b128 v[190:193], v159
	ds_read_b128 v[194:197], v159 offset:1024
	ds_read_b128 v[198:201], v159 offset:2048
	ds_read_b128 v[202:205], v159 offset:3072
	s_add_u32 s45, s0, 0xfff00080
	s_addc_u32 s46, s1, -1
	s_cmp_eq_u32 s37, 60
	s_cselect_b32 s67, s55, s46
	s_cselect_b32 s66, s54, s45
	s_cselect_b32 s65, s29, s36
	s_cselect_b32 s64, s33, s35
	v_lshl_add_u64 v[166:167], s[0:1], 0, v[138:139]
	s_add_i32 m0, s13, 0xc000
	ds_read_b128 v[206:209], v160
	ds_read_b128 v[212:215], v160 offset:1024
	ds_read_b128 v[216:219], v160 offset:2048
	ds_read_b128 v[220:223], v160 offset:3072
	ds_read_b128 v[224:227], v160 offset:4096
	ds_read_b128 v[228:231], v160 offset:5120
	ds_read_b128 v[232:235], v160 offset:6144
	ds_read_b128 v[236:239], v160 offset:7168
	global_load_lds_dwordx4 v[166:167], off
	v_lshl_add_u64 v[166:167], s[0:1], 0, v[140:141]
	s_add_i32 m0, s13, 0xe000
	s_nop 0
	global_load_lds_dwordx4 v[166:167], off
	s_waitcnt vmcnt(8)
	s_waitcnt lgkmcnt(0)
	s_barrier
	s_setprio 1
	s_waitcnt lgkmcnt(0)
	v_mfma_f32_16x16x32_bf16 v[126:129], v[146:149], v[206:209], 0
	v_mfma_f32_16x16x32_bf16 v[126:129], v[162:165], v[212:215], v[126:129]
	v_mfma_f32_16x16x32_bf16 v[122:125], v[186:189], v[212:215], 0
	v_mfma_f32_16x16x32_bf16 v[122:125], v[182:185], v[206:209], v[122:125]
	v_mfma_f32_16x16x32_bf16 v[110:113], v[182:185], v[216:219], 0
	v_mfma_f32_16x16x32_bf16 v[110:113], v[186:189], v[220:223], v[110:113]
	v_mfma_f32_16x16x32_bf16 v[118:121], v[162:165], v[220:223], 0
	v_mfma_f32_16x16x32_bf16 v[118:121], v[146:149], v[216:219], v[118:121]
	v_mfma_f32_16x16x32_bf16 v[102:105], v[146:149], v[224:227], 0
	v_mfma_f32_16x16x32_bf16 v[102:105], v[162:165], v[228:231], v[102:105]
	v_mfma_f32_16x16x32_bf16 v[94:97], v[186:189], v[228:231], 0
	v_mfma_f32_16x16x32_bf16 v[94:97], v[182:185], v[224:227], v[94:97]
	v_mfma_f32_16x16x32_bf16 v[78:81], v[182:185], v[232:235], 0
	v_mfma_f32_16x16x32_bf16 v[78:81], v[186:189], v[236:239], v[78:81]
	v_mfma_f32_16x16x32_bf16 v[86:89], v[162:165], v[236:239], 0
	v_mfma_f32_16x16x32_bf16 v[86:89], v[146:149], v[232:235], v[86:89]
	s_setprio 0
	s_setprio 1
	v_mfma_f32_16x16x32_bf16 v[70:73], v[190:193], v[232:235], 0
	v_mfma_f32_16x16x32_bf16 v[70:73], v[194:197], v[236:239], v[70:73]
	v_mfma_f32_16x16x32_bf16 v[66:69], v[202:205], v[236:239], 0
	v_mfma_f32_16x16x32_bf16 v[66:69], v[198:201], v[232:235], v[66:69]
	v_mfma_f32_16x16x32_bf16 v[74:77], v[198:201], v[224:227], 0
	v_mfma_f32_16x16x32_bf16 v[74:77], v[202:205], v[228:231], v[74:77]
	v_mfma_f32_16x16x32_bf16 v[82:85], v[194:197], v[228:231], 0
	v_mfma_f32_16x16x32_bf16 v[82:85], v[190:193], v[224:227], v[82:85]
	v_mfma_f32_16x16x32_bf16 v[98:101], v[190:193], v[216:219], 0
	v_mfma_f32_16x16x32_bf16 v[98:101], v[194:197], v[220:223], v[98:101]
	v_mfma_f32_16x16x32_bf16 v[90:93], v[202:205], v[220:223], 0
	v_mfma_f32_16x16x32_bf16 v[90:93], v[198:201], v[216:219], v[90:93]
	v_mfma_f32_16x16x32_bf16 v[106:109], v[198:201], v[206:209], 0
	v_mfma_f32_16x16x32_bf16 v[106:109], v[202:205], v[212:215], v[106:109]
	v_mfma_f32_16x16x32_bf16 v[114:117], v[194:197], v[212:215], 0
	v_mfma_f32_16x16x32_bf16 v[114:117], v[190:193], v[206:209], v[114:117]
	s_setprio 0
	s_barrier
	s_add_i32 s45, s26, s12
	v_lshl_add_u64 v[166:167], s[64:65], 0, v[132:133]
	s_mov_b32 m0, s45
	ds_read_b128 v[206:209], v160 offset:16384
	ds_read_b128 v[212:215], v160 offset:17408
	ds_read_b128 v[216:219], v160 offset:18432
	ds_read_b128 v[220:223], v160 offset:19456
	ds_read_b128 v[224:227], v160 offset:20480
	ds_read_b128 v[228:231], v160 offset:21504
	ds_read_b128 v[232:235], v160 offset:22528
	ds_read_b128 v[236:239], v160 offset:23552
	global_load_lds_dwordx4 v[166:167], off
	s_add_i32 m0, s45, 0x2000
	s_add_u32 s46, s64, 0x100000
	v_lshl_add_u64 v[176:177], s[64:65], 0, v[136:137]
	s_addc_u32 s47, s65, 0
	s_add_i32 s45, s27, s12
	global_load_lds_dwordx4 v[176:177], off
	v_lshl_add_u64 v[240:241], s[46:47], 0, v[132:133]
	s_mov_b32 m0, s45
	v_lshl_add_u64 v[242:243], s[66:67], 0, v[134:135]
	global_load_lds_dwordx4 v[240:241], off
	v_lshl_add_u64 v[240:241], s[46:47], 0, v[136:137]
	s_add_i32 m0, s45, 0x2000
	s_nop 0
	global_load_lds_dwordx4 v[240:241], off
	v_lshl_add_u64 v[240:241], s[66:67], 0, v[130:131]
	s_mov_b32 m0, s13
	s_nop 0
	global_load_lds_dwordx4 v[240:241], off
	s_mov_b32 m0, s18
	s_nop 0
	global_load_lds_dwordx4 v[242:243], off
	s_waitcnt vmcnt(8)
	s_waitcnt lgkmcnt(0)
	s_barrier
; #define PG8_STAGE(bufoff, gbase, voff) do { _Pragma("unroll") for (int _i = 0; _i < 2; ++_i) \
;         __builtin_amdgcn_global_load_lds((const unsigned*)((const char*)(gbase) + (voff)[_i]), (PG8_LAS unsigned*)(lds + (bufoff) + ldsw + _i * 8192), 16, 0, 0); } while (0)
; #define PG8_LDA(dst, b, h) do { _Pragma("unroll") for (int m = 0; m < 4; ++m) _Pragma("unroll") for (int k = 0; k < 2; ++k) dst[m][k] = *(const PG8_LAS bf16x8*)(lds + PG8_SA(b, h) + aoff + m * 2048 + k * 1024); } while (0)
; #define PG8_LDB(dst, b, h) do { _Pragma("unroll") for (int n = 0; n < 2; ++n) _Pragma("unroll") for (int k = 0; k < 2; ++k) dst[n][k] = *(const PG8_LAS bf16x8*)(lds + PG8_SB(b, h) + boff + n * 2048 + k * 1024); } while (0)
; #define PG8_MMA(ai, bj, At, Bt) do { __builtin_amdgcn_s_setprio(1); _Pragma("unroll") for (int m = 0; m < 4; ++m) _Pragma("unroll") for (int n = 0; n < 2; ++n) _Pragma("unroll") for (int k = 0; k < 2; ++k) \
;         acc[ai][bj][m][n] = mma16(Bt[n][k], At[m][k], acc[ai][bj][m][n]); __builtin_amdgcn_s_setprio(0); } while (0)
; #define PG8_WAIT_V(n) asm volatile("s_waitcnt vmcnt(" #n ")" ::: "memory")
; #define PG8_WAIT_L(n) asm volatile("s_waitcnt lgkmcnt(" #n ")" ::: "memory")
; #define PG8_BAR __builtin_amdgcn_s_barrier()
; #define PG8_SCHED __builtin_amdgcn_sched_barrier(0)
; template <class Epi, class Sched, bool ALIGN_EPI = false, bool SP2 = false>
; __device__ __forceinline__ void gemm_phase(PG8_LAS unsigned char* lds, const Gemm g, const Sched& S, const Epi& E) {
;     ...
;             PG8_WAIT_V(8); PG8_WAIT_L(0); PG8_BAR; PG8_MMA(0, 0, At, B0); PG8_MMA(0, 1, At, B1); PG8_BAR; PG8_SCHED;
;             PG8_LDA(At, 0, 1); PG8_STAGE(PG8_SB(0, 0), b2, voffB); PG8_STAGE(PG8_SB(0, 1), b2 + hstepB, voffB); PG8_STAGE(PG8_SA(0, 0), a2, voffA);
;             PG8_WAIT_V(8); PG8_WAIT_L(0); PG8_BAR; PG8_MMA(1, 0, At, B0); PG8_MMA(1, 1, At, B1); PG8_BAR; PG8_SCHED;
;             PG8_LDB(B0, 1, 0); PG8_LDB(B1, 1, 1); PG8_SCHED; PG8_LDA(At, 1, 0); PG8_STAGE(PG8_SA(0, 1), a2 + hstepA, voffA);
;             PG8_WAIT_V(8); PG8_WAIT_L(0); PG8_BAR; PG8_MMA(0, 0, At, B0); PG8_MMA(0, 1, At, B1); PG8_BAR; PG8_SCHED;
	s_setprio 1
	s_waitcnt lgkmcnt(0)
	v_mfma_f32_16x16x32_bf16 v[62:65], v[146:149], v[206:209], 0
	v_mfma_f32_16x16x32_bf16 v[62:65], v[162:165], v[212:215], v[62:65]
	v_mfma_f32_16x16x32_bf16 v[58:61], v[186:189], v[212:215], 0
	v_mfma_f32_16x16x32_bf16 v[58:61], v[182:185], v[206:209], v[58:61]
	v_mfma_f32_16x16x32_bf16 v[46:49], v[182:185], v[216:219], 0
	v_mfma_f32_16x16x32_bf16 v[46:49], v[186:189], v[220:223], v[46:49]
	v_mfma_f32_16x16x32_bf16 v[54:57], v[162:165], v[220:223], 0
	v_mfma_f32_16x16x32_bf16 v[54:57], v[146:149], v[216:219], v[54:57]
	v_mfma_f32_16x16x32_bf16 v[38:41], v[146:149], v[224:227], 0
	v_mfma_f32_16x16x32_bf16 v[38:41], v[162:165], v[228:231], v[38:41]
	v_mfma_f32_16x16x32_bf16 v[30:33], v[186:189], v[228:231], 0
	v_mfma_f32_16x16x32_bf16 v[30:33], v[182:185], v[224:227], v[30:33]
	v_mfma_f32_16x16x32_bf16 v[14:17], v[182:185], v[232:235], 0
	v_mfma_f32_16x16x32_bf16 v[14:17], v[186:189], v[236:239], v[14:17]
	v_mfma_f32_16x16x32_bf16 v[22:25], v[162:165], v[236:239], 0
	v_mfma_f32_16x16x32_bf16 v[22:25], v[146:149], v[232:235], v[22:25]
	s_setprio 0
	s_setprio 1
	v_mfma_f32_16x16x32_bf16 v[6:9], v[190:193], v[232:235], 0
	v_mfma_f32_16x16x32_bf16 v[6:9], v[194:197], v[236:239], v[6:9]
	v_mfma_f32_16x16x32_bf16 v[2:5], v[202:205], v[236:239], 0
	v_mfma_f32_16x16x32_bf16 v[2:5], v[198:201], v[232:235], v[2:5]
	v_mfma_f32_16x16x32_bf16 v[10:13], v[198:201], v[224:227], 0
	v_mfma_f32_16x16x32_bf16 v[10:13], v[202:205], v[228:231], v[10:13]
	v_mfma_f32_16x16x32_bf16 v[18:21], v[194:197], v[228:231], 0
	v_mfma_f32_16x16x32_bf16 v[18:21], v[190:193], v[224:227], v[18:21]
	v_mfma_f32_16x16x32_bf16 v[34:37], v[190:193], v[216:219], 0
	v_mfma_f32_16x16x32_bf16 v[34:37], v[194:197], v[220:223], v[34:37]
	v_mfma_f32_16x16x32_bf16 v[26:29], v[202:205], v[220:223], 0
	v_mfma_f32_16x16x32_bf16 v[26:29], v[198:201], v[216:219], v[26:29]
	v_mfma_f32_16x16x32_bf16 v[42:45], v[198:201], v[206:209], 0
	v_mfma_f32_16x16x32_bf16 v[42:45], v[202:205], v[212:215], v[42:45]
	v_mfma_f32_16x16x32_bf16 v[50:53], v[194:197], v[212:215], 0
	v_mfma_f32_16x16x32_bf16 v[50:53], v[190:193], v[206:209], v[50:53]
	s_setprio 0
	s_barrier
	s_add_i32 s45, 0, 0x18000
	v_add_u32_e32 v161, s45, v156
	s_add_i32 s49, 0, 0x1c000
	ds_read_b128 v[146:149], v161
	ds_read_b128 v[162:165], v161 offset:1024
	ds_read_b128 v[182:185], v161 offset:2048
	ds_read_b128 v[186:189], v161 offset:3072
	v_add_u32_e32 v161, s49, v156
	ds_read_b128 v[190:193], v161
	ds_read_b128 v[194:197], v161 offset:1024
	ds_read_b128 v[198:201], v161 offset:2048
	ds_read_b128 v[202:205], v161 offset:3072
	s_add_u32 s46, s66, 0x100000
	s_addc_u32 s47, s67, 0
	s_mov_b32 m0, s19
	v_lshl_add_u64 v[244:245], s[46:47], 0, v[130:131]
	ds_read_b128 v[206:209], v160 offset:32768
	ds_read_b128 v[212:215], v160 offset:33792
	ds_read_b128 v[216:219], v160 offset:34816
	ds_read_b128 v[220:223], v160 offset:35840
	ds_read_b128 v[224:227], v160 offset:36864
	ds_read_b128 v[228:231], v160 offset:37888
	ds_read_b128 v[232:235], v160 offset:38912
	ds_read_b128 v[236:239], v160 offset:39936
	global_load_lds_dwordx4 v[244:245], off
	v_lshl_add_u64 v[244:245], s[46:47], 0, v[134:135]
	s_mov_b32 m0, s20
	s_nop 0
	global_load_lds_dwordx4 v[244:245], off
	s_waitcnt vmcnt(8)
	s_waitcnt lgkmcnt(0)
	s_barrier
	s_setprio 1
	s_waitcnt lgkmcnt(0)
	v_mfma_f32_16x16x32_bf16 v[126:129], v[146:149], v[206:209], v[126:129]
	v_mfma_f32_16x16x32_bf16 v[126:129], v[162:165], v[212:215], v[126:129]
	v_mfma_f32_16x16x32_bf16 v[122:125], v[186:189], v[212:215], v[122:125]
	v_mfma_f32_16x16x32_bf16 v[122:125], v[182:185], v[206:209], v[122:125]
	v_mfma_f32_16x16x32_bf16 v[110:113], v[182:185], v[216:219], v[110:113]
	v_mfma_f32_16x16x32_bf16 v[110:113], v[186:189], v[220:223], v[110:113]
	v_mfma_f32_16x16x32_bf16 v[118:121], v[162:165], v[220:223], v[118:121]
	v_mfma_f32_16x16x32_bf16 v[118:121], v[146:149], v[216:219], v[118:121]
	v_mfma_f32_16x16x32_bf16 v[102:105], v[146:149], v[224:227], v[102:105]
	v_mfma_f32_16x16x32_bf16 v[102:105], v[162:165], v[228:231], v[102:105]
	v_mfma_f32_16x16x32_bf16 v[94:97], v[186:189], v[228:231], v[94:97]
	v_mfma_f32_16x16x32_bf16 v[94:97], v[182:185], v[224:227], v[94:97]
	v_mfma_f32_16x16x32_bf16 v[78:81], v[182:185], v[232:235], v[78:81]
	v_mfma_f32_16x16x32_bf16 v[78:81], v[186:189], v[236:239], v[78:81]
	v_mfma_f32_16x16x32_bf16 v[86:89], v[162:165], v[236:239], v[86:89]
	v_mfma_f32_16x16x32_bf16 v[86:89], v[146:149], v[232:235], v[86:89]
	s_setprio 0
	s_setprio 1
	v_mfma_f32_16x16x32_bf16 v[70:73], v[190:193], v[232:235], v[70:73]
	v_mfma_f32_16x16x32_bf16 v[70:73], v[194:197], v[236:239], v[70:73]
	v_mfma_f32_16x16x32_bf16 v[66:69], v[202:205], v[236:239], v[66:69]
	v_mfma_f32_16x16x32_bf16 v[66:69], v[198:201], v[232:235], v[66:69]
	v_mfma_f32_16x16x32_bf16 v[74:77], v[198:201], v[224:227], v[74:77]
	v_mfma_f32_16x16x32_bf16 v[74:77], v[202:205], v[228:231], v[74:77]
	v_mfma_f32_16x16x32_bf16 v[82:85], v[194:197], v[228:231], v[82:85]
	v_mfma_f32_16x16x32_bf16 v[82:85], v[190:193], v[224:227], v[82:85]
	v_mfma_f32_16x16x32_bf16 v[98:101], v[190:193], v[216:219], v[98:101]
	v_mfma_f32_16x16x32_bf16 v[98:101], v[194:197], v[220:223], v[98:101]
	v_mfma_f32_16x16x32_bf16 v[90:93], v[202:205], v[220:223], v[90:93]
	v_mfma_f32_16x16x32_bf16 v[90:93], v[198:201], v[216:219], v[90:93]
	v_mfma_f32_16x16x32_bf16 v[106:109], v[198:201], v[206:209], v[106:109]
	v_mfma_f32_16x16x32_bf16 v[106:109], v[202:205], v[212:215], v[106:109]
	v_mfma_f32_16x16x32_bf16 v[114:117], v[194:197], v[212:215], v[114:117]
	v_mfma_f32_16x16x32_bf16 v[114:117], v[190:193], v[206:209], v[114:117]
	s_setprio 0
	s_barrier
; #define PG8_STAGE(bufoff, gbase, voff) do { _Pragma("unroll") for (int _i = 0; _i < 2; ++_i) \
;         __builtin_amdgcn_global_load_lds((const unsigned*)((const char*)(gbase) + (voff)[_i]), (PG8_LAS unsigned*)(lds + (bufoff) + ldsw + _i * 8192), 16, 0, 0); } while (0)
; #define PG8_LDA(dst, b, h) do { _Pragma("unroll") for (int m = 0; m < 4; ++m) _Pragma("unroll") for (int k = 0; k < 2; ++k) dst[m][k] = *(const PG8_LAS bf16x8*)(lds + PG8_SA(b, h) + aoff + m * 2048 + k * 1024); } while (0)
; #define PG8_LDB(dst, b, h) do { _Pragma("unroll") for (int n = 0; n < 2; ++n) _Pragma("unroll") for (int k = 0; k < 2; ++k) dst[n][k] = *(const PG8_LAS bf16x8*)(lds + PG8_SB(b, h) + boff + n * 2048 + k * 1024); } while (0)
; #define PG8_MMA(ai, bj, At, Bt) do { __builtin_amdgcn_s_setprio(1); _Pragma("unroll") for (int m = 0; m < 4; ++m) _Pragma("unroll") for (int n = 0; n < 2; ++n) _Pragma("unroll") for (int k = 0; k < 2; ++k) \
;         acc[ai][bj][m][n] = mma16(Bt[n][k], At[m][k], acc[ai][bj][m][n]); __builtin_amdgcn_s_setprio(0); } while (0)
; #define PG8_WAIT_V(n) asm volatile("s_waitcnt vmcnt(" #n ")" ::: "memory")
; template <class Epi, class Sched, bool ALIGN_EPI = false, bool SP2 = false>
; __device__ __forceinline__ void gemm_phase(PG8_LAS unsigned char* lds, const Gemm g, const Sched& S, const Epi& E) {
;     ...
;             PG8_LDB(B0, 0, 0); PG8_LDB(B1, 0, 1); PG8_SCHED; PG8_LDA(At, 0, 0); PG8_STAGE(PG8_SA(1, 1), a1 + hstepA, voffA);
;             PG8_WAIT_V(8); PG8_WAIT_L(0); PG8_BAR; PG8_MMA(0, 0, At, B0); PG8_MMA(0, 1, At, B1); PG8_BAR; PG8_SCHED;
;             PG8_LDA(At, 0, 1); PG8_STAGE(PG8_SB(0, 0), b2, voffB); PG8_STAGE(PG8_SB(0, 1), b2 + hstepB, voffB); PG8_STAGE(PG8_SA(0, 0), a2, voffA);
;             PG8_WAIT_V(8); PG8_WAIT_L(0); PG8_BAR; PG8_MMA(1, 0, At, B0); PG8_MMA(1, 1, At, B1); PG8_BAR; PG8_SCHED;
;             PG8_LDB(B0, 1, 0); PG8_LDB(B1, 1, 1); PG8_SCHED; PG8_LDA(At, 1, 0); PG8_STAGE(PG8_SA(0, 1), a2 + hstepA, voffA);
;             PG8_WAIT_V(8); PG8_WAIT_L(0); PG8_BAR; PG8_MMA(0, 0, At, B0); PG8_MMA(0, 1, At, B1); PG8_BAR; PG8_SCHED;
;             PG8_LDA(At, 1, 1); PG8_STAGE(PG8_SB(1, 0), b3, voffB); PG8_STAGE(PG8_SB(1, 1), b3 + hstepB, voffB); PG8_STAGE(PG8_SA(1, 0), a3, voffA);
;             PG8_WAIT_V(8); PG8_WAIT_L(0); PG8_BAR; PG8_MMA(1, 0, At, B0); PG8_MMA(1, 1, At, B1); PG8_BAR; PG8_SCHED;
	s_add_i32 s45, s45, s12
	v_lshl_add_u64 v[166:167], v[166:167], 0, s[40:41]
	s_mov_b32 m0, s45
	ds_read_b128 v[206:209], v160 offset:49152
	ds_read_b128 v[212:215], v160 offset:50176
	ds_read_b128 v[216:219], v160 offset:51200
	ds_read_b128 v[220:223], v160 offset:52224
	ds_read_b128 v[224:227], v160 offset:53248
	ds_read_b128 v[228:231], v160 offset:54272
	ds_read_b128 v[232:235], v160 offset:55296
	ds_read_b128 v[236:239], v160 offset:56320
	global_load_lds_dwordx4 v[166:167], off
	s_add_i32 m0, s45, 0x2000
	s_add_u32 s46, s64, 0x100080
	v_lshl_add_u64 v[166:167], v[176:177], 0, s[40:41]
	s_addc_u32 s47, s65, 0
	s_add_i32 s45, s49, s12
	global_load_lds_dwordx4 v[166:167], off
	v_lshl_add_u64 v[166:167], s[46:47], 0, v[132:133]
	s_mov_b32 m0, s45
	s_nop 0
	global_load_lds_dwordx4 v[166:167], off
	v_lshl_add_u64 v[166:167], s[46:47], 0, v[136:137]
	s_add_i32 m0, s45, 0x2000
	s_nop 0
	global_load_lds_dwordx4 v[166:167], off
	v_lshl_add_u64 v[166:167], v[240:241], 0, s[40:41]
	s_mov_b32 m0, s22
	s_nop 0
	global_load_lds_dwordx4 v[166:167], off
	v_lshl_add_u64 v[166:167], v[242:243], 0, s[40:41]
	s_mov_b32 m0, s23
	s_nop 0
	global_load_lds_dwordx4 v[166:167], off
	s_waitcnt vmcnt(8)
	s_waitcnt lgkmcnt(0)
	s_barrier
	s_setprio 1
	s_waitcnt lgkmcnt(0)
	v_mfma_f32_16x16x32_bf16 v[62:65], v[146:149], v[206:209], v[62:65]
	v_mfma_f32_16x16x32_bf16 v[62:65], v[162:165], v[212:215], v[62:65]
	v_mfma_f32_16x16x32_bf16 v[58:61], v[186:189], v[212:215], v[58:61]
	v_mfma_f32_16x16x32_bf16 v[58:61], v[182:185], v[206:209], v[58:61]
	v_mfma_f32_16x16x32_bf16 v[46:49], v[182:185], v[216:219], v[46:49]
	v_mfma_f32_16x16x32_bf16 v[46:49], v[186:189], v[220:223], v[46:49]
	v_mfma_f32_16x16x32_bf16 v[54:57], v[162:165], v[220:223], v[54:57]
	v_mfma_f32_16x16x32_bf16 v[54:57], v[146:149], v[216:219], v[54:57]
	v_mfma_f32_16x16x32_bf16 v[38:41], v[146:149], v[224:227], v[38:41]
	v_mfma_f32_16x16x32_bf16 v[38:41], v[162:165], v[228:231], v[38:41]
	v_mfma_f32_16x16x32_bf16 v[30:33], v[186:189], v[228:231], v[30:33]
	v_mfma_f32_16x16x32_bf16 v[30:33], v[182:185], v[224:227], v[30:33]
	v_mfma_f32_16x16x32_bf16 v[14:17], v[182:185], v[232:235], v[14:17]
	v_mfma_f32_16x16x32_bf16 v[14:17], v[186:189], v[236:239], v[14:17]
	v_mfma_f32_16x16x32_bf16 v[22:25], v[162:165], v[236:239], v[22:25]
	v_mfma_f32_16x16x32_bf16 v[22:25], v[146:149], v[232:235], v[22:25]
	s_setprio 0
	s_setprio 1
	v_mfma_f32_16x16x32_bf16 v[6:9], v[190:193], v[232:235], v[6:9]
	v_mfma_f32_16x16x32_bf16 v[6:9], v[194:197], v[236:239], v[6:9]
	v_mfma_f32_16x16x32_bf16 v[2:5], v[202:205], v[236:239], v[2:5]
	v_mfma_f32_16x16x32_bf16 v[2:5], v[198:201], v[232:235], v[2:5]
	v_mfma_f32_16x16x32_bf16 v[10:13], v[198:201], v[224:227], v[10:13]
	v_mfma_f32_16x16x32_bf16 v[10:13], v[202:205], v[228:231], v[10:13]
	v_mfma_f32_16x16x32_bf16 v[18:21], v[194:197], v[228:231], v[18:21]
	v_mfma_f32_16x16x32_bf16 v[18:21], v[190:193], v[224:227], v[18:21]
	v_mfma_f32_16x16x32_bf16 v[34:37], v[190:193], v[216:219], v[34:37]
	v_mfma_f32_16x16x32_bf16 v[34:37], v[194:197], v[220:223], v[34:37]
	v_mfma_f32_16x16x32_bf16 v[26:29], v[202:205], v[220:223], v[26:29]
	v_mfma_f32_16x16x32_bf16 v[26:29], v[198:201], v[216:219], v[26:29]
	v_mfma_f32_16x16x32_bf16 v[42:45], v[198:201], v[206:209], v[42:45]
	v_mfma_f32_16x16x32_bf16 v[42:45], v[202:205], v[212:215], v[42:45]
	v_mfma_f32_16x16x32_bf16 v[50:53], v[194:197], v[212:215], v[50:53]
	v_mfma_f32_16x16x32_bf16 v[50:53], v[190:193], v[206:209], v[50:53]
	s_setprio 0
	s_barrier
	s_add_i32 s37, s37, 2
	s_add_u32 s0, s0, 0x100
	s_addc_u32 s1, s1, 0
	s_add_u32 s35, s35, 0x100
	s_addc_u32 s36, s36, 0
.LBB0_231:
	ds_read_b128 v[146:149], v158
	ds_read_b128 v[162:165], v158 offset:1024
	ds_read_b128 v[182:185], v158 offset:2048
	ds_read_b128 v[186:189], v158 offset:3072
	ds_read_b128 v[190:193], v159
	ds_read_b128 v[194:197], v159 offset:1024
	ds_read_b128 v[198:201], v159 offset:2048
	ds_read_b128 v[202:205], v159 offset:3072
	s_add_u32 s45, s0, 0xfff00080
	s_addc_u32 s46, s1, -1
	s_cmp_eq_u32 s37, 60
	s_cselect_b32 s67, s55, s46
	s_cselect_b32 s66, s54, s45
	s_cselect_b32 s65, s29, s36
	s_cselect_b32 s64, s33, s35
	v_lshl_add_u64 v[166:167], s[0:1], 0, v[138:139]
	s_add_i32 m0, s13, 0xc000
	ds_read_b128 v[206:209], v160
	ds_read_b128 v[212:215], v160 offset:1024
	ds_read_b128 v[216:219], v160 offset:2048
	ds_read_b128 v[220:223], v160 offset:3072
	ds_read_b128 v[224:227], v160 offset:4096
	ds_read_b128 v[228:231], v160 offset:5120
	ds_read_b128 v[232:235], v160 offset:6144
	ds_read_b128 v[236:239], v160 offset:7168
	global_load_lds_dwordx4 v[166:167], off
	v_lshl_add_u64 v[166:167], s[0:1], 0, v[140:141]
	s_add_i32 m0, s13, 0xe000
	s_nop 0
	global_load_lds_dwordx4 v[166:167], off
	s_waitcnt vmcnt(8)
	s_waitcnt lgkmcnt(0)
	s_barrier
; #define PG8_STAGE(bufoff, gbase, voff) do { _Pragma("unroll") for (int _i = 0; _i < 2; ++_i) \
;         __builtin_amdgcn_global_load_lds((const unsigned*)((const char*)(gbase) + (voff)[_i]), (PG8_LAS unsigned*)(lds + (bufoff) + ldsw + _i * 8192), 16, 0, 0); } while (0)
; #define PG8_LDA(dst, b, h) do { _Pragma("unroll") for (int m = 0; m < 4; ++m) _Pragma("unroll") for (int k = 0; k < 2; ++k) dst[m][k] = *(const PG8_LAS bf16x8*)(lds + PG8_SA(b, h) + aoff + m * 2048 + k * 1024); } while (0)
; #define PG8_MMA(ai, bj, At, Bt) do { __builtin_amdgcn_s_setprio(1); _Pragma("unroll") for (int m = 0; m < 4; ++m) _Pragma("unroll") for (int n = 0; n < 2; ++n) _Pragma("unroll") for (int k = 0; k < 2; ++k) \
;         acc[ai][bj][m][n] = mma16(Bt[n][k], At[m][k], acc[ai][bj][m][n]); __builtin_amdgcn_s_setprio(0); } while (0)
; #define PG8_WAIT_V(n) asm volatile("s_waitcnt vmcnt(" #n ")" ::: "memory")
; #define PG8_WAIT_L(n) asm volatile("s_waitcnt lgkmcnt(" #n ")" ::: "memory")
; #define PG8_BAR __builtin_amdgcn_s_barrier()
; #define PG8_SCHED __builtin_amdgcn_sched_barrier(0)
; template <class Epi, class Sched, bool ALIGN_EPI = false, bool SP2 = false>
; __device__ __forceinline__ void gemm_phase(PG8_LAS unsigned char* lds, const Gemm g, const Sched& S, const Epi& E) {
;     ...
;             PG8_WAIT_V(8); PG8_WAIT_L(0); PG8_BAR; PG8_MMA(0, 0, At, B0); PG8_MMA(0, 1, At, B1); PG8_BAR; PG8_SCHED;
;             PG8_LDA(At, 0, 1); PG8_STAGE(PG8_SB(0, 0), b2, voffB); PG8_STAGE(PG8_SB(0, 1), b2 + hstepB, voffB); PG8_STAGE(PG8_SA(0, 0), a2, voffA);
;             PG8_WAIT_V(8); PG8_WAIT_L(0); PG8_BAR; PG8_MMA(1, 0, At, B0); PG8_MMA(1, 1, At, B1); PG8_BAR; PG8_SCHED;
	s_setprio 1
	s_waitcnt lgkmcnt(0)
	v_mfma_f32_16x16x32_bf16 v[126:129], v[146:149], v[206:209], v[126:129]
	v_mfma_f32_16x16x32_bf16 v[126:129], v[162:165], v[212:215], v[126:129]
	v_mfma_f32_16x16x32_bf16 v[122:125], v[186:189], v[212:215], v[122:125]
	v_mfma_f32_16x16x32_bf16 v[122:125], v[182:185], v[206:209], v[122:125]
	v_mfma_f32_16x16x32_bf16 v[110:113], v[182:185], v[216:219], v[110:113]
	v_mfma_f32_16x16x32_bf16 v[110:113], v[186:189], v[220:223], v[110:113]
	v_mfma_f32_16x16x32_bf16 v[118:121], v[162:165], v[220:223], v[118:121]
	v_mfma_f32_16x16x32_bf16 v[118:121], v[146:149], v[216:219], v[118:121]
	v_mfma_f32_16x16x32_bf16 v[102:105], v[146:149], v[224:227], v[102:105]
	v_mfma_f32_16x16x32_bf16 v[102:105], v[162:165], v[228:231], v[102:105]
	v_mfma_f32_16x16x32_bf16 v[94:97], v[186:189], v[228:231], v[94:97]
	v_mfma_f32_16x16x32_bf16 v[94:97], v[182:185], v[224:227], v[94:97]
	v_mfma_f32_16x16x32_bf16 v[78:81], v[182:185], v[232:235], v[78:81]
	v_mfma_f32_16x16x32_bf16 v[78:81], v[186:189], v[236:239], v[78:81]
	v_mfma_f32_16x16x32_bf16 v[86:89], v[162:165], v[236:239], v[86:89]
	v_mfma_f32_16x16x32_bf16 v[86:89], v[146:149], v[232:235], v[86:89]
	s_setprio 0
	s_setprio 1
	v_mfma_f32_16x16x32_bf16 v[70:73], v[190:193], v[232:235], v[70:73]
	v_mfma_f32_16x16x32_bf16 v[70:73], v[194:197], v[236:239], v[70:73]
	v_mfma_f32_16x16x32_bf16 v[66:69], v[202:205], v[236:239], v[66:69]
	v_mfma_f32_16x16x32_bf16 v[66:69], v[198:201], v[232:235], v[66:69]
	v_mfma_f32_16x16x32_bf16 v[74:77], v[198:201], v[224:227], v[74:77]
	v_mfma_f32_16x16x32_bf16 v[74:77], v[202:205], v[228:231], v[74:77]
	v_mfma_f32_16x16x32_bf16 v[82:85], v[194:197], v[228:231], v[82:85]
	v_mfma_f32_16x16x32_bf16 v[82:85], v[190:193], v[224:227], v[82:85]
	v_mfma_f32_16x16x32_bf16 v[98:101], v[190:193], v[216:219], v[98:101]
	v_mfma_f32_16x16x32_bf16 v[98:101], v[194:197], v[220:223], v[98:101]
	v_mfma_f32_16x16x32_bf16 v[90:93], v[202:205], v[220:223], v[90:93]
	v_mfma_f32_16x16x32_bf16 v[90:93], v[198:201], v[216:219], v[90:93]
	v_mfma_f32_16x16x32_bf16 v[106:109], v[198:201], v[206:209], v[106:109]
	v_mfma_f32_16x16x32_bf16 v[106:109], v[202:205], v[212:215], v[106:109]
	v_mfma_f32_16x16x32_bf16 v[114:117], v[194:197], v[212:215], v[114:117]
	v_mfma_f32_16x16x32_bf16 v[114:117], v[190:193], v[206:209], v[114:117]
	s_setprio 0
	s_barrier
	s_add_i32 s45, s26, s12
	v_lshl_add_u64 v[166:167], s[64:65], 0, v[132:133]
	s_mov_b32 m0, s45
	ds_read_b128 v[206:209], v160 offset:16384
	ds_read_b128 v[212:215], v160 offset:17408
	ds_read_b128 v[216:219], v160 offset:18432
	ds_read_b128 v[220:223], v160 offset:19456
	ds_read_b128 v[224:227], v160 offset:20480
	ds_read_b128 v[228:231], v160 offset:21504
	ds_read_b128 v[232:235], v160 offset:22528
	ds_read_b128 v[236:239], v160 offset:23552
	global_load_lds_dwordx4 v[166:167], off
	s_add_i32 m0, s45, 0x2000
	s_add_u32 s46, s64, 0x100000
	v_lshl_add_u64 v[176:177], s[64:65], 0, v[136:137]
	s_addc_u32 s47, s65, 0
	s_add_i32 s45, s27, s12
	global_load_lds_dwordx4 v[176:177], off
	v_lshl_add_u64 v[240:241], s[46:47], 0, v[132:133]
	s_mov_b32 m0, s45
	v_lshl_add_u64 v[242:243], s[66:67], 0, v[134:135]
	global_load_lds_dwordx4 v[240:241], off
	v_lshl_add_u64 v[240:241], s[46:47], 0, v[136:137]
	s_add_i32 m0, s45, 0x2000
	s_nop 0
	global_load_lds_dwordx4 v[240:241], off
	v_lshl_add_u64 v[240:241], s[66:67], 0, v[130:131]
	s_mov_b32 m0, s13
	s_nop 0
	global_load_lds_dwordx4 v[240:241], off
	s_mov_b32 m0, s18
	s_nop 0
	global_load_lds_dwordx4 v[242:243], off
	s_waitcnt vmcnt(8)
	s_waitcnt lgkmcnt(0)
	s_barrier
	s_setprio 1
	s_waitcnt lgkmcnt(0)
	v_mfma_f32_16x16x32_bf16 v[62:65], v[146:149], v[206:209], v[62:65]
	v_mfma_f32_16x16x32_bf16 v[62:65], v[162:165], v[212:215], v[62:65]
	v_mfma_f32_16x16x32_bf16 v[58:61], v[186:189], v[212:215], v[58:61]
	v_mfma_f32_16x16x32_bf16 v[58:61], v[182:185], v[206:209], v[58:61]
	v_mfma_f32_16x16x32_bf16 v[46:49], v[182:185], v[216:219], v[46:49]
	v_mfma_f32_16x16x32_bf16 v[46:49], v[186:189], v[220:223], v[46:49]
	v_mfma_f32_16x16x32_bf16 v[54:57], v[162:165], v[220:223], v[54:57]
	v_mfma_f32_16x16x32_bf16 v[54:57], v[146:149], v[216:219], v[54:57]
	v_mfma_f32_16x16x32_bf16 v[38:41], v[146:149], v[224:227], v[38:41]
	v_mfma_f32_16x16x32_bf16 v[38:41], v[162:165], v[228:231], v[38:41]
	v_mfma_f32_16x16x32_bf16 v[30:33], v[186:189], v[228:231], v[30:33]
	v_mfma_f32_16x16x32_bf16 v[30:33], v[182:185], v[224:227], v[30:33]
	v_mfma_f32_16x16x32_bf16 v[14:17], v[182:185], v[232:235], v[14:17]
	v_mfma_f32_16x16x32_bf16 v[14:17], v[186:189], v[236:239], v[14:17]
	v_mfma_f32_16x16x32_bf16 v[22:25], v[162:165], v[236:239], v[22:25]
	v_mfma_f32_16x16x32_bf16 v[22:25], v[146:149], v[232:235], v[22:25]
	s_setprio 0
	s_setprio 1
	v_mfma_f32_16x16x32_bf16 v[6:9], v[190:193], v[232:235], v[6:9]
	v_mfma_f32_16x16x32_bf16 v[6:9], v[194:197], v[236:239], v[6:9]
	v_mfma_f32_16x16x32_bf16 v[2:5], v[202:205], v[236:239], v[2:5]
	v_mfma_f32_16x16x32_bf16 v[2:5], v[198:201], v[232:235], v[2:5]
	v_mfma_f32_16x16x32_bf16 v[10:13], v[198:201], v[224:227], v[10:13]
	v_mfma_f32_16x16x32_bf16 v[10:13], v[202:205], v[228:231], v[10:13]
	v_mfma_f32_16x16x32_bf16 v[18:21], v[194:197], v[228:231], v[18:21]
	v_mfma_f32_16x16x32_bf16 v[18:21], v[190:193], v[224:227], v[18:21]
	v_mfma_f32_16x16x32_bf16 v[34:37], v[190:193], v[216:219], v[34:37]
	v_mfma_f32_16x16x32_bf16 v[34:37], v[194:197], v[220:223], v[34:37]
	v_mfma_f32_16x16x32_bf16 v[26:29], v[202:205], v[220:223], v[26:29]
	v_mfma_f32_16x16x32_bf16 v[26:29], v[198:201], v[216:219], v[26:29]
	v_mfma_f32_16x16x32_bf16 v[42:45], v[198:201], v[206:209], v[42:45]
	v_mfma_f32_16x16x32_bf16 v[42:45], v[202:205], v[212:215], v[42:45]
	v_mfma_f32_16x16x32_bf16 v[50:53], v[194:197], v[212:215], v[50:53]
	v_mfma_f32_16x16x32_bf16 v[50:53], v[190:193], v[206:209], v[50:53]
	s_setprio 0
	s_barrier
; #define PG8_STAGE(bufoff, gbase, voff) do { _Pragma("unroll") for (int _i = 0; _i < 2; ++_i) \
;         __builtin_amdgcn_global_load_lds((const unsigned*)((const char*)(gbase) + (voff)[_i]), (PG8_LAS unsigned*)(lds + (bufoff) + ldsw + _i * 8192), 16, 0, 0); } while (0)
; #define PG8_LDA(dst, b, h) do { _Pragma("unroll") for (int m = 0; m < 4; ++m) _Pragma("unroll") for (int k = 0; k < 2; ++k) dst[m][k] = *(const PG8_LAS bf16x8*)(lds + PG8_SA(b, h) + aoff + m * 2048 + k * 1024); } while (0)
; #define PG8_LDB(dst, b, h) do { _Pragma("unroll") for (int n = 0; n < 2; ++n) _Pragma("unroll") for (int k = 0; k < 2; ++k) dst[n][k] = *(const PG8_LAS bf16x8*)(lds + PG8_SB(b, h) + boff + n * 2048 + k * 1024); } while (0)
; #define PG8_MMA(ai, bj, At, Bt) do { __builtin_amdgcn_s_setprio(1); _Pragma("unroll") for (int m = 0; m < 4; ++m) _Pragma("unroll") for (int n = 0; n < 2; ++n) _Pragma("unroll") for (int k = 0; k < 2; ++k) \
;         acc[ai][bj][m][n] = mma16(Bt[n][k], At[m][k], acc[ai][bj][m][n]); __builtin_amdgcn_s_setprio(0); } while (0)
; #define PG8_WAIT_V(n) asm volatile("s_waitcnt vmcnt(" #n ")" ::: "memory")
; #define PG8_WAIT_L(n) asm volatile("s_waitcnt lgkmcnt(" #n ")" ::: "memory")
; #define PG8_BAR __builtin_amdgcn_s_barrier()
; #define PG8_SCHED __builtin_amdgcn_sched_barrier(0)
; template <class Epi, class Sched, bool ALIGN_EPI = false, bool SP2 = false>
; __device__ __forceinline__ void gemm_phase(PG8_LAS unsigned char* lds, const Gemm g, const Sched& S, const Epi& E) {
;     ...
;             PG8_LDB(B0, 1, 0); PG8_LDB(B1, 1, 1); PG8_SCHED; PG8_LDA(At, 1, 0); PG8_STAGE(PG8_SA(0, 1), a2 + hstepA, voffA);
;             PG8_WAIT_V(8); PG8_WAIT_L(0); PG8_BAR; PG8_MMA(0, 0, At, B0); PG8_MMA(0, 1, At, B1); PG8_BAR; PG8_SCHED;
	s_add_i32 s45, 0, 0x18000
	v_add_u32_e32 v161, s45, v156
	s_add_i32 s49, 0, 0x1c000
	ds_read_b128 v[146:149], v161
	ds_read_b128 v[162:165], v161 offset:1024
	ds_read_b128 v[182:185], v161 offset:2048
	ds_read_b128 v[186:189], v161 offset:3072
	v_add_u32_e32 v161, s49, v156
	ds_read_b128 v[190:193], v161
	ds_read_b128 v[194:197], v161 offset:1024
	ds_read_b128 v[198:201], v161 offset:2048
	ds_read_b128 v[202:205], v161 offset:3072
	s_add_u32 s46, s66, 0x100000
	s_addc_u32 s47, s67, 0
	s_mov_b32 m0, s19
	v_lshl_add_u64 v[244:245], s[46:47], 0, v[130:131]
	ds_read_b128 v[206:209], v160 offset:32768
	ds_read_b128 v[212:215], v160 offset:33792
	ds_read_b128 v[216:219], v160 offset:34816
	ds_read_b128 v[220:223], v160 offset:35840
	ds_read_b128 v[224:227], v160 offset:36864
	ds_read_b128 v[228:231], v160 offset:37888
	ds_read_b128 v[232:235], v160 offset:38912
	ds_read_b128 v[236:239], v160 offset:39936
	global_load_lds_dwordx4 v[244:245], off
	v_lshl_add_u64 v[244:245], s[46:47], 0, v[134:135]
	s_mov_b32 m0, s20
	s_nop 0
	global_load_lds_dwordx4 v[244:245], off
	s_waitcnt vmcnt(8)
	s_waitcnt lgkmcnt(0)
	s_barrier
	s_setprio 1
	s_waitcnt lgkmcnt(0)
	v_mfma_f32_16x16x32_bf16 v[126:129], v[146:149], v[206:209], v[126:129]
	v_mfma_f32_16x16x32_bf16 v[126:129], v[162:165], v[212:215], v[126:129]
	v_mfma_f32_16x16x32_bf16 v[122:125], v[186:189], v[212:215], v[122:125]
	v_mfma_f32_16x16x32_bf16 v[122:125], v[182:185], v[206:209], v[122:125]
	v_mfma_f32_16x16x32_bf16 v[110:113], v[182:185], v[216:219], v[110:113]
	v_mfma_f32_16x16x32_bf16 v[110:113], v[186:189], v[220:223], v[110:113]
	v_mfma_f32_16x16x32_bf16 v[118:121], v[162:165], v[220:223], v[118:121]
	v_mfma_f32_16x16x32_bf16 v[118:121], v[146:149], v[216:219], v[118:121]
	v_mfma_f32_16x16x32_bf16 v[102:105], v[146:149], v[224:227], v[102:105]
	v_mfma_f32_16x16x32_bf16 v[102:105], v[162:165], v[228:231], v[102:105]
	v_mfma_f32_16x16x32_bf16 v[94:97], v[186:189], v[228:231], v[94:97]
	v_mfma_f32_16x16x32_bf16 v[94:97], v[182:185], v[224:227], v[94:97]
	v_mfma_f32_16x16x32_bf16 v[78:81], v[182:185], v[232:235], v[78:81]
	v_mfma_f32_16x16x32_bf16 v[78:81], v[186:189], v[236:239], v[78:81]
	v_mfma_f32_16x16x32_bf16 v[86:89], v[162:165], v[236:239], v[86:89]
	v_mfma_f32_16x16x32_bf16 v[86:89], v[146:149], v[232:235], v[86:89]
	s_setprio 0
	s_setprio 1
	v_mfma_f32_16x16x32_bf16 v[70:73], v[190:193], v[232:235], v[70:73]
	v_mfma_f32_16x16x32_bf16 v[70:73], v[194:197], v[236:239], v[70:73]
	v_mfma_f32_16x16x32_bf16 v[66:69], v[202:205], v[236:239], v[66:69]
	v_mfma_f32_16x16x32_bf16 v[66:69], v[198:201], v[232:235], v[66:69]
	v_mfma_f32_16x16x32_bf16 v[74:77], v[198:201], v[224:227], v[74:77]
	v_mfma_f32_16x16x32_bf16 v[74:77], v[202:205], v[228:231], v[74:77]
	v_mfma_f32_16x16x32_bf16 v[82:85], v[194:197], v[228:231], v[82:85]
	v_mfma_f32_16x16x32_bf16 v[82:85], v[190:193], v[224:227], v[82:85]
	v_mfma_f32_16x16x32_bf16 v[98:101], v[190:193], v[216:219], v[98:101]
	v_mfma_f32_16x16x32_bf16 v[98:101], v[194:197], v[220:223], v[98:101]
	v_mfma_f32_16x16x32_bf16 v[90:93], v[202:205], v[220:223], v[90:93]
	v_mfma_f32_16x16x32_bf16 v[90:93], v[198:201], v[216:219], v[90:93]
	v_mfma_f32_16x16x32_bf16 v[106:109], v[198:201], v[206:209], v[106:109]
	v_mfma_f32_16x16x32_bf16 v[106:109], v[202:205], v[212:215], v[106:109]
	v_mfma_f32_16x16x32_bf16 v[114:117], v[194:197], v[212:215], v[114:117]
	v_mfma_f32_16x16x32_bf16 v[114:117], v[190:193], v[206:209], v[114:117]
	s_setprio 0
	s_barrier
; #define PG8_STAGE(bufoff, gbase, voff) do { _Pragma("unroll") for (int _i = 0; _i < 2; ++_i) \
;         __builtin_amdgcn_global_load_lds((const unsigned*)((const char*)(gbase) + (voff)[_i]), (PG8_LAS unsigned*)(lds + (bufoff) + ldsw + _i * 8192), 16, 0, 0); } while (0)
; #define PG8_LDA(dst, b, h) do { _Pragma("unroll") for (int m = 0; m < 4; ++m) _Pragma("unroll") for (int k = 0; k < 2; ++k) dst[m][k] = *(const PG8_LAS bf16x8*)(lds + PG8_SA(b, h) + aoff + m * 2048 + k * 1024); } while (0)
; #define PG8_MMA(ai, bj, At, Bt) do { __builtin_amdgcn_s_setprio(1); _Pragma("unroll") for (int m = 0; m < 4; ++m) _Pragma("unroll") for (int n = 0; n < 2; ++n) _Pragma("unroll") for (int k = 0; k < 2; ++k) \
;         acc[ai][bj][m][n] = mma16(Bt[n][k], At[m][k], acc[ai][bj][m][n]); __builtin_amdgcn_s_setprio(0); } while (0)
; #define PG8_WAIT_V(n) asm volatile("s_waitcnt vmcnt(" #n ")" ::: "memory")
; #define PG8_WAIT_L(n) asm volatile("s_waitcnt lgkmcnt(" #n ")" ::: "memory")
; #define PG8_BAR __builtin_amdgcn_s_barrier()
; #define PG8_SCHED __builtin_amdgcn_sched_barrier(0)
; template <class Epi, class Sched, bool ALIGN_EPI = false, bool SP2 = false>
; __device__ __forceinline__ void gemm_phase(PG8_LAS unsigned char* lds, const Gemm g, const Sched& S, const Epi& E) {
;     ...
;             PG8_LDA(At, 1, 1); PG8_STAGE(PG8_SB(1, 0), b3, voffB); PG8_STAGE(PG8_SB(1, 1), b3 + hstepB, voffB); PG8_STAGE(PG8_SA(1, 0), a3, voffA);
;             PG8_WAIT_V(8); PG8_WAIT_L(0); PG8_BAR; PG8_MMA(1, 0, At, B0); PG8_MMA(1, 1, At, B1); PG8_BAR; PG8_SCHED;
;     ...
;         if constexpr (ALIGN_EPI) { if (wr == 0) PG8_BAR; }
	s_add_i32 s45, s45, s12
	v_lshl_add_u64 v[166:167], v[166:167], 0, s[40:41]
	s_mov_b32 m0, s45
	ds_read_b128 v[206:209], v160 offset:49152
	ds_read_b128 v[212:215], v160 offset:50176
	ds_read_b128 v[216:219], v160 offset:51200
	ds_read_b128 v[220:223], v160 offset:52224
	ds_read_b128 v[224:227], v160 offset:53248
	ds_read_b128 v[228:231], v160 offset:54272
	ds_read_b128 v[232:235], v160 offset:55296
	ds_read_b128 v[236:239], v160 offset:56320
	global_load_lds_dwordx4 v[166:167], off
	s_add_i32 m0, s45, 0x2000
	s_add_u32 s46, s64, 0x100080
	v_lshl_add_u64 v[166:167], v[176:177], 0, s[40:41]
	s_addc_u32 s47, s65, 0
	s_add_i32 s45, s49, s12
	global_load_lds_dwordx4 v[166:167], off
	v_lshl_add_u64 v[166:167], s[46:47], 0, v[132:133]
	s_mov_b32 m0, s45
	s_nop 0
	global_load_lds_dwordx4 v[166:167], off
	v_lshl_add_u64 v[166:167], s[46:47], 0, v[136:137]
	s_add_i32 m0, s45, 0x2000
	s_nop 0
	global_load_lds_dwordx4 v[166:167], off
	v_lshl_add_u64 v[166:167], v[240:241], 0, s[40:41]
	s_mov_b32 m0, s22
	s_nop 0
	global_load_lds_dwordx4 v[166:167], off
	v_lshl_add_u64 v[166:167], v[242:243], 0, s[40:41]
	s_mov_b32 m0, s23
	s_nop 0
	global_load_lds_dwordx4 v[166:167], off
	s_waitcnt vmcnt(8)
	s_waitcnt lgkmcnt(0)
	s_barrier
	s_setprio 1
	s_waitcnt lgkmcnt(0)
	v_mfma_f32_16x16x32_bf16 v[62:65], v[146:149], v[206:209], v[62:65]
	v_mfma_f32_16x16x32_bf16 v[62:65], v[162:165], v[212:215], v[62:65]
	v_mfma_f32_16x16x32_bf16 v[58:61], v[186:189], v[212:215], v[58:61]
	v_mfma_f32_16x16x32_bf16 v[58:61], v[182:185], v[206:209], v[58:61]
	v_mfma_f32_16x16x32_bf16 v[46:49], v[182:185], v[216:219], v[46:49]
	v_mfma_f32_16x16x32_bf16 v[46:49], v[186:189], v[220:223], v[46:49]
	v_mfma_f32_16x16x32_bf16 v[54:57], v[162:165], v[220:223], v[54:57]
	v_mfma_f32_16x16x32_bf16 v[54:57], v[146:149], v[216:219], v[54:57]
	v_mfma_f32_16x16x32_bf16 v[38:41], v[146:149], v[224:227], v[38:41]
	v_mfma_f32_16x16x32_bf16 v[38:41], v[162:165], v[228:231], v[38:41]
	v_mfma_f32_16x16x32_bf16 v[30:33], v[186:189], v[228:231], v[30:33]
	v_mfma_f32_16x16x32_bf16 v[30:33], v[182:185], v[224:227], v[30:33]
	v_mfma_f32_16x16x32_bf16 v[14:17], v[182:185], v[232:235], v[14:17]
	v_mfma_f32_16x16x32_bf16 v[14:17], v[186:189], v[236:239], v[14:17]
	v_mfma_f32_16x16x32_bf16 v[22:25], v[162:165], v[236:239], v[22:25]
	v_mfma_f32_16x16x32_bf16 v[22:25], v[146:149], v[232:235], v[22:25]
	s_setprio 0
	s_setprio 1
	v_mfma_f32_16x16x32_bf16 v[6:9], v[190:193], v[232:235], v[6:9]
	v_mfma_f32_16x16x32_bf16 v[6:9], v[194:197], v[236:239], v[6:9]
	v_mfma_f32_16x16x32_bf16 v[2:5], v[202:205], v[236:239], v[2:5]
	v_mfma_f32_16x16x32_bf16 v[2:5], v[198:201], v[232:235], v[2:5]
	v_mfma_f32_16x16x32_bf16 v[10:13], v[198:201], v[224:227], v[10:13]
	v_mfma_f32_16x16x32_bf16 v[10:13], v[202:205], v[228:231], v[10:13]
	v_mfma_f32_16x16x32_bf16 v[18:21], v[194:197], v[228:231], v[18:21]
	v_mfma_f32_16x16x32_bf16 v[18:21], v[190:193], v[224:227], v[18:21]
	v_mfma_f32_16x16x32_bf16 v[34:37], v[190:193], v[216:219], v[34:37]
	v_mfma_f32_16x16x32_bf16 v[34:37], v[194:197], v[220:223], v[34:37]
	v_mfma_f32_16x16x32_bf16 v[26:29], v[202:205], v[220:223], v[26:29]
	v_mfma_f32_16x16x32_bf16 v[26:29], v[198:201], v[216:219], v[26:29]
	v_mfma_f32_16x16x32_bf16 v[42:45], v[198:201], v[206:209], v[42:45]
	v_mfma_f32_16x16x32_bf16 v[42:45], v[202:205], v[212:215], v[42:45]
	v_mfma_f32_16x16x32_bf16 v[50:53], v[194:197], v[212:215], v[50:53]
	v_mfma_f32_16x16x32_bf16 v[50:53], v[190:193], v[206:209], v[50:53]
	s_setprio 0
	s_barrier
	s_add_i32 s37, s37, 2
	s_add_u32 s0, s0, 0x100
	s_addc_u32 s1, s1, 0
	s_add_u32 s35, s35, 0x100
	s_addc_u32 s36, s36, 0
	s_cmp_gt_u32 s37, 61
	s_cbranch_scc0 .LBB0_231
	s_and_b64 vcc, exec, s[42:43]
	s_cbranch_vccz .LBB0_234
	s_barrier

; #define PG8_STAGE(bufoff, gbase, voff) do { _Pragma("unroll") for (int _i = 0; _i < 2; ++_i) \
;         __builtin_amdgcn_global_load_lds((const unsigned*)((const char*)(gbase) + (voff)[_i]), (PG8_LAS unsigned*)(lds + (bufoff) + ldsw + _i * 8192), 16, 0, 0); } while (0)
; #define PG8_LDA(dst, b, h) do { _Pragma("unroll") for (int m = 0; m < 4; ++m) _Pragma("unroll") for (int k = 0; k < 2; ++k) dst[m][k] = *(const PG8_LAS bf16x8*)(lds + PG8_SA(b, h) + aoff + m * 2048 + k * 1024); } while (0)
; #define PG8_LDB(dst, b, h) do { _Pragma("unroll") for (int n = 0; n < 2; ++n) _Pragma("unroll") for (int k = 0; k < 2; ++k) dst[n][k] = *(const PG8_LAS bf16x8*)(lds + PG8_SB(b, h) + boff + n * 2048 + k * 1024); } while (0)
; #define PG8_MMA(ai, bj, At, Bt) do { __builtin_amdgcn_s_setprio(1); _Pragma("unroll") for (int m = 0; m < 4; ++m) _Pragma("unroll") for (int n = 0; n < 2; ++n) _Pragma("unroll") for (int k = 0; k < 2; ++k) \
;         acc[ai][bj][m][n] = mma16(Bt[n][k], At[m][k], acc[ai][bj][m][n]); __builtin_amdgcn_s_setprio(0); } while (0)
; #define PG8_WAIT_V(n) asm volatile("s_waitcnt vmcnt(" #n ")" ::: "memory")
; #define PG8_WAIT_L(n) asm volatile("s_waitcnt lgkmcnt(" #n ")" ::: "memory")
; #define PG8_BAR __builtin_amdgcn_s_barrier()
; #define PG8_SCHED __builtin_amdgcn_sched_barrier(0)
; template <class Epi, class Sched, bool ALIGN_EPI = false, bool SP2 = false>
; __device__ __forceinline__ void gemm_phase(PG8_LAS unsigned char* lds, const Gemm g, const Sched& S, const Epi& E) {
;     ...
;         for (int t = 0; t < nt; t += 2) {
;             const bool last = (t == nt - 2);
;             const char* a1 = cA + (size_t)(t + 1) * kstep;
;             const char* a2 = last ? nA : cA + (size_t)(t + 2) * kstep; const char* b2 = last ? nB : cB + (size_t)(t + 2) * kstep;
;             const char* a3 = a2 + kstep; const char* b3 = b2 + kstep;
;             if (last && has_next) S.a_ready(nxt);
;             if constexpr (SP2) {
;             PG8_LDB(B0, 0, 0); PG8_LDB(B1, 0, 1); PG8_SCHED; PG8_LDA(At, 0, 0); PG8_STAGE(PG8_SA(1, 1), a1 + hstepA, voffA);
;             PG8_WAIT_V(8); PG8_WAIT_L(0); PG8_BAR; PG8_MMA(0, 0, At, B0); PG8_MMA(0, 1, At, B1); PG8_BAR; PG8_SCHED;
;             PG8_LDA(At, 0, 1); PG8_STAGE(PG8_SB(0, 0), b2, voffB); PG8_STAGE(PG8_SB(0, 1), b2 + hstepB, voffB); PG8_STAGE(PG8_SA(0, 0), a2, voffA);
.LBB0_248:
	s_ashr_i32 s59, s58, 31
	s_lshl_b64 s[36:37], s[58:59], 20
	s_add_u32 s66, s74, s36
	s_addc_u32 s67, s75, s37
	s_and_b64 s[0:1], s[0:1], exec
	s_cselect_b32 s36, s67, s95
	s_cselect_b32 s37, s66, s94
	s_add_u32 s0, s96, 0x80080
	s_addc_u32 s1, s97, 0
	s_add_u32 s46, s94, 0x100
	s_addc_u32 s47, s95, 0
	s_mov_b32 s50, -2
	ds_read_b128 v[122:125], v181
	ds_read_b128 v[126:129], v181 offset:1024
	ds_read_b128 v[134:137], v181 offset:2048
	ds_read_b128 v[142:145], v181 offset:3072
	ds_read_b128 v[184:187], v182
	ds_read_b128 v[188:191], v182 offset:1024
	ds_read_b128 v[192:195], v182 offset:2048
	ds_read_b128 v[196:199], v182 offset:3072
	s_add_u32 s51, s0, 0xfff80080
	s_addc_u32 s63, s1, -1
	s_cmp_eq_u32 s50, 28
	s_cselect_b32 s95, s65, s63
	s_cselect_b32 s94, s64, s51
	s_cselect_b32 s91, s36, s47
	s_cselect_b32 s90, s37, s46
	v_lshl_add_u64 v[166:167], s[0:1], 0, v[158:159]
	s_add_i32 m0, s13, 0xc000
	ds_read_b128 v[200:203], v183
	ds_read_b128 v[204:207], v183 offset:1024
	ds_read_b128 v[212:215], v183 offset:2048
	ds_read_b128 v[216:219], v183 offset:3072
	ds_read_b128 v[220:223], v183 offset:4096
	ds_read_b128 v[224:227], v183 offset:5120
	ds_read_b128 v[228:231], v183 offset:6144
	ds_read_b128 v[232:235], v183 offset:7168
	global_load_lds_dwordx4 v[166:167], off
	v_lshl_add_u64 v[166:167], s[0:1], 0, v[160:161]
	s_add_i32 m0, s13, 0xe000
	s_nop 0
	global_load_lds_dwordx4 v[166:167], off
	s_waitcnt vmcnt(8)
	s_waitcnt lgkmcnt(0)
	s_barrier
	s_setprio 1
	s_waitcnt lgkmcnt(0)
	v_mfma_i32_16x16x64_i8 v[138:141], v[122:125], v[200:203], 0
	v_mfma_i32_16x16x64_i8 v[138:141], v[126:129], v[204:207], v[138:141]
	v_mfma_i32_16x16x64_i8 v[130:133], v[142:145], v[204:207], 0
	v_mfma_i32_16x16x64_i8 v[130:133], v[134:137], v[200:203], v[130:133]
	v_mfma_i32_16x16x64_i8 v[106:109], v[134:137], v[212:215], 0
	v_mfma_i32_16x16x64_i8 v[106:109], v[142:145], v[216:219], v[106:109]
	v_mfma_i32_16x16x64_i8 v[110:113], v[126:129], v[216:219], 0
	v_mfma_i32_16x16x64_i8 v[110:113], v[122:125], v[212:215], v[110:113]
	v_mfma_i32_16x16x64_i8 v[94:97], v[122:125], v[220:223], 0
	v_mfma_i32_16x16x64_i8 v[94:97], v[126:129], v[224:227], v[94:97]
	v_mfma_i32_16x16x64_i8 v[90:93], v[142:145], v[224:227], 0
	v_mfma_i32_16x16x64_i8 v[90:93], v[134:137], v[220:223], v[90:93]
	v_mfma_i32_16x16x64_i8 v[74:77], v[134:137], v[228:231], 0
	v_mfma_i32_16x16x64_i8 v[74:77], v[142:145], v[232:235], v[74:77]
	v_mfma_i32_16x16x64_i8 v[78:81], v[126:129], v[232:235], 0
	v_mfma_i32_16x16x64_i8 v[78:81], v[122:125], v[228:231], v[78:81]
	s_setprio 0
	s_setprio 1
	v_mfma_i32_16x16x64_i8 v[70:73], v[184:187], v[228:231], 0
	v_mfma_i32_16x16x64_i8 v[70:73], v[188:191], v[232:235], v[70:73]
	v_mfma_i32_16x16x64_i8 v[66:69], v[196:199], v[232:235], 0
	v_mfma_i32_16x16x64_i8 v[66:69], v[192:195], v[228:231], v[66:69]
	v_mfma_i32_16x16x64_i8 v[82:85], v[192:195], v[220:223], 0
	v_mfma_i32_16x16x64_i8 v[82:85], v[196:199], v[224:227], v[82:85]
	v_mfma_i32_16x16x64_i8 v[86:89], v[188:191], v[224:227], 0
	v_mfma_i32_16x16x64_i8 v[86:89], v[184:187], v[220:223], v[86:89]
	v_mfma_i32_16x16x64_i8 v[102:105], v[184:187], v[212:215], 0
	v_mfma_i32_16x16x64_i8 v[102:105], v[188:191], v[216:219], v[102:105]
	v_mfma_i32_16x16x64_i8 v[98:101], v[196:199], v[216:219], 0
	v_mfma_i32_16x16x64_i8 v[98:101], v[192:195], v[212:215], v[98:101]
	v_mfma_i32_16x16x64_i8 v[114:117], v[192:195], v[200:203], 0
	v_mfma_i32_16x16x64_i8 v[114:117], v[196:199], v[204:207], v[114:117]
	v_mfma_i32_16x16x64_i8 v[118:121], v[188:191], v[204:207], 0
	v_mfma_i32_16x16x64_i8 v[118:121], v[184:187], v[200:203], v[118:121]
	s_setprio 0
	s_barrier
	s_add_i32 s51, s27, s7
	v_lshl_add_u64 v[166:167], s[90:91], 0, v[148:149]
	s_mov_b32 m0, s51
	ds_read_b128 v[200:203], v183 offset:16384
	ds_read_b128 v[204:207], v183 offset:17408
	ds_read_b128 v[212:215], v183 offset:18432
	ds_read_b128 v[216:219], v183 offset:19456
	ds_read_b128 v[220:223], v183 offset:20480
	ds_read_b128 v[224:227], v183 offset:21504
	ds_read_b128 v[228:231], v183 offset:22528
	ds_read_b128 v[232:235], v183 offset:23552
	global_load_lds_dwordx4 v[166:167], off
	s_add_i32 m0, s51, 0x2000
	s_add_u32 s68, s90, 0x80000
	v_lshl_add_u64 v[208:209], s[90:91], 0, v[152:153]
	s_addc_u32 s69, s91, 0
	s_add_i32 s51, s28, s7
	global_load_lds_dwordx4 v[208:209], off
	v_lshl_add_u64 v[236:237], s[68:69], 0, v[148:149]
	s_mov_b32 m0, s51
	v_lshl_add_u64 v[238:239], s[94:95], 0, v[150:151]
	global_load_lds_dwordx4 v[236:237], off
	v_lshl_add_u64 v[236:237], s[68:69], 0, v[152:153]
	s_add_i32 m0, s51, 0x2000
	s_nop 0
	global_load_lds_dwordx4 v[236:237], off
	v_lshl_add_u64 v[236:237], s[94:95], 0, v[146:147]
	s_mov_b32 m0, s13
	s_nop 0
	global_load_lds_dwordx4 v[236:237], off
	s_mov_b32 m0, s18
	s_nop 0
	global_load_lds_dwordx4 v[238:239], off
	s_waitcnt vmcnt(8)
	s_waitcnt lgkmcnt(0)
	s_barrier
; #define PG8_STAGE(bufoff, gbase, voff) do { _Pragma("unroll") for (int _i = 0; _i < 2; ++_i) \
;         __builtin_amdgcn_global_load_lds((const unsigned*)((const char*)(gbase) + (voff)[_i]), (PG8_LAS unsigned*)(lds + (bufoff) + ldsw + _i * 8192), 16, 0, 0); } while (0)
; #define PG8_LDA(dst, b, h) do { _Pragma("unroll") for (int m = 0; m < 4; ++m) _Pragma("unroll") for (int k = 0; k < 2; ++k) dst[m][k] = *(const PG8_LAS bf16x8*)(lds + PG8_SA(b, h) + aoff + m * 2048 + k * 1024); } while (0)
; #define PG8_LDB(dst, b, h) do { _Pragma("unroll") for (int n = 0; n < 2; ++n) _Pragma("unroll") for (int k = 0; k < 2; ++k) dst[n][k] = *(const PG8_LAS bf16x8*)(lds + PG8_SB(b, h) + boff + n * 2048 + k * 1024); } while (0)
; #define PG8_MMA(ai, bj, At, Bt) do { __builtin_amdgcn_s_setprio(1); _Pragma("unroll") for (int m = 0; m < 4; ++m) _Pragma("unroll") for (int n = 0; n < 2; ++n) _Pragma("unroll") for (int k = 0; k < 2; ++k) \
;         acc[ai][bj][m][n] = mma16(Bt[n][k], At[m][k], acc[ai][bj][m][n]); __builtin_amdgcn_s_setprio(0); } while (0)
; #define PG8_WAIT_V(n) asm volatile("s_waitcnt vmcnt(" #n ")" ::: "memory")
; #define PG8_WAIT_L(n) asm volatile("s_waitcnt lgkmcnt(" #n ")" ::: "memory")
; #define PG8_BAR __builtin_amdgcn_s_barrier()
; #define PG8_SCHED __builtin_amdgcn_sched_barrier(0)
; template <class Epi, class Sched, bool ALIGN_EPI = false, bool SP2 = false>
; __device__ __forceinline__ void gemm_phase(PG8_LAS unsigned char* lds, const Gemm g, const Sched& S, const Epi& E) {
;     ...
;             PG8_WAIT_V(8); PG8_WAIT_L(0); PG8_BAR; PG8_MMA(0, 0, At, B0); PG8_MMA(0, 1, At, B1); PG8_BAR; PG8_SCHED;
;             PG8_LDA(At, 0, 1); PG8_STAGE(PG8_SB(0, 0), b2, voffB); PG8_STAGE(PG8_SB(0, 1), b2 + hstepB, voffB); PG8_STAGE(PG8_SA(0, 0), a2, voffA);
;             PG8_WAIT_V(8); PG8_WAIT_L(0); PG8_BAR; PG8_MMA(1, 0, At, B0); PG8_MMA(1, 1, At, B1); PG8_BAR; PG8_SCHED;
;             PG8_LDB(B0, 1, 0); PG8_LDB(B1, 1, 1); PG8_SCHED; PG8_LDA(At, 1, 0); PG8_STAGE(PG8_SA(0, 1), a2 + hstepA, voffA);
;             PG8_WAIT_V(8); PG8_WAIT_L(0); PG8_BAR; PG8_MMA(0, 0, At, B0); PG8_MMA(0, 1, At, B1); PG8_BAR; PG8_SCHED;
	s_setprio 1
	s_waitcnt lgkmcnt(0)
	v_mfma_i32_16x16x64_i8 v[62:65], v[122:125], v[200:203], 0
	v_mfma_i32_16x16x64_i8 v[62:65], v[126:129], v[204:207], v[62:65]
	v_mfma_i32_16x16x64_i8 v[58:61], v[142:145], v[204:207], 0
	v_mfma_i32_16x16x64_i8 v[58:61], v[134:137], v[200:203], v[58:61]
	v_mfma_i32_16x16x64_i8 v[42:45], v[134:137], v[212:215], 0
	v_mfma_i32_16x16x64_i8 v[42:45], v[142:145], v[216:219], v[42:45]
	v_mfma_i32_16x16x64_i8 v[46:49], v[126:129], v[216:219], 0
	v_mfma_i32_16x16x64_i8 v[46:49], v[122:125], v[212:215], v[46:49]
	v_mfma_i32_16x16x64_i8 v[30:33], v[122:125], v[220:223], 0
	v_mfma_i32_16x16x64_i8 v[30:33], v[126:129], v[224:227], v[30:33]
	v_mfma_i32_16x16x64_i8 v[26:29], v[142:145], v[224:227], 0
	v_mfma_i32_16x16x64_i8 v[26:29], v[134:137], v[220:223], v[26:29]
	v_mfma_i32_16x16x64_i8 v[10:13], v[134:137], v[228:231], 0
	v_mfma_i32_16x16x64_i8 v[10:13], v[142:145], v[232:235], v[10:13]
	v_mfma_i32_16x16x64_i8 v[14:17], v[126:129], v[232:235], 0
	v_mfma_i32_16x16x64_i8 v[14:17], v[122:125], v[228:231], v[14:17]
	s_setprio 0
	s_setprio 1
	v_mfma_i32_16x16x64_i8 v[6:9], v[184:187], v[228:231], 0
	v_mfma_i32_16x16x64_i8 v[6:9], v[188:191], v[232:235], v[6:9]
	v_mfma_i32_16x16x64_i8 v[2:5], v[196:199], v[232:235], 0
	v_mfma_i32_16x16x64_i8 v[2:5], v[192:195], v[228:231], v[2:5]
	v_mfma_i32_16x16x64_i8 v[18:21], v[192:195], v[220:223], 0
	v_mfma_i32_16x16x64_i8 v[18:21], v[196:199], v[224:227], v[18:21]
	v_mfma_i32_16x16x64_i8 v[22:25], v[188:191], v[224:227], 0
	v_mfma_i32_16x16x64_i8 v[22:25], v[184:187], v[220:223], v[22:25]
	v_mfma_i32_16x16x64_i8 v[38:41], v[184:187], v[212:215], 0
	v_mfma_i32_16x16x64_i8 v[38:41], v[188:191], v[216:219], v[38:41]
	v_mfma_i32_16x16x64_i8 v[34:37], v[196:199], v[216:219], 0
	v_mfma_i32_16x16x64_i8 v[34:37], v[192:195], v[212:215], v[34:37]
	v_mfma_i32_16x16x64_i8 v[50:53], v[192:195], v[200:203], 0
	v_mfma_i32_16x16x64_i8 v[50:53], v[196:199], v[204:207], v[50:53]
	v_mfma_i32_16x16x64_i8 v[54:57], v[188:191], v[204:207], 0
	v_mfma_i32_16x16x64_i8 v[54:57], v[184:187], v[200:203], v[54:57]
	s_setprio 0
	s_barrier
	s_add_i32 s51, 0, 0x18000
	s_add_i32 s63, 0, 0x1c000
	v_add_u32_e32 v142, s51, v176
	v_add_u32_e32 v196, s63, v176
	ds_read_b128 v[122:125], v142
	ds_read_b128 v[126:129], v142 offset:1024
	ds_read_b128 v[134:137], v142 offset:2048
	ds_read_b128 v[142:145], v142 offset:3072
	ds_read_b128 v[184:187], v196
	ds_read_b128 v[188:191], v196 offset:1024
	ds_read_b128 v[192:195], v196 offset:2048
	ds_read_b128 v[196:199], v196 offset:3072
	s_add_u32 s68, s94, 0x80000
	s_addc_u32 s69, s95, 0
	s_mov_b32 m0, s19
	v_lshl_add_u64 v[240:241], s[68:69], 0, v[146:147]
	ds_read_b128 v[200:203], v183 offset:32768
	ds_read_b128 v[204:207], v183 offset:33792
	ds_read_b128 v[212:215], v183 offset:34816
	ds_read_b128 v[216:219], v183 offset:35840
	ds_read_b128 v[220:223], v183 offset:36864
	ds_read_b128 v[224:227], v183 offset:37888
	ds_read_b128 v[228:231], v183 offset:38912
	ds_read_b128 v[232:235], v183 offset:39936
	global_load_lds_dwordx4 v[240:241], off
	v_lshl_add_u64 v[240:241], s[68:69], 0, v[150:151]
	s_mov_b32 m0, s20
	s_nop 0
	global_load_lds_dwordx4 v[240:241], off
	s_waitcnt vmcnt(8)
	s_waitcnt lgkmcnt(0)
	s_barrier
	s_setprio 1
	s_waitcnt lgkmcnt(0)
	v_mfma_i32_16x16x64_i8 v[138:141], v[122:125], v[200:203], v[138:141]
	v_mfma_i32_16x16x64_i8 v[138:141], v[126:129], v[204:207], v[138:141]
	v_mfma_i32_16x16x64_i8 v[130:133], v[142:145], v[204:207], v[130:133]
	v_mfma_i32_16x16x64_i8 v[130:133], v[134:137], v[200:203], v[130:133]
	v_mfma_i32_16x16x64_i8 v[106:109], v[134:137], v[212:215], v[106:109]
	v_mfma_i32_16x16x64_i8 v[106:109], v[142:145], v[216:219], v[106:109]
	v_mfma_i32_16x16x64_i8 v[110:113], v[126:129], v[216:219], v[110:113]
	v_mfma_i32_16x16x64_i8 v[110:113], v[122:125], v[212:215], v[110:113]
	v_mfma_i32_16x16x64_i8 v[94:97], v[122:125], v[220:223], v[94:97]
	v_mfma_i32_16x16x64_i8 v[94:97], v[126:129], v[224:227], v[94:97]
	v_mfma_i32_16x16x64_i8 v[90:93], v[142:145], v[224:227], v[90:93]
	v_mfma_i32_16x16x64_i8 v[90:93], v[134:137], v[220:223], v[90:93]
	v_mfma_i32_16x16x64_i8 v[74:77], v[134:137], v[228:231], v[74:77]
	v_mfma_i32_16x16x64_i8 v[74:77], v[142:145], v[232:235], v[74:77]
	v_mfma_i32_16x16x64_i8 v[78:81], v[126:129], v[232:235], v[78:81]
	v_mfma_i32_16x16x64_i8 v[78:81], v[122:125], v[228:231], v[78:81]
	s_setprio 0
	s_setprio 1
	v_mfma_i32_16x16x64_i8 v[70:73], v[184:187], v[228:231], v[70:73]
	v_mfma_i32_16x16x64_i8 v[70:73], v[188:191], v[232:235], v[70:73]
	v_mfma_i32_16x16x64_i8 v[66:69], v[196:199], v[232:235], v[66:69]
	v_mfma_i32_16x16x64_i8 v[66:69], v[192:195], v[228:231], v[66:69]
	v_mfma_i32_16x16x64_i8 v[82:85], v[192:195], v[220:223], v[82:85]
	v_mfma_i32_16x16x64_i8 v[82:85], v[196:199], v[224:227], v[82:85]
	v_mfma_i32_16x16x64_i8 v[86:89], v[188:191], v[224:227], v[86:89]
	v_mfma_i32_16x16x64_i8 v[86:89], v[184:187], v[220:223], v[86:89]
	v_mfma_i32_16x16x64_i8 v[102:105], v[184:187], v[212:215], v[102:105]
	v_mfma_i32_16x16x64_i8 v[102:105], v[188:191], v[216:219], v[102:105]
	v_mfma_i32_16x16x64_i8 v[98:101], v[196:199], v[216:219], v[98:101]
	v_mfma_i32_16x16x64_i8 v[98:101], v[192:195], v[212:215], v[98:101]
	v_mfma_i32_16x16x64_i8 v[114:117], v[192:195], v[200:203], v[114:117]
	v_mfma_i32_16x16x64_i8 v[114:117], v[196:199], v[204:207], v[114:117]
	v_mfma_i32_16x16x64_i8 v[118:121], v[188:191], v[204:207], v[118:121]
	v_mfma_i32_16x16x64_i8 v[118:121], v[184:187], v[200:203], v[118:121]
	s_setprio 0
	s_barrier
; #define PG8_STAGE(bufoff, gbase, voff) do { _Pragma("unroll") for (int _i = 0; _i < 2; ++_i) \
;         __builtin_amdgcn_global_load_lds((const unsigned*)((const char*)(gbase) + (voff)[_i]), (PG8_LAS unsigned*)(lds + (bufoff) + ldsw + _i * 8192), 16, 0, 0); } while (0)
; #define PG8_LDA(dst, b, h) do { _Pragma("unroll") for (int m = 0; m < 4; ++m) _Pragma("unroll") for (int k = 0; k < 2; ++k) dst[m][k] = *(const PG8_LAS bf16x8*)(lds + PG8_SA(b, h) + aoff + m * 2048 + k * 1024); } while (0)
; #define PG8_LDB(dst, b, h) do { _Pragma("unroll") for (int n = 0; n < 2; ++n) _Pragma("unroll") for (int k = 0; k < 2; ++k) dst[n][k] = *(const PG8_LAS bf16x8*)(lds + PG8_SB(b, h) + boff + n * 2048 + k * 1024); } while (0)
; template <class Epi, class Sched, bool ALIGN_EPI = false, bool SP2 = false>
; __device__ __forceinline__ void gemm_phase(PG8_LAS unsigned char* lds, const Gemm g, const Sched& S, const Epi& E) {
;     ...
;         for (int t = 0; t < nt; t += 2) {
;             const bool last = (t == nt - 2);
;             const char* a1 = cA + (size_t)(t + 1) * kstep;
;             const char* a2 = last ? nA : cA + (size_t)(t + 2) * kstep; const char* b2 = last ? nB : cB + (size_t)(t + 2) * kstep;
;             const char* a3 = a2 + kstep; const char* b3 = b2 + kstep;
;             if (last && has_next) S.a_ready(nxt);
;             if constexpr (SP2) {
;             PG8_LDB(B0, 0, 0); PG8_LDB(B1, 0, 1); PG8_SCHED; PG8_LDA(At, 0, 0); PG8_STAGE(PG8_SA(1, 1), a1 + hstepA, voffA);
;             PG8_WAIT_V(8); PG8_WAIT_L(0); PG8_BAR; PG8_MMA(0, 0, At, B0); PG8_MMA(0, 1, At, B1); PG8_BAR; PG8_SCHED;
;             PG8_LDA(At, 0, 1); PG8_STAGE(PG8_SB(0, 0), b2, voffB); PG8_STAGE(PG8_SB(0, 1), b2 + hstepB, voffB); PG8_STAGE(PG8_SA(0, 0), a2, voffA);
;             PG8_WAIT_V(8); PG8_WAIT_L(0); PG8_BAR; PG8_MMA(1, 0, At, B0); PG8_MMA(1, 1, At, B1); PG8_BAR; PG8_SCHED;
;             PG8_LDB(B0, 1, 0); PG8_LDB(B1, 1, 1); PG8_SCHED; PG8_LDA(At, 1, 0); PG8_STAGE(PG8_SA(0, 1), a2 + hstepA, voffA);
;             PG8_WAIT_V(8); PG8_WAIT_L(0); PG8_BAR; PG8_MMA(0, 0, At, B0); PG8_MMA(0, 1, At, B1); PG8_BAR; PG8_SCHED;
;             PG8_LDA(At, 1, 1); PG8_STAGE(PG8_SB(1, 0), b3, voffB); PG8_STAGE(PG8_SB(1, 1), b3 + hstepB, voffB); PG8_STAGE(PG8_SA(1, 0), a3, voffA);
;             PG8_WAIT_V(8); PG8_WAIT_L(0); PG8_BAR; PG8_MMA(1, 0, At, B0); PG8_MMA(1, 1, At, B1); PG8_BAR; PG8_SCHED;
	s_add_i32 s51, s51, s7
	v_lshl_add_u64 v[166:167], v[166:167], 0, s[48:49]
	s_mov_b32 m0, s51
	ds_read_b128 v[200:203], v183 offset:49152
	ds_read_b128 v[204:207], v183 offset:50176
	ds_read_b128 v[212:215], v183 offset:51200
	ds_read_b128 v[216:219], v183 offset:52224
	ds_read_b128 v[220:223], v183 offset:53248
	ds_read_b128 v[224:227], v183 offset:54272
	ds_read_b128 v[228:231], v183 offset:55296
	ds_read_b128 v[232:235], v183 offset:56320
	global_load_lds_dwordx4 v[166:167], off
	s_add_i32 m0, s51, 0x2000
	s_add_u32 s68, s90, 0x80080
	v_lshl_add_u64 v[166:167], v[208:209], 0, s[48:49]
	s_addc_u32 s69, s91, 0
	s_add_i32 s51, s63, s7
	global_load_lds_dwordx4 v[166:167], off
	v_lshl_add_u64 v[166:167], s[68:69], 0, v[148:149]
	s_mov_b32 m0, s51
	s_nop 0
	global_load_lds_dwordx4 v[166:167], off
	v_lshl_add_u64 v[166:167], s[68:69], 0, v[152:153]
	s_add_i32 m0, s51, 0x2000
	s_nop 0
	global_load_lds_dwordx4 v[166:167], off
	v_lshl_add_u64 v[166:167], v[236:237], 0, s[48:49]
	s_mov_b32 m0, s23
	s_nop 0
	global_load_lds_dwordx4 v[166:167], off
	v_lshl_add_u64 v[166:167], v[238:239], 0, s[48:49]
	s_mov_b32 m0, s24
	s_nop 0
	global_load_lds_dwordx4 v[166:167], off
	s_waitcnt vmcnt(8)
	s_waitcnt lgkmcnt(0)
	s_barrier
	s_setprio 1
	s_waitcnt lgkmcnt(0)
	v_mfma_i32_16x16x64_i8 v[62:65], v[122:125], v[200:203], v[62:65]
	v_mfma_i32_16x16x64_i8 v[62:65], v[126:129], v[204:207], v[62:65]
	v_mfma_i32_16x16x64_i8 v[58:61], v[142:145], v[204:207], v[58:61]
	v_mfma_i32_16x16x64_i8 v[58:61], v[134:137], v[200:203], v[58:61]
	v_mfma_i32_16x16x64_i8 v[42:45], v[134:137], v[212:215], v[42:45]
	v_mfma_i32_16x16x64_i8 v[42:45], v[142:145], v[216:219], v[42:45]
	v_mfma_i32_16x16x64_i8 v[46:49], v[126:129], v[216:219], v[46:49]
	v_mfma_i32_16x16x64_i8 v[46:49], v[122:125], v[212:215], v[46:49]
	v_mfma_i32_16x16x64_i8 v[30:33], v[122:125], v[220:223], v[30:33]
	v_mfma_i32_16x16x64_i8 v[30:33], v[126:129], v[224:227], v[30:33]
	v_mfma_i32_16x16x64_i8 v[26:29], v[142:145], v[224:227], v[26:29]
	v_mfma_i32_16x16x64_i8 v[26:29], v[134:137], v[220:223], v[26:29]
	v_mfma_i32_16x16x64_i8 v[10:13], v[134:137], v[228:231], v[10:13]
	v_mfma_i32_16x16x64_i8 v[10:13], v[142:145], v[232:235], v[10:13]
	v_mfma_i32_16x16x64_i8 v[14:17], v[126:129], v[232:235], v[14:17]
	v_mfma_i32_16x16x64_i8 v[14:17], v[122:125], v[228:231], v[14:17]
	s_setprio 0
	s_setprio 1
	v_mfma_i32_16x16x64_i8 v[6:9], v[184:187], v[228:231], v[6:9]
	v_mfma_i32_16x16x64_i8 v[6:9], v[188:191], v[232:235], v[6:9]
	v_mfma_i32_16x16x64_i8 v[2:5], v[196:199], v[232:235], v[2:5]
	v_mfma_i32_16x16x64_i8 v[2:5], v[192:195], v[228:231], v[2:5]
	v_mfma_i32_16x16x64_i8 v[18:21], v[192:195], v[220:223], v[18:21]
	v_mfma_i32_16x16x64_i8 v[18:21], v[196:199], v[224:227], v[18:21]
	v_mfma_i32_16x16x64_i8 v[22:25], v[188:191], v[224:227], v[22:25]
	v_mfma_i32_16x16x64_i8 v[22:25], v[184:187], v[220:223], v[22:25]
	v_mfma_i32_16x16x64_i8 v[38:41], v[184:187], v[212:215], v[38:41]
	v_mfma_i32_16x16x64_i8 v[38:41], v[188:191], v[216:219], v[38:41]
	v_mfma_i32_16x16x64_i8 v[34:37], v[196:199], v[216:219], v[34:37]
	v_mfma_i32_16x16x64_i8 v[34:37], v[192:195], v[212:215], v[34:37]
	v_mfma_i32_16x16x64_i8 v[50:53], v[192:195], v[200:203], v[50:53]
	v_mfma_i32_16x16x64_i8 v[50:53], v[196:199], v[204:207], v[50:53]
	v_mfma_i32_16x16x64_i8 v[54:57], v[188:191], v[204:207], v[54:57]
	v_mfma_i32_16x16x64_i8 v[54:57], v[184:187], v[200:203], v[54:57]
	s_setprio 0
	s_barrier
	s_add_i32 s50, s50, 2
	s_add_u32 s0, s0, 0x100
	s_addc_u32 s1, s1, 0
	s_add_u32 s46, s46, 0x100
	s_addc_u32 s47, s47, 0
.LBB0_249:
	ds_read_b128 v[122:125], v181
	ds_read_b128 v[126:129], v181 offset:1024
	ds_read_b128 v[134:137], v181 offset:2048
	ds_read_b128 v[142:145], v181 offset:3072
	ds_read_b128 v[184:187], v182
	ds_read_b128 v[188:191], v182 offset:1024
	ds_read_b128 v[192:195], v182 offset:2048
	ds_read_b128 v[196:199], v182 offset:3072
	s_add_u32 s51, s0, 0xfff80080
	s_addc_u32 s63, s1, -1
	s_cmp_eq_u32 s50, 28
	s_cselect_b32 s95, s65, s63
	s_cselect_b32 s94, s64, s51
	s_cselect_b32 s91, s36, s47
	s_cselect_b32 s90, s37, s46
	v_lshl_add_u64 v[166:167], s[0:1], 0, v[158:159]
	s_add_i32 m0, s13, 0xc000
	ds_read_b128 v[200:203], v183
	ds_read_b128 v[204:207], v183 offset:1024
	ds_read_b128 v[212:215], v183 offset:2048
	ds_read_b128 v[216:219], v183 offset:3072
	ds_read_b128 v[220:223], v183 offset:4096
	ds_read_b128 v[224:227], v183 offset:5120
	ds_read_b128 v[228:231], v183 offset:6144
	ds_read_b128 v[232:235], v183 offset:7168
	global_load_lds_dwordx4 v[166:167], off
	v_lshl_add_u64 v[166:167], s[0:1], 0, v[160:161]
	s_add_i32 m0, s13, 0xe000
	s_nop 0
	global_load_lds_dwordx4 v[166:167], off
	s_waitcnt vmcnt(8)
	s_waitcnt lgkmcnt(0)
	s_barrier
; #define PG8_STAGE(bufoff, gbase, voff) do { _Pragma("unroll") for (int _i = 0; _i < 2; ++_i) \
;         __builtin_amdgcn_global_load_lds((const unsigned*)((const char*)(gbase) + (voff)[_i]), (PG8_LAS unsigned*)(lds + (bufoff) + ldsw + _i * 8192), 16, 0, 0); } while (0)
; #define PG8_LDA(dst, b, h) do { _Pragma("unroll") for (int m = 0; m < 4; ++m) _Pragma("unroll") for (int k = 0; k < 2; ++k) dst[m][k] = *(const PG8_LAS bf16x8*)(lds + PG8_SA(b, h) + aoff + m * 2048 + k * 1024); } while (0)
; #define PG8_LDB(dst, b, h) do { _Pragma("unroll") for (int n = 0; n < 2; ++n) _Pragma("unroll") for (int k = 0; k < 2; ++k) dst[n][k] = *(const PG8_LAS bf16x8*)(lds + PG8_SB(b, h) + boff + n * 2048 + k * 1024); } while (0)
; #define PG8_MMA(ai, bj, At, Bt) do { __builtin_amdgcn_s_setprio(1); _Pragma("unroll") for (int m = 0; m < 4; ++m) _Pragma("unroll") for (int n = 0; n < 2; ++n) _Pragma("unroll") for (int k = 0; k < 2; ++k) \
;         acc[ai][bj][m][n] = mma16(Bt[n][k], At[m][k], acc[ai][bj][m][n]); __builtin_amdgcn_s_setprio(0); } while (0)
; #define PG8_WAIT_V(n) asm volatile("s_waitcnt vmcnt(" #n ")" ::: "memory")
; #define PG8_WAIT_L(n) asm volatile("s_waitcnt lgkmcnt(" #n ")" ::: "memory")
; #define PG8_BAR __builtin_amdgcn_s_barrier()
; #define PG8_SCHED __builtin_amdgcn_sched_barrier(0)
; template <class Epi, class Sched, bool ALIGN_EPI = false, bool SP2 = false>
; __device__ __forceinline__ void gemm_phase(PG8_LAS unsigned char* lds, const Gemm g, const Sched& S, const Epi& E) {
;     ...
;             PG8_LDB(B0, 0, 0); PG8_LDB(B1, 0, 1); PG8_SCHED; PG8_LDA(At, 0, 0); PG8_STAGE(PG8_SA(1, 1), a1 + hstepA, voffA);
;             PG8_WAIT_V(8); PG8_WAIT_L(0); PG8_BAR; PG8_MMA(0, 0, At, B0); PG8_MMA(0, 1, At, B1); PG8_BAR; PG8_SCHED;
;             PG8_LDA(At, 0, 1); PG8_STAGE(PG8_SB(0, 0), b2, voffB); PG8_STAGE(PG8_SB(0, 1), b2 + hstepB, voffB); PG8_STAGE(PG8_SA(0, 0), a2, voffA);
;             PG8_WAIT_V(8); PG8_WAIT_L(0); PG8_BAR; PG8_MMA(1, 0, At, B0); PG8_MMA(1, 1, At, B1); PG8_BAR; PG8_SCHED;
	s_setprio 1
	s_waitcnt lgkmcnt(0)
	v_mfma_i32_16x16x64_i8 v[138:141], v[122:125], v[200:203], v[138:141]
	v_mfma_i32_16x16x64_i8 v[138:141], v[126:129], v[204:207], v[138:141]
	v_mfma_i32_16x16x64_i8 v[130:133], v[142:145], v[204:207], v[130:133]
	v_mfma_i32_16x16x64_i8 v[130:133], v[134:137], v[200:203], v[130:133]
	v_mfma_i32_16x16x64_i8 v[106:109], v[134:137], v[212:215], v[106:109]
	v_mfma_i32_16x16x64_i8 v[106:109], v[142:145], v[216:219], v[106:109]
	v_mfma_i32_16x16x64_i8 v[110:113], v[126:129], v[216:219], v[110:113]
	v_mfma_i32_16x16x64_i8 v[110:113], v[122:125], v[212:215], v[110:113]
	v_mfma_i32_16x16x64_i8 v[94:97], v[122:125], v[220:223], v[94:97]
	v_mfma_i32_16x16x64_i8 v[94:97], v[126:129], v[224:227], v[94:97]
	v_mfma_i32_16x16x64_i8 v[90:93], v[142:145], v[224:227], v[90:93]
	v_mfma_i32_16x16x64_i8 v[90:93], v[134:137], v[220:223], v[90:93]
	v_mfma_i32_16x16x64_i8 v[74:77], v[134:137], v[228:231], v[74:77]
	v_mfma_i32_16x16x64_i8 v[74:77], v[142:145], v[232:235], v[74:77]
	v_mfma_i32_16x16x64_i8 v[78:81], v[126:129], v[232:235], v[78:81]
	v_mfma_i32_16x16x64_i8 v[78:81], v[122:125], v[228:231], v[78:81]
	s_setprio 0
	s_setprio 1
	v_mfma_i32_16x16x64_i8 v[70:73], v[184:187], v[228:231], v[70:73]
	v_mfma_i32_16x16x64_i8 v[70:73], v[188:191], v[232:235], v[70:73]
	v_mfma_i32_16x16x64_i8 v[66:69], v[196:199], v[232:235], v[66:69]
	v_mfma_i32_16x16x64_i8 v[66:69], v[192:195], v[228:231], v[66:69]
	v_mfma_i32_16x16x64_i8 v[82:85], v[192:195], v[220:223], v[82:85]
	v_mfma_i32_16x16x64_i8 v[82:85], v[196:199], v[224:227], v[82:85]
	v_mfma_i32_16x16x64_i8 v[86:89], v[188:191], v[224:227], v[86:89]
	v_mfma_i32_16x16x64_i8 v[86:89], v[184:187], v[220:223], v[86:89]
	v_mfma_i32_16x16x64_i8 v[102:105], v[184:187], v[212:215], v[102:105]
	v_mfma_i32_16x16x64_i8 v[102:105], v[188:191], v[216:219], v[102:105]
	v_mfma_i32_16x16x64_i8 v[98:101], v[196:199], v[216:219], v[98:101]
	v_mfma_i32_16x16x64_i8 v[98:101], v[192:195], v[212:215], v[98:101]
	v_mfma_i32_16x16x64_i8 v[114:117], v[192:195], v[200:203], v[114:117]
	v_mfma_i32_16x16x64_i8 v[114:117], v[196:199], v[204:207], v[114:117]
	v_mfma_i32_16x16x64_i8 v[118:121], v[188:191], v[204:207], v[118:121]
	v_mfma_i32_16x16x64_i8 v[118:121], v[184:187], v[200:203], v[118:121]
	s_setprio 0
	s_barrier
	s_add_i32 s51, s27, s7
	v_lshl_add_u64 v[166:167], s[90:91], 0, v[148:149]
	s_mov_b32 m0, s51
	ds_read_b128 v[200:203], v183 offset:16384
	ds_read_b128 v[204:207], v183 offset:17408
	ds_read_b128 v[212:215], v183 offset:18432
	ds_read_b128 v[216:219], v183 offset:19456
	ds_read_b128 v[220:223], v183 offset:20480
	ds_read_b128 v[224:227], v183 offset:21504
	ds_read_b128 v[228:231], v183 offset:22528
	ds_read_b128 v[232:235], v183 offset:23552
	global_load_lds_dwordx4 v[166:167], off
	s_add_i32 m0, s51, 0x2000
	s_add_u32 s68, s90, 0x80000
	v_lshl_add_u64 v[208:209], s[90:91], 0, v[152:153]
	s_addc_u32 s69, s91, 0
	s_add_i32 s51, s28, s7
	global_load_lds_dwordx4 v[208:209], off
	v_lshl_add_u64 v[236:237], s[68:69], 0, v[148:149]
	s_mov_b32 m0, s51
	v_lshl_add_u64 v[238:239], s[94:95], 0, v[150:151]
	global_load_lds_dwordx4 v[236:237], off
	v_lshl_add_u64 v[236:237], s[68:69], 0, v[152:153]
	s_add_i32 m0, s51, 0x2000
	s_nop 0
	global_load_lds_dwordx4 v[236:237], off
	v_lshl_add_u64 v[236:237], s[94:95], 0, v[146:147]
	s_mov_b32 m0, s13
	s_nop 0
	global_load_lds_dwordx4 v[236:237], off
	s_mov_b32 m0, s18
	s_nop 0
	global_load_lds_dwordx4 v[238:239], off
	s_waitcnt vmcnt(8)
	s_waitcnt lgkmcnt(0)
	s_barrier
	s_setprio 1
	s_waitcnt lgkmcnt(0)
	v_mfma_i32_16x16x64_i8 v[62:65], v[122:125], v[200:203], v[62:65]
	v_mfma_i32_16x16x64_i8 v[62:65], v[126:129], v[204:207], v[62:65]
	v_mfma_i32_16x16x64_i8 v[58:61], v[142:145], v[204:207], v[58:61]
	v_mfma_i32_16x16x64_i8 v[58:61], v[134:137], v[200:203], v[58:61]
	v_mfma_i32_16x16x64_i8 v[42:45], v[134:137], v[212:215], v[42:45]
	v_mfma_i32_16x16x64_i8 v[42:45], v[142:145], v[216:219], v[42:45]
	v_mfma_i32_16x16x64_i8 v[46:49], v[126:129], v[216:219], v[46:49]
	v_mfma_i32_16x16x64_i8 v[46:49], v[122:125], v[212:215], v[46:49]
	v_mfma_i32_16x16x64_i8 v[30:33], v[122:125], v[220:223], v[30:33]
	v_mfma_i32_16x16x64_i8 v[30:33], v[126:129], v[224:227], v[30:33]
	v_mfma_i32_16x16x64_i8 v[26:29], v[142:145], v[224:227], v[26:29]
	v_mfma_i32_16x16x64_i8 v[26:29], v[134:137], v[220:223], v[26:29]
	v_mfma_i32_16x16x64_i8 v[10:13], v[134:137], v[228:231], v[10:13]
	v_mfma_i32_16x16x64_i8 v[10:13], v[142:145], v[232:235], v[10:13]
	v_mfma_i32_16x16x64_i8 v[14:17], v[126:129], v[232:235], v[14:17]
	v_mfma_i32_16x16x64_i8 v[14:17], v[122:125], v[228:231], v[14:17]
	s_setprio 0
	s_setprio 1
	v_mfma_i32_16x16x64_i8 v[6:9], v[184:187], v[228:231], v[6:9]
	v_mfma_i32_16x16x64_i8 v[6:9], v[188:191], v[232:235], v[6:9]
	v_mfma_i32_16x16x64_i8 v[2:5], v[196:199], v[232:235], v[2:5]
	v_mfma_i32_16x16x64_i8 v[2:5], v[192:195], v[228:231], v[2:5]
	v_mfma_i32_16x16x64_i8 v[18:21], v[192:195], v[220:223], v[18:21]
	v_mfma_i32_16x16x64_i8 v[18:21], v[196:199], v[224:227], v[18:21]
	v_mfma_i32_16x16x64_i8 v[22:25], v[188:191], v[224:227], v[22:25]
	v_mfma_i32_16x16x64_i8 v[22:25], v[184:187], v[220:223], v[22:25]
	v_mfma_i32_16x16x64_i8 v[38:41], v[184:187], v[212:215], v[38:41]
	v_mfma_i32_16x16x64_i8 v[38:41], v[188:191], v[216:219], v[38:41]
	v_mfma_i32_16x16x64_i8 v[34:37], v[196:199], v[216:219], v[34:37]
	v_mfma_i32_16x16x64_i8 v[34:37], v[192:195], v[212:215], v[34:37]
	v_mfma_i32_16x16x64_i8 v[50:53], v[192:195], v[200:203], v[50:53]
	v_mfma_i32_16x16x64_i8 v[50:53], v[196:199], v[204:207], v[50:53]
	v_mfma_i32_16x16x64_i8 v[54:57], v[188:191], v[204:207], v[54:57]
	v_mfma_i32_16x16x64_i8 v[54:57], v[184:187], v[200:203], v[54:57]
	s_setprio 0
	s_barrier
; #define PG8_STAGE(bufoff, gbase, voff) do { _Pragma("unroll") for (int _i = 0; _i < 2; ++_i) \
;         __builtin_amdgcn_global_load_lds((const unsigned*)((const char*)(gbase) + (voff)[_i]), (PG8_LAS unsigned*)(lds + (bufoff) + ldsw + _i * 8192), 16, 0, 0); } while (0)
; #define PG8_LDA(dst, b, h) do { _Pragma("unroll") for (int m = 0; m < 4; ++m) _Pragma("unroll") for (int k = 0; k < 2; ++k) dst[m][k] = *(const PG8_LAS bf16x8*)(lds + PG8_SA(b, h) + aoff + m * 2048 + k * 1024); } while (0)
; #define PG8_LDB(dst, b, h) do { _Pragma("unroll") for (int n = 0; n < 2; ++n) _Pragma("unroll") for (int k = 0; k < 2; ++k) dst[n][k] = *(const PG8_LAS bf16x8*)(lds + PG8_SB(b, h) + boff + n * 2048 + k * 1024); } while (0)
; #define PG8_MMA(ai, bj, At, Bt) do { __builtin_amdgcn_s_setprio(1); _Pragma("unroll") for (int m = 0; m < 4; ++m) _Pragma("unroll") for (int n = 0; n < 2; ++n) _Pragma("unroll") for (int k = 0; k < 2; ++k) \
;         acc[ai][bj][m][n] = mma16(Bt[n][k], At[m][k], acc[ai][bj][m][n]); __builtin_amdgcn_s_setprio(0); } while (0)
; #define PG8_WAIT_V(n) asm volatile("s_waitcnt vmcnt(" #n ")" ::: "memory")
; #define PG8_WAIT_L(n) asm volatile("s_waitcnt lgkmcnt(" #n ")" ::: "memory")
; #define PG8_BAR __builtin_amdgcn_s_barrier()
; #define PG8_SCHED __builtin_amdgcn_sched_barrier(0)
; template <class Epi, class Sched, bool ALIGN_EPI = false, bool SP2 = false>
; __device__ __forceinline__ void gemm_phase(PG8_LAS unsigned char* lds, const Gemm g, const Sched& S, const Epi& E) {
;     ...
;             PG8_LDB(B0, 1, 0); PG8_LDB(B1, 1, 1); PG8_SCHED; PG8_LDA(At, 1, 0); PG8_STAGE(PG8_SA(0, 1), a2 + hstepA, voffA);
;             PG8_WAIT_V(8); PG8_WAIT_L(0); PG8_BAR; PG8_MMA(0, 0, At, B0); PG8_MMA(0, 1, At, B1); PG8_BAR; PG8_SCHED;
	s_add_i32 s51, 0, 0x18000
	s_add_i32 s63, 0, 0x1c000
	v_add_u32_e32 v142, s51, v176
	v_add_u32_e32 v196, s63, v176
	ds_read_b128 v[122:125], v142
	ds_read_b128 v[126:129], v142 offset:1024
	ds_read_b128 v[134:137], v142 offset:2048
	ds_read_b128 v[142:145], v142 offset:3072
	ds_read_b128 v[184:187], v196
	ds_read_b128 v[188:191], v196 offset:1024
	ds_read_b128 v[192:195], v196 offset:2048
	ds_read_b128 v[196:199], v196 offset:3072
	s_add_u32 s68, s94, 0x80000
	s_addc_u32 s69, s95, 0
	s_mov_b32 m0, s19
	v_lshl_add_u64 v[240:241], s[68:69], 0, v[146:147]
	ds_read_b128 v[200:203], v183 offset:32768
	ds_read_b128 v[204:207], v183 offset:33792
	ds_read_b128 v[212:215], v183 offset:34816
	ds_read_b128 v[216:219], v183 offset:35840
	ds_read_b128 v[220:223], v183 offset:36864
	ds_read_b128 v[224:227], v183 offset:37888
	ds_read_b128 v[228:231], v183 offset:38912
	ds_read_b128 v[232:235], v183 offset:39936
	global_load_lds_dwordx4 v[240:241], off
	v_lshl_add_u64 v[240:241], s[68:69], 0, v[150:151]
	s_mov_b32 m0, s20
	s_nop 0
	global_load_lds_dwordx4 v[240:241], off
	s_waitcnt vmcnt(8)
	s_waitcnt lgkmcnt(0)
	s_barrier
	s_setprio 1
	s_waitcnt lgkmcnt(0)
	v_mfma_i32_16x16x64_i8 v[138:141], v[122:125], v[200:203], v[138:141]
	v_mfma_i32_16x16x64_i8 v[138:141], v[126:129], v[204:207], v[138:141]
	v_mfma_i32_16x16x64_i8 v[130:133], v[142:145], v[204:207], v[130:133]
	v_mfma_i32_16x16x64_i8 v[130:133], v[134:137], v[200:203], v[130:133]
	v_mfma_i32_16x16x64_i8 v[106:109], v[134:137], v[212:215], v[106:109]
	v_mfma_i32_16x16x64_i8 v[106:109], v[142:145], v[216:219], v[106:109]
	v_mfma_i32_16x16x64_i8 v[110:113], v[126:129], v[216:219], v[110:113]
	v_mfma_i32_16x16x64_i8 v[110:113], v[122:125], v[212:215], v[110:113]
	v_mfma_i32_16x16x64_i8 v[94:97], v[122:125], v[220:223], v[94:97]
	v_mfma_i32_16x16x64_i8 v[94:97], v[126:129], v[224:227], v[94:97]
	v_mfma_i32_16x16x64_i8 v[90:93], v[142:145], v[224:227], v[90:93]
	v_mfma_i32_16x16x64_i8 v[90:93], v[134:137], v[220:223], v[90:93]
	v_mfma_i32_16x16x64_i8 v[74:77], v[134:137], v[228:231], v[74:77]
	v_mfma_i32_16x16x64_i8 v[74:77], v[142:145], v[232:235], v[74:77]
	v_mfma_i32_16x16x64_i8 v[78:81], v[126:129], v[232:235], v[78:81]
	v_mfma_i32_16x16x64_i8 v[78:81], v[122:125], v[228:231], v[78:81]
	s_setprio 0
	s_setprio 1
	v_mfma_i32_16x16x64_i8 v[70:73], v[184:187], v[228:231], v[70:73]
	v_mfma_i32_16x16x64_i8 v[70:73], v[188:191], v[232:235], v[70:73]
	v_mfma_i32_16x16x64_i8 v[66:69], v[196:199], v[232:235], v[66:69]
	v_mfma_i32_16x16x64_i8 v[66:69], v[192:195], v[228:231], v[66:69]
	v_mfma_i32_16x16x64_i8 v[82:85], v[192:195], v[220:223], v[82:85]
	v_mfma_i32_16x16x64_i8 v[82:85], v[196:199], v[224:227], v[82:85]
	v_mfma_i32_16x16x64_i8 v[86:89], v[188:191], v[224:227], v[86:89]
	v_mfma_i32_16x16x64_i8 v[86:89], v[184:187], v[220:223], v[86:89]
	v_mfma_i32_16x16x64_i8 v[102:105], v[184:187], v[212:215], v[102:105]
	v_mfma_i32_16x16x64_i8 v[102:105], v[188:191], v[216:219], v[102:105]
	v_mfma_i32_16x16x64_i8 v[98:101], v[196:199], v[216:219], v[98:101]
	v_mfma_i32_16x16x64_i8 v[98:101], v[192:195], v[212:215], v[98:101]
	v_mfma_i32_16x16x64_i8 v[114:117], v[192:195], v[200:203], v[114:117]
	v_mfma_i32_16x16x64_i8 v[114:117], v[196:199], v[204:207], v[114:117]
	v_mfma_i32_16x16x64_i8 v[118:121], v[188:191], v[204:207], v[118:121]
	v_mfma_i32_16x16x64_i8 v[118:121], v[184:187], v[200:203], v[118:121]
	s_setprio 0
	s_barrier
; #define PG8_STAGE(bufoff, gbase, voff) do { _Pragma("unroll") for (int _i = 0; _i < 2; ++_i) \
;         __builtin_amdgcn_global_load_lds((const unsigned*)((const char*)(gbase) + (voff)[_i]), (PG8_LAS unsigned*)(lds + (bufoff) + ldsw + _i * 8192), 16, 0, 0); } while (0)
; #define PG8_LDA(dst, b, h) do { _Pragma("unroll") for (int m = 0; m < 4; ++m) _Pragma("unroll") for (int k = 0; k < 2; ++k) dst[m][k] = *(const PG8_LAS bf16x8*)(lds + PG8_SA(b, h) + aoff + m * 2048 + k * 1024); } while (0)
; #define PG8_MMA(ai, bj, At, Bt) do { __builtin_amdgcn_s_setprio(1); _Pragma("unroll") for (int m = 0; m < 4; ++m) _Pragma("unroll") for (int n = 0; n < 2; ++n) _Pragma("unroll") for (int k = 0; k < 2; ++k) \
;         acc[ai][bj][m][n] = mma16(Bt[n][k], At[m][k], acc[ai][bj][m][n]); __builtin_amdgcn_s_setprio(0); } while (0)
; #define PG8_WAIT_V(n) asm volatile("s_waitcnt vmcnt(" #n ")" ::: "memory")
; #define PG8_WAIT_L(n) asm volatile("s_waitcnt lgkmcnt(" #n ")" ::: "memory")
; #define PG8_BAR __builtin_amdgcn_s_barrier()
; #define PG8_SCHED __builtin_amdgcn_sched_barrier(0)
; template <class Epi, class Sched, bool ALIGN_EPI = false, bool SP2 = false>
; __device__ __forceinline__ void gemm_phase(PG8_LAS unsigned char* lds, const Gemm g, const Sched& S, const Epi& E) {
;     ...
;             PG8_LDA(At, 1, 1); PG8_STAGE(PG8_SB(1, 0), b3, voffB); PG8_STAGE(PG8_SB(1, 1), b3 + hstepB, voffB); PG8_STAGE(PG8_SA(1, 0), a3, voffA);
;             PG8_WAIT_V(8); PG8_WAIT_L(0); PG8_BAR; PG8_MMA(1, 0, At, B0); PG8_MMA(1, 1, At, B1); PG8_BAR; PG8_SCHED;
;     ...
;         if constexpr (ALIGN_EPI) { if (wr == 0) PG8_BAR; }
	s_add_i32 s51, s51, s7
	v_lshl_add_u64 v[166:167], v[166:167], 0, s[48:49]
	s_mov_b32 m0, s51
	ds_read_b128 v[200:203], v183 offset:49152
	ds_read_b128 v[204:207], v183 offset:50176
	ds_read_b128 v[212:215], v183 offset:51200
	ds_read_b128 v[216:219], v183 offset:52224
	ds_read_b128 v[220:223], v183 offset:53248
	ds_read_b128 v[224:227], v183 offset:54272
	ds_read_b128 v[228:231], v183 offset:55296
	ds_read_b128 v[232:235], v183 offset:56320
	global_load_lds_dwordx4 v[166:167], off
	s_add_i32 m0, s51, 0x2000
	s_add_u32 s68, s90, 0x80080
	v_lshl_add_u64 v[166:167], v[208:209], 0, s[48:49]
	s_addc_u32 s69, s91, 0
	s_add_i32 s51, s63, s7
	global_load_lds_dwordx4 v[166:167], off
	v_lshl_add_u64 v[166:167], s[68:69], 0, v[148:149]
	s_mov_b32 m0, s51
	s_nop 0
	global_load_lds_dwordx4 v[166:167], off
	v_lshl_add_u64 v[166:167], s[68:69], 0, v[152:153]
	s_add_i32 m0, s51, 0x2000
	s_nop 0
	global_load_lds_dwordx4 v[166:167], off
	v_lshl_add_u64 v[166:167], v[236:237], 0, s[48:49]
	s_mov_b32 m0, s23
	s_nop 0
	global_load_lds_dwordx4 v[166:167], off
	v_lshl_add_u64 v[166:167], v[238:239], 0, s[48:49]
	s_mov_b32 m0, s24
	s_nop 0
	global_load_lds_dwordx4 v[166:167], off
	s_waitcnt vmcnt(8)
	s_waitcnt lgkmcnt(0)
	s_barrier
	s_setprio 1
	s_waitcnt lgkmcnt(0)
	v_mfma_i32_16x16x64_i8 v[62:65], v[122:125], v[200:203], v[62:65]
	v_mfma_i32_16x16x64_i8 v[62:65], v[126:129], v[204:207], v[62:65]
	v_mfma_i32_16x16x64_i8 v[58:61], v[142:145], v[204:207], v[58:61]
	v_mfma_i32_16x16x64_i8 v[58:61], v[134:137], v[200:203], v[58:61]
	v_mfma_i32_16x16x64_i8 v[42:45], v[134:137], v[212:215], v[42:45]
	v_mfma_i32_16x16x64_i8 v[42:45], v[142:145], v[216:219], v[42:45]
	v_mfma_i32_16x16x64_i8 v[46:49], v[126:129], v[216:219], v[46:49]
	v_mfma_i32_16x16x64_i8 v[46:49], v[122:125], v[212:215], v[46:49]
	v_mfma_i32_16x16x64_i8 v[30:33], v[122:125], v[220:223], v[30:33]
	v_mfma_i32_16x16x64_i8 v[30:33], v[126:129], v[224:227], v[30:33]
	v_mfma_i32_16x16x64_i8 v[26:29], v[142:145], v[224:227], v[26:29]
	v_mfma_i32_16x16x64_i8 v[26:29], v[134:137], v[220:223], v[26:29]
	v_mfma_i32_16x16x64_i8 v[10:13], v[134:137], v[228:231], v[10:13]
	v_mfma_i32_16x16x64_i8 v[10:13], v[142:145], v[232:235], v[10:13]
	v_mfma_i32_16x16x64_i8 v[14:17], v[126:129], v[232:235], v[14:17]
	v_mfma_i32_16x16x64_i8 v[14:17], v[122:125], v[228:231], v[14:17]
	s_setprio 0
	s_setprio 1
	v_mfma_i32_16x16x64_i8 v[6:9], v[184:187], v[228:231], v[6:9]
	v_mfma_i32_16x16x64_i8 v[6:9], v[188:191], v[232:235], v[6:9]
	v_mfma_i32_16x16x64_i8 v[2:5], v[196:199], v[232:235], v[2:5]
	v_mfma_i32_16x16x64_i8 v[2:5], v[192:195], v[228:231], v[2:5]
	v_mfma_i32_16x16x64_i8 v[18:21], v[192:195], v[220:223], v[18:21]
	v_mfma_i32_16x16x64_i8 v[18:21], v[196:199], v[224:227], v[18:21]
	v_mfma_i32_16x16x64_i8 v[22:25], v[188:191], v[224:227], v[22:25]
	v_mfma_i32_16x16x64_i8 v[22:25], v[184:187], v[220:223], v[22:25]
	v_mfma_i32_16x16x64_i8 v[38:41], v[184:187], v[212:215], v[38:41]
	v_mfma_i32_16x16x64_i8 v[38:41], v[188:191], v[216:219], v[38:41]
	v_mfma_i32_16x16x64_i8 v[34:37], v[196:199], v[216:219], v[34:37]
	v_mfma_i32_16x16x64_i8 v[34:37], v[192:195], v[212:215], v[34:37]
	v_mfma_i32_16x16x64_i8 v[50:53], v[192:195], v[200:203], v[50:53]
	v_mfma_i32_16x16x64_i8 v[50:53], v[196:199], v[204:207], v[50:53]
	v_mfma_i32_16x16x64_i8 v[54:57], v[188:191], v[204:207], v[54:57]
	v_mfma_i32_16x16x64_i8 v[54:57], v[184:187], v[200:203], v[54:57]
	s_setprio 0
	s_barrier
	s_add_i32 s50, s50, 2
	s_add_u32 s0, s0, 0x100
	s_addc_u32 s1, s1, 0
	s_add_u32 s46, s46, 0x100
	s_addc_u32 s47, s47, 0
	s_cmp_gt_u32 s50, 29
	s_cbranch_scc0 .LBB0_249
	s_and_b64 vcc, exec, s[54:55]
	s_cbranch_vccz .LBB0_252
	s_barrier

; #define PG8_STAGE(bufoff, gbase, voff) do { _Pragma("unroll") for (int _i = 0; _i < 2; ++_i) \
;         __builtin_amdgcn_global_load_lds((const unsigned*)((const char*)(gbase) + (voff)[_i]), (PG8_LAS unsigned*)(lds + (bufoff) + ldsw + _i * 8192), 16, 0, 0); } while (0)
; #define PG8_LDA(dst, b, h) do { _Pragma("unroll") for (int m = 0; m < 4; ++m) _Pragma("unroll") for (int k = 0; k < 2; ++k) dst[m][k] = *(const PG8_LAS bf16x8*)(lds + PG8_SA(b, h) + aoff + m * 2048 + k * 1024); } while (0)
; #define PG8_LDB(dst, b, h) do { _Pragma("unroll") for (int n = 0; n < 2; ++n) _Pragma("unroll") for (int k = 0; k < 2; ++k) dst[n][k] = *(const PG8_LAS bf16x8*)(lds + PG8_SB(b, h) + boff + n * 2048 + k * 1024); } while (0)
; #define PG8_MMA(ai, bj, At, Bt) do { __builtin_amdgcn_s_setprio(1); _Pragma("unroll") for (int m = 0; m < 4; ++m) _Pragma("unroll") for (int n = 0; n < 2; ++n) _Pragma("unroll") for (int k = 0; k < 2; ++k) \
;         acc[ai][bj][m][n] = mma16(Bt[n][k], At[m][k], acc[ai][bj][m][n]); __builtin_amdgcn_s_setprio(0); } while (0)
; template <class Epi, class Sched, bool ALIGN_EPI = false, bool SP2 = false>
; __device__ __forceinline__ void gemm_phase(PG8_LAS unsigned char* lds, const Gemm g, const Sched& S, const Epi& E) {
;     ...
;         const bool has_next = S.next(ui + 1, nxt);
;         const char* nA = has_next ? PG8_ABASE(nxt) : cA; const char* nB = has_next ? PG8_BBASE(nxt) : cB;
; #pragma unroll 1
;         for (int t = 0; t < nt; t += 2) {
;             const bool last = (t == nt - 2);
;             const char* a1 = cA + (size_t)(t + 1) * kstep;
;             const char* a2 = last ? nA : cA + (size_t)(t + 2) * kstep; const char* b2 = last ? nB : cB + (size_t)(t + 2) * kstep;
;             const char* a3 = a2 + kstep; const char* b3 = b2 + kstep;
;             if (last && has_next) S.a_ready(nxt);
;             if constexpr (SP2) {
;             PG8_LDB(B0, 0, 0); PG8_LDB(B1, 0, 1); PG8_SCHED; PG8_LDA(At, 0, 0); PG8_STAGE(PG8_SA(1, 1), a1 + hstepA, voffA);
;             PG8_WAIT_V(8); PG8_WAIT_L(0); PG8_BAR; PG8_MMA(0, 0, At, B0); PG8_MMA(0, 1, At, B1); PG8_BAR; PG8_SCHED;
;             PG8_LDA(At, 0, 1); PG8_STAGE(PG8_SB(0, 0), b2, voffB); PG8_STAGE(PG8_SB(0, 1), b2 + hstepB, voffB); PG8_STAGE(PG8_SA(0, 0), a2, voffA);
;             PG8_WAIT_V(8); PG8_WAIT_L(0); PG8_BAR; PG8_MMA(1, 0, At, B0); PG8_MMA(1, 1, At, B1); PG8_BAR; PG8_SCHED;
.LBB0_274:
	s_ashr_i32 s39, s38, 31
	s_lshl_b64 s[46:47], s[38:39], 20
	s_add_u32 s58, s8, s46
	s_addc_u32 s59, s11, s47
	s_and_b64 s[0:1], s[0:1], exec
	s_cselect_b32 s37, s59, s65
	s_cselect_b32 s46, s58, s64
	s_add_u32 s0, s66, 0x80080
	s_addc_u32 s1, s67, 0
	s_add_u32 s47, s64, 0x100
	s_addc_u32 s49, s65, 0
	s_mov_b32 s50, -2
	ds_read_b128 v[122:125], v169
	ds_read_b128 v[126:129], v169 offset:1024
	ds_read_b128 v[134:137], v169 offset:2048
	ds_read_b128 v[142:145], v169 offset:3072
	ds_read_b128 v[182:185], v170
	ds_read_b128 v[186:189], v170 offset:1024
	ds_read_b128 v[190:193], v170 offset:2048
	ds_read_b128 v[194:197], v170 offset:3072
	s_add_u32 s51, s0, 0xfff80080
	s_addc_u32 s63, s1, -1
	s_cmp_eq_u32 s50, 28
	s_cselect_b32 s67, s55, s63
	s_cselect_b32 s66, s54, s51
	s_cselect_b32 s65, s37, s49
	s_cselect_b32 s64, s46, s47
	v_lshl_add_u64 v[166:167], s[0:1], 0, v[158:159]
	s_add_i32 m0, s18, 0xc000
	ds_read_b128 v[198:201], v171
	ds_read_b128 v[202:205], v171 offset:1024
	ds_read_b128 v[206:209], v171 offset:2048
	ds_read_b128 v[212:215], v171 offset:3072
	ds_read_b128 v[216:219], v171 offset:4096
	ds_read_b128 v[220:223], v171 offset:5120
	ds_read_b128 v[224:227], v171 offset:6144
	ds_read_b128 v[228:231], v171 offset:7168
	global_load_lds_dwordx4 v[166:167], off
	v_lshl_add_u64 v[166:167], s[0:1], 0, v[160:161]
	s_add_i32 m0, s18, 0xe000
	s_nop 0
	global_load_lds_dwordx4 v[166:167], off
	s_waitcnt vmcnt(8)
	s_waitcnt lgkmcnt(0)
	s_barrier
	s_setprio 1
	s_waitcnt lgkmcnt(0)
	v_mfma_i32_16x16x64_i8 v[138:141], v[122:125], v[198:201], 0
	v_mfma_i32_16x16x64_i8 v[138:141], v[126:129], v[202:205], v[138:141]
	v_mfma_i32_16x16x64_i8 v[130:133], v[142:145], v[202:205], 0
	v_mfma_i32_16x16x64_i8 v[130:133], v[134:137], v[198:201], v[130:133]
	v_mfma_i32_16x16x64_i8 v[106:109], v[134:137], v[206:209], 0
	v_mfma_i32_16x16x64_i8 v[106:109], v[142:145], v[212:215], v[106:109]
	v_mfma_i32_16x16x64_i8 v[110:113], v[126:129], v[212:215], 0
	v_mfma_i32_16x16x64_i8 v[110:113], v[122:125], v[206:209], v[110:113]
	v_mfma_i32_16x16x64_i8 v[94:97], v[122:125], v[216:219], 0
	v_mfma_i32_16x16x64_i8 v[94:97], v[126:129], v[220:223], v[94:97]
	v_mfma_i32_16x16x64_i8 v[90:93], v[142:145], v[220:223], 0
	v_mfma_i32_16x16x64_i8 v[90:93], v[134:137], v[216:219], v[90:93]
	v_mfma_i32_16x16x64_i8 v[74:77], v[134:137], v[224:227], 0
	v_mfma_i32_16x16x64_i8 v[74:77], v[142:145], v[228:231], v[74:77]
	v_mfma_i32_16x16x64_i8 v[78:81], v[126:129], v[228:231], 0
	v_mfma_i32_16x16x64_i8 v[78:81], v[122:125], v[224:227], v[78:81]
	s_setprio 0
	s_setprio 1
	v_mfma_i32_16x16x64_i8 v[70:73], v[182:185], v[224:227], 0
	v_mfma_i32_16x16x64_i8 v[70:73], v[186:189], v[228:231], v[70:73]
	v_mfma_i32_16x16x64_i8 v[66:69], v[194:197], v[228:231], 0
	v_mfma_i32_16x16x64_i8 v[66:69], v[190:193], v[224:227], v[66:69]
	v_mfma_i32_16x16x64_i8 v[82:85], v[190:193], v[216:219], 0
	v_mfma_i32_16x16x64_i8 v[82:85], v[194:197], v[220:223], v[82:85]
	v_mfma_i32_16x16x64_i8 v[86:89], v[186:189], v[220:223], 0
	v_mfma_i32_16x16x64_i8 v[86:89], v[182:185], v[216:219], v[86:89]
	v_mfma_i32_16x16x64_i8 v[102:105], v[182:185], v[206:209], 0
	v_mfma_i32_16x16x64_i8 v[102:105], v[186:189], v[212:215], v[102:105]
	v_mfma_i32_16x16x64_i8 v[98:101], v[194:197], v[212:215], 0
	v_mfma_i32_16x16x64_i8 v[98:101], v[190:193], v[206:209], v[98:101]
	v_mfma_i32_16x16x64_i8 v[114:117], v[190:193], v[198:201], 0
	v_mfma_i32_16x16x64_i8 v[114:117], v[194:197], v[202:205], v[114:117]
	v_mfma_i32_16x16x64_i8 v[118:121], v[186:189], v[202:205], 0
	v_mfma_i32_16x16x64_i8 v[118:121], v[182:185], v[198:201], v[118:121]
	s_setprio 0
	s_barrier
	s_add_i32 s51, s28, s12
	v_lshl_add_u64 v[166:167], s[64:65], 0, v[148:149]
	s_mov_b32 m0, s51
	ds_read_b128 v[198:201], v171 offset:16384
	ds_read_b128 v[202:205], v171 offset:17408
	ds_read_b128 v[206:209], v171 offset:18432
	ds_read_b128 v[212:215], v171 offset:19456
	ds_read_b128 v[216:219], v171 offset:20480
	ds_read_b128 v[220:223], v171 offset:21504
	ds_read_b128 v[224:227], v171 offset:22528
	ds_read_b128 v[228:231], v171 offset:23552
	global_load_lds_dwordx4 v[166:167], off
	s_add_i32 m0, s51, 0x2000
	s_add_u32 s68, s64, 0x80000
	v_lshl_add_u64 v[176:177], s[64:65], 0, v[152:153]
	s_addc_u32 s69, s65, 0
	s_add_i32 s51, s29, s12
	global_load_lds_dwordx4 v[176:177], off
	v_lshl_add_u64 v[232:233], s[68:69], 0, v[148:149]
	s_mov_b32 m0, s51
	v_lshl_add_u64 v[234:235], s[66:67], 0, v[150:151]
	global_load_lds_dwordx4 v[232:233], off
	v_lshl_add_u64 v[232:233], s[68:69], 0, v[152:153]
	s_add_i32 m0, s51, 0x2000
	s_nop 0
	global_load_lds_dwordx4 v[232:233], off
	v_lshl_add_u64 v[232:233], s[66:67], 0, v[146:147]
	s_mov_b32 m0, s18
	s_nop 0
	global_load_lds_dwordx4 v[232:233], off
	s_mov_b32 m0, s19
	s_nop 0
	global_load_lds_dwordx4 v[234:235], off
	s_waitcnt vmcnt(8)
	s_waitcnt lgkmcnt(0)
	s_barrier
; #define PG8_STAGE(bufoff, gbase, voff) do { _Pragma("unroll") for (int _i = 0; _i < 2; ++_i) \
;         __builtin_amdgcn_global_load_lds((const unsigned*)((const char*)(gbase) + (voff)[_i]), (PG8_LAS unsigned*)(lds + (bufoff) + ldsw + _i * 8192), 16, 0, 0); } while (0)
; #define PG8_LDA(dst, b, h) do { _Pragma("unroll") for (int m = 0; m < 4; ++m) _Pragma("unroll") for (int k = 0; k < 2; ++k) dst[m][k] = *(const PG8_LAS bf16x8*)(lds + PG8_SA(b, h) + aoff + m * 2048 + k * 1024); } while (0)
; #define PG8_LDB(dst, b, h) do { _Pragma("unroll") for (int n = 0; n < 2; ++n) _Pragma("unroll") for (int k = 0; k < 2; ++k) dst[n][k] = *(const PG8_LAS bf16x8*)(lds + PG8_SB(b, h) + boff + n * 2048 + k * 1024); } while (0)
; #define PG8_MMA(ai, bj, At, Bt) do { __builtin_amdgcn_s_setprio(1); _Pragma("unroll") for (int m = 0; m < 4; ++m) _Pragma("unroll") for (int n = 0; n < 2; ++n) _Pragma("unroll") for (int k = 0; k < 2; ++k) \
;         acc[ai][bj][m][n] = mma16(Bt[n][k], At[m][k], acc[ai][bj][m][n]); __builtin_amdgcn_s_setprio(0); } while (0)
; #define PG8_WAIT_V(n) asm volatile("s_waitcnt vmcnt(" #n ")" ::: "memory")
; #define PG8_WAIT_L(n) asm volatile("s_waitcnt lgkmcnt(" #n ")" ::: "memory")
; #define PG8_BAR __builtin_amdgcn_s_barrier()
; #define PG8_SCHED __builtin_amdgcn_sched_barrier(0)
; template <class Epi, class Sched, bool ALIGN_EPI = false, bool SP2 = false>
; __device__ __forceinline__ void gemm_phase(PG8_LAS unsigned char* lds, const Gemm g, const Sched& S, const Epi& E) {
;     ...
;             PG8_WAIT_V(8); PG8_WAIT_L(0); PG8_BAR; PG8_MMA(0, 0, At, B0); PG8_MMA(0, 1, At, B1); PG8_BAR; PG8_SCHED;
;             PG8_LDA(At, 0, 1); PG8_STAGE(PG8_SB(0, 0), b2, voffB); PG8_STAGE(PG8_SB(0, 1), b2 + hstepB, voffB); PG8_STAGE(PG8_SA(0, 0), a2, voffA);
;             PG8_WAIT_V(8); PG8_WAIT_L(0); PG8_BAR; PG8_MMA(1, 0, At, B0); PG8_MMA(1, 1, At, B1); PG8_BAR; PG8_SCHED;
;             PG8_LDB(B0, 1, 0); PG8_LDB(B1, 1, 1); PG8_SCHED; PG8_LDA(At, 1, 0); PG8_STAGE(PG8_SA(0, 1), a2 + hstepA, voffA);
;             PG8_WAIT_V(8); PG8_WAIT_L(0); PG8_BAR; PG8_MMA(0, 0, At, B0); PG8_MMA(0, 1, At, B1); PG8_BAR; PG8_SCHED;
	s_setprio 1
	s_waitcnt lgkmcnt(0)
	v_mfma_i32_16x16x64_i8 v[62:65], v[122:125], v[198:201], 0
	v_mfma_i32_16x16x64_i8 v[62:65], v[126:129], v[202:205], v[62:65]
	v_mfma_i32_16x16x64_i8 v[58:61], v[142:145], v[202:205], 0
	v_mfma_i32_16x16x64_i8 v[58:61], v[134:137], v[198:201], v[58:61]
	v_mfma_i32_16x16x64_i8 v[42:45], v[134:137], v[206:209], 0
	v_mfma_i32_16x16x64_i8 v[42:45], v[142:145], v[212:215], v[42:45]
	v_mfma_i32_16x16x64_i8 v[46:49], v[126:129], v[212:215], 0
	v_mfma_i32_16x16x64_i8 v[46:49], v[122:125], v[206:209], v[46:49]
	v_mfma_i32_16x16x64_i8 v[30:33], v[122:125], v[216:219], 0
	v_mfma_i32_16x16x64_i8 v[30:33], v[126:129], v[220:223], v[30:33]
	v_mfma_i32_16x16x64_i8 v[26:29], v[142:145], v[220:223], 0
	v_mfma_i32_16x16x64_i8 v[26:29], v[134:137], v[216:219], v[26:29]
	v_mfma_i32_16x16x64_i8 v[10:13], v[134:137], v[224:227], 0
	v_mfma_i32_16x16x64_i8 v[10:13], v[142:145], v[228:231], v[10:13]
	v_mfma_i32_16x16x64_i8 v[14:17], v[126:129], v[228:231], 0
	v_mfma_i32_16x16x64_i8 v[14:17], v[122:125], v[224:227], v[14:17]
	s_setprio 0
	s_setprio 1
	v_mfma_i32_16x16x64_i8 v[6:9], v[182:185], v[224:227], 0
	v_mfma_i32_16x16x64_i8 v[6:9], v[186:189], v[228:231], v[6:9]
	v_mfma_i32_16x16x64_i8 v[2:5], v[194:197], v[228:231], 0
	v_mfma_i32_16x16x64_i8 v[2:5], v[190:193], v[224:227], v[2:5]
	v_mfma_i32_16x16x64_i8 v[18:21], v[190:193], v[216:219], 0
	v_mfma_i32_16x16x64_i8 v[18:21], v[194:197], v[220:223], v[18:21]
	v_mfma_i32_16x16x64_i8 v[22:25], v[186:189], v[220:223], 0
	v_mfma_i32_16x16x64_i8 v[22:25], v[182:185], v[216:219], v[22:25]
	v_mfma_i32_16x16x64_i8 v[38:41], v[182:185], v[206:209], 0
	v_mfma_i32_16x16x64_i8 v[38:41], v[186:189], v[212:215], v[38:41]
	v_mfma_i32_16x16x64_i8 v[34:37], v[194:197], v[212:215], 0
	v_mfma_i32_16x16x64_i8 v[34:37], v[190:193], v[206:209], v[34:37]
	v_mfma_i32_16x16x64_i8 v[50:53], v[190:193], v[198:201], 0
	v_mfma_i32_16x16x64_i8 v[50:53], v[194:197], v[202:205], v[50:53]
	v_mfma_i32_16x16x64_i8 v[54:57], v[186:189], v[202:205], 0
	v_mfma_i32_16x16x64_i8 v[54:57], v[182:185], v[198:201], v[54:57]
	s_setprio 0
	s_barrier
	s_add_i32 s51, 0, 0x18000
	s_add_i32 s63, 0, 0x1c000
	v_add_u32_e32 v142, s51, v173
	v_add_u32_e32 v172, s63, v173
	ds_read_b128 v[122:125], v142
	ds_read_b128 v[126:129], v142 offset:1024
	ds_read_b128 v[134:137], v142 offset:2048
	ds_read_b128 v[142:145], v142 offset:3072
	ds_read_b128 v[182:185], v172
	ds_read_b128 v[186:189], v172 offset:1024
	ds_read_b128 v[190:193], v172 offset:2048
	ds_read_b128 v[194:197], v172 offset:3072
	s_add_u32 s66, s66, 0x80000
	s_addc_u32 s67, s67, 0
	s_mov_b32 m0, s20
	v_lshl_add_u64 v[236:237], s[66:67], 0, v[146:147]
	ds_read_b128 v[198:201], v171 offset:32768
	ds_read_b128 v[202:205], v171 offset:33792
	ds_read_b128 v[206:209], v171 offset:34816
	ds_read_b128 v[212:215], v171 offset:35840
	ds_read_b128 v[216:219], v171 offset:36864
	ds_read_b128 v[220:223], v171 offset:37888
	ds_read_b128 v[224:227], v171 offset:38912
	ds_read_b128 v[228:231], v171 offset:39936
	global_load_lds_dwordx4 v[236:237], off
	v_lshl_add_u64 v[236:237], s[66:67], 0, v[150:151]
	s_mov_b32 m0, s21
	s_nop 0
	global_load_lds_dwordx4 v[236:237], off
	s_waitcnt vmcnt(8)
	s_waitcnt lgkmcnt(0)
	s_barrier
	s_setprio 1
	s_waitcnt lgkmcnt(0)
	v_mfma_i32_16x16x64_i8 v[138:141], v[122:125], v[198:201], v[138:141]
	v_mfma_i32_16x16x64_i8 v[138:141], v[126:129], v[202:205], v[138:141]
	v_mfma_i32_16x16x64_i8 v[130:133], v[142:145], v[202:205], v[130:133]
	v_mfma_i32_16x16x64_i8 v[130:133], v[134:137], v[198:201], v[130:133]
	v_mfma_i32_16x16x64_i8 v[106:109], v[134:137], v[206:209], v[106:109]
	v_mfma_i32_16x16x64_i8 v[106:109], v[142:145], v[212:215], v[106:109]
	v_mfma_i32_16x16x64_i8 v[110:113], v[126:129], v[212:215], v[110:113]
	v_mfma_i32_16x16x64_i8 v[110:113], v[122:125], v[206:209], v[110:113]
	v_mfma_i32_16x16x64_i8 v[94:97], v[122:125], v[216:219], v[94:97]
	v_mfma_i32_16x16x64_i8 v[94:97], v[126:129], v[220:223], v[94:97]
	v_mfma_i32_16x16x64_i8 v[90:93], v[142:145], v[220:223], v[90:93]
	v_mfma_i32_16x16x64_i8 v[90:93], v[134:137], v[216:219], v[90:93]
	v_mfma_i32_16x16x64_i8 v[74:77], v[134:137], v[224:227], v[74:77]
	v_mfma_i32_16x16x64_i8 v[74:77], v[142:145], v[228:231], v[74:77]
	v_mfma_i32_16x16x64_i8 v[78:81], v[126:129], v[228:231], v[78:81]
	v_mfma_i32_16x16x64_i8 v[78:81], v[122:125], v[224:227], v[78:81]
	s_setprio 0
	s_setprio 1
	v_mfma_i32_16x16x64_i8 v[70:73], v[182:185], v[224:227], v[70:73]
	v_mfma_i32_16x16x64_i8 v[70:73], v[186:189], v[228:231], v[70:73]
	v_mfma_i32_16x16x64_i8 v[66:69], v[194:197], v[228:231], v[66:69]
	v_mfma_i32_16x16x64_i8 v[66:69], v[190:193], v[224:227], v[66:69]
	v_mfma_i32_16x16x64_i8 v[82:85], v[190:193], v[216:219], v[82:85]
	v_mfma_i32_16x16x64_i8 v[82:85], v[194:197], v[220:223], v[82:85]
	v_mfma_i32_16x16x64_i8 v[86:89], v[186:189], v[220:223], v[86:89]
	v_mfma_i32_16x16x64_i8 v[86:89], v[182:185], v[216:219], v[86:89]
	v_mfma_i32_16x16x64_i8 v[102:105], v[182:185], v[206:209], v[102:105]
	v_mfma_i32_16x16x64_i8 v[102:105], v[186:189], v[212:215], v[102:105]
	v_mfma_i32_16x16x64_i8 v[98:101], v[194:197], v[212:215], v[98:101]
	v_mfma_i32_16x16x64_i8 v[98:101], v[190:193], v[206:209], v[98:101]
	v_mfma_i32_16x16x64_i8 v[114:117], v[190:193], v[198:201], v[114:117]
	v_mfma_i32_16x16x64_i8 v[114:117], v[194:197], v[202:205], v[114:117]
	v_mfma_i32_16x16x64_i8 v[118:121], v[186:189], v[202:205], v[118:121]
	v_mfma_i32_16x16x64_i8 v[118:121], v[182:185], v[198:201], v[118:121]
	s_setprio 0
	s_barrier
; #define PG8_STAGE(bufoff, gbase, voff) do { _Pragma("unroll") for (int _i = 0; _i < 2; ++_i) \
;         __builtin_amdgcn_global_load_lds((const unsigned*)((const char*)(gbase) + (voff)[_i]), (PG8_LAS unsigned*)(lds + (bufoff) + ldsw + _i * 8192), 16, 0, 0); } while (0)
; #define PG8_LDA(dst, b, h) do { _Pragma("unroll") for (int m = 0; m < 4; ++m) _Pragma("unroll") for (int k = 0; k < 2; ++k) dst[m][k] = *(const PG8_LAS bf16x8*)(lds + PG8_SA(b, h) + aoff + m * 2048 + k * 1024); } while (0)
; #define PG8_LDB(dst, b, h) do { _Pragma("unroll") for (int n = 0; n < 2; ++n) _Pragma("unroll") for (int k = 0; k < 2; ++k) dst[n][k] = *(const PG8_LAS bf16x8*)(lds + PG8_SB(b, h) + boff + n * 2048 + k * 1024); } while (0)
; template <class Epi, class Sched, bool ALIGN_EPI = false, bool SP2 = false>
; __device__ __forceinline__ void gemm_phase(PG8_LAS unsigned char* lds, const Gemm g, const Sched& S, const Epi& E) {
;     ...
;         for (int t = 0; t < nt; t += 2) {
;             const bool last = (t == nt - 2);
;             const char* a1 = cA + (size_t)(t + 1) * kstep;
;             const char* a2 = last ? nA : cA + (size_t)(t + 2) * kstep; const char* b2 = last ? nB : cB + (size_t)(t + 2) * kstep;
;             const char* a3 = a2 + kstep; const char* b3 = b2 + kstep;
;             if (last && has_next) S.a_ready(nxt);
;             if constexpr (SP2) {
;             PG8_LDB(B0, 0, 0); PG8_LDB(B1, 0, 1); PG8_SCHED; PG8_LDA(At, 0, 0); PG8_STAGE(PG8_SA(1, 1), a1 + hstepA, voffA);
;             PG8_WAIT_V(8); PG8_WAIT_L(0); PG8_BAR; PG8_MMA(0, 0, At, B0); PG8_MMA(0, 1, At, B1); PG8_BAR; PG8_SCHED;
;             PG8_LDA(At, 0, 1); PG8_STAGE(PG8_SB(0, 0), b2, voffB); PG8_STAGE(PG8_SB(0, 1), b2 + hstepB, voffB); PG8_STAGE(PG8_SA(0, 0), a2, voffA);
;             PG8_WAIT_V(8); PG8_WAIT_L(0); PG8_BAR; PG8_MMA(1, 0, At, B0); PG8_MMA(1, 1, At, B1); PG8_BAR; PG8_SCHED;
;             PG8_LDB(B0, 1, 0); PG8_LDB(B1, 1, 1); PG8_SCHED; PG8_LDA(At, 1, 0); PG8_STAGE(PG8_SA(0, 1), a2 + hstepA, voffA);
;             PG8_WAIT_V(8); PG8_WAIT_L(0); PG8_BAR; PG8_MMA(0, 0, At, B0); PG8_MMA(0, 1, At, B1); PG8_BAR; PG8_SCHED;
;             PG8_LDA(At, 1, 1); PG8_STAGE(PG8_SB(1, 0), b3, voffB); PG8_STAGE(PG8_SB(1, 1), b3 + hstepB, voffB); PG8_STAGE(PG8_SA(1, 0), a3, voffA);
;             PG8_WAIT_V(8); PG8_WAIT_L(0); PG8_BAR; PG8_MMA(1, 0, At, B0); PG8_MMA(1, 1, At, B1); PG8_BAR; PG8_SCHED;
	s_add_i32 s51, s51, s12
	v_lshl_add_u64 v[166:167], v[166:167], 0, s[42:43]
	s_mov_b32 m0, s51
	ds_read_b128 v[198:201], v171 offset:49152
	ds_read_b128 v[202:205], v171 offset:50176
	ds_read_b128 v[206:209], v171 offset:51200
	ds_read_b128 v[212:215], v171 offset:52224
	ds_read_b128 v[216:219], v171 offset:53248
	ds_read_b128 v[220:223], v171 offset:54272
	ds_read_b128 v[224:227], v171 offset:55296
	ds_read_b128 v[228:231], v171 offset:56320
	global_load_lds_dwordx4 v[166:167], off
	s_add_i32 m0, s51, 0x2000
	s_add_u32 s64, s64, 0x80080
	v_lshl_add_u64 v[166:167], v[176:177], 0, s[42:43]
	s_addc_u32 s65, s65, 0
	s_add_i32 s51, s63, s12
	global_load_lds_dwordx4 v[166:167], off
	v_lshl_add_u64 v[166:167], s[64:65], 0, v[148:149]
	s_mov_b32 m0, s51
	s_nop 0
	global_load_lds_dwordx4 v[166:167], off
	v_lshl_add_u64 v[166:167], s[64:65], 0, v[152:153]
	s_add_i32 m0, s51, 0x2000
	s_nop 0
	global_load_lds_dwordx4 v[166:167], off
	v_lshl_add_u64 v[166:167], v[232:233], 0, s[42:43]
	s_mov_b32 m0, s24
	s_nop 0
	global_load_lds_dwordx4 v[166:167], off
	v_lshl_add_u64 v[166:167], v[234:235], 0, s[42:43]
	s_mov_b32 m0, s25
	s_nop 0
	global_load_lds_dwordx4 v[166:167], off
	s_waitcnt vmcnt(8)
	s_waitcnt lgkmcnt(0)
	s_barrier
	s_setprio 1
	s_waitcnt lgkmcnt(0)
	v_mfma_i32_16x16x64_i8 v[62:65], v[122:125], v[198:201], v[62:65]
	v_mfma_i32_16x16x64_i8 v[62:65], v[126:129], v[202:205], v[62:65]
	v_mfma_i32_16x16x64_i8 v[58:61], v[142:145], v[202:205], v[58:61]
	v_mfma_i32_16x16x64_i8 v[58:61], v[134:137], v[198:201], v[58:61]
	v_mfma_i32_16x16x64_i8 v[42:45], v[134:137], v[206:209], v[42:45]
	v_mfma_i32_16x16x64_i8 v[42:45], v[142:145], v[212:215], v[42:45]
	v_mfma_i32_16x16x64_i8 v[46:49], v[126:129], v[212:215], v[46:49]
	v_mfma_i32_16x16x64_i8 v[46:49], v[122:125], v[206:209], v[46:49]
	v_mfma_i32_16x16x64_i8 v[30:33], v[122:125], v[216:219], v[30:33]
	v_mfma_i32_16x16x64_i8 v[30:33], v[126:129], v[220:223], v[30:33]
	v_mfma_i32_16x16x64_i8 v[26:29], v[142:145], v[220:223], v[26:29]
	v_mfma_i32_16x16x64_i8 v[26:29], v[134:137], v[216:219], v[26:29]
	v_mfma_i32_16x16x64_i8 v[10:13], v[134:137], v[224:227], v[10:13]
	v_mfma_i32_16x16x64_i8 v[10:13], v[142:145], v[228:231], v[10:13]
	v_mfma_i32_16x16x64_i8 v[14:17], v[126:129], v[228:231], v[14:17]
	v_mfma_i32_16x16x64_i8 v[14:17], v[122:125], v[224:227], v[14:17]
	s_setprio 0
	s_setprio 1
	v_mfma_i32_16x16x64_i8 v[6:9], v[182:185], v[224:227], v[6:9]
	v_mfma_i32_16x16x64_i8 v[6:9], v[186:189], v[228:231], v[6:9]
	v_mfma_i32_16x16x64_i8 v[2:5], v[194:197], v[228:231], v[2:5]
	v_mfma_i32_16x16x64_i8 v[2:5], v[190:193], v[224:227], v[2:5]
	v_mfma_i32_16x16x64_i8 v[18:21], v[190:193], v[216:219], v[18:21]
	v_mfma_i32_16x16x64_i8 v[18:21], v[194:197], v[220:223], v[18:21]
	v_mfma_i32_16x16x64_i8 v[22:25], v[186:189], v[220:223], v[22:25]
	v_mfma_i32_16x16x64_i8 v[22:25], v[182:185], v[216:219], v[22:25]
	v_mfma_i32_16x16x64_i8 v[38:41], v[182:185], v[206:209], v[38:41]
	v_mfma_i32_16x16x64_i8 v[38:41], v[186:189], v[212:215], v[38:41]
	v_mfma_i32_16x16x64_i8 v[34:37], v[194:197], v[212:215], v[34:37]
	v_mfma_i32_16x16x64_i8 v[34:37], v[190:193], v[206:209], v[34:37]
	v_mfma_i32_16x16x64_i8 v[50:53], v[190:193], v[198:201], v[50:53]
	v_mfma_i32_16x16x64_i8 v[50:53], v[194:197], v[202:205], v[50:53]
	v_mfma_i32_16x16x64_i8 v[54:57], v[186:189], v[202:205], v[54:57]
	v_mfma_i32_16x16x64_i8 v[54:57], v[182:185], v[198:201], v[54:57]
	s_setprio 0
	s_barrier
	s_add_i32 s50, s50, 2
	s_add_u32 s0, s0, 0x100
	s_addc_u32 s1, s1, 0
	s_add_u32 s47, s47, 0x100
	s_addc_u32 s49, s49, 0
.LBB0_275:
	ds_read_b128 v[122:125], v169
	ds_read_b128 v[126:129], v169 offset:1024
	ds_read_b128 v[134:137], v169 offset:2048
	ds_read_b128 v[142:145], v169 offset:3072
	ds_read_b128 v[182:185], v170
	ds_read_b128 v[186:189], v170 offset:1024
	ds_read_b128 v[190:193], v170 offset:2048
	ds_read_b128 v[194:197], v170 offset:3072
	s_add_u32 s51, s0, 0xfff80080
	s_addc_u32 s63, s1, -1
	s_cmp_eq_u32 s50, 28
	s_cselect_b32 s67, s55, s63
	s_cselect_b32 s66, s54, s51
	s_cselect_b32 s65, s37, s49
	s_cselect_b32 s64, s46, s47
	v_lshl_add_u64 v[166:167], s[0:1], 0, v[158:159]
	s_add_i32 m0, s18, 0xc000
	ds_read_b128 v[198:201], v171
	ds_read_b128 v[202:205], v171 offset:1024
	ds_read_b128 v[206:209], v171 offset:2048
	ds_read_b128 v[212:215], v171 offset:3072
	ds_read_b128 v[216:219], v171 offset:4096
	ds_read_b128 v[220:223], v171 offset:5120
	ds_read_b128 v[224:227], v171 offset:6144
	ds_read_b128 v[228:231], v171 offset:7168
	global_load_lds_dwordx4 v[166:167], off
	v_lshl_add_u64 v[166:167], s[0:1], 0, v[160:161]
	s_add_i32 m0, s18, 0xe000
	s_nop 0
	global_load_lds_dwordx4 v[166:167], off
	s_waitcnt vmcnt(8)
	s_waitcnt lgkmcnt(0)
	s_barrier
; #define PG8_STAGE(bufoff, gbase, voff) do { _Pragma("unroll") for (int _i = 0; _i < 2; ++_i) \
;         __builtin_amdgcn_global_load_lds((const unsigned*)((const char*)(gbase) + (voff)[_i]), (PG8_LAS unsigned*)(lds + (bufoff) + ldsw + _i * 8192), 16, 0, 0); } while (0)
; #define PG8_LDA(dst, b, h) do { _Pragma("unroll") for (int m = 0; m < 4; ++m) _Pragma("unroll") for (int k = 0; k < 2; ++k) dst[m][k] = *(const PG8_LAS bf16x8*)(lds + PG8_SA(b, h) + aoff + m * 2048 + k * 1024); } while (0)
; #define PG8_LDB(dst, b, h) do { _Pragma("unroll") for (int n = 0; n < 2; ++n) _Pragma("unroll") for (int k = 0; k < 2; ++k) dst[n][k] = *(const PG8_LAS bf16x8*)(lds + PG8_SB(b, h) + boff + n * 2048 + k * 1024); } while (0)
; #define PG8_MMA(ai, bj, At, Bt) do { __builtin_amdgcn_s_setprio(1); _Pragma("unroll") for (int m = 0; m < 4; ++m) _Pragma("unroll") for (int n = 0; n < 2; ++n) _Pragma("unroll") for (int k = 0; k < 2; ++k) \
;         acc[ai][bj][m][n] = mma16(Bt[n][k], At[m][k], acc[ai][bj][m][n]); __builtin_amdgcn_s_setprio(0); } while (0)
; #define PG8_WAIT_V(n) asm volatile("s_waitcnt vmcnt(" #n ")" ::: "memory")
; #define PG8_WAIT_L(n) asm volatile("s_waitcnt lgkmcnt(" #n ")" ::: "memory")
; #define PG8_BAR __builtin_amdgcn_s_barrier()
; #define PG8_SCHED __builtin_amdgcn_sched_barrier(0)
; template <class Epi, class Sched, bool ALIGN_EPI = false, bool SP2 = false>
; __device__ __forceinline__ void gemm_phase(PG8_LAS unsigned char* lds, const Gemm g, const Sched& S, const Epi& E) {
;     ...
;             PG8_LDB(B0, 0, 0); PG8_LDB(B1, 0, 1); PG8_SCHED; PG8_LDA(At, 0, 0); PG8_STAGE(PG8_SA(1, 1), a1 + hstepA, voffA);
;             PG8_WAIT_V(8); PG8_WAIT_L(0); PG8_BAR; PG8_MMA(0, 0, At, B0); PG8_MMA(0, 1, At, B1); PG8_BAR; PG8_SCHED;
;             PG8_LDA(At, 0, 1); PG8_STAGE(PG8_SB(0, 0), b2, voffB); PG8_STAGE(PG8_SB(0, 1), b2 + hstepB, voffB); PG8_STAGE(PG8_SA(0, 0), a2, voffA);
;             PG8_WAIT_V(8); PG8_WAIT_L(0); PG8_BAR; PG8_MMA(1, 0, At, B0); PG8_MMA(1, 1, At, B1); PG8_BAR; PG8_SCHED;
	s_setprio 1
	s_waitcnt lgkmcnt(0)
	v_mfma_i32_16x16x64_i8 v[138:141], v[122:125], v[198:201], v[138:141]
	v_mfma_i32_16x16x64_i8 v[138:141], v[126:129], v[202:205], v[138:141]
	v_mfma_i32_16x16x64_i8 v[130:133], v[142:145], v[202:205], v[130:133]
	v_mfma_i32_16x16x64_i8 v[130:133], v[134:137], v[198:201], v[130:133]
	v_mfma_i32_16x16x64_i8 v[106:109], v[134:137], v[206:209], v[106:109]
	v_mfma_i32_16x16x64_i8 v[106:109], v[142:145], v[212:215], v[106:109]
	v_mfma_i32_16x16x64_i8 v[110:113], v[126:129], v[212:215], v[110:113]
	v_mfma_i32_16x16x64_i8 v[110:113], v[122:125], v[206:209], v[110:113]
	v_mfma_i32_16x16x64_i8 v[94:97], v[122:125], v[216:219], v[94:97]
	v_mfma_i32_16x16x64_i8 v[94:97], v[126:129], v[220:223], v[94:97]
	v_mfma_i32_16x16x64_i8 v[90:93], v[142:145], v[220:223], v[90:93]
	v_mfma_i32_16x16x64_i8 v[90:93], v[134:137], v[216:219], v[90:93]
	v_mfma_i32_16x16x64_i8 v[74:77], v[134:137], v[224:227], v[74:77]
	v_mfma_i32_16x16x64_i8 v[74:77], v[142:145], v[228:231], v[74:77]
	v_mfma_i32_16x16x64_i8 v[78:81], v[126:129], v[228:231], v[78:81]
	v_mfma_i32_16x16x64_i8 v[78:81], v[122:125], v[224:227], v[78:81]
	s_setprio 0
	s_setprio 1
	v_mfma_i32_16x16x64_i8 v[70:73], v[182:185], v[224:227], v[70:73]
	v_mfma_i32_16x16x64_i8 v[70:73], v[186:189], v[228:231], v[70:73]
	v_mfma_i32_16x16x64_i8 v[66:69], v[194:197], v[228:231], v[66:69]
	v_mfma_i32_16x16x64_i8 v[66:69], v[190:193], v[224:227], v[66:69]
	v_mfma_i32_16x16x64_i8 v[82:85], v[190:193], v[216:219], v[82:85]
	v_mfma_i32_16x16x64_i8 v[82:85], v[194:197], v[220:223], v[82:85]
	v_mfma_i32_16x16x64_i8 v[86:89], v[186:189], v[220:223], v[86:89]
	v_mfma_i32_16x16x64_i8 v[86:89], v[182:185], v[216:219], v[86:89]
	v_mfma_i32_16x16x64_i8 v[102:105], v[182:185], v[206:209], v[102:105]
	v_mfma_i32_16x16x64_i8 v[102:105], v[186:189], v[212:215], v[102:105]
	v_mfma_i32_16x16x64_i8 v[98:101], v[194:197], v[212:215], v[98:101]
	v_mfma_i32_16x16x64_i8 v[98:101], v[190:193], v[206:209], v[98:101]
	v_mfma_i32_16x16x64_i8 v[114:117], v[190:193], v[198:201], v[114:117]
	v_mfma_i32_16x16x64_i8 v[114:117], v[194:197], v[202:205], v[114:117]
	v_mfma_i32_16x16x64_i8 v[118:121], v[186:189], v[202:205], v[118:121]
	v_mfma_i32_16x16x64_i8 v[118:121], v[182:185], v[198:201], v[118:121]
	s_setprio 0
	s_barrier
	s_add_i32 s51, s28, s12
	v_lshl_add_u64 v[166:167], s[64:65], 0, v[148:149]
	s_mov_b32 m0, s51
	ds_read_b128 v[198:201], v171 offset:16384
	ds_read_b128 v[202:205], v171 offset:17408
	ds_read_b128 v[206:209], v171 offset:18432
	ds_read_b128 v[212:215], v171 offset:19456
	ds_read_b128 v[216:219], v171 offset:20480
	ds_read_b128 v[220:223], v171 offset:21504
	ds_read_b128 v[224:227], v171 offset:22528
	ds_read_b128 v[228:231], v171 offset:23552
	global_load_lds_dwordx4 v[166:167], off
	s_add_i32 m0, s51, 0x2000
	s_add_u32 s68, s64, 0x80000
	v_lshl_add_u64 v[176:177], s[64:65], 0, v[152:153]
	s_addc_u32 s69, s65, 0
	s_add_i32 s51, s29, s12
	global_load_lds_dwordx4 v[176:177], off
	v_lshl_add_u64 v[232:233], s[68:69], 0, v[148:149]
	s_mov_b32 m0, s51
	v_lshl_add_u64 v[234:235], s[66:67], 0, v[150:151]
	global_load_lds_dwordx4 v[232:233], off
	v_lshl_add_u64 v[232:233], s[68:69], 0, v[152:153]
	s_add_i32 m0, s51, 0x2000
	s_nop 0
	global_load_lds_dwordx4 v[232:233], off
	v_lshl_add_u64 v[232:233], s[66:67], 0, v[146:147]
	s_mov_b32 m0, s18
	s_nop 0
	global_load_lds_dwordx4 v[232:233], off
	s_mov_b32 m0, s19
	s_nop 0
	global_load_lds_dwordx4 v[234:235], off
	s_waitcnt vmcnt(8)
	s_waitcnt lgkmcnt(0)
	s_barrier
	s_setprio 1
	s_waitcnt lgkmcnt(0)
	v_mfma_i32_16x16x64_i8 v[62:65], v[122:125], v[198:201], v[62:65]
	v_mfma_i32_16x16x64_i8 v[62:65], v[126:129], v[202:205], v[62:65]
	v_mfma_i32_16x16x64_i8 v[58:61], v[142:145], v[202:205], v[58:61]
	v_mfma_i32_16x16x64_i8 v[58:61], v[134:137], v[198:201], v[58:61]
	v_mfma_i32_16x16x64_i8 v[42:45], v[134:137], v[206:209], v[42:45]
	v_mfma_i32_16x16x64_i8 v[42:45], v[142:145], v[212:215], v[42:45]
	v_mfma_i32_16x16x64_i8 v[46:49], v[126:129], v[212:215], v[46:49]
	v_mfma_i32_16x16x64_i8 v[46:49], v[122:125], v[206:209], v[46:49]
	v_mfma_i32_16x16x64_i8 v[30:33], v[122:125], v[216:219], v[30:33]
	v_mfma_i32_16x16x64_i8 v[30:33], v[126:129], v[220:223], v[30:33]
	v_mfma_i32_16x16x64_i8 v[26:29], v[142:145], v[220:223], v[26:29]
	v_mfma_i32_16x16x64_i8 v[26:29], v[134:137], v[216:219], v[26:29]
	v_mfma_i32_16x16x64_i8 v[10:13], v[134:137], v[224:227], v[10:13]
	v_mfma_i32_16x16x64_i8 v[10:13], v[142:145], v[228:231], v[10:13]
	v_mfma_i32_16x16x64_i8 v[14:17], v[126:129], v[228:231], v[14:17]
	v_mfma_i32_16x16x64_i8 v[14:17], v[122:125], v[224:227], v[14:17]
	s_setprio 0
	s_setprio 1
	v_mfma_i32_16x16x64_i8 v[6:9], v[182:185], v[224:227], v[6:9]
	v_mfma_i32_16x16x64_i8 v[6:9], v[186:189], v[228:231], v[6:9]
	v_mfma_i32_16x16x64_i8 v[2:5], v[194:197], v[228:231], v[2:5]
	v_mfma_i32_16x16x64_i8 v[2:5], v[190:193], v[224:227], v[2:5]
	v_mfma_i32_16x16x64_i8 v[18:21], v[190:193], v[216:219], v[18:21]
	v_mfma_i32_16x16x64_i8 v[18:21], v[194:197], v[220:223], v[18:21]
	v_mfma_i32_16x16x64_i8 v[22:25], v[186:189], v[220:223], v[22:25]
	v_mfma_i32_16x16x64_i8 v[22:25], v[182:185], v[216:219], v[22:25]
	v_mfma_i32_16x16x64_i8 v[38:41], v[182:185], v[206:209], v[38:41]
	v_mfma_i32_16x16x64_i8 v[38:41], v[186:189], v[212:215], v[38:41]
	v_mfma_i32_16x16x64_i8 v[34:37], v[194:197], v[212:215], v[34:37]
	v_mfma_i32_16x16x64_i8 v[34:37], v[190:193], v[206:209], v[34:37]
	v_mfma_i32_16x16x64_i8 v[50:53], v[190:193], v[198:201], v[50:53]
	v_mfma_i32_16x16x64_i8 v[50:53], v[194:197], v[202:205], v[50:53]
	v_mfma_i32_16x16x64_i8 v[54:57], v[186:189], v[202:205], v[54:57]
	v_mfma_i32_16x16x64_i8 v[54:57], v[182:185], v[198:201], v[54:57]
	s_setprio 0
	s_barrier
; #define PG8_STAGE(bufoff, gbase, voff) do { _Pragma("unroll") for (int _i = 0; _i < 2; ++_i) \
;         __builtin_amdgcn_global_load_lds((const unsigned*)((const char*)(gbase) + (voff)[_i]), (PG8_LAS unsigned*)(lds + (bufoff) + ldsw + _i * 8192), 16, 0, 0); } while (0)
; #define PG8_LDA(dst, b, h) do { _Pragma("unroll") for (int m = 0; m < 4; ++m) _Pragma("unroll") for (int k = 0; k < 2; ++k) dst[m][k] = *(const PG8_LAS bf16x8*)(lds + PG8_SA(b, h) + aoff + m * 2048 + k * 1024); } while (0)
; #define PG8_LDB(dst, b, h) do { _Pragma("unroll") for (int n = 0; n < 2; ++n) _Pragma("unroll") for (int k = 0; k < 2; ++k) dst[n][k] = *(const PG8_LAS bf16x8*)(lds + PG8_SB(b, h) + boff + n * 2048 + k * 1024); } while (0)
; #define PG8_MMA(ai, bj, At, Bt) do { __builtin_amdgcn_s_setprio(1); _Pragma("unroll") for (int m = 0; m < 4; ++m) _Pragma("unroll") for (int n = 0; n < 2; ++n) _Pragma("unroll") for (int k = 0; k < 2; ++k) \
;         acc[ai][bj][m][n] = mma16(Bt[n][k], At[m][k], acc[ai][bj][m][n]); __builtin_amdgcn_s_setprio(0); } while (0)
; #define PG8_WAIT_V(n) asm volatile("s_waitcnt vmcnt(" #n ")" ::: "memory")
; #define PG8_WAIT_L(n) asm volatile("s_waitcnt lgkmcnt(" #n ")" ::: "memory")
; #define PG8_BAR __builtin_amdgcn_s_barrier()
; #define PG8_SCHED __builtin_amdgcn_sched_barrier(0)
; template <class Epi, class Sched, bool ALIGN_EPI = false, bool SP2 = false>
; __device__ __forceinline__ void gemm_phase(PG8_LAS unsigned char* lds, const Gemm g, const Sched& S, const Epi& E) {
;     ...
;             PG8_LDB(B0, 1, 0); PG8_LDB(B1, 1, 1); PG8_SCHED; PG8_LDA(At, 1, 0); PG8_STAGE(PG8_SA(0, 1), a2 + hstepA, voffA);
;             PG8_WAIT_V(8); PG8_WAIT_L(0); PG8_BAR; PG8_MMA(0, 0, At, B0); PG8_MMA(0, 1, At, B1); PG8_BAR; PG8_SCHED;
	s_add_i32 s51, 0, 0x18000
	s_add_i32 s63, 0, 0x1c000
	v_add_u32_e32 v142, s51, v173
	v_add_u32_e32 v172, s63, v173
	ds_read_b128 v[122:125], v142
	ds_read_b128 v[126:129], v142 offset:1024
	ds_read_b128 v[134:137], v142 offset:2048
	ds_read_b128 v[142:145], v142 offset:3072
	ds_read_b128 v[182:185], v172
	ds_read_b128 v[186:189], v172 offset:1024
	ds_read_b128 v[190:193], v172 offset:2048
	ds_read_b128 v[194:197], v172 offset:3072
	s_add_u32 s66, s66, 0x80000
	s_addc_u32 s67, s67, 0
	s_mov_b32 m0, s20
	v_lshl_add_u64 v[236:237], s[66:67], 0, v[146:147]
	ds_read_b128 v[198:201], v171 offset:32768
	ds_read_b128 v[202:205], v171 offset:33792
	ds_read_b128 v[206:209], v171 offset:34816
	ds_read_b128 v[212:215], v171 offset:35840
	ds_read_b128 v[216:219], v171 offset:36864
	ds_read_b128 v[220:223], v171 offset:37888
	ds_read_b128 v[224:227], v171 offset:38912
	ds_read_b128 v[228:231], v171 offset:39936
	global_load_lds_dwordx4 v[236:237], off
	v_lshl_add_u64 v[236:237], s[66:67], 0, v[150:151]
	s_mov_b32 m0, s21
	s_nop 0
	global_load_lds_dwordx4 v[236:237], off
	s_waitcnt vmcnt(8)
	s_waitcnt lgkmcnt(0)
	s_barrier
	s_setprio 1
	s_waitcnt lgkmcnt(0)
	v_mfma_i32_16x16x64_i8 v[138:141], v[122:125], v[198:201], v[138:141]
	v_mfma_i32_16x16x64_i8 v[138:141], v[126:129], v[202:205], v[138:141]
	v_mfma_i32_16x16x64_i8 v[130:133], v[142:145], v[202:205], v[130:133]
	v_mfma_i32_16x16x64_i8 v[130:133], v[134:137], v[198:201], v[130:133]
	v_mfma_i32_16x16x64_i8 v[106:109], v[134:137], v[206:209], v[106:109]
	v_mfma_i32_16x16x64_i8 v[106:109], v[142:145], v[212:215], v[106:109]
	v_mfma_i32_16x16x64_i8 v[110:113], v[126:129], v[212:215], v[110:113]
	v_mfma_i32_16x16x64_i8 v[110:113], v[122:125], v[206:209], v[110:113]
	v_mfma_i32_16x16x64_i8 v[94:97], v[122:125], v[216:219], v[94:97]
	v_mfma_i32_16x16x64_i8 v[94:97], v[126:129], v[220:223], v[94:97]
	v_mfma_i32_16x16x64_i8 v[90:93], v[142:145], v[220:223], v[90:93]
	v_mfma_i32_16x16x64_i8 v[90:93], v[134:137], v[216:219], v[90:93]
	v_mfma_i32_16x16x64_i8 v[74:77], v[134:137], v[224:227], v[74:77]
	v_mfma_i32_16x16x64_i8 v[74:77], v[142:145], v[228:231], v[74:77]
	v_mfma_i32_16x16x64_i8 v[78:81], v[126:129], v[228:231], v[78:81]
	v_mfma_i32_16x16x64_i8 v[78:81], v[122:125], v[224:227], v[78:81]
	s_setprio 0
	s_setprio 1
	v_mfma_i32_16x16x64_i8 v[70:73], v[182:185], v[224:227], v[70:73]
	v_mfma_i32_16x16x64_i8 v[70:73], v[186:189], v[228:231], v[70:73]
	v_mfma_i32_16x16x64_i8 v[66:69], v[194:197], v[228:231], v[66:69]
	v_mfma_i32_16x16x64_i8 v[66:69], v[190:193], v[224:227], v[66:69]
	v_mfma_i32_16x16x64_i8 v[82:85], v[190:193], v[216:219], v[82:85]
	v_mfma_i32_16x16x64_i8 v[82:85], v[194:197], v[220:223], v[82:85]
	v_mfma_i32_16x16x64_i8 v[86:89], v[186:189], v[220:223], v[86:89]
	v_mfma_i32_16x16x64_i8 v[86:89], v[182:185], v[216:219], v[86:89]
	v_mfma_i32_16x16x64_i8 v[102:105], v[182:185], v[206:209], v[102:105]
	v_mfma_i32_16x16x64_i8 v[102:105], v[186:189], v[212:215], v[102:105]
	v_mfma_i32_16x16x64_i8 v[98:101], v[194:197], v[212:215], v[98:101]
	v_mfma_i32_16x16x64_i8 v[98:101], v[190:193], v[206:209], v[98:101]
	v_mfma_i32_16x16x64_i8 v[114:117], v[190:193], v[198:201], v[114:117]
	v_mfma_i32_16x16x64_i8 v[114:117], v[194:197], v[202:205], v[114:117]
	v_mfma_i32_16x16x64_i8 v[118:121], v[186:189], v[202:205], v[118:121]
	v_mfma_i32_16x16x64_i8 v[118:121], v[182:185], v[198:201], v[118:121]
	s_setprio 0
	s_barrier
; #define PG8_STAGE(bufoff, gbase, voff) do { _Pragma("unroll") for (int _i = 0; _i < 2; ++_i) \
;         __builtin_amdgcn_global_load_lds((const unsigned*)((const char*)(gbase) + (voff)[_i]), (PG8_LAS unsigned*)(lds + (bufoff) + ldsw + _i * 8192), 16, 0, 0); } while (0)
; #define PG8_LDA(dst, b, h) do { _Pragma("unroll") for (int m = 0; m < 4; ++m) _Pragma("unroll") for (int k = 0; k < 2; ++k) dst[m][k] = *(const PG8_LAS bf16x8*)(lds + PG8_SA(b, h) + aoff + m * 2048 + k * 1024); } while (0)
; #define PG8_MMA(ai, bj, At, Bt) do { __builtin_amdgcn_s_setprio(1); _Pragma("unroll") for (int m = 0; m < 4; ++m) _Pragma("unroll") for (int n = 0; n < 2; ++n) _Pragma("unroll") for (int k = 0; k < 2; ++k) \
;         acc[ai][bj][m][n] = mma16(Bt[n][k], At[m][k], acc[ai][bj][m][n]); __builtin_amdgcn_s_setprio(0); } while (0)
; #define PG8_WAIT_V(n) asm volatile("s_waitcnt vmcnt(" #n ")" ::: "memory")
; #define PG8_WAIT_L(n) asm volatile("s_waitcnt lgkmcnt(" #n ")" ::: "memory")
; #define PG8_BAR __builtin_amdgcn_s_barrier()
; #define PG8_SCHED __builtin_amdgcn_sched_barrier(0)
; template <class Epi, class Sched, bool ALIGN_EPI = false, bool SP2 = false>
; __device__ __forceinline__ void gemm_phase(PG8_LAS unsigned char* lds, const Gemm g, const Sched& S, const Epi& E) {
;     ...
;             PG8_LDA(At, 1, 1); PG8_STAGE(PG8_SB(1, 0), b3, voffB); PG8_STAGE(PG8_SB(1, 1), b3 + hstepB, voffB); PG8_STAGE(PG8_SA(1, 0), a3, voffA);
;             PG8_WAIT_V(8); PG8_WAIT_L(0); PG8_BAR; PG8_MMA(1, 0, At, B0); PG8_MMA(1, 1, At, B1); PG8_BAR; PG8_SCHED;
;     ...
;         if constexpr (ALIGN_EPI) { if (wr == 0) PG8_BAR; }
	s_add_i32 s51, s51, s12
	v_lshl_add_u64 v[166:167], v[166:167], 0, s[42:43]
	s_mov_b32 m0, s51
	ds_read_b128 v[198:201], v171 offset:49152
	ds_read_b128 v[202:205], v171 offset:50176
	ds_read_b128 v[206:209], v171 offset:51200
	ds_read_b128 v[212:215], v171 offset:52224
	ds_read_b128 v[216:219], v171 offset:53248
	ds_read_b128 v[220:223], v171 offset:54272
	ds_read_b128 v[224:227], v171 offset:55296
	ds_read_b128 v[228:231], v171 offset:56320
	global_load_lds_dwordx4 v[166:167], off
	s_add_i32 m0, s51, 0x2000
	s_add_u32 s64, s64, 0x80080
	v_lshl_add_u64 v[166:167], v[176:177], 0, s[42:43]
	s_addc_u32 s65, s65, 0
	s_add_i32 s51, s63, s12
	global_load_lds_dwordx4 v[166:167], off
	v_lshl_add_u64 v[166:167], s[64:65], 0, v[148:149]
	s_mov_b32 m0, s51
	s_nop 0
	global_load_lds_dwordx4 v[166:167], off
	v_lshl_add_u64 v[166:167], s[64:65], 0, v[152:153]
	s_add_i32 m0, s51, 0x2000
	s_nop 0
	global_load_lds_dwordx4 v[166:167], off
	v_lshl_add_u64 v[166:167], v[232:233], 0, s[42:43]
	s_mov_b32 m0, s24
	s_nop 0
	global_load_lds_dwordx4 v[166:167], off
	v_lshl_add_u64 v[166:167], v[234:235], 0, s[42:43]
	s_mov_b32 m0, s25
	s_nop 0
	global_load_lds_dwordx4 v[166:167], off
	s_waitcnt vmcnt(8)
	s_waitcnt lgkmcnt(0)
	s_barrier
	s_setprio 1
	s_waitcnt lgkmcnt(0)
	v_mfma_i32_16x16x64_i8 v[62:65], v[122:125], v[198:201], v[62:65]
	v_mfma_i32_16x16x64_i8 v[62:65], v[126:129], v[202:205], v[62:65]
	v_mfma_i32_16x16x64_i8 v[58:61], v[142:145], v[202:205], v[58:61]
	v_mfma_i32_16x16x64_i8 v[58:61], v[134:137], v[198:201], v[58:61]
	v_mfma_i32_16x16x64_i8 v[42:45], v[134:137], v[206:209], v[42:45]
	v_mfma_i32_16x16x64_i8 v[42:45], v[142:145], v[212:215], v[42:45]
	v_mfma_i32_16x16x64_i8 v[46:49], v[126:129], v[212:215], v[46:49]
	v_mfma_i32_16x16x64_i8 v[46:49], v[122:125], v[206:209], v[46:49]
	v_mfma_i32_16x16x64_i8 v[30:33], v[122:125], v[216:219], v[30:33]
	v_mfma_i32_16x16x64_i8 v[30:33], v[126:129], v[220:223], v[30:33]
	v_mfma_i32_16x16x64_i8 v[26:29], v[142:145], v[220:223], v[26:29]
	v_mfma_i32_16x16x64_i8 v[26:29], v[134:137], v[216:219], v[26:29]
	v_mfma_i32_16x16x64_i8 v[10:13], v[134:137], v[224:227], v[10:13]
	v_mfma_i32_16x16x64_i8 v[10:13], v[142:145], v[228:231], v[10:13]
	v_mfma_i32_16x16x64_i8 v[14:17], v[126:129], v[228:231], v[14:17]
	v_mfma_i32_16x16x64_i8 v[14:17], v[122:125], v[224:227], v[14:17]
	s_setprio 0
	s_setprio 1
	v_mfma_i32_16x16x64_i8 v[6:9], v[182:185], v[224:227], v[6:9]
	v_mfma_i32_16x16x64_i8 v[6:9], v[186:189], v[228:231], v[6:9]
	v_mfma_i32_16x16x64_i8 v[2:5], v[194:197], v[228:231], v[2:5]
	v_mfma_i32_16x16x64_i8 v[2:5], v[190:193], v[224:227], v[2:5]
	v_mfma_i32_16x16x64_i8 v[18:21], v[190:193], v[216:219], v[18:21]
	v_mfma_i32_16x16x64_i8 v[18:21], v[194:197], v[220:223], v[18:21]
	v_mfma_i32_16x16x64_i8 v[22:25], v[186:189], v[220:223], v[22:25]
	v_mfma_i32_16x16x64_i8 v[22:25], v[182:185], v[216:219], v[22:25]
	v_mfma_i32_16x16x64_i8 v[38:41], v[182:185], v[206:209], v[38:41]
	v_mfma_i32_16x16x64_i8 v[38:41], v[186:189], v[212:215], v[38:41]
	v_mfma_i32_16x16x64_i8 v[34:37], v[194:197], v[212:215], v[34:37]
	v_mfma_i32_16x16x64_i8 v[34:37], v[190:193], v[206:209], v[34:37]
	v_mfma_i32_16x16x64_i8 v[50:53], v[190:193], v[198:201], v[50:53]
	v_mfma_i32_16x16x64_i8 v[50:53], v[194:197], v[202:205], v[50:53]
	v_mfma_i32_16x16x64_i8 v[54:57], v[186:189], v[202:205], v[54:57]
	v_mfma_i32_16x16x64_i8 v[54:57], v[182:185], v[198:201], v[54:57]
	s_setprio 0
	s_barrier
	s_add_i32 s50, s50, 2
	s_add_u32 s0, s0, 0x100
	s_addc_u32 s1, s1, 0
	s_add_u32 s47, s47, 0x100
	s_addc_u32 s49, s49, 0
	s_cmp_gt_u32 s50, 29
	s_cbranch_scc0 .LBB0_275
	s_and_b64 vcc, exec, s[44:45]
	s_cbranch_vccz .LBB0_278
	s_barrier

; #define PG8_STAGE(bufoff, gbase, voff) do { _Pragma("unroll") for (int _i = 0; _i < 2; ++_i) \
;         __builtin_amdgcn_global_load_lds((const unsigned*)((const char*)(gbase) + (voff)[_i]), (PG8_LAS unsigned*)(lds + (bufoff) + ldsw + _i * 8192), 16, 0, 0); } while (0)
; #define PG8_LDA(dst, b, h) do { _Pragma("unroll") for (int m = 0; m < 4; ++m) _Pragma("unroll") for (int k = 0; k < 2; ++k) dst[m][k] = *(const PG8_LAS bf16x8*)(lds + PG8_SA(b, h) + aoff + m * 2048 + k * 1024); } while (0)
; #define PG8_LDB(dst, b, h) do { _Pragma("unroll") for (int n = 0; n < 2; ++n) _Pragma("unroll") for (int k = 0; k < 2; ++k) dst[n][k] = *(const PG8_LAS bf16x8*)(lds + PG8_SB(b, h) + boff + n * 2048 + k * 1024); } while (0)
; #define PG8_MMA(ai, bj, At, Bt) do { __builtin_amdgcn_s_setprio(1); _Pragma("unroll") for (int m = 0; m < 4; ++m) _Pragma("unroll") for (int n = 0; n < 2; ++n) _Pragma("unroll") for (int k = 0; k < 2; ++k) \
;         acc[ai][bj][m][n] = mma16(Bt[n][k], At[m][k], acc[ai][bj][m][n]); __builtin_amdgcn_s_setprio(0); } while (0)
; template <class Epi, class Sched, bool ALIGN_EPI = false, bool SP2 = false>
; __device__ __forceinline__ void gemm_phase(PG8_LAS unsigned char* lds, const Gemm g, const Sched& S, const Epi& E) {
;     ...
;         const bool has_next = S.next(ui + 1, nxt);
;         const char* nA = has_next ? PG8_ABASE(nxt) : cA; const char* nB = has_next ? PG8_BBASE(nxt) : cB;
; #pragma unroll 1
;         for (int t = 0; t < nt; t += 2) {
;             const bool last = (t == nt - 2);
;             const char* a1 = cA + (size_t)(t + 1) * kstep;
;             const char* a2 = last ? nA : cA + (size_t)(t + 2) * kstep; const char* b2 = last ? nB : cB + (size_t)(t + 2) * kstep;
;             const char* a3 = a2 + kstep; const char* b3 = b2 + kstep;
;             if (last && has_next) S.a_ready(nxt);
;             if constexpr (SP2) {
;             PG8_LDB(B0, 0, 0); PG8_LDB(B1, 0, 1); PG8_SCHED; PG8_LDA(At, 0, 0); PG8_STAGE(PG8_SA(1, 1), a1 + hstepA, voffA);
;             PG8_WAIT_V(8); PG8_WAIT_L(0); PG8_BAR; PG8_MMA(0, 0, At, B0); PG8_MMA(0, 1, At, B1); PG8_BAR; PG8_SCHED;
;             PG8_LDA(At, 0, 1); PG8_STAGE(PG8_SB(0, 0), b2, voffB); PG8_STAGE(PG8_SB(0, 1), b2 + hstepB, voffB); PG8_STAGE(PG8_SA(0, 0), a2, voffA);
;             PG8_WAIT_V(8); PG8_WAIT_L(0); PG8_BAR; PG8_MMA(1, 0, At, B0); PG8_MMA(1, 1, At, B1); PG8_BAR; PG8_SCHED;
.LBB0_388:
	s_ashr_i32 s43, s42, 31
	s_lshl_b64 s[26:27], s[42:43], 19
	s_add_u32 s50, s8, s26
	s_addc_u32 s51, s11, s27
	s_and_b64 s[0:1], s[0:1], exec
	s_cselect_b32 s25, s51, s55
	s_cselect_b32 s26, s50, s54
	s_add_u32 s0, s58, 0x100080
	s_addc_u32 s1, s59, 0
	s_add_u32 s27, s54, 0x100
	s_addc_u32 s28, s55, 0
	s_mov_b32 s29, -2
	ds_read_b128 v[154:157], v150
	ds_read_b128 v[158:161], v150 offset:1024
	ds_read_b128 v[162:165], v150 offset:2048
	ds_read_b128 v[166:169], v150 offset:3072
	ds_read_b128 v[170:173], v151
	ds_read_b128 v[174:177], v151 offset:1024
	ds_read_b128 v[182:185], v151 offset:2048
	ds_read_b128 v[186:189], v151 offset:3072
	s_add_u32 s33, s0, 0xfff00080
	s_addc_u32 s35, s1, -1
	s_cmp_eq_u32 s29, 12
	s_cselect_b32 s59, s49, s35
	s_cselect_b32 s58, s48, s33
	s_cselect_b32 s55, s25, s28
	s_cselect_b32 s54, s26, s27
	v_lshl_add_u64 v[146:147], s[0:1], 0, v[138:139]
	s_add_i32 m0, s12, 0xc000
	ds_read_b128 v[190:193], v152
	ds_read_b128 v[194:197], v152 offset:1024
	ds_read_b128 v[198:201], v152 offset:2048
	ds_read_b128 v[202:205], v152 offset:3072
	ds_read_b128 v[206:209], v152 offset:4096
	ds_read_b128 v[212:215], v152 offset:5120
	ds_read_b128 v[216:219], v152 offset:6144
	ds_read_b128 v[220:223], v152 offset:7168
	global_load_lds_dwordx4 v[146:147], off
	v_lshl_add_u64 v[146:147], s[0:1], 0, v[140:141]
	s_add_i32 m0, s12, 0xe000
	s_nop 0
	global_load_lds_dwordx4 v[146:147], off
	s_waitcnt vmcnt(8)
	s_waitcnt lgkmcnt(0)
	s_barrier
	s_setprio 1
	s_waitcnt lgkmcnt(0)
	v_mfma_f32_16x16x32_bf16 v[126:129], v[154:157], v[190:193], 0
	v_mfma_f32_16x16x32_bf16 v[126:129], v[158:161], v[194:197], v[126:129]
	v_mfma_f32_16x16x32_bf16 v[122:125], v[166:169], v[194:197], 0
	v_mfma_f32_16x16x32_bf16 v[122:125], v[162:165], v[190:193], v[122:125]
	v_mfma_f32_16x16x32_bf16 v[110:113], v[162:165], v[198:201], 0
	v_mfma_f32_16x16x32_bf16 v[110:113], v[166:169], v[202:205], v[110:113]
	v_mfma_f32_16x16x32_bf16 v[118:121], v[158:161], v[202:205], 0
	v_mfma_f32_16x16x32_bf16 v[118:121], v[154:157], v[198:201], v[118:121]
	v_mfma_f32_16x16x32_bf16 v[102:105], v[154:157], v[206:209], 0
	v_mfma_f32_16x16x32_bf16 v[102:105], v[158:161], v[212:215], v[102:105]
	v_mfma_f32_16x16x32_bf16 v[94:97], v[166:169], v[212:215], 0
	v_mfma_f32_16x16x32_bf16 v[94:97], v[162:165], v[206:209], v[94:97]
	v_mfma_f32_16x16x32_bf16 v[78:81], v[162:165], v[216:219], 0
	v_mfma_f32_16x16x32_bf16 v[78:81], v[166:169], v[220:223], v[78:81]
	v_mfma_f32_16x16x32_bf16 v[86:89], v[158:161], v[220:223], 0
	v_mfma_f32_16x16x32_bf16 v[86:89], v[154:157], v[216:219], v[86:89]
	s_setprio 0
	s_setprio 1
	v_mfma_f32_16x16x32_bf16 v[70:73], v[170:173], v[216:219], 0
	v_mfma_f32_16x16x32_bf16 v[70:73], v[174:177], v[220:223], v[70:73]
	v_mfma_f32_16x16x32_bf16 v[66:69], v[186:189], v[220:223], 0
	v_mfma_f32_16x16x32_bf16 v[66:69], v[182:185], v[216:219], v[66:69]
	v_mfma_f32_16x16x32_bf16 v[74:77], v[182:185], v[206:209], 0
	v_mfma_f32_16x16x32_bf16 v[74:77], v[186:189], v[212:215], v[74:77]
	v_mfma_f32_16x16x32_bf16 v[82:85], v[174:177], v[212:215], 0
	v_mfma_f32_16x16x32_bf16 v[82:85], v[170:173], v[206:209], v[82:85]
	v_mfma_f32_16x16x32_bf16 v[98:101], v[170:173], v[198:201], 0
	v_mfma_f32_16x16x32_bf16 v[98:101], v[174:177], v[202:205], v[98:101]
	v_mfma_f32_16x16x32_bf16 v[90:93], v[186:189], v[202:205], 0
	v_mfma_f32_16x16x32_bf16 v[90:93], v[182:185], v[198:201], v[90:93]
	v_mfma_f32_16x16x32_bf16 v[106:109], v[182:185], v[190:193], 0
	v_mfma_f32_16x16x32_bf16 v[106:109], v[186:189], v[194:197], v[106:109]
	v_mfma_f32_16x16x32_bf16 v[114:117], v[174:177], v[194:197], 0
	v_mfma_f32_16x16x32_bf16 v[114:117], v[170:173], v[190:193], v[114:117]
	s_setprio 0
	s_barrier
	s_add_i32 s33, s22, s7
	v_lshl_add_u64 v[146:147], s[54:55], 0, v[132:133]
	s_mov_b32 m0, s33
	ds_read_b128 v[190:193], v152 offset:16384
	ds_read_b128 v[194:197], v152 offset:17408
	ds_read_b128 v[198:201], v152 offset:18432
	ds_read_b128 v[202:205], v152 offset:19456
	ds_read_b128 v[206:209], v152 offset:20480
	ds_read_b128 v[212:215], v152 offset:21504
	ds_read_b128 v[216:219], v152 offset:22528
	ds_read_b128 v[220:223], v152 offset:23552
	global_load_lds_dwordx4 v[146:147], off
	s_add_i32 m0, s33, 0x2000
	s_add_u32 s36, s54, 0x40000
	v_lshl_add_u64 v[224:225], s[54:55], 0, v[136:137]
	s_addc_u32 s37, s55, 0
	s_add_i32 s33, s23, s7
	global_load_lds_dwordx4 v[224:225], off
	v_lshl_add_u64 v[226:227], s[36:37], 0, v[132:133]
	s_mov_b32 m0, s33
	v_lshl_add_u64 v[228:229], s[58:59], 0, v[134:135]
	global_load_lds_dwordx4 v[226:227], off
	v_lshl_add_u64 v[226:227], s[36:37], 0, v[136:137]
	s_add_i32 m0, s33, 0x2000
	s_nop 0
	global_load_lds_dwordx4 v[226:227], off
	v_lshl_add_u64 v[226:227], s[58:59], 0, v[130:131]
	s_mov_b32 m0, s12
	s_nop 0
	global_load_lds_dwordx4 v[226:227], off
	s_mov_b32 m0, s13
	s_nop 0
	global_load_lds_dwordx4 v[228:229], off
	s_waitcnt vmcnt(8)
	s_waitcnt lgkmcnt(0)
	s_barrier
; #define PG8_STAGE(bufoff, gbase, voff) do { _Pragma("unroll") for (int _i = 0; _i < 2; ++_i) \
;         __builtin_amdgcn_global_load_lds((const unsigned*)((const char*)(gbase) + (voff)[_i]), (PG8_LAS unsigned*)(lds + (bufoff) + ldsw + _i * 8192), 16, 0, 0); } while (0)
; #define PG8_LDA(dst, b, h) do { _Pragma("unroll") for (int m = 0; m < 4; ++m) _Pragma("unroll") for (int k = 0; k < 2; ++k) dst[m][k] = *(const PG8_LAS bf16x8*)(lds + PG8_SA(b, h) + aoff + m * 2048 + k * 1024); } while (0)
; #define PG8_LDB(dst, b, h) do { _Pragma("unroll") for (int n = 0; n < 2; ++n) _Pragma("unroll") for (int k = 0; k < 2; ++k) dst[n][k] = *(const PG8_LAS bf16x8*)(lds + PG8_SB(b, h) + boff + n * 2048 + k * 1024); } while (0)
; #define PG8_MMA(ai, bj, At, Bt) do { __builtin_amdgcn_s_setprio(1); _Pragma("unroll") for (int m = 0; m < 4; ++m) _Pragma("unroll") for (int n = 0; n < 2; ++n) _Pragma("unroll") for (int k = 0; k < 2; ++k) \
;         acc[ai][bj][m][n] = mma16(Bt[n][k], At[m][k], acc[ai][bj][m][n]); __builtin_amdgcn_s_setprio(0); } while (0)
; #define PG8_WAIT_V(n) asm volatile("s_waitcnt vmcnt(" #n ")" ::: "memory")
; #define PG8_WAIT_L(n) asm volatile("s_waitcnt lgkmcnt(" #n ")" ::: "memory")
; #define PG8_BAR __builtin_amdgcn_s_barrier()
; #define PG8_SCHED __builtin_amdgcn_sched_barrier(0)
; template <class Epi, class Sched, bool ALIGN_EPI = false, bool SP2 = false>
; __device__ __forceinline__ void gemm_phase(PG8_LAS unsigned char* lds, const Gemm g, const Sched& S, const Epi& E) {
;     ...
;             PG8_WAIT_V(8); PG8_WAIT_L(0); PG8_BAR; PG8_MMA(0, 0, At, B0); PG8_MMA(0, 1, At, B1); PG8_BAR; PG8_SCHED;
;             PG8_LDA(At, 0, 1); PG8_STAGE(PG8_SB(0, 0), b2, voffB); PG8_STAGE(PG8_SB(0, 1), b2 + hstepB, voffB); PG8_STAGE(PG8_SA(0, 0), a2, voffA);
;             PG8_WAIT_V(8); PG8_WAIT_L(0); PG8_BAR; PG8_MMA(1, 0, At, B0); PG8_MMA(1, 1, At, B1); PG8_BAR; PG8_SCHED;
;             PG8_LDB(B0, 1, 0); PG8_LDB(B1, 1, 1); PG8_SCHED; PG8_LDA(At, 1, 0); PG8_STAGE(PG8_SA(0, 1), a2 + hstepA, voffA);
;             PG8_WAIT_V(8); PG8_WAIT_L(0); PG8_BAR; PG8_MMA(0, 0, At, B0); PG8_MMA(0, 1, At, B1); PG8_BAR; PG8_SCHED;
	s_setprio 1
	s_waitcnt lgkmcnt(0)
	v_mfma_f32_16x16x32_bf16 v[62:65], v[154:157], v[190:193], 0
	v_mfma_f32_16x16x32_bf16 v[62:65], v[158:161], v[194:197], v[62:65]
	v_mfma_f32_16x16x32_bf16 v[58:61], v[166:169], v[194:197], 0
	v_mfma_f32_16x16x32_bf16 v[58:61], v[162:165], v[190:193], v[58:61]
	v_mfma_f32_16x16x32_bf16 v[46:49], v[162:165], v[198:201], 0
	v_mfma_f32_16x16x32_bf16 v[46:49], v[166:169], v[202:205], v[46:49]
	v_mfma_f32_16x16x32_bf16 v[54:57], v[158:161], v[202:205], 0
	v_mfma_f32_16x16x32_bf16 v[54:57], v[154:157], v[198:201], v[54:57]
	v_mfma_f32_16x16x32_bf16 v[38:41], v[154:157], v[206:209], 0
	v_mfma_f32_16x16x32_bf16 v[38:41], v[158:161], v[212:215], v[38:41]
	v_mfma_f32_16x16x32_bf16 v[30:33], v[166:169], v[212:215], 0
	v_mfma_f32_16x16x32_bf16 v[30:33], v[162:165], v[206:209], v[30:33]
	v_mfma_f32_16x16x32_bf16 v[14:17], v[162:165], v[216:219], 0
	v_mfma_f32_16x16x32_bf16 v[14:17], v[166:169], v[220:223], v[14:17]
	v_mfma_f32_16x16x32_bf16 v[22:25], v[158:161], v[220:223], 0
	v_mfma_f32_16x16x32_bf16 v[22:25], v[154:157], v[216:219], v[22:25]
	s_setprio 0
	s_setprio 1
	v_mfma_f32_16x16x32_bf16 v[6:9], v[170:173], v[216:219], 0
	v_mfma_f32_16x16x32_bf16 v[6:9], v[174:177], v[220:223], v[6:9]
	v_mfma_f32_16x16x32_bf16 v[2:5], v[186:189], v[220:223], 0
	v_mfma_f32_16x16x32_bf16 v[2:5], v[182:185], v[216:219], v[2:5]
	v_mfma_f32_16x16x32_bf16 v[10:13], v[182:185], v[206:209], 0
	v_mfma_f32_16x16x32_bf16 v[10:13], v[186:189], v[212:215], v[10:13]
	v_mfma_f32_16x16x32_bf16 v[18:21], v[174:177], v[212:215], 0
	v_mfma_f32_16x16x32_bf16 v[18:21], v[170:173], v[206:209], v[18:21]
	v_mfma_f32_16x16x32_bf16 v[34:37], v[170:173], v[198:201], 0
	v_mfma_f32_16x16x32_bf16 v[34:37], v[174:177], v[202:205], v[34:37]
	v_mfma_f32_16x16x32_bf16 v[26:29], v[186:189], v[202:205], 0
	v_mfma_f32_16x16x32_bf16 v[26:29], v[182:185], v[198:201], v[26:29]
	v_mfma_f32_16x16x32_bf16 v[42:45], v[182:185], v[190:193], 0
	v_mfma_f32_16x16x32_bf16 v[42:45], v[186:189], v[194:197], v[42:45]
	v_mfma_f32_16x16x32_bf16 v[50:53], v[174:177], v[194:197], 0
	v_mfma_f32_16x16x32_bf16 v[50:53], v[170:173], v[190:193], v[50:53]
	s_setprio 0
	s_barrier
	s_add_i32 s33, 0, 0x18000
	v_add_u32_e32 v153, s33, v148
	s_add_i32 s35, 0, 0x1c000
	ds_read_b128 v[154:157], v153
	ds_read_b128 v[158:161], v153 offset:1024
	ds_read_b128 v[162:165], v153 offset:2048
	ds_read_b128 v[166:169], v153 offset:3072
	v_add_u32_e32 v153, s35, v148
	ds_read_b128 v[170:173], v153
	ds_read_b128 v[174:177], v153 offset:1024
	ds_read_b128 v[182:185], v153 offset:2048
	ds_read_b128 v[186:189], v153 offset:3072
	s_add_u32 s36, s58, 0x100000
	s_addc_u32 s37, s59, 0
	s_mov_b32 m0, s16
	v_lshl_add_u64 v[230:231], s[36:37], 0, v[130:131]
	ds_read_b128 v[190:193], v152 offset:32768
	ds_read_b128 v[194:197], v152 offset:33792
	ds_read_b128 v[198:201], v152 offset:34816
	ds_read_b128 v[202:205], v152 offset:35840
	ds_read_b128 v[206:209], v152 offset:36864
	ds_read_b128 v[212:215], v152 offset:37888
	ds_read_b128 v[216:219], v152 offset:38912
	ds_read_b128 v[220:223], v152 offset:39936
	global_load_lds_dwordx4 v[230:231], off
	v_lshl_add_u64 v[230:231], s[36:37], 0, v[134:135]
	s_mov_b32 m0, s17
	s_nop 0
	global_load_lds_dwordx4 v[230:231], off
	s_waitcnt vmcnt(8)
	s_waitcnt lgkmcnt(0)
	s_barrier
	s_setprio 1
	s_waitcnt lgkmcnt(0)
	v_mfma_f32_16x16x32_bf16 v[126:129], v[154:157], v[190:193], v[126:129]
	v_mfma_f32_16x16x32_bf16 v[126:129], v[158:161], v[194:197], v[126:129]
	v_mfma_f32_16x16x32_bf16 v[122:125], v[166:169], v[194:197], v[122:125]
	v_mfma_f32_16x16x32_bf16 v[122:125], v[162:165], v[190:193], v[122:125]
	v_mfma_f32_16x16x32_bf16 v[110:113], v[162:165], v[198:201], v[110:113]
	v_mfma_f32_16x16x32_bf16 v[110:113], v[166:169], v[202:205], v[110:113]
	v_mfma_f32_16x16x32_bf16 v[118:121], v[158:161], v[202:205], v[118:121]
	v_mfma_f32_16x16x32_bf16 v[118:121], v[154:157], v[198:201], v[118:121]
	v_mfma_f32_16x16x32_bf16 v[102:105], v[154:157], v[206:209], v[102:105]
	v_mfma_f32_16x16x32_bf16 v[102:105], v[158:161], v[212:215], v[102:105]
	v_mfma_f32_16x16x32_bf16 v[94:97], v[166:169], v[212:215], v[94:97]
	v_mfma_f32_16x16x32_bf16 v[94:97], v[162:165], v[206:209], v[94:97]
	v_mfma_f32_16x16x32_bf16 v[78:81], v[162:165], v[216:219], v[78:81]
	v_mfma_f32_16x16x32_bf16 v[78:81], v[166:169], v[220:223], v[78:81]
	v_mfma_f32_16x16x32_bf16 v[86:89], v[158:161], v[220:223], v[86:89]
	v_mfma_f32_16x16x32_bf16 v[86:89], v[154:157], v[216:219], v[86:89]
	s_setprio 0
	s_setprio 1
	v_mfma_f32_16x16x32_bf16 v[70:73], v[170:173], v[216:219], v[70:73]
	v_mfma_f32_16x16x32_bf16 v[70:73], v[174:177], v[220:223], v[70:73]
	v_mfma_f32_16x16x32_bf16 v[66:69], v[186:189], v[220:223], v[66:69]
	v_mfma_f32_16x16x32_bf16 v[66:69], v[182:185], v[216:219], v[66:69]
	v_mfma_f32_16x16x32_bf16 v[74:77], v[182:185], v[206:209], v[74:77]
	v_mfma_f32_16x16x32_bf16 v[74:77], v[186:189], v[212:215], v[74:77]
	v_mfma_f32_16x16x32_bf16 v[82:85], v[174:177], v[212:215], v[82:85]
	v_mfma_f32_16x16x32_bf16 v[82:85], v[170:173], v[206:209], v[82:85]
	v_mfma_f32_16x16x32_bf16 v[98:101], v[170:173], v[198:201], v[98:101]
	v_mfma_f32_16x16x32_bf16 v[98:101], v[174:177], v[202:205], v[98:101]
	v_mfma_f32_16x16x32_bf16 v[90:93], v[186:189], v[202:205], v[90:93]
	v_mfma_f32_16x16x32_bf16 v[90:93], v[182:185], v[198:201], v[90:93]
	v_mfma_f32_16x16x32_bf16 v[106:109], v[182:185], v[190:193], v[106:109]
	v_mfma_f32_16x16x32_bf16 v[106:109], v[186:189], v[194:197], v[106:109]
	v_mfma_f32_16x16x32_bf16 v[114:117], v[174:177], v[194:197], v[114:117]
	v_mfma_f32_16x16x32_bf16 v[114:117], v[170:173], v[190:193], v[114:117]
	s_setprio 0
	s_barrier
; #define PG8_STAGE(bufoff, gbase, voff) do { _Pragma("unroll") for (int _i = 0; _i < 2; ++_i) \
;         __builtin_amdgcn_global_load_lds((const unsigned*)((const char*)(gbase) + (voff)[_i]), (PG8_LAS unsigned*)(lds + (bufoff) + ldsw + _i * 8192), 16, 0, 0); } while (0)
; #define PG8_LDA(dst, b, h) do { _Pragma("unroll") for (int m = 0; m < 4; ++m) _Pragma("unroll") for (int k = 0; k < 2; ++k) dst[m][k] = *(const PG8_LAS bf16x8*)(lds + PG8_SA(b, h) + aoff + m * 2048 + k * 1024); } while (0)
; #define PG8_LDB(dst, b, h) do { _Pragma("unroll") for (int n = 0; n < 2; ++n) _Pragma("unroll") for (int k = 0; k < 2; ++k) dst[n][k] = *(const PG8_LAS bf16x8*)(lds + PG8_SB(b, h) + boff + n * 2048 + k * 1024); } while (0)
; template <class Epi, class Sched, bool ALIGN_EPI = false, bool SP2 = false>
; __device__ __forceinline__ void gemm_phase(PG8_LAS unsigned char* lds, const Gemm g, const Sched& S, const Epi& E) {
;     ...
;         for (int t = 0; t < nt; t += 2) {
;             const bool last = (t == nt - 2);
;             const char* a1 = cA + (size_t)(t + 1) * kstep;
;             const char* a2 = last ? nA : cA + (size_t)(t + 2) * kstep; const char* b2 = last ? nB : cB + (size_t)(t + 2) * kstep;
;             const char* a3 = a2 + kstep; const char* b3 = b2 + kstep;
;             if (last && has_next) S.a_ready(nxt);
;             if constexpr (SP2) {
;             PG8_LDB(B0, 0, 0); PG8_LDB(B1, 0, 1); PG8_SCHED; PG8_LDA(At, 0, 0); PG8_STAGE(PG8_SA(1, 1), a1 + hstepA, voffA);
;             PG8_WAIT_V(8); PG8_WAIT_L(0); PG8_BAR; PG8_MMA(0, 0, At, B0); PG8_MMA(0, 1, At, B1); PG8_BAR; PG8_SCHED;
;             PG8_LDA(At, 0, 1); PG8_STAGE(PG8_SB(0, 0), b2, voffB); PG8_STAGE(PG8_SB(0, 1), b2 + hstepB, voffB); PG8_STAGE(PG8_SA(0, 0), a2, voffA);
;             PG8_WAIT_V(8); PG8_WAIT_L(0); PG8_BAR; PG8_MMA(1, 0, At, B0); PG8_MMA(1, 1, At, B1); PG8_BAR; PG8_SCHED;
;             PG8_LDB(B0, 1, 0); PG8_LDB(B1, 1, 1); PG8_SCHED; PG8_LDA(At, 1, 0); PG8_STAGE(PG8_SA(0, 1), a2 + hstepA, voffA);
;             PG8_WAIT_V(8); PG8_WAIT_L(0); PG8_BAR; PG8_MMA(0, 0, At, B0); PG8_MMA(0, 1, At, B1); PG8_BAR; PG8_SCHED;
;             PG8_LDA(At, 1, 1); PG8_STAGE(PG8_SB(1, 0), b3, voffB); PG8_STAGE(PG8_SB(1, 1), b3 + hstepB, voffB); PG8_STAGE(PG8_SA(1, 0), a3, voffA);
;             PG8_WAIT_V(8); PG8_WAIT_L(0); PG8_BAR; PG8_MMA(1, 0, At, B0); PG8_MMA(1, 1, At, B1); PG8_BAR; PG8_SCHED;
	s_add_i32 s33, s33, s7
	v_lshl_add_u64 v[146:147], v[146:147], 0, s[38:39]
	s_mov_b32 m0, s33
	ds_read_b128 v[190:193], v152 offset:49152
	ds_read_b128 v[194:197], v152 offset:50176
	ds_read_b128 v[198:201], v152 offset:51200
	ds_read_b128 v[202:205], v152 offset:52224
	ds_read_b128 v[206:209], v152 offset:53248
	ds_read_b128 v[212:215], v152 offset:54272
	ds_read_b128 v[216:219], v152 offset:55296
	ds_read_b128 v[220:223], v152 offset:56320
	global_load_lds_dwordx4 v[146:147], off
	s_add_i32 m0, s33, 0x2000
	s_add_u32 s36, s54, 0x40080
	v_lshl_add_u64 v[146:147], v[224:225], 0, s[38:39]
	s_addc_u32 s37, s55, 0
	s_add_i32 s33, s35, s7
	global_load_lds_dwordx4 v[146:147], off
	v_lshl_add_u64 v[146:147], s[36:37], 0, v[132:133]
	s_mov_b32 m0, s33
	s_nop 0
	global_load_lds_dwordx4 v[146:147], off
	v_lshl_add_u64 v[146:147], s[36:37], 0, v[136:137]
	s_add_i32 m0, s33, 0x2000
	s_nop 0
	global_load_lds_dwordx4 v[146:147], off
	v_lshl_add_u64 v[146:147], v[226:227], 0, s[38:39]
	s_mov_b32 m0, s19
	s_nop 0
	global_load_lds_dwordx4 v[146:147], off
	v_lshl_add_u64 v[146:147], v[228:229], 0, s[38:39]
	s_mov_b32 m0, s20
	s_nop 0
	global_load_lds_dwordx4 v[146:147], off
	s_waitcnt vmcnt(8)
	s_waitcnt lgkmcnt(0)
	s_barrier
	s_setprio 1
	s_waitcnt lgkmcnt(0)
	v_mfma_f32_16x16x32_bf16 v[62:65], v[154:157], v[190:193], v[62:65]
	v_mfma_f32_16x16x32_bf16 v[62:65], v[158:161], v[194:197], v[62:65]
	v_mfma_f32_16x16x32_bf16 v[58:61], v[166:169], v[194:197], v[58:61]
	v_mfma_f32_16x16x32_bf16 v[58:61], v[162:165], v[190:193], v[58:61]
	v_mfma_f32_16x16x32_bf16 v[46:49], v[162:165], v[198:201], v[46:49]
	v_mfma_f32_16x16x32_bf16 v[46:49], v[166:169], v[202:205], v[46:49]
	v_mfma_f32_16x16x32_bf16 v[54:57], v[158:161], v[202:205], v[54:57]
	v_mfma_f32_16x16x32_bf16 v[54:57], v[154:157], v[198:201], v[54:57]
	v_mfma_f32_16x16x32_bf16 v[38:41], v[154:157], v[206:209], v[38:41]
	v_mfma_f32_16x16x32_bf16 v[38:41], v[158:161], v[212:215], v[38:41]
	v_mfma_f32_16x16x32_bf16 v[30:33], v[166:169], v[212:215], v[30:33]
	v_mfma_f32_16x16x32_bf16 v[30:33], v[162:165], v[206:209], v[30:33]
	v_mfma_f32_16x16x32_bf16 v[14:17], v[162:165], v[216:219], v[14:17]
	v_mfma_f32_16x16x32_bf16 v[14:17], v[166:169], v[220:223], v[14:17]
	v_mfma_f32_16x16x32_bf16 v[22:25], v[158:161], v[220:223], v[22:25]
	v_mfma_f32_16x16x32_bf16 v[22:25], v[154:157], v[216:219], v[22:25]
	s_setprio 0
	s_setprio 1
	v_mfma_f32_16x16x32_bf16 v[6:9], v[170:173], v[216:219], v[6:9]
	v_mfma_f32_16x16x32_bf16 v[6:9], v[174:177], v[220:223], v[6:9]
	v_mfma_f32_16x16x32_bf16 v[2:5], v[186:189], v[220:223], v[2:5]
	v_mfma_f32_16x16x32_bf16 v[2:5], v[182:185], v[216:219], v[2:5]
	v_mfma_f32_16x16x32_bf16 v[10:13], v[182:185], v[206:209], v[10:13]
	v_mfma_f32_16x16x32_bf16 v[10:13], v[186:189], v[212:215], v[10:13]
	v_mfma_f32_16x16x32_bf16 v[18:21], v[174:177], v[212:215], v[18:21]
	v_mfma_f32_16x16x32_bf16 v[18:21], v[170:173], v[206:209], v[18:21]
	v_mfma_f32_16x16x32_bf16 v[34:37], v[170:173], v[198:201], v[34:37]
	v_mfma_f32_16x16x32_bf16 v[34:37], v[174:177], v[202:205], v[34:37]
	v_mfma_f32_16x16x32_bf16 v[26:29], v[186:189], v[202:205], v[26:29]
	v_mfma_f32_16x16x32_bf16 v[26:29], v[182:185], v[198:201], v[26:29]
	v_mfma_f32_16x16x32_bf16 v[42:45], v[182:185], v[190:193], v[42:45]
	v_mfma_f32_16x16x32_bf16 v[42:45], v[186:189], v[194:197], v[42:45]
	v_mfma_f32_16x16x32_bf16 v[50:53], v[174:177], v[194:197], v[50:53]
	v_mfma_f32_16x16x32_bf16 v[50:53], v[170:173], v[190:193], v[50:53]
	s_setprio 0
	s_barrier
	s_add_i32 s29, s29, 2
	s_add_u32 s0, s0, 0x100
	s_addc_u32 s1, s1, 0
	s_add_u32 s27, s27, 0x100
	s_addc_u32 s28, s28, 0
.LBB0_389:
	ds_read_b128 v[154:157], v150
	ds_read_b128 v[158:161], v150 offset:1024
	ds_read_b128 v[162:165], v150 offset:2048
	ds_read_b128 v[166:169], v150 offset:3072
	ds_read_b128 v[170:173], v151
	ds_read_b128 v[174:177], v151 offset:1024
	ds_read_b128 v[182:185], v151 offset:2048
	ds_read_b128 v[186:189], v151 offset:3072
	s_add_u32 s33, s0, 0xfff00080
	s_addc_u32 s35, s1, -1
	s_cmp_eq_u32 s29, 12
	s_cselect_b32 s59, s49, s35
	s_cselect_b32 s58, s48, s33
	s_cselect_b32 s55, s25, s28
	s_cselect_b32 s54, s26, s27
	v_lshl_add_u64 v[146:147], s[0:1], 0, v[138:139]
	s_add_i32 m0, s12, 0xc000
	ds_read_b128 v[190:193], v152
	ds_read_b128 v[194:197], v152 offset:1024
	ds_read_b128 v[198:201], v152 offset:2048
	ds_read_b128 v[202:205], v152 offset:3072
	ds_read_b128 v[206:209], v152 offset:4096
	ds_read_b128 v[212:215], v152 offset:5120
	ds_read_b128 v[216:219], v152 offset:6144
	ds_read_b128 v[220:223], v152 offset:7168
	global_load_lds_dwordx4 v[146:147], off
	v_lshl_add_u64 v[146:147], s[0:1], 0, v[140:141]
	s_add_i32 m0, s12, 0xe000
	s_nop 0
	global_load_lds_dwordx4 v[146:147], off
	s_waitcnt vmcnt(8)
	s_waitcnt lgkmcnt(0)
	s_barrier
; #define PG8_STAGE(bufoff, gbase, voff) do { _Pragma("unroll") for (int _i = 0; _i < 2; ++_i) \
;         __builtin_amdgcn_global_load_lds((const unsigned*)((const char*)(gbase) + (voff)[_i]), (PG8_LAS unsigned*)(lds + (bufoff) + ldsw + _i * 8192), 16, 0, 0); } while (0)
; #define PG8_LDA(dst, b, h) do { _Pragma("unroll") for (int m = 0; m < 4; ++m) _Pragma("unroll") for (int k = 0; k < 2; ++k) dst[m][k] = *(const PG8_LAS bf16x8*)(lds + PG8_SA(b, h) + aoff + m * 2048 + k * 1024); } while (0)
; #define PG8_LDB(dst, b, h) do { _Pragma("unroll") for (int n = 0; n < 2; ++n) _Pragma("unroll") for (int k = 0; k < 2; ++k) dst[n][k] = *(const PG8_LAS bf16x8*)(lds + PG8_SB(b, h) + boff + n * 2048 + k * 1024); } while (0)
; #define PG8_MMA(ai, bj, At, Bt) do { __builtin_amdgcn_s_setprio(1); _Pragma("unroll") for (int m = 0; m < 4; ++m) _Pragma("unroll") for (int n = 0; n < 2; ++n) _Pragma("unroll") for (int k = 0; k < 2; ++k) \
;         acc[ai][bj][m][n] = mma16(Bt[n][k], At[m][k], acc[ai][bj][m][n]); __builtin_amdgcn_s_setprio(0); } while (0)
; #define PG8_WAIT_V(n) asm volatile("s_waitcnt vmcnt(" #n ")" ::: "memory")
; #define PG8_WAIT_L(n) asm volatile("s_waitcnt lgkmcnt(" #n ")" ::: "memory")
; #define PG8_BAR __builtin_amdgcn_s_barrier()
; #define PG8_SCHED __builtin_amdgcn_sched_barrier(0)
; template <class Epi, class Sched, bool ALIGN_EPI = false, bool SP2 = false>
; __device__ __forceinline__ void gemm_phase(PG8_LAS unsigned char* lds, const Gemm g, const Sched& S, const Epi& E) {
;     ...
;             PG8_LDB(B0, 0, 0); PG8_LDB(B1, 0, 1); PG8_SCHED; PG8_LDA(At, 0, 0); PG8_STAGE(PG8_SA(1, 1), a1 + hstepA, voffA);
;             PG8_WAIT_V(8); PG8_WAIT_L(0); PG8_BAR; PG8_MMA(0, 0, At, B0); PG8_MMA(0, 1, At, B1); PG8_BAR; PG8_SCHED;
;             PG8_LDA(At, 0, 1); PG8_STAGE(PG8_SB(0, 0), b2, voffB); PG8_STAGE(PG8_SB(0, 1), b2 + hstepB, voffB); PG8_STAGE(PG8_SA(0, 0), a2, voffA);
;             PG8_WAIT_V(8); PG8_WAIT_L(0); PG8_BAR; PG8_MMA(1, 0, At, B0); PG8_MMA(1, 1, At, B1); PG8_BAR; PG8_SCHED;
	s_setprio 1
	s_waitcnt lgkmcnt(0)
	v_mfma_f32_16x16x32_bf16 v[126:129], v[154:157], v[190:193], v[126:129]
	v_mfma_f32_16x16x32_bf16 v[126:129], v[158:161], v[194:197], v[126:129]
	v_mfma_f32_16x16x32_bf16 v[122:125], v[166:169], v[194:197], v[122:125]
	v_mfma_f32_16x16x32_bf16 v[122:125], v[162:165], v[190:193], v[122:125]
	v_mfma_f32_16x16x32_bf16 v[110:113], v[162:165], v[198:201], v[110:113]
	v_mfma_f32_16x16x32_bf16 v[110:113], v[166:169], v[202:205], v[110:113]
	v_mfma_f32_16x16x32_bf16 v[118:121], v[158:161], v[202:205], v[118:121]
	v_mfma_f32_16x16x32_bf16 v[118:121], v[154:157], v[198:201], v[118:121]
	v_mfma_f32_16x16x32_bf16 v[102:105], v[154:157], v[206:209], v[102:105]
	v_mfma_f32_16x16x32_bf16 v[102:105], v[158:161], v[212:215], v[102:105]
	v_mfma_f32_16x16x32_bf16 v[94:97], v[166:169], v[212:215], v[94:97]
	v_mfma_f32_16x16x32_bf16 v[94:97], v[162:165], v[206:209], v[94:97]
	v_mfma_f32_16x16x32_bf16 v[78:81], v[162:165], v[216:219], v[78:81]
	v_mfma_f32_16x16x32_bf16 v[78:81], v[166:169], v[220:223], v[78:81]
	v_mfma_f32_16x16x32_bf16 v[86:89], v[158:161], v[220:223], v[86:89]
	v_mfma_f32_16x16x32_bf16 v[86:89], v[154:157], v[216:219], v[86:89]
	s_setprio 0
	s_setprio 1
	v_mfma_f32_16x16x32_bf16 v[70:73], v[170:173], v[216:219], v[70:73]
	v_mfma_f32_16x16x32_bf16 v[70:73], v[174:177], v[220:223], v[70:73]
	v_mfma_f32_16x16x32_bf16 v[66:69], v[186:189], v[220:223], v[66:69]
	v_mfma_f32_16x16x32_bf16 v[66:69], v[182:185], v[216:219], v[66:69]
	v_mfma_f32_16x16x32_bf16 v[74:77], v[182:185], v[206:209], v[74:77]
	v_mfma_f32_16x16x32_bf16 v[74:77], v[186:189], v[212:215], v[74:77]
	v_mfma_f32_16x16x32_bf16 v[82:85], v[174:177], v[212:215], v[82:85]
	v_mfma_f32_16x16x32_bf16 v[82:85], v[170:173], v[206:209], v[82:85]
	v_mfma_f32_16x16x32_bf16 v[98:101], v[170:173], v[198:201], v[98:101]
	v_mfma_f32_16x16x32_bf16 v[98:101], v[174:177], v[202:205], v[98:101]
	v_mfma_f32_16x16x32_bf16 v[90:93], v[186:189], v[202:205], v[90:93]
	v_mfma_f32_16x16x32_bf16 v[90:93], v[182:185], v[198:201], v[90:93]
	v_mfma_f32_16x16x32_bf16 v[106:109], v[182:185], v[190:193], v[106:109]
	v_mfma_f32_16x16x32_bf16 v[106:109], v[186:189], v[194:197], v[106:109]
	v_mfma_f32_16x16x32_bf16 v[114:117], v[174:177], v[194:197], v[114:117]
	v_mfma_f32_16x16x32_bf16 v[114:117], v[170:173], v[190:193], v[114:117]
	s_setprio 0
	s_barrier
	s_add_i32 s33, s22, s7
	v_lshl_add_u64 v[146:147], s[54:55], 0, v[132:133]
	s_mov_b32 m0, s33
	ds_read_b128 v[190:193], v152 offset:16384
	ds_read_b128 v[194:197], v152 offset:17408
	ds_read_b128 v[198:201], v152 offset:18432
	ds_read_b128 v[202:205], v152 offset:19456
	ds_read_b128 v[206:209], v152 offset:20480
	ds_read_b128 v[212:215], v152 offset:21504
	ds_read_b128 v[216:219], v152 offset:22528
	ds_read_b128 v[220:223], v152 offset:23552
	global_load_lds_dwordx4 v[146:147], off
	s_add_i32 m0, s33, 0x2000
	s_add_u32 s36, s54, 0x40000
	v_lshl_add_u64 v[224:225], s[54:55], 0, v[136:137]
	s_addc_u32 s37, s55, 0
	s_add_i32 s33, s23, s7
	global_load_lds_dwordx4 v[224:225], off
	v_lshl_add_u64 v[226:227], s[36:37], 0, v[132:133]
	s_mov_b32 m0, s33
	v_lshl_add_u64 v[228:229], s[58:59], 0, v[134:135]
	global_load_lds_dwordx4 v[226:227], off
	v_lshl_add_u64 v[226:227], s[36:37], 0, v[136:137]
	s_add_i32 m0, s33, 0x2000
	s_nop 0
	global_load_lds_dwordx4 v[226:227], off
	v_lshl_add_u64 v[226:227], s[58:59], 0, v[130:131]
	s_mov_b32 m0, s12
	s_nop 0
	global_load_lds_dwordx4 v[226:227], off
	s_mov_b32 m0, s13
	s_nop 0
	global_load_lds_dwordx4 v[228:229], off
	s_waitcnt vmcnt(8)
	s_waitcnt lgkmcnt(0)
	s_barrier
	s_setprio 1
	s_waitcnt lgkmcnt(0)
	v_mfma_f32_16x16x32_bf16 v[62:65], v[154:157], v[190:193], v[62:65]
	v_mfma_f32_16x16x32_bf16 v[62:65], v[158:161], v[194:197], v[62:65]
	v_mfma_f32_16x16x32_bf16 v[58:61], v[166:169], v[194:197], v[58:61]
	v_mfma_f32_16x16x32_bf16 v[58:61], v[162:165], v[190:193], v[58:61]
	v_mfma_f32_16x16x32_bf16 v[46:49], v[162:165], v[198:201], v[46:49]
	v_mfma_f32_16x16x32_bf16 v[46:49], v[166:169], v[202:205], v[46:49]
	v_mfma_f32_16x16x32_bf16 v[54:57], v[158:161], v[202:205], v[54:57]
	v_mfma_f32_16x16x32_bf16 v[54:57], v[154:157], v[198:201], v[54:57]
	v_mfma_f32_16x16x32_bf16 v[38:41], v[154:157], v[206:209], v[38:41]
	v_mfma_f32_16x16x32_bf16 v[38:41], v[158:161], v[212:215], v[38:41]
	v_mfma_f32_16x16x32_bf16 v[30:33], v[166:169], v[212:215], v[30:33]
	v_mfma_f32_16x16x32_bf16 v[30:33], v[162:165], v[206:209], v[30:33]
	v_mfma_f32_16x16x32_bf16 v[14:17], v[162:165], v[216:219], v[14:17]
	v_mfma_f32_16x16x32_bf16 v[14:17], v[166:169], v[220:223], v[14:17]
	v_mfma_f32_16x16x32_bf16 v[22:25], v[158:161], v[220:223], v[22:25]
	v_mfma_f32_16x16x32_bf16 v[22:25], v[154:157], v[216:219], v[22:25]
	s_setprio 0
	s_setprio 1
	v_mfma_f32_16x16x32_bf16 v[6:9], v[170:173], v[216:219], v[6:9]
	v_mfma_f32_16x16x32_bf16 v[6:9], v[174:177], v[220:223], v[6:9]
	v_mfma_f32_16x16x32_bf16 v[2:5], v[186:189], v[220:223], v[2:5]
	v_mfma_f32_16x16x32_bf16 v[2:5], v[182:185], v[216:219], v[2:5]
	v_mfma_f32_16x16x32_bf16 v[10:13], v[182:185], v[206:209], v[10:13]
	v_mfma_f32_16x16x32_bf16 v[10:13], v[186:189], v[212:215], v[10:13]
	v_mfma_f32_16x16x32_bf16 v[18:21], v[174:177], v[212:215], v[18:21]
	v_mfma_f32_16x16x32_bf16 v[18:21], v[170:173], v[206:209], v[18:21]
	v_mfma_f32_16x16x32_bf16 v[34:37], v[170:173], v[198:201], v[34:37]
	v_mfma_f32_16x16x32_bf16 v[34:37], v[174:177], v[202:205], v[34:37]
	v_mfma_f32_16x16x32_bf16 v[26:29], v[186:189], v[202:205], v[26:29]
	v_mfma_f32_16x16x32_bf16 v[26:29], v[182:185], v[198:201], v[26:29]
	v_mfma_f32_16x16x32_bf16 v[42:45], v[182:185], v[190:193], v[42:45]
	v_mfma_f32_16x16x32_bf16 v[42:45], v[186:189], v[194:197], v[42:45]
	v_mfma_f32_16x16x32_bf16 v[50:53], v[174:177], v[194:197], v[50:53]
	v_mfma_f32_16x16x32_bf16 v[50:53], v[170:173], v[190:193], v[50:53]
	s_setprio 0
	s_barrier
; #define PG8_STAGE(bufoff, gbase, voff) do { _Pragma("unroll") for (int _i = 0; _i < 2; ++_i) \
;         __builtin_amdgcn_global_load_lds((const unsigned*)((const char*)(gbase) + (voff)[_i]), (PG8_LAS unsigned*)(lds + (bufoff) + ldsw + _i * 8192), 16, 0, 0); } while (0)
; #define PG8_LDA(dst, b, h) do { _Pragma("unroll") for (int m = 0; m < 4; ++m) _Pragma("unroll") for (int k = 0; k < 2; ++k) dst[m][k] = *(const PG8_LAS bf16x8*)(lds + PG8_SA(b, h) + aoff + m * 2048 + k * 1024); } while (0)
; #define PG8_LDB(dst, b, h) do { _Pragma("unroll") for (int n = 0; n < 2; ++n) _Pragma("unroll") for (int k = 0; k < 2; ++k) dst[n][k] = *(const PG8_LAS bf16x8*)(lds + PG8_SB(b, h) + boff + n * 2048 + k * 1024); } while (0)
; #define PG8_MMA(ai, bj, At, Bt) do { __builtin_amdgcn_s_setprio(1); _Pragma("unroll") for (int m = 0; m < 4; ++m) _Pragma("unroll") for (int n = 0; n < 2; ++n) _Pragma("unroll") for (int k = 0; k < 2; ++k) \
;         acc[ai][bj][m][n] = mma16(Bt[n][k], At[m][k], acc[ai][bj][m][n]); __builtin_amdgcn_s_setprio(0); } while (0)
; #define PG8_WAIT_V(n) asm volatile("s_waitcnt vmcnt(" #n ")" ::: "memory")
; #define PG8_WAIT_L(n) asm volatile("s_waitcnt lgkmcnt(" #n ")" ::: "memory")
; #define PG8_BAR __builtin_amdgcn_s_barrier()
; #define PG8_SCHED __builtin_amdgcn_sched_barrier(0)
; template <class Epi, class Sched, bool ALIGN_EPI = false, bool SP2 = false>
; __device__ __forceinline__ void gemm_phase(PG8_LAS unsigned char* lds, const Gemm g, const Sched& S, const Epi& E) {
;     ...
;             PG8_LDB(B0, 1, 0); PG8_LDB(B1, 1, 1); PG8_SCHED; PG8_LDA(At, 1, 0); PG8_STAGE(PG8_SA(0, 1), a2 + hstepA, voffA);
;             PG8_WAIT_V(8); PG8_WAIT_L(0); PG8_BAR; PG8_MMA(0, 0, At, B0); PG8_MMA(0, 1, At, B1); PG8_BAR; PG8_SCHED;
	s_add_i32 s33, 0, 0x18000
	v_add_u32_e32 v153, s33, v148
	s_add_i32 s35, 0, 0x1c000
	ds_read_b128 v[154:157], v153
	ds_read_b128 v[158:161], v153 offset:1024
	ds_read_b128 v[162:165], v153 offset:2048
	ds_read_b128 v[166:169], v153 offset:3072
	v_add_u32_e32 v153, s35, v148
	ds_read_b128 v[170:173], v153
	ds_read_b128 v[174:177], v153 offset:1024
	ds_read_b128 v[182:185], v153 offset:2048
	ds_read_b128 v[186:189], v153 offset:3072
	s_add_u32 s36, s58, 0x100000
	s_addc_u32 s37, s59, 0
	s_mov_b32 m0, s16
	v_lshl_add_u64 v[230:231], s[36:37], 0, v[130:131]
	ds_read_b128 v[190:193], v152 offset:32768
	ds_read_b128 v[194:197], v152 offset:33792
	ds_read_b128 v[198:201], v152 offset:34816
	ds_read_b128 v[202:205], v152 offset:35840
	ds_read_b128 v[206:209], v152 offset:36864
	ds_read_b128 v[212:215], v152 offset:37888
	ds_read_b128 v[216:219], v152 offset:38912
	ds_read_b128 v[220:223], v152 offset:39936
	global_load_lds_dwordx4 v[230:231], off
	v_lshl_add_u64 v[230:231], s[36:37], 0, v[134:135]
	s_mov_b32 m0, s17
	s_nop 0
	global_load_lds_dwordx4 v[230:231], off
	s_waitcnt vmcnt(8)
	s_waitcnt lgkmcnt(0)
	s_barrier
	s_setprio 1
	s_waitcnt lgkmcnt(0)
	v_mfma_f32_16x16x32_bf16 v[126:129], v[154:157], v[190:193], v[126:129]
	v_mfma_f32_16x16x32_bf16 v[126:129], v[158:161], v[194:197], v[126:129]
	v_mfma_f32_16x16x32_bf16 v[122:125], v[166:169], v[194:197], v[122:125]
	v_mfma_f32_16x16x32_bf16 v[122:125], v[162:165], v[190:193], v[122:125]
	v_mfma_f32_16x16x32_bf16 v[110:113], v[162:165], v[198:201], v[110:113]
	v_mfma_f32_16x16x32_bf16 v[110:113], v[166:169], v[202:205], v[110:113]
	v_mfma_f32_16x16x32_bf16 v[118:121], v[158:161], v[202:205], v[118:121]
	v_mfma_f32_16x16x32_bf16 v[118:121], v[154:157], v[198:201], v[118:121]
	v_mfma_f32_16x16x32_bf16 v[102:105], v[154:157], v[206:209], v[102:105]
	v_mfma_f32_16x16x32_bf16 v[102:105], v[158:161], v[212:215], v[102:105]
	v_mfma_f32_16x16x32_bf16 v[94:97], v[166:169], v[212:215], v[94:97]
	v_mfma_f32_16x16x32_bf16 v[94:97], v[162:165], v[206:209], v[94:97]
	v_mfma_f32_16x16x32_bf16 v[78:81], v[162:165], v[216:219], v[78:81]
	v_mfma_f32_16x16x32_bf16 v[78:81], v[166:169], v[220:223], v[78:81]
	v_mfma_f32_16x16x32_bf16 v[86:89], v[158:161], v[220:223], v[86:89]
	v_mfma_f32_16x16x32_bf16 v[86:89], v[154:157], v[216:219], v[86:89]
	s_setprio 0
	s_setprio 1
	v_mfma_f32_16x16x32_bf16 v[70:73], v[170:173], v[216:219], v[70:73]
	v_mfma_f32_16x16x32_bf16 v[70:73], v[174:177], v[220:223], v[70:73]
	v_mfma_f32_16x16x32_bf16 v[66:69], v[186:189], v[220:223], v[66:69]
	v_mfma_f32_16x16x32_bf16 v[66:69], v[182:185], v[216:219], v[66:69]
	v_mfma_f32_16x16x32_bf16 v[74:77], v[182:185], v[206:209], v[74:77]
	v_mfma_f32_16x16x32_bf16 v[74:77], v[186:189], v[212:215], v[74:77]
	v_mfma_f32_16x16x32_bf16 v[82:85], v[174:177], v[212:215], v[82:85]
	v_mfma_f32_16x16x32_bf16 v[82:85], v[170:173], v[206:209], v[82:85]
	v_mfma_f32_16x16x32_bf16 v[98:101], v[170:173], v[198:201], v[98:101]
	v_mfma_f32_16x16x32_bf16 v[98:101], v[174:177], v[202:205], v[98:101]
	v_mfma_f32_16x16x32_bf16 v[90:93], v[186:189], v[202:205], v[90:93]
	v_mfma_f32_16x16x32_bf16 v[90:93], v[182:185], v[198:201], v[90:93]
	v_mfma_f32_16x16x32_bf16 v[106:109], v[182:185], v[190:193], v[106:109]
	v_mfma_f32_16x16x32_bf16 v[106:109], v[186:189], v[194:197], v[106:109]
	v_mfma_f32_16x16x32_bf16 v[114:117], v[174:177], v[194:197], v[114:117]
	v_mfma_f32_16x16x32_bf16 v[114:117], v[170:173], v[190:193], v[114:117]
	s_setprio 0
	s_barrier
; #define PG8_STAGE(bufoff, gbase, voff) do { _Pragma("unroll") for (int _i = 0; _i < 2; ++_i) \
;         __builtin_amdgcn_global_load_lds((const unsigned*)((const char*)(gbase) + (voff)[_i]), (PG8_LAS unsigned*)(lds + (bufoff) + ldsw + _i * 8192), 16, 0, 0); } while (0)
; #define PG8_LDA(dst, b, h) do { _Pragma("unroll") for (int m = 0; m < 4; ++m) _Pragma("unroll") for (int k = 0; k < 2; ++k) dst[m][k] = *(const PG8_LAS bf16x8*)(lds + PG8_SA(b, h) + aoff + m * 2048 + k * 1024); } while (0)
; #define PG8_MMA(ai, bj, At, Bt) do { __builtin_amdgcn_s_setprio(1); _Pragma("unroll") for (int m = 0; m < 4; ++m) _Pragma("unroll") for (int n = 0; n < 2; ++n) _Pragma("unroll") for (int k = 0; k < 2; ++k) \
;         acc[ai][bj][m][n] = mma16(Bt[n][k], At[m][k], acc[ai][bj][m][n]); __builtin_amdgcn_s_setprio(0); } while (0)
; #define PG8_WAIT_V(n) asm volatile("s_waitcnt vmcnt(" #n ")" ::: "memory")
; #define PG8_WAIT_L(n) asm volatile("s_waitcnt lgkmcnt(" #n ")" ::: "memory")
; #define PG8_BAR __builtin_amdgcn_s_barrier()
; #define PG8_SCHED __builtin_amdgcn_sched_barrier(0)
; template <class Epi, class Sched, bool ALIGN_EPI = false, bool SP2 = false>
; __device__ __forceinline__ void gemm_phase(PG8_LAS unsigned char* lds, const Gemm g, const Sched& S, const Epi& E) {
;     ...
;             PG8_LDA(At, 1, 1); PG8_STAGE(PG8_SB(1, 0), b3, voffB); PG8_STAGE(PG8_SB(1, 1), b3 + hstepB, voffB); PG8_STAGE(PG8_SA(1, 0), a3, voffA);
;             PG8_WAIT_V(8); PG8_WAIT_L(0); PG8_BAR; PG8_MMA(1, 0, At, B0); PG8_MMA(1, 1, At, B1); PG8_BAR; PG8_SCHED;
;     ...
;         if constexpr (ALIGN_EPI) { if (wr == 0) PG8_BAR; }
	s_add_i32 s33, s33, s7
	v_lshl_add_u64 v[146:147], v[146:147], 0, s[38:39]
	s_mov_b32 m0, s33
	ds_read_b128 v[190:193], v152 offset:49152
	ds_read_b128 v[194:197], v152 offset:50176
	ds_read_b128 v[198:201], v152 offset:51200
	ds_read_b128 v[202:205], v152 offset:52224
	ds_read_b128 v[206:209], v152 offset:53248
	ds_read_b128 v[212:215], v152 offset:54272
	ds_read_b128 v[216:219], v152 offset:55296
	ds_read_b128 v[220:223], v152 offset:56320
	global_load_lds_dwordx4 v[146:147], off
	s_add_i32 m0, s33, 0x2000
	s_add_u32 s36, s54, 0x40080
	v_lshl_add_u64 v[146:147], v[224:225], 0, s[38:39]
	s_addc_u32 s37, s55, 0
	s_add_i32 s33, s35, s7
	global_load_lds_dwordx4 v[146:147], off
	v_lshl_add_u64 v[146:147], s[36:37], 0, v[132:133]
	s_mov_b32 m0, s33
	s_nop 0
	global_load_lds_dwordx4 v[146:147], off
	v_lshl_add_u64 v[146:147], s[36:37], 0, v[136:137]
	s_add_i32 m0, s33, 0x2000
	s_nop 0
	global_load_lds_dwordx4 v[146:147], off
	v_lshl_add_u64 v[146:147], v[226:227], 0, s[38:39]
	s_mov_b32 m0, s19
	s_nop 0
	global_load_lds_dwordx4 v[146:147], off
	v_lshl_add_u64 v[146:147], v[228:229], 0, s[38:39]
	s_mov_b32 m0, s20
	s_nop 0
	global_load_lds_dwordx4 v[146:147], off
	s_waitcnt vmcnt(8)
	s_waitcnt lgkmcnt(0)
	s_barrier
	s_setprio 1
	s_waitcnt lgkmcnt(0)
	v_mfma_f32_16x16x32_bf16 v[62:65], v[154:157], v[190:193], v[62:65]
	v_mfma_f32_16x16x32_bf16 v[62:65], v[158:161], v[194:197], v[62:65]
	v_mfma_f32_16x16x32_bf16 v[58:61], v[166:169], v[194:197], v[58:61]
	v_mfma_f32_16x16x32_bf16 v[58:61], v[162:165], v[190:193], v[58:61]
	v_mfma_f32_16x16x32_bf16 v[46:49], v[162:165], v[198:201], v[46:49]
	v_mfma_f32_16x16x32_bf16 v[46:49], v[166:169], v[202:205], v[46:49]
	v_mfma_f32_16x16x32_bf16 v[54:57], v[158:161], v[202:205], v[54:57]
	v_mfma_f32_16x16x32_bf16 v[54:57], v[154:157], v[198:201], v[54:57]
	v_mfma_f32_16x16x32_bf16 v[38:41], v[154:157], v[206:209], v[38:41]
	v_mfma_f32_16x16x32_bf16 v[38:41], v[158:161], v[212:215], v[38:41]
	v_mfma_f32_16x16x32_bf16 v[30:33], v[166:169], v[212:215], v[30:33]
	v_mfma_f32_16x16x32_bf16 v[30:33], v[162:165], v[206:209], v[30:33]
	v_mfma_f32_16x16x32_bf16 v[14:17], v[162:165], v[216:219], v[14:17]
	v_mfma_f32_16x16x32_bf16 v[14:17], v[166:169], v[220:223], v[14:17]
	v_mfma_f32_16x16x32_bf16 v[22:25], v[158:161], v[220:223], v[22:25]
	v_mfma_f32_16x16x32_bf16 v[22:25], v[154:157], v[216:219], v[22:25]
	s_setprio 0
	s_setprio 1
	v_mfma_f32_16x16x32_bf16 v[6:9], v[170:173], v[216:219], v[6:9]
	v_mfma_f32_16x16x32_bf16 v[6:9], v[174:177], v[220:223], v[6:9]
	v_mfma_f32_16x16x32_bf16 v[2:5], v[186:189], v[220:223], v[2:5]
	v_mfma_f32_16x16x32_bf16 v[2:5], v[182:185], v[216:219], v[2:5]
	v_mfma_f32_16x16x32_bf16 v[10:13], v[182:185], v[206:209], v[10:13]
	v_mfma_f32_16x16x32_bf16 v[10:13], v[186:189], v[212:215], v[10:13]
	v_mfma_f32_16x16x32_bf16 v[18:21], v[174:177], v[212:215], v[18:21]
	v_mfma_f32_16x16x32_bf16 v[18:21], v[170:173], v[206:209], v[18:21]
	v_mfma_f32_16x16x32_bf16 v[34:37], v[170:173], v[198:201], v[34:37]
	v_mfma_f32_16x16x32_bf16 v[34:37], v[174:177], v[202:205], v[34:37]
	v_mfma_f32_16x16x32_bf16 v[26:29], v[186:189], v[202:205], v[26:29]
	v_mfma_f32_16x16x32_bf16 v[26:29], v[182:185], v[198:201], v[26:29]
	v_mfma_f32_16x16x32_bf16 v[42:45], v[182:185], v[190:193], v[42:45]
	v_mfma_f32_16x16x32_bf16 v[42:45], v[186:189], v[194:197], v[42:45]
	v_mfma_f32_16x16x32_bf16 v[50:53], v[174:177], v[194:197], v[50:53]
	v_mfma_f32_16x16x32_bf16 v[50:53], v[170:173], v[190:193], v[50:53]
	s_setprio 0
	s_barrier
	s_add_i32 s29, s29, 2
	s_add_u32 s0, s0, 0x100
	s_addc_u32 s1, s1, 0
	s_add_u32 s27, s27, 0x100
	s_addc_u32 s28, s28, 0
	s_cmp_gt_u32 s29, 13
	s_cbranch_scc0 .LBB0_389
	s_and_b64 vcc, exec, s[40:41]
	s_cbranch_vccz .LBB0_392
	s_barrier

; #define PG8_STAGE(bufoff, gbase, voff) do { _Pragma("unroll") for (int _i = 0; _i < 2; ++_i) \
;         __builtin_amdgcn_global_load_lds((const unsigned*)((const char*)(gbase) + (voff)[_i]), (PG8_LAS unsigned*)(lds + (bufoff) + ldsw + _i * 8192), 16, 0, 0); } while (0)
; #define PG8_LDA(dst, b, h) do { _Pragma("unroll") for (int m = 0; m < 4; ++m) _Pragma("unroll") for (int k = 0; k < 2; ++k) dst[m][k] = *(const PG8_LAS bf16x8*)(lds + PG8_SA(b, h) + aoff + m * 2048 + k * 1024); } while (0)
; #define PG8_LDB(dst, b, h) do { _Pragma("unroll") for (int n = 0; n < 2; ++n) _Pragma("unroll") for (int k = 0; k < 2; ++k) dst[n][k] = *(const PG8_LAS bf16x8*)(lds + PG8_SB(b, h) + boff + n * 2048 + k * 1024); } while (0)
; #define PG8_MMA(ai, bj, At, Bt) do { __builtin_amdgcn_s_setprio(1); _Pragma("unroll") for (int m = 0; m < 4; ++m) _Pragma("unroll") for (int n = 0; n < 2; ++n) _Pragma("unroll") for (int k = 0; k < 2; ++k) \
;         acc[ai][bj][m][n] = mma16(Bt[n][k], At[m][k], acc[ai][bj][m][n]); __builtin_amdgcn_s_setprio(0); } while (0)
; template <class Epi, class Sched, bool ALIGN_EPI = false, bool SP2 = false>
; __device__ __forceinline__ void gemm_phase(PG8_LAS unsigned char* lds, const Gemm g, const Sched& S, const Epi& E) {
;     ...
;         const bool has_next = S.next(ui + 1, nxt);
;         const char* nA = has_next ? PG8_ABASE(nxt) : cA; const char* nB = has_next ? PG8_BBASE(nxt) : cB;
; #pragma unroll 1
;         for (int t = 0; t < nt; t += 2) {
;             const bool last = (t == nt - 2);
;             const char* a1 = cA + (size_t)(t + 1) * kstep;
;             const char* a2 = last ? nA : cA + (size_t)(t + 2) * kstep; const char* b2 = last ? nB : cB + (size_t)(t + 2) * kstep;
;             const char* a3 = a2 + kstep; const char* b3 = b2 + kstep;
;             if (last && has_next) S.a_ready(nxt);
;             if constexpr (SP2) {
;             PG8_LDB(B0, 0, 0); PG8_LDB(B1, 0, 1); PG8_SCHED; PG8_LDA(At, 0, 0); PG8_STAGE(PG8_SA(1, 1), a1 + hstepA, voffA);
;             PG8_WAIT_V(8); PG8_WAIT_L(0); PG8_BAR; PG8_MMA(0, 0, At, B0); PG8_MMA(0, 1, At, B1); PG8_BAR; PG8_SCHED;
;             PG8_LDA(At, 0, 1); PG8_STAGE(PG8_SB(0, 0), b2, voffB); PG8_STAGE(PG8_SB(0, 1), b2 + hstepB, voffB); PG8_STAGE(PG8_SA(0, 0), a2, voffA);
;             PG8_WAIT_V(8); PG8_WAIT_L(0); PG8_BAR; PG8_MMA(1, 0, At, B0); PG8_MMA(1, 1, At, B1); PG8_BAR; PG8_SCHED;
.LBB0_554:
	s_ashr_i32 s55, s54, 31
	s_lshl_b64 s[28:29], s[54:55], 20
	s_add_u32 s1, s14, s28
	s_addc_u32 s33, s15, s29
	s_ashr_i32 s28, s0, 30
	s_ashr_i32 s29, s28, 31
	s_lshl_b64 s[28:29], s[28:29], 12
	s_add_u32 s56, s1, s28
	s_addc_u32 s57, s33, s29
	s_and_b64 s[28:29], s[4:5], exec
	s_cselect_b32 s28, s57, s63
	s_cselect_b32 s29, s56, s62
	s_ashr_i32 s1, s0, 31
	s_lshl_b64 s[36:37], s[0:1], 20
	s_add_u32 s58, s74, s36
	s_addc_u32 s59, s75, s37
	s_and_b64 s[36:37], s[4:5], exec
	s_cselect_b32 s33, s59, s65
	s_cselect_b32 s35, s58, s64
	s_add_u32 s62, s62, 0x80080
	s_addc_u32 s63, s63, 0
	s_add_u32 s36, s64, 0x100
	s_addc_u32 s37, s65, 0
	s_mov_b32 s46, -2
	ds_read_b128 v[82:85], v181
	ds_read_b128 v[86:89], v181 offset:1024
	ds_read_b128 v[138:141], v181 offset:2048
	ds_read_b128 v[142:145], v181 offset:3072
	ds_read_b128 v[146:149], v213
	ds_read_b128 v[150:153], v213 offset:1024
	ds_read_b128 v[154:157], v213 offset:2048
	ds_read_b128 v[158:161], v213 offset:3072
	s_add_u32 s47, s62, 0xfff80080
	s_addc_u32 s61, s63, -1
	s_cmp_eq_u32 s46, 28
	s_cselect_b32 s67, s28, s61
	s_cselect_b32 s66, s29, s47
	s_cselect_b32 s65, s33, s37
	s_cselect_b32 s64, s35, s36
	v_lshl_add_u64 v[194:195], s[62:63], 0, v[174:175]
	s_add_i32 m0, s11, 0xc000
	ds_read_b128 v[186:189], v214
	ds_read_b128 v[190:193], v214 offset:1024
	ds_read_b128 v[216:219], v214 offset:2048
	ds_read_b128 v[220:223], v214 offset:3072
	ds_read_b128 v[224:227], v214 offset:4096
	ds_read_b128 v[228:231], v214 offset:5120
	ds_read_b128 v[232:235], v214 offset:6144
	ds_read_b128 v[236:239], v214 offset:7168
	global_load_lds_dwordx4 v[194:195], off
	v_lshl_add_u64 v[194:195], s[62:63], 0, v[176:177]
	s_add_i32 m0, s11, 0xe000
	s_nop 0
	global_load_lds_dwordx4 v[194:195], off
	s_waitcnt vmcnt(8)
	s_waitcnt lgkmcnt(0)
	s_barrier
	s_setprio 1
	s_waitcnt lgkmcnt(0)
	v_mfma_i32_16x16x64_i8 v[70:73], v[82:85], v[186:189], 0
	v_mfma_i32_16x16x64_i8 v[70:73], v[86:89], v[190:193], v[70:73]
	v_mfma_i32_16x16x64_i8 v[66:69], v[142:145], v[190:193], 0
	v_mfma_i32_16x16x64_i8 v[66:69], v[138:141], v[186:189], v[66:69]
	v_mfma_i32_16x16x64_i8 v[122:125], v[138:141], v[216:219], 0
	v_mfma_i32_16x16x64_i8 v[122:125], v[142:145], v[220:223], v[122:125]
	v_mfma_i32_16x16x64_i8 v[126:129], v[86:89], v[220:223], 0
	v_mfma_i32_16x16x64_i8 v[126:129], v[82:85], v[216:219], v[126:129]
	v_mfma_i32_16x16x64_i8 v[110:113], v[82:85], v[224:227], 0
	v_mfma_i32_16x16x64_i8 v[110:113], v[86:89], v[228:231], v[110:113]
	v_mfma_i32_16x16x64_i8 v[106:109], v[142:145], v[228:231], 0
	v_mfma_i32_16x16x64_i8 v[106:109], v[138:141], v[224:227], v[106:109]
	v_mfma_i32_16x16x64_i8 v[90:93], v[138:141], v[232:235], 0
	v_mfma_i32_16x16x64_i8 v[90:93], v[142:145], v[236:239], v[90:93]
	v_mfma_i32_16x16x64_i8 v[94:97], v[86:89], v[236:239], 0
	v_mfma_i32_16x16x64_i8 v[94:97], v[82:85], v[232:235], v[94:97]
	s_setprio 0
	s_setprio 1
	v_mfma_i32_16x16x64_i8 v[78:81], v[146:149], v[232:235], 0
	v_mfma_i32_16x16x64_i8 v[78:81], v[150:153], v[236:239], v[78:81]
	v_mfma_i32_16x16x64_i8 v[74:77], v[158:161], v[236:239], 0
	v_mfma_i32_16x16x64_i8 v[74:77], v[154:157], v[232:235], v[74:77]
	v_mfma_i32_16x16x64_i8 v[98:101], v[154:157], v[224:227], 0
	v_mfma_i32_16x16x64_i8 v[98:101], v[158:161], v[228:231], v[98:101]
	v_mfma_i32_16x16x64_i8 v[102:105], v[150:153], v[228:231], 0
	v_mfma_i32_16x16x64_i8 v[102:105], v[146:149], v[224:227], v[102:105]
	v_mfma_i32_16x16x64_i8 v[118:121], v[146:149], v[216:219], 0
	v_mfma_i32_16x16x64_i8 v[118:121], v[150:153], v[220:223], v[118:121]
	v_mfma_i32_16x16x64_i8 v[114:117], v[158:161], v[220:223], 0
	v_mfma_i32_16x16x64_i8 v[114:117], v[154:157], v[216:219], v[114:117]
	v_mfma_i32_16x16x64_i8 v[130:133], v[154:157], v[186:189], 0
	v_mfma_i32_16x16x64_i8 v[130:133], v[158:161], v[190:193], v[130:133]
	v_mfma_i32_16x16x64_i8 v[134:137], v[150:153], v[190:193], 0
	v_mfma_i32_16x16x64_i8 v[134:137], v[146:149], v[186:189], v[134:137]
	s_setprio 0
	s_barrier
	s_add_i32 s47, s23, s7
	v_lshl_add_u64 v[194:195], s[64:65], 0, v[164:165]
	s_mov_b32 m0, s47
	ds_read_b128 v[186:189], v214 offset:16384
	ds_read_b128 v[190:193], v214 offset:17408
	ds_read_b128 v[216:219], v214 offset:18432
	ds_read_b128 v[220:223], v214 offset:19456
	ds_read_b128 v[224:227], v214 offset:20480
	ds_read_b128 v[228:231], v214 offset:21504
	ds_read_b128 v[232:235], v214 offset:22528
	ds_read_b128 v[236:239], v214 offset:23552
	global_load_lds_dwordx4 v[194:195], off
	s_add_i32 m0, s47, 0x2000
	s_add_u32 s68, s64, 0x80000
	v_lshl_add_u64 v[240:241], s[64:65], 0, v[168:169]
	s_addc_u32 s69, s65, 0
	s_add_i32 s47, s24, s7
	global_load_lds_dwordx4 v[240:241], off
	v_lshl_add_u64 v[242:243], s[68:69], 0, v[164:165]
	s_mov_b32 m0, s47
	v_lshl_add_u64 v[244:245], s[66:67], 0, v[166:167]
	global_load_lds_dwordx4 v[242:243], off
	v_lshl_add_u64 v[242:243], s[68:69], 0, v[168:169]
	s_add_i32 m0, s47, 0x2000
	s_nop 0
	global_load_lds_dwordx4 v[242:243], off
	v_lshl_add_u64 v[242:243], s[66:67], 0, v[162:163]
	s_mov_b32 m0, s11
	s_nop 0
	global_load_lds_dwordx4 v[242:243], off
	s_mov_b32 m0, s12
	s_nop 0
	global_load_lds_dwordx4 v[244:245], off
	s_waitcnt vmcnt(8)
	s_waitcnt lgkmcnt(0)
	s_barrier
; #define PG8_STAGE(bufoff, gbase, voff) do { _Pragma("unroll") for (int _i = 0; _i < 2; ++_i) \
;         __builtin_amdgcn_global_load_lds((const unsigned*)((const char*)(gbase) + (voff)[_i]), (PG8_LAS unsigned*)(lds + (bufoff) + ldsw + _i * 8192), 16, 0, 0); } while (0)
; #define PG8_LDA(dst, b, h) do { _Pragma("unroll") for (int m = 0; m < 4; ++m) _Pragma("unroll") for (int k = 0; k < 2; ++k) dst[m][k] = *(const PG8_LAS bf16x8*)(lds + PG8_SA(b, h) + aoff + m * 2048 + k * 1024); } while (0)
; #define PG8_LDB(dst, b, h) do { _Pragma("unroll") for (int n = 0; n < 2; ++n) _Pragma("unroll") for (int k = 0; k < 2; ++k) dst[n][k] = *(const PG8_LAS bf16x8*)(lds + PG8_SB(b, h) + boff + n * 2048 + k * 1024); } while (0)
; #define PG8_MMA(ai, bj, At, Bt) do { __builtin_amdgcn_s_setprio(1); _Pragma("unroll") for (int m = 0; m < 4; ++m) _Pragma("unroll") for (int n = 0; n < 2; ++n) _Pragma("unroll") for (int k = 0; k < 2; ++k) \
;         acc[ai][bj][m][n] = mma16(Bt[n][k], At[m][k], acc[ai][bj][m][n]); __builtin_amdgcn_s_setprio(0); } while (0)
; #define PG8_WAIT_V(n) asm volatile("s_waitcnt vmcnt(" #n ")" ::: "memory")
; #define PG8_WAIT_L(n) asm volatile("s_waitcnt lgkmcnt(" #n ")" ::: "memory")
; #define PG8_BAR __builtin_amdgcn_s_barrier()
; #define PG8_SCHED __builtin_amdgcn_sched_barrier(0)
; template <class Epi, class Sched, bool ALIGN_EPI = false, bool SP2 = false>
; __device__ __forceinline__ void gemm_phase(PG8_LAS unsigned char* lds, const Gemm g, const Sched& S, const Epi& E) {
;     ...
;             PG8_WAIT_V(8); PG8_WAIT_L(0); PG8_BAR; PG8_MMA(0, 0, At, B0); PG8_MMA(0, 1, At, B1); PG8_BAR; PG8_SCHED;
;             PG8_LDA(At, 0, 1); PG8_STAGE(PG8_SB(0, 0), b2, voffB); PG8_STAGE(PG8_SB(0, 1), b2 + hstepB, voffB); PG8_STAGE(PG8_SA(0, 0), a2, voffA);
;             PG8_WAIT_V(8); PG8_WAIT_L(0); PG8_BAR; PG8_MMA(1, 0, At, B0); PG8_MMA(1, 1, At, B1); PG8_BAR; PG8_SCHED;
;             PG8_LDB(B0, 1, 0); PG8_LDB(B1, 1, 1); PG8_SCHED; PG8_LDA(At, 1, 0); PG8_STAGE(PG8_SA(0, 1), a2 + hstepA, voffA);
;             PG8_WAIT_V(8); PG8_WAIT_L(0); PG8_BAR; PG8_MMA(0, 0, At, B0); PG8_MMA(0, 1, At, B1); PG8_BAR; PG8_SCHED;
	s_setprio 1
	s_waitcnt lgkmcnt(0)
	v_mfma_i32_16x16x64_i8 v[62:65], v[82:85], v[186:189], 0
	v_mfma_i32_16x16x64_i8 v[62:65], v[86:89], v[190:193], v[62:65]
	v_mfma_i32_16x16x64_i8 v[58:61], v[142:145], v[190:193], 0
	v_mfma_i32_16x16x64_i8 v[58:61], v[138:141], v[186:189], v[58:61]
	v_mfma_i32_16x16x64_i8 v[42:45], v[138:141], v[216:219], 0
	v_mfma_i32_16x16x64_i8 v[42:45], v[142:145], v[220:223], v[42:45]
	v_mfma_i32_16x16x64_i8 v[46:49], v[86:89], v[220:223], 0
	v_mfma_i32_16x16x64_i8 v[46:49], v[82:85], v[216:219], v[46:49]
	v_mfma_i32_16x16x64_i8 v[30:33], v[82:85], v[224:227], 0
	v_mfma_i32_16x16x64_i8 v[30:33], v[86:89], v[228:231], v[30:33]
	v_mfma_i32_16x16x64_i8 v[26:29], v[142:145], v[228:231], 0
	v_mfma_i32_16x16x64_i8 v[26:29], v[138:141], v[224:227], v[26:29]
	v_mfma_i32_16x16x64_i8 v[10:13], v[138:141], v[232:235], 0
	v_mfma_i32_16x16x64_i8 v[10:13], v[142:145], v[236:239], v[10:13]
	v_mfma_i32_16x16x64_i8 v[14:17], v[86:89], v[236:239], 0
	v_mfma_i32_16x16x64_i8 v[14:17], v[82:85], v[232:235], v[14:17]
	s_setprio 0
	s_setprio 1
	v_mfma_i32_16x16x64_i8 v[6:9], v[146:149], v[232:235], 0
	v_mfma_i32_16x16x64_i8 v[6:9], v[150:153], v[236:239], v[6:9]
	v_mfma_i32_16x16x64_i8 v[2:5], v[158:161], v[236:239], 0
	v_mfma_i32_16x16x64_i8 v[2:5], v[154:157], v[232:235], v[2:5]
	v_mfma_i32_16x16x64_i8 v[18:21], v[154:157], v[224:227], 0
	v_mfma_i32_16x16x64_i8 v[18:21], v[158:161], v[228:231], v[18:21]
	v_mfma_i32_16x16x64_i8 v[22:25], v[150:153], v[228:231], 0
	v_mfma_i32_16x16x64_i8 v[22:25], v[146:149], v[224:227], v[22:25]
	v_mfma_i32_16x16x64_i8 v[38:41], v[146:149], v[216:219], 0
	v_mfma_i32_16x16x64_i8 v[38:41], v[150:153], v[220:223], v[38:41]
	v_mfma_i32_16x16x64_i8 v[34:37], v[158:161], v[220:223], 0
	v_mfma_i32_16x16x64_i8 v[34:37], v[154:157], v[216:219], v[34:37]
	v_mfma_i32_16x16x64_i8 v[50:53], v[154:157], v[186:189], 0
	v_mfma_i32_16x16x64_i8 v[50:53], v[158:161], v[190:193], v[50:53]
	v_mfma_i32_16x16x64_i8 v[54:57], v[150:153], v[190:193], 0
	v_mfma_i32_16x16x64_i8 v[54:57], v[146:149], v[186:189], v[54:57]
	s_setprio 0
	s_barrier
	s_add_i32 s47, 0, 0x18000
	s_add_i32 s61, 0, 0x1c000
	v_add_u32_e32 v142, s47, v209
	v_add_u32_e32 v158, s61, v209
	ds_read_b128 v[82:85], v142
	ds_read_b128 v[86:89], v142 offset:1024
	ds_read_b128 v[138:141], v142 offset:2048
	ds_read_b128 v[142:145], v142 offset:3072
	ds_read_b128 v[146:149], v158
	ds_read_b128 v[150:153], v158 offset:1024
	ds_read_b128 v[154:157], v158 offset:2048
	ds_read_b128 v[158:161], v158 offset:3072
	s_add_u32 s66, s66, 0x80000
	s_addc_u32 s67, s67, 0
	s_mov_b32 m0, s13
	v_lshl_add_u64 v[246:247], s[66:67], 0, v[162:163]
	ds_read_b128 v[186:189], v214 offset:32768
	ds_read_b128 v[190:193], v214 offset:33792
	ds_read_b128 v[216:219], v214 offset:34816
	ds_read_b128 v[220:223], v214 offset:35840
	ds_read_b128 v[224:227], v214 offset:36864
	ds_read_b128 v[228:231], v214 offset:37888
	ds_read_b128 v[232:235], v214 offset:38912
	ds_read_b128 v[236:239], v214 offset:39936
	global_load_lds_dwordx4 v[246:247], off
	v_lshl_add_u64 v[246:247], s[66:67], 0, v[166:167]
	s_mov_b32 m0, s16
	s_nop 0
	global_load_lds_dwordx4 v[246:247], off
	s_waitcnt vmcnt(8)
	s_waitcnt lgkmcnt(0)
	s_barrier
	s_setprio 1
	s_waitcnt lgkmcnt(0)
	v_mfma_i32_16x16x64_i8 v[70:73], v[82:85], v[186:189], v[70:73]
	v_mfma_i32_16x16x64_i8 v[70:73], v[86:89], v[190:193], v[70:73]
	v_mfma_i32_16x16x64_i8 v[66:69], v[142:145], v[190:193], v[66:69]
	v_mfma_i32_16x16x64_i8 v[66:69], v[138:141], v[186:189], v[66:69]
	v_mfma_i32_16x16x64_i8 v[122:125], v[138:141], v[216:219], v[122:125]
	v_mfma_i32_16x16x64_i8 v[122:125], v[142:145], v[220:223], v[122:125]
	v_mfma_i32_16x16x64_i8 v[126:129], v[86:89], v[220:223], v[126:129]
	v_mfma_i32_16x16x64_i8 v[126:129], v[82:85], v[216:219], v[126:129]
	v_mfma_i32_16x16x64_i8 v[110:113], v[82:85], v[224:227], v[110:113]
	v_mfma_i32_16x16x64_i8 v[110:113], v[86:89], v[228:231], v[110:113]
	v_mfma_i32_16x16x64_i8 v[106:109], v[142:145], v[228:231], v[106:109]
	v_mfma_i32_16x16x64_i8 v[106:109], v[138:141], v[224:227], v[106:109]
	v_mfma_i32_16x16x64_i8 v[90:93], v[138:141], v[232:235], v[90:93]
	v_mfma_i32_16x16x64_i8 v[90:93], v[142:145], v[236:239], v[90:93]
	v_mfma_i32_16x16x64_i8 v[94:97], v[86:89], v[236:239], v[94:97]
	v_mfma_i32_16x16x64_i8 v[94:97], v[82:85], v[232:235], v[94:97]
	s_setprio 0
	s_setprio 1
	v_mfma_i32_16x16x64_i8 v[78:81], v[146:149], v[232:235], v[78:81]
	v_mfma_i32_16x16x64_i8 v[78:81], v[150:153], v[236:239], v[78:81]
	v_mfma_i32_16x16x64_i8 v[74:77], v[158:161], v[236:239], v[74:77]
	v_mfma_i32_16x16x64_i8 v[74:77], v[154:157], v[232:235], v[74:77]
	v_mfma_i32_16x16x64_i8 v[98:101], v[154:157], v[224:227], v[98:101]
	v_mfma_i32_16x16x64_i8 v[98:101], v[158:161], v[228:231], v[98:101]
	v_mfma_i32_16x16x64_i8 v[102:105], v[150:153], v[228:231], v[102:105]
	v_mfma_i32_16x16x64_i8 v[102:105], v[146:149], v[224:227], v[102:105]
	v_mfma_i32_16x16x64_i8 v[118:121], v[146:149], v[216:219], v[118:121]
	v_mfma_i32_16x16x64_i8 v[118:121], v[150:153], v[220:223], v[118:121]
	v_mfma_i32_16x16x64_i8 v[114:117], v[158:161], v[220:223], v[114:117]
	v_mfma_i32_16x16x64_i8 v[114:117], v[154:157], v[216:219], v[114:117]
	v_mfma_i32_16x16x64_i8 v[130:133], v[154:157], v[186:189], v[130:133]
	v_mfma_i32_16x16x64_i8 v[130:133], v[158:161], v[190:193], v[130:133]
	v_mfma_i32_16x16x64_i8 v[134:137], v[150:153], v[190:193], v[134:137]
	v_mfma_i32_16x16x64_i8 v[134:137], v[146:149], v[186:189], v[134:137]
	s_setprio 0
	s_barrier
; #define PG8_STAGE(bufoff, gbase, voff) do { _Pragma("unroll") for (int _i = 0; _i < 2; ++_i) \
;         __builtin_amdgcn_global_load_lds((const unsigned*)((const char*)(gbase) + (voff)[_i]), (PG8_LAS unsigned*)(lds + (bufoff) + ldsw + _i * 8192), 16, 0, 0); } while (0)
; #define PG8_LDA(dst, b, h) do { _Pragma("unroll") for (int m = 0; m < 4; ++m) _Pragma("unroll") for (int k = 0; k < 2; ++k) dst[m][k] = *(const PG8_LAS bf16x8*)(lds + PG8_SA(b, h) + aoff + m * 2048 + k * 1024); } while (0)
; #define PG8_LDB(dst, b, h) do { _Pragma("unroll") for (int n = 0; n < 2; ++n) _Pragma("unroll") for (int k = 0; k < 2; ++k) dst[n][k] = *(const PG8_LAS bf16x8*)(lds + PG8_SB(b, h) + boff + n * 2048 + k * 1024); } while (0)
; template <class Epi, class Sched, bool ALIGN_EPI = false, bool SP2 = false>
; __device__ __forceinline__ void gemm_phase(PG8_LAS unsigned char* lds, const Gemm g, const Sched& S, const Epi& E) {
;     ...
;         for (int t = 0; t < nt; t += 2) {
;             const bool last = (t == nt - 2);
;             const char* a1 = cA + (size_t)(t + 1) * kstep;
;             const char* a2 = last ? nA : cA + (size_t)(t + 2) * kstep; const char* b2 = last ? nB : cB + (size_t)(t + 2) * kstep;
;             const char* a3 = a2 + kstep; const char* b3 = b2 + kstep;
;             if (last && has_next) S.a_ready(nxt);
;             if constexpr (SP2) {
;             PG8_LDB(B0, 0, 0); PG8_LDB(B1, 0, 1); PG8_SCHED; PG8_LDA(At, 0, 0); PG8_STAGE(PG8_SA(1, 1), a1 + hstepA, voffA);
;             PG8_WAIT_V(8); PG8_WAIT_L(0); PG8_BAR; PG8_MMA(0, 0, At, B0); PG8_MMA(0, 1, At, B1); PG8_BAR; PG8_SCHED;
;             PG8_LDA(At, 0, 1); PG8_STAGE(PG8_SB(0, 0), b2, voffB); PG8_STAGE(PG8_SB(0, 1), b2 + hstepB, voffB); PG8_STAGE(PG8_SA(0, 0), a2, voffA);
;             PG8_WAIT_V(8); PG8_WAIT_L(0); PG8_BAR; PG8_MMA(1, 0, At, B0); PG8_MMA(1, 1, At, B1); PG8_BAR; PG8_SCHED;
;             PG8_LDB(B0, 1, 0); PG8_LDB(B1, 1, 1); PG8_SCHED; PG8_LDA(At, 1, 0); PG8_STAGE(PG8_SA(0, 1), a2 + hstepA, voffA);
;             PG8_WAIT_V(8); PG8_WAIT_L(0); PG8_BAR; PG8_MMA(0, 0, At, B0); PG8_MMA(0, 1, At, B1); PG8_BAR; PG8_SCHED;
;             PG8_LDA(At, 1, 1); PG8_STAGE(PG8_SB(1, 0), b3, voffB); PG8_STAGE(PG8_SB(1, 1), b3 + hstepB, voffB); PG8_STAGE(PG8_SA(1, 0), a3, voffA);
;             PG8_WAIT_V(8); PG8_WAIT_L(0); PG8_BAR; PG8_MMA(1, 0, At, B0); PG8_MMA(1, 1, At, B1); PG8_BAR; PG8_SCHED;
	s_add_i32 s47, s47, s7
	v_lshl_add_u64 v[194:195], v[194:195], 0, s[50:51]
	s_mov_b32 m0, s47
	ds_read_b128 v[186:189], v214 offset:49152
	ds_read_b128 v[190:193], v214 offset:50176
	ds_read_b128 v[216:219], v214 offset:51200
	ds_read_b128 v[220:223], v214 offset:52224
	ds_read_b128 v[224:227], v214 offset:53248
	ds_read_b128 v[228:231], v214 offset:54272
	ds_read_b128 v[232:235], v214 offset:55296
	ds_read_b128 v[236:239], v214 offset:56320
	global_load_lds_dwordx4 v[194:195], off
	s_add_i32 m0, s47, 0x2000
	s_add_u32 s64, s64, 0x80080
	v_lshl_add_u64 v[194:195], v[240:241], 0, s[50:51]
	s_addc_u32 s65, s65, 0
	s_add_i32 s47, s61, s7
	global_load_lds_dwordx4 v[194:195], off
	v_lshl_add_u64 v[194:195], s[64:65], 0, v[164:165]
	s_mov_b32 m0, s47
	s_nop 0
	global_load_lds_dwordx4 v[194:195], off
	v_lshl_add_u64 v[194:195], s[64:65], 0, v[168:169]
	s_add_i32 m0, s47, 0x2000
	s_nop 0
	global_load_lds_dwordx4 v[194:195], off
	v_lshl_add_u64 v[194:195], v[242:243], 0, s[50:51]
	s_mov_b32 m0, s19
	s_nop 0
	global_load_lds_dwordx4 v[194:195], off
	v_lshl_add_u64 v[194:195], v[244:245], 0, s[50:51]
	s_mov_b32 m0, s20
	s_nop 0
	global_load_lds_dwordx4 v[194:195], off
	s_waitcnt vmcnt(8)
	s_waitcnt lgkmcnt(0)
	s_barrier
	s_setprio 1
	s_waitcnt lgkmcnt(0)
	v_mfma_i32_16x16x64_i8 v[62:65], v[82:85], v[186:189], v[62:65]
	v_mfma_i32_16x16x64_i8 v[62:65], v[86:89], v[190:193], v[62:65]
	v_mfma_i32_16x16x64_i8 v[58:61], v[142:145], v[190:193], v[58:61]
	v_mfma_i32_16x16x64_i8 v[58:61], v[138:141], v[186:189], v[58:61]
	v_mfma_i32_16x16x64_i8 v[42:45], v[138:141], v[216:219], v[42:45]
	v_mfma_i32_16x16x64_i8 v[42:45], v[142:145], v[220:223], v[42:45]
	v_mfma_i32_16x16x64_i8 v[46:49], v[86:89], v[220:223], v[46:49]
	v_mfma_i32_16x16x64_i8 v[46:49], v[82:85], v[216:219], v[46:49]
	v_mfma_i32_16x16x64_i8 v[30:33], v[82:85], v[224:227], v[30:33]
	v_mfma_i32_16x16x64_i8 v[30:33], v[86:89], v[228:231], v[30:33]
	v_mfma_i32_16x16x64_i8 v[26:29], v[142:145], v[228:231], v[26:29]
	v_mfma_i32_16x16x64_i8 v[26:29], v[138:141], v[224:227], v[26:29]
	v_mfma_i32_16x16x64_i8 v[10:13], v[138:141], v[232:235], v[10:13]
	v_mfma_i32_16x16x64_i8 v[10:13], v[142:145], v[236:239], v[10:13]
	v_mfma_i32_16x16x64_i8 v[14:17], v[86:89], v[236:239], v[14:17]
	v_mfma_i32_16x16x64_i8 v[14:17], v[82:85], v[232:235], v[14:17]
	s_setprio 0
	s_setprio 1
	v_mfma_i32_16x16x64_i8 v[6:9], v[146:149], v[232:235], v[6:9]
	v_mfma_i32_16x16x64_i8 v[6:9], v[150:153], v[236:239], v[6:9]
	v_mfma_i32_16x16x64_i8 v[2:5], v[158:161], v[236:239], v[2:5]
	v_mfma_i32_16x16x64_i8 v[2:5], v[154:157], v[232:235], v[2:5]
	v_mfma_i32_16x16x64_i8 v[18:21], v[154:157], v[224:227], v[18:21]
	v_mfma_i32_16x16x64_i8 v[18:21], v[158:161], v[228:231], v[18:21]
	v_mfma_i32_16x16x64_i8 v[22:25], v[150:153], v[228:231], v[22:25]
	v_mfma_i32_16x16x64_i8 v[22:25], v[146:149], v[224:227], v[22:25]
	v_mfma_i32_16x16x64_i8 v[38:41], v[146:149], v[216:219], v[38:41]
	v_mfma_i32_16x16x64_i8 v[38:41], v[150:153], v[220:223], v[38:41]
	v_mfma_i32_16x16x64_i8 v[34:37], v[158:161], v[220:223], v[34:37]
	v_mfma_i32_16x16x64_i8 v[34:37], v[154:157], v[216:219], v[34:37]
	v_mfma_i32_16x16x64_i8 v[50:53], v[154:157], v[186:189], v[50:53]
	v_mfma_i32_16x16x64_i8 v[50:53], v[158:161], v[190:193], v[50:53]
	v_mfma_i32_16x16x64_i8 v[54:57], v[150:153], v[190:193], v[54:57]
	v_mfma_i32_16x16x64_i8 v[54:57], v[146:149], v[186:189], v[54:57]
	s_setprio 0
	s_barrier
	s_add_i32 s46, s46, 2
	s_add_u32 s62, s62, 0x100
	s_addc_u32 s63, s63, 0
	s_add_u32 s36, s36, 0x100
	s_addc_u32 s37, s37, 0
.LBB0_555:
	ds_read_b128 v[82:85], v181
	ds_read_b128 v[86:89], v181 offset:1024
	ds_read_b128 v[138:141], v181 offset:2048
	ds_read_b128 v[142:145], v181 offset:3072
	ds_read_b128 v[146:149], v213
	ds_read_b128 v[150:153], v213 offset:1024
	ds_read_b128 v[154:157], v213 offset:2048
	ds_read_b128 v[158:161], v213 offset:3072
	s_add_u32 s47, s62, 0xfff80080
	s_addc_u32 s61, s63, -1
	s_cmp_eq_u32 s46, 28
	s_cselect_b32 s67, s28, s61
	s_cselect_b32 s66, s29, s47
	s_cselect_b32 s65, s33, s37
	s_cselect_b32 s64, s35, s36
	v_lshl_add_u64 v[194:195], s[62:63], 0, v[174:175]
	s_add_i32 m0, s11, 0xc000
	ds_read_b128 v[186:189], v214
	ds_read_b128 v[190:193], v214 offset:1024
	ds_read_b128 v[216:219], v214 offset:2048
	ds_read_b128 v[220:223], v214 offset:3072
	ds_read_b128 v[224:227], v214 offset:4096
	ds_read_b128 v[228:231], v214 offset:5120
	ds_read_b128 v[232:235], v214 offset:6144
	ds_read_b128 v[236:239], v214 offset:7168
	global_load_lds_dwordx4 v[194:195], off
	v_lshl_add_u64 v[194:195], s[62:63], 0, v[176:177]
	s_add_i32 m0, s11, 0xe000
	s_nop 0
	global_load_lds_dwordx4 v[194:195], off
	s_waitcnt vmcnt(8)
	s_waitcnt lgkmcnt(0)
	s_barrier
; #define PG8_STAGE(bufoff, gbase, voff) do { _Pragma("unroll") for (int _i = 0; _i < 2; ++_i) \
;         __builtin_amdgcn_global_load_lds((const unsigned*)((const char*)(gbase) + (voff)[_i]), (PG8_LAS unsigned*)(lds + (bufoff) + ldsw + _i * 8192), 16, 0, 0); } while (0)
; #define PG8_LDA(dst, b, h) do { _Pragma("unroll") for (int m = 0; m < 4; ++m) _Pragma("unroll") for (int k = 0; k < 2; ++k) dst[m][k] = *(const PG8_LAS bf16x8*)(lds + PG8_SA(b, h) + aoff + m * 2048 + k * 1024); } while (0)
; #define PG8_LDB(dst, b, h) do { _Pragma("unroll") for (int n = 0; n < 2; ++n) _Pragma("unroll") for (int k = 0; k < 2; ++k) dst[n][k] = *(const PG8_LAS bf16x8*)(lds + PG8_SB(b, h) + boff + n * 2048 + k * 1024); } while (0)
; #define PG8_MMA(ai, bj, At, Bt) do { __builtin_amdgcn_s_setprio(1); _Pragma("unroll") for (int m = 0; m < 4; ++m) _Pragma("unroll") for (int n = 0; n < 2; ++n) _Pragma("unroll") for (int k = 0; k < 2; ++k) \
;         acc[ai][bj][m][n] = mma16(Bt[n][k], At[m][k], acc[ai][bj][m][n]); __builtin_amdgcn_s_setprio(0); } while (0)
; #define PG8_WAIT_V(n) asm volatile("s_waitcnt vmcnt(" #n ")" ::: "memory")
; #define PG8_WAIT_L(n) asm volatile("s_waitcnt lgkmcnt(" #n ")" ::: "memory")
; #define PG8_BAR __builtin_amdgcn_s_barrier()
; #define PG8_SCHED __builtin_amdgcn_sched_barrier(0)
; template <class Epi, class Sched, bool ALIGN_EPI = false, bool SP2 = false>
; __device__ __forceinline__ void gemm_phase(PG8_LAS unsigned char* lds, const Gemm g, const Sched& S, const Epi& E) {
;     ...
;             PG8_LDB(B0, 0, 0); PG8_LDB(B1, 0, 1); PG8_SCHED; PG8_LDA(At, 0, 0); PG8_STAGE(PG8_SA(1, 1), a1 + hstepA, voffA);
;             PG8_WAIT_V(8); PG8_WAIT_L(0); PG8_BAR; PG8_MMA(0, 0, At, B0); PG8_MMA(0, 1, At, B1); PG8_BAR; PG8_SCHED;
;             PG8_LDA(At, 0, 1); PG8_STAGE(PG8_SB(0, 0), b2, voffB); PG8_STAGE(PG8_SB(0, 1), b2 + hstepB, voffB); PG8_STAGE(PG8_SA(0, 0), a2, voffA);
;             PG8_WAIT_V(8); PG8_WAIT_L(0); PG8_BAR; PG8_MMA(1, 0, At, B0); PG8_MMA(1, 1, At, B1); PG8_BAR; PG8_SCHED;
	s_setprio 1
	s_waitcnt lgkmcnt(0)
	v_mfma_i32_16x16x64_i8 v[70:73], v[82:85], v[186:189], v[70:73]
	v_mfma_i32_16x16x64_i8 v[70:73], v[86:89], v[190:193], v[70:73]
	v_mfma_i32_16x16x64_i8 v[66:69], v[142:145], v[190:193], v[66:69]
	v_mfma_i32_16x16x64_i8 v[66:69], v[138:141], v[186:189], v[66:69]
	v_mfma_i32_16x16x64_i8 v[122:125], v[138:141], v[216:219], v[122:125]
	v_mfma_i32_16x16x64_i8 v[122:125], v[142:145], v[220:223], v[122:125]
	v_mfma_i32_16x16x64_i8 v[126:129], v[86:89], v[220:223], v[126:129]
	v_mfma_i32_16x16x64_i8 v[126:129], v[82:85], v[216:219], v[126:129]
	v_mfma_i32_16x16x64_i8 v[110:113], v[82:85], v[224:227], v[110:113]
	v_mfma_i32_16x16x64_i8 v[110:113], v[86:89], v[228:231], v[110:113]
	v_mfma_i32_16x16x64_i8 v[106:109], v[142:145], v[228:231], v[106:109]
	v_mfma_i32_16x16x64_i8 v[106:109], v[138:141], v[224:227], v[106:109]
	v_mfma_i32_16x16x64_i8 v[90:93], v[138:141], v[232:235], v[90:93]
	v_mfma_i32_16x16x64_i8 v[90:93], v[142:145], v[236:239], v[90:93]
	v_mfma_i32_16x16x64_i8 v[94:97], v[86:89], v[236:239], v[94:97]
	v_mfma_i32_16x16x64_i8 v[94:97], v[82:85], v[232:235], v[94:97]
	s_setprio 0
	s_setprio 1
	v_mfma_i32_16x16x64_i8 v[78:81], v[146:149], v[232:235], v[78:81]
	v_mfma_i32_16x16x64_i8 v[78:81], v[150:153], v[236:239], v[78:81]
	v_mfma_i32_16x16x64_i8 v[74:77], v[158:161], v[236:239], v[74:77]
	v_mfma_i32_16x16x64_i8 v[74:77], v[154:157], v[232:235], v[74:77]
	v_mfma_i32_16x16x64_i8 v[98:101], v[154:157], v[224:227], v[98:101]
	v_mfma_i32_16x16x64_i8 v[98:101], v[158:161], v[228:231], v[98:101]
	v_mfma_i32_16x16x64_i8 v[102:105], v[150:153], v[228:231], v[102:105]
	v_mfma_i32_16x16x64_i8 v[102:105], v[146:149], v[224:227], v[102:105]
	v_mfma_i32_16x16x64_i8 v[118:121], v[146:149], v[216:219], v[118:121]
	v_mfma_i32_16x16x64_i8 v[118:121], v[150:153], v[220:223], v[118:121]
	v_mfma_i32_16x16x64_i8 v[114:117], v[158:161], v[220:223], v[114:117]
	v_mfma_i32_16x16x64_i8 v[114:117], v[154:157], v[216:219], v[114:117]
	v_mfma_i32_16x16x64_i8 v[130:133], v[154:157], v[186:189], v[130:133]
	v_mfma_i32_16x16x64_i8 v[130:133], v[158:161], v[190:193], v[130:133]
	v_mfma_i32_16x16x64_i8 v[134:137], v[150:153], v[190:193], v[134:137]
	v_mfma_i32_16x16x64_i8 v[134:137], v[146:149], v[186:189], v[134:137]
	s_setprio 0
	s_barrier
	s_add_i32 s47, s23, s7
	v_lshl_add_u64 v[194:195], s[64:65], 0, v[164:165]
	s_mov_b32 m0, s47
	ds_read_b128 v[186:189], v214 offset:16384
	ds_read_b128 v[190:193], v214 offset:17408
	ds_read_b128 v[216:219], v214 offset:18432
	ds_read_b128 v[220:223], v214 offset:19456
	ds_read_b128 v[224:227], v214 offset:20480
	ds_read_b128 v[228:231], v214 offset:21504
	ds_read_b128 v[232:235], v214 offset:22528
	ds_read_b128 v[236:239], v214 offset:23552
	global_load_lds_dwordx4 v[194:195], off
	s_add_i32 m0, s47, 0x2000
	s_add_u32 s68, s64, 0x80000
	v_lshl_add_u64 v[240:241], s[64:65], 0, v[168:169]
	s_addc_u32 s69, s65, 0
	s_add_i32 s47, s24, s7
	global_load_lds_dwordx4 v[240:241], off
	v_lshl_add_u64 v[242:243], s[68:69], 0, v[164:165]
	s_mov_b32 m0, s47
	v_lshl_add_u64 v[244:245], s[66:67], 0, v[166:167]
	global_load_lds_dwordx4 v[242:243], off
	v_lshl_add_u64 v[242:243], s[68:69], 0, v[168:169]
	s_add_i32 m0, s47, 0x2000
	s_nop 0
	global_load_lds_dwordx4 v[242:243], off
	v_lshl_add_u64 v[242:243], s[66:67], 0, v[162:163]
	s_mov_b32 m0, s11
	s_nop 0
	global_load_lds_dwordx4 v[242:243], off
	s_mov_b32 m0, s12
	s_nop 0
	global_load_lds_dwordx4 v[244:245], off
	s_waitcnt vmcnt(8)
	s_waitcnt lgkmcnt(0)
	s_barrier
	s_setprio 1
	s_waitcnt lgkmcnt(0)
	v_mfma_i32_16x16x64_i8 v[62:65], v[82:85], v[186:189], v[62:65]
	v_mfma_i32_16x16x64_i8 v[62:65], v[86:89], v[190:193], v[62:65]
	v_mfma_i32_16x16x64_i8 v[58:61], v[142:145], v[190:193], v[58:61]
	v_mfma_i32_16x16x64_i8 v[58:61], v[138:141], v[186:189], v[58:61]
	v_mfma_i32_16x16x64_i8 v[42:45], v[138:141], v[216:219], v[42:45]
	v_mfma_i32_16x16x64_i8 v[42:45], v[142:145], v[220:223], v[42:45]
	v_mfma_i32_16x16x64_i8 v[46:49], v[86:89], v[220:223], v[46:49]
	v_mfma_i32_16x16x64_i8 v[46:49], v[82:85], v[216:219], v[46:49]
	v_mfma_i32_16x16x64_i8 v[30:33], v[82:85], v[224:227], v[30:33]
	v_mfma_i32_16x16x64_i8 v[30:33], v[86:89], v[228:231], v[30:33]
	v_mfma_i32_16x16x64_i8 v[26:29], v[142:145], v[228:231], v[26:29]
	v_mfma_i32_16x16x64_i8 v[26:29], v[138:141], v[224:227], v[26:29]
	v_mfma_i32_16x16x64_i8 v[10:13], v[138:141], v[232:235], v[10:13]
	v_mfma_i32_16x16x64_i8 v[10:13], v[142:145], v[236:239], v[10:13]
	v_mfma_i32_16x16x64_i8 v[14:17], v[86:89], v[236:239], v[14:17]
	v_mfma_i32_16x16x64_i8 v[14:17], v[82:85], v[232:235], v[14:17]
	s_setprio 0
	s_setprio 1
	v_mfma_i32_16x16x64_i8 v[6:9], v[146:149], v[232:235], v[6:9]
	v_mfma_i32_16x16x64_i8 v[6:9], v[150:153], v[236:239], v[6:9]
	v_mfma_i32_16x16x64_i8 v[2:5], v[158:161], v[236:239], v[2:5]
	v_mfma_i32_16x16x64_i8 v[2:5], v[154:157], v[232:235], v[2:5]
	v_mfma_i32_16x16x64_i8 v[18:21], v[154:157], v[224:227], v[18:21]
	v_mfma_i32_16x16x64_i8 v[18:21], v[158:161], v[228:231], v[18:21]
	v_mfma_i32_16x16x64_i8 v[22:25], v[150:153], v[228:231], v[22:25]
	v_mfma_i32_16x16x64_i8 v[22:25], v[146:149], v[224:227], v[22:25]
	v_mfma_i32_16x16x64_i8 v[38:41], v[146:149], v[216:219], v[38:41]
	v_mfma_i32_16x16x64_i8 v[38:41], v[150:153], v[220:223], v[38:41]
	v_mfma_i32_16x16x64_i8 v[34:37], v[158:161], v[220:223], v[34:37]
	v_mfma_i32_16x16x64_i8 v[34:37], v[154:157], v[216:219], v[34:37]
	v_mfma_i32_16x16x64_i8 v[50:53], v[154:157], v[186:189], v[50:53]
	v_mfma_i32_16x16x64_i8 v[50:53], v[158:161], v[190:193], v[50:53]
	v_mfma_i32_16x16x64_i8 v[54:57], v[150:153], v[190:193], v[54:57]
	v_mfma_i32_16x16x64_i8 v[54:57], v[146:149], v[186:189], v[54:57]
	s_setprio 0
	s_barrier
; #define PG8_STAGE(bufoff, gbase, voff) do { _Pragma("unroll") for (int _i = 0; _i < 2; ++_i) \
;         __builtin_amdgcn_global_load_lds((const unsigned*)((const char*)(gbase) + (voff)[_i]), (PG8_LAS unsigned*)(lds + (bufoff) + ldsw + _i * 8192), 16, 0, 0); } while (0)
; #define PG8_LDA(dst, b, h) do { _Pragma("unroll") for (int m = 0; m < 4; ++m) _Pragma("unroll") for (int k = 0; k < 2; ++k) dst[m][k] = *(const PG8_LAS bf16x8*)(lds + PG8_SA(b, h) + aoff + m * 2048 + k * 1024); } while (0)
; #define PG8_LDB(dst, b, h) do { _Pragma("unroll") for (int n = 0; n < 2; ++n) _Pragma("unroll") for (int k = 0; k < 2; ++k) dst[n][k] = *(const PG8_LAS bf16x8*)(lds + PG8_SB(b, h) + boff + n * 2048 + k * 1024); } while (0)
; #define PG8_MMA(ai, bj, At, Bt) do { __builtin_amdgcn_s_setprio(1); _Pragma("unroll") for (int m = 0; m < 4; ++m) _Pragma("unroll") for (int n = 0; n < 2; ++n) _Pragma("unroll") for (int k = 0; k < 2; ++k) \
;         acc[ai][bj][m][n] = mma16(Bt[n][k], At[m][k], acc[ai][bj][m][n]); __builtin_amdgcn_s_setprio(0); } while (0)
; #define PG8_WAIT_V(n) asm volatile("s_waitcnt vmcnt(" #n ")" ::: "memory")
; #define PG8_WAIT_L(n) asm volatile("s_waitcnt lgkmcnt(" #n ")" ::: "memory")
; #define PG8_BAR __builtin_amdgcn_s_barrier()
; #define PG8_SCHED __builtin_amdgcn_sched_barrier(0)
; template <class Epi, class Sched, bool ALIGN_EPI = false, bool SP2 = false>
; __device__ __forceinline__ void gemm_phase(PG8_LAS unsigned char* lds, const Gemm g, const Sched& S, const Epi& E) {
;     ...
;             PG8_LDB(B0, 1, 0); PG8_LDB(B1, 1, 1); PG8_SCHED; PG8_LDA(At, 1, 0); PG8_STAGE(PG8_SA(0, 1), a2 + hstepA, voffA);
;             PG8_WAIT_V(8); PG8_WAIT_L(0); PG8_BAR; PG8_MMA(0, 0, At, B0); PG8_MMA(0, 1, At, B1); PG8_BAR; PG8_SCHED;
	s_add_i32 s47, 0, 0x18000
	s_add_i32 s61, 0, 0x1c000
	v_add_u32_e32 v142, s47, v209
	v_add_u32_e32 v158, s61, v209
	ds_read_b128 v[82:85], v142
	ds_read_b128 v[86:89], v142 offset:1024
	ds_read_b128 v[138:141], v142 offset:2048
	ds_read_b128 v[142:145], v142 offset:3072
	ds_read_b128 v[146:149], v158
	ds_read_b128 v[150:153], v158 offset:1024
	ds_read_b128 v[154:157], v158 offset:2048
	ds_read_b128 v[158:161], v158 offset:3072
	s_add_u32 s66, s66, 0x80000
	s_addc_u32 s67, s67, 0
	s_mov_b32 m0, s13
	v_lshl_add_u64 v[246:247], s[66:67], 0, v[162:163]
	ds_read_b128 v[186:189], v214 offset:32768
	ds_read_b128 v[190:193], v214 offset:33792
	ds_read_b128 v[216:219], v214 offset:34816
	ds_read_b128 v[220:223], v214 offset:35840
	ds_read_b128 v[224:227], v214 offset:36864
	ds_read_b128 v[228:231], v214 offset:37888
	ds_read_b128 v[232:235], v214 offset:38912
	ds_read_b128 v[236:239], v214 offset:39936
	global_load_lds_dwordx4 v[246:247], off
	v_lshl_add_u64 v[246:247], s[66:67], 0, v[166:167]
	s_mov_b32 m0, s16
	s_nop 0
	global_load_lds_dwordx4 v[246:247], off
	s_waitcnt vmcnt(8)
	s_waitcnt lgkmcnt(0)
	s_barrier
	s_setprio 1
	s_waitcnt lgkmcnt(0)
	v_mfma_i32_16x16x64_i8 v[70:73], v[82:85], v[186:189], v[70:73]
	v_mfma_i32_16x16x64_i8 v[70:73], v[86:89], v[190:193], v[70:73]
	v_mfma_i32_16x16x64_i8 v[66:69], v[142:145], v[190:193], v[66:69]
	v_mfma_i32_16x16x64_i8 v[66:69], v[138:141], v[186:189], v[66:69]
	v_mfma_i32_16x16x64_i8 v[122:125], v[138:141], v[216:219], v[122:125]
	v_mfma_i32_16x16x64_i8 v[122:125], v[142:145], v[220:223], v[122:125]
	v_mfma_i32_16x16x64_i8 v[126:129], v[86:89], v[220:223], v[126:129]
	v_mfma_i32_16x16x64_i8 v[126:129], v[82:85], v[216:219], v[126:129]
	v_mfma_i32_16x16x64_i8 v[110:113], v[82:85], v[224:227], v[110:113]
	v_mfma_i32_16x16x64_i8 v[110:113], v[86:89], v[228:231], v[110:113]
	v_mfma_i32_16x16x64_i8 v[106:109], v[142:145], v[228:231], v[106:109]
	v_mfma_i32_16x16x64_i8 v[106:109], v[138:141], v[224:227], v[106:109]
	v_mfma_i32_16x16x64_i8 v[90:93], v[138:141], v[232:235], v[90:93]
	v_mfma_i32_16x16x64_i8 v[90:93], v[142:145], v[236:239], v[90:93]
	v_mfma_i32_16x16x64_i8 v[94:97], v[86:89], v[236:239], v[94:97]
	v_mfma_i32_16x16x64_i8 v[94:97], v[82:85], v[232:235], v[94:97]
	s_setprio 0
	s_setprio 1
	v_mfma_i32_16x16x64_i8 v[78:81], v[146:149], v[232:235], v[78:81]
	v_mfma_i32_16x16x64_i8 v[78:81], v[150:153], v[236:239], v[78:81]
	v_mfma_i32_16x16x64_i8 v[74:77], v[158:161], v[236:239], v[74:77]
	v_mfma_i32_16x16x64_i8 v[74:77], v[154:157], v[232:235], v[74:77]
	v_mfma_i32_16x16x64_i8 v[98:101], v[154:157], v[224:227], v[98:101]
	v_mfma_i32_16x16x64_i8 v[98:101], v[158:161], v[228:231], v[98:101]
	v_mfma_i32_16x16x64_i8 v[102:105], v[150:153], v[228:231], v[102:105]
	v_mfma_i32_16x16x64_i8 v[102:105], v[146:149], v[224:227], v[102:105]
	v_mfma_i32_16x16x64_i8 v[118:121], v[146:149], v[216:219], v[118:121]
	v_mfma_i32_16x16x64_i8 v[118:121], v[150:153], v[220:223], v[118:121]
	v_mfma_i32_16x16x64_i8 v[114:117], v[158:161], v[220:223], v[114:117]
	v_mfma_i32_16x16x64_i8 v[114:117], v[154:157], v[216:219], v[114:117]
	v_mfma_i32_16x16x64_i8 v[130:133], v[154:157], v[186:189], v[130:133]
	v_mfma_i32_16x16x64_i8 v[130:133], v[158:161], v[190:193], v[130:133]
	v_mfma_i32_16x16x64_i8 v[134:137], v[150:153], v[190:193], v[134:137]
	v_mfma_i32_16x16x64_i8 v[134:137], v[146:149], v[186:189], v[134:137]
	s_setprio 0
	s_barrier
; #define PG8_STAGE(bufoff, gbase, voff) do { _Pragma("unroll") for (int _i = 0; _i < 2; ++_i) \
;         __builtin_amdgcn_global_load_lds((const unsigned*)((const char*)(gbase) + (voff)[_i]), (PG8_LAS unsigned*)(lds + (bufoff) + ldsw + _i * 8192), 16, 0, 0); } while (0)
; #define PG8_LDA(dst, b, h) do { _Pragma("unroll") for (int m = 0; m < 4; ++m) _Pragma("unroll") for (int k = 0; k < 2; ++k) dst[m][k] = *(const PG8_LAS bf16x8*)(lds + PG8_SA(b, h) + aoff + m * 2048 + k * 1024); } while (0)
; #define PG8_MMA(ai, bj, At, Bt) do { __builtin_amdgcn_s_setprio(1); _Pragma("unroll") for (int m = 0; m < 4; ++m) _Pragma("unroll") for (int n = 0; n < 2; ++n) _Pragma("unroll") for (int k = 0; k < 2; ++k) \
;         acc[ai][bj][m][n] = mma16(Bt[n][k], At[m][k], acc[ai][bj][m][n]); __builtin_amdgcn_s_setprio(0); } while (0)
; #define PG8_WAIT_V(n) asm volatile("s_waitcnt vmcnt(" #n ")" ::: "memory")
; #define PG8_WAIT_L(n) asm volatile("s_waitcnt lgkmcnt(" #n ")" ::: "memory")
; #define PG8_BAR __builtin_amdgcn_s_barrier()
; #define PG8_SCHED __builtin_amdgcn_sched_barrier(0)
; template <class Epi, class Sched, bool ALIGN_EPI = false, bool SP2 = false>
; __device__ __forceinline__ void gemm_phase(PG8_LAS unsigned char* lds, const Gemm g, const Sched& S, const Epi& E) {
;     ...
;         for (int t = 0; t < nt; t += 2) {
;     ...
;             PG8_LDA(At, 1, 1); PG8_STAGE(PG8_SB(1, 0), b3, voffB); PG8_STAGE(PG8_SB(1, 1), b3 + hstepB, voffB); PG8_STAGE(PG8_SA(1, 0), a3, voffA);
;             PG8_WAIT_V(8); PG8_WAIT_L(0); PG8_BAR; PG8_MMA(1, 0, At, B0); PG8_MMA(1, 1, At, B1); PG8_BAR; PG8_SCHED;
	s_add_i32 s47, s47, s7
	v_lshl_add_u64 v[194:195], v[194:195], 0, s[50:51]
	s_mov_b32 m0, s47
	ds_read_b128 v[186:189], v214 offset:49152
	ds_read_b128 v[190:193], v214 offset:50176
	ds_read_b128 v[216:219], v214 offset:51200
	ds_read_b128 v[220:223], v214 offset:52224
	ds_read_b128 v[224:227], v214 offset:53248
	ds_read_b128 v[228:231], v214 offset:54272
	ds_read_b128 v[232:235], v214 offset:55296
	ds_read_b128 v[236:239], v214 offset:56320
	global_load_lds_dwordx4 v[194:195], off
	s_add_i32 m0, s47, 0x2000
	s_add_u32 s64, s64, 0x80080
	v_lshl_add_u64 v[194:195], v[240:241], 0, s[50:51]
	s_addc_u32 s65, s65, 0
	s_add_i32 s47, s61, s7
	global_load_lds_dwordx4 v[194:195], off
	v_lshl_add_u64 v[194:195], s[64:65], 0, v[164:165]
	s_mov_b32 m0, s47
	s_nop 0
	global_load_lds_dwordx4 v[194:195], off
	v_lshl_add_u64 v[194:195], s[64:65], 0, v[168:169]
	s_add_i32 m0, s47, 0x2000
	s_nop 0
	global_load_lds_dwordx4 v[194:195], off
	v_lshl_add_u64 v[194:195], v[242:243], 0, s[50:51]
	s_mov_b32 m0, s19
	s_nop 0
	global_load_lds_dwordx4 v[194:195], off
	v_lshl_add_u64 v[194:195], v[244:245], 0, s[50:51]
	s_mov_b32 m0, s20
	s_nop 0
	global_load_lds_dwordx4 v[194:195], off
	s_waitcnt vmcnt(8)
	s_waitcnt lgkmcnt(0)
	s_barrier
	s_setprio 1
	s_waitcnt lgkmcnt(0)
	v_mfma_i32_16x16x64_i8 v[62:65], v[82:85], v[186:189], v[62:65]
	v_mfma_i32_16x16x64_i8 v[62:65], v[86:89], v[190:193], v[62:65]
	v_mfma_i32_16x16x64_i8 v[58:61], v[142:145], v[190:193], v[58:61]
	v_mfma_i32_16x16x64_i8 v[58:61], v[138:141], v[186:189], v[58:61]
	v_mfma_i32_16x16x64_i8 v[42:45], v[138:141], v[216:219], v[42:45]
	v_mfma_i32_16x16x64_i8 v[42:45], v[142:145], v[220:223], v[42:45]
	v_mfma_i32_16x16x64_i8 v[46:49], v[86:89], v[220:223], v[46:49]
	v_mfma_i32_16x16x64_i8 v[46:49], v[82:85], v[216:219], v[46:49]
	v_mfma_i32_16x16x64_i8 v[30:33], v[82:85], v[224:227], v[30:33]
	v_mfma_i32_16x16x64_i8 v[30:33], v[86:89], v[228:231], v[30:33]
	v_mfma_i32_16x16x64_i8 v[26:29], v[142:145], v[228:231], v[26:29]
	v_mfma_i32_16x16x64_i8 v[26:29], v[138:141], v[224:227], v[26:29]
	v_mfma_i32_16x16x64_i8 v[10:13], v[138:141], v[232:235], v[10:13]
	v_mfma_i32_16x16x64_i8 v[10:13], v[142:145], v[236:239], v[10:13]
	v_mfma_i32_16x16x64_i8 v[14:17], v[86:89], v[236:239], v[14:17]
	v_mfma_i32_16x16x64_i8 v[14:17], v[82:85], v[232:235], v[14:17]
	s_setprio 0
	s_setprio 1
	v_mfma_i32_16x16x64_i8 v[6:9], v[146:149], v[232:235], v[6:9]
	v_mfma_i32_16x16x64_i8 v[6:9], v[150:153], v[236:239], v[6:9]
	v_mfma_i32_16x16x64_i8 v[2:5], v[158:161], v[236:239], v[2:5]
	v_mfma_i32_16x16x64_i8 v[2:5], v[154:157], v[232:235], v[2:5]
	v_mfma_i32_16x16x64_i8 v[18:21], v[154:157], v[224:227], v[18:21]
	v_mfma_i32_16x16x64_i8 v[18:21], v[158:161], v[228:231], v[18:21]
	v_mfma_i32_16x16x64_i8 v[22:25], v[150:153], v[228:231], v[22:25]
	v_mfma_i32_16x16x64_i8 v[22:25], v[146:149], v[224:227], v[22:25]
	v_mfma_i32_16x16x64_i8 v[38:41], v[146:149], v[216:219], v[38:41]
	v_mfma_i32_16x16x64_i8 v[38:41], v[150:153], v[220:223], v[38:41]
	v_mfma_i32_16x16x64_i8 v[34:37], v[158:161], v[220:223], v[34:37]
	v_mfma_i32_16x16x64_i8 v[34:37], v[154:157], v[216:219], v[34:37]
	v_mfma_i32_16x16x64_i8 v[50:53], v[154:157], v[186:189], v[50:53]
	v_mfma_i32_16x16x64_i8 v[50:53], v[158:161], v[190:193], v[50:53]
	v_mfma_i32_16x16x64_i8 v[54:57], v[150:153], v[190:193], v[54:57]
	v_mfma_i32_16x16x64_i8 v[54:57], v[146:149], v[186:189], v[54:57]
	s_setprio 0
	s_barrier
	s_add_i32 s46, s46, 2
	s_add_u32 s62, s62, 0x100
	s_addc_u32 s63, s63, 0
	s_add_u32 s36, s36, 0x100
	s_addc_u32 s37, s37, 0
	s_cmp_gt_u32 s46, 29
	s_cbranch_scc0 .LBB0_555
	s_and_b64 vcc, exec, s[52:53]
	s_cbranch_vccz .LBB0_558
	s_barrier

; #define PG8_STAGE(bufoff, gbase, voff) do { _Pragma("unroll") for (int _i = 0; _i < 2; ++_i) \
;         __builtin_amdgcn_global_load_lds((const unsigned*)((const char*)(gbase) + (voff)[_i]), (PG8_LAS unsigned*)(lds + (bufoff) + ldsw + _i * 8192), 16, 0, 0); } while (0)
; #define PG8_LDA(dst, b, h) do { _Pragma("unroll") for (int m = 0; m < 4; ++m) _Pragma("unroll") for (int k = 0; k < 2; ++k) dst[m][k] = *(const PG8_LAS bf16x8*)(lds + PG8_SA(b, h) + aoff + m * 2048 + k * 1024); } while (0)
; #define PG8_LDB(dst, b, h) do { _Pragma("unroll") for (int n = 0; n < 2; ++n) _Pragma("unroll") for (int k = 0; k < 2; ++k) dst[n][k] = *(const PG8_LAS bf16x8*)(lds + PG8_SB(b, h) + boff + n * 2048 + k * 1024); } while (0)
; #define PG8_MMA(ai, bj, At, Bt) do { __builtin_amdgcn_s_setprio(1); _Pragma("unroll") for (int m = 0; m < 4; ++m) _Pragma("unroll") for (int n = 0; n < 2; ++n) _Pragma("unroll") for (int k = 0; k < 2; ++k) \
;         acc[ai][bj][m][n] = mma16(Bt[n][k], At[m][k], acc[ai][bj][m][n]); __builtin_amdgcn_s_setprio(0); } while (0)
; template <class Epi, class Sched, bool ALIGN_EPI = false, bool SP2 = false>
; __device__ __forceinline__ void gemm_phase(PG8_LAS unsigned char* lds, const Gemm g, const Sched& S, const Epi& E) {
;     ...
;         const bool has_next = S.next(ui + 1, nxt);
;         const char* nA = has_next ? PG8_ABASE(nxt) : cA; const char* nB = has_next ? PG8_BBASE(nxt) : cB;
; #pragma unroll 1
;         for (int t = 0; t < nt; t += 2) {
;             const bool last = (t == nt - 2);
;             const char* a1 = cA + (size_t)(t + 1) * kstep;
;             const char* a2 = last ? nA : cA + (size_t)(t + 2) * kstep; const char* b2 = last ? nB : cB + (size_t)(t + 2) * kstep;
;             const char* a3 = a2 + kstep; const char* b3 = b2 + kstep;
;             if (last && has_next) S.a_ready(nxt);
;             if constexpr (SP2) {
;             PG8_LDB(B0, 0, 0); PG8_LDB(B1, 0, 1); PG8_SCHED; PG8_LDA(At, 0, 0); PG8_STAGE(PG8_SA(1, 1), a1 + hstepA, voffA);
;             PG8_WAIT_V(8); PG8_WAIT_L(0); PG8_BAR; PG8_MMA(0, 0, At, B0); PG8_MMA(0, 1, At, B1); PG8_BAR; PG8_SCHED;
;             PG8_LDA(At, 0, 1); PG8_STAGE(PG8_SB(0, 0), b2, voffB); PG8_STAGE(PG8_SB(0, 1), b2 + hstepB, voffB); PG8_STAGE(PG8_SA(0, 0), a2, voffA);
;             PG8_WAIT_V(8); PG8_WAIT_L(0); PG8_BAR; PG8_MMA(1, 0, At, B0); PG8_MMA(1, 1, At, B1); PG8_BAR; PG8_SCHED;
.LBB0_578:
	s_ashr_i32 s49, s48, 31
	s_lshl_b64 s[24:25], s[48:49], 21
	s_add_u32 s26, s44, s24
	s_addc_u32 s27, s45, s25
	s_ashr_i32 s24, s42, 30
	s_ashr_i32 s25, s24, 31
	s_lshl_b64 s[24:25], s[24:25], 13
	s_add_u32 s50, s26, s24
	s_addc_u32 s51, s27, s25
	s_and_b64 s[24:25], s[2:3], exec
	s_cselect_b32 s24, s51, s57
	s_cselect_b32 s25, s50, s56
	s_ashr_i32 s43, s42, 31
	s_lshl_b64 s[26:27], s[42:43], 21
	s_add_u32 s52, s62, s26
	s_addc_u32 s53, s63, s27
	s_and_b64 s[26:27], s[2:3], exec
	s_cselect_b32 s26, s53, s59
	s_cselect_b32 s27, s52, s58
	s_add_u32 s56, s56, 0x100080
	s_addc_u32 s57, s57, 0
	s_add_u32 s28, s58, 0x100
	s_addc_u32 s29, s59, 0
	s_mov_b32 s33, -2
	ds_read_b128 v[130:133], v1
	ds_read_b128 v[134:137], v1 offset:1024
	ds_read_b128 v[138:141], v1 offset:2048
	ds_read_b128 v[142:145], v1 offset:3072
	ds_read_b128 v[146:149], v214
	ds_read_b128 v[150:153], v214 offset:1024
	ds_read_b128 v[154:157], v214 offset:2048
	ds_read_b128 v[158:161], v214 offset:3072
	s_add_u32 s35, s56, 0xfff00080
	s_addc_u32 s36, s57, -1
	s_cmp_eq_u32 s33, 60
	s_cselect_b32 s61, s24, s36
	s_cselect_b32 s60, s25, s35
	s_cselect_b32 s59, s26, s29
	s_cselect_b32 s58, s27, s28
	v_lshl_add_u64 v[220:221], s[56:57], 0, v[190:191]
	s_add_i32 m0, s8, 0xc000
	ds_read_b128 v[162:165], v215
	ds_read_b128 v[166:169], v215 offset:1024
	ds_read_b128 v[170:173], v215 offset:2048
	ds_read_b128 v[174:177], v215 offset:3072
	ds_read_b128 v[198:201], v215 offset:4096
	ds_read_b128 v[202:205], v215 offset:5120
	ds_read_b128 v[206:209], v215 offset:6144
	ds_read_b128 v[216:219], v215 offset:7168
	global_load_lds_dwordx4 v[220:221], off
	v_lshl_add_u64 v[220:221], s[56:57], 0, v[192:193]
	s_add_i32 m0, s8, 0xe000
	s_nop 0
	global_load_lds_dwordx4 v[220:221], off
	s_waitcnt vmcnt(8)
	s_waitcnt lgkmcnt(0)
	s_barrier
	s_setprio 1
	s_waitcnt lgkmcnt(0)
	v_mfma_f32_16x16x32_bf16 v[126:129], v[130:133], v[162:165], 0
	v_mfma_f32_16x16x32_bf16 v[126:129], v[134:137], v[166:169], v[126:129]
	v_mfma_f32_16x16x32_bf16 v[122:125], v[142:145], v[166:169], 0
	v_mfma_f32_16x16x32_bf16 v[122:125], v[138:141], v[162:165], v[122:125]
	v_mfma_f32_16x16x32_bf16 v[106:109], v[138:141], v[170:173], 0
	v_mfma_f32_16x16x32_bf16 v[106:109], v[142:145], v[174:177], v[106:109]
	v_mfma_f32_16x16x32_bf16 v[110:113], v[134:137], v[174:177], 0
	v_mfma_f32_16x16x32_bf16 v[110:113], v[130:133], v[170:173], v[110:113]
	v_mfma_f32_16x16x32_bf16 v[94:97], v[130:133], v[198:201], 0
	v_mfma_f32_16x16x32_bf16 v[94:97], v[134:137], v[202:205], v[94:97]
	v_mfma_f32_16x16x32_bf16 v[90:93], v[142:145], v[202:205], 0
	v_mfma_f32_16x16x32_bf16 v[90:93], v[138:141], v[198:201], v[90:93]
	v_mfma_f32_16x16x32_bf16 v[74:77], v[138:141], v[206:209], 0
	v_mfma_f32_16x16x32_bf16 v[74:77], v[142:145], v[216:219], v[74:77]
	v_mfma_f32_16x16x32_bf16 v[78:81], v[134:137], v[216:219], 0
	v_mfma_f32_16x16x32_bf16 v[78:81], v[130:133], v[206:209], v[78:81]
	s_setprio 0
	s_setprio 1
	v_mfma_f32_16x16x32_bf16 v[70:73], v[146:149], v[206:209], 0
	v_mfma_f32_16x16x32_bf16 v[70:73], v[150:153], v[216:219], v[70:73]
	v_mfma_f32_16x16x32_bf16 v[66:69], v[158:161], v[216:219], 0
	v_mfma_f32_16x16x32_bf16 v[66:69], v[154:157], v[206:209], v[66:69]
	v_mfma_f32_16x16x32_bf16 v[82:85], v[154:157], v[198:201], 0
	v_mfma_f32_16x16x32_bf16 v[82:85], v[158:161], v[202:205], v[82:85]
	v_mfma_f32_16x16x32_bf16 v[86:89], v[150:153], v[202:205], 0
	v_mfma_f32_16x16x32_bf16 v[86:89], v[146:149], v[198:201], v[86:89]
	v_mfma_f32_16x16x32_bf16 v[102:105], v[146:149], v[170:173], 0
	v_mfma_f32_16x16x32_bf16 v[102:105], v[150:153], v[174:177], v[102:105]
	v_mfma_f32_16x16x32_bf16 v[98:101], v[158:161], v[174:177], 0
	v_mfma_f32_16x16x32_bf16 v[98:101], v[154:157], v[170:173], v[98:101]
	v_mfma_f32_16x16x32_bf16 v[114:117], v[154:157], v[162:165], 0
	v_mfma_f32_16x16x32_bf16 v[114:117], v[158:161], v[166:169], v[114:117]
	v_mfma_f32_16x16x32_bf16 v[118:121], v[150:153], v[166:169], 0
	v_mfma_f32_16x16x32_bf16 v[118:121], v[146:149], v[162:165], v[118:121]
	s_setprio 0
	s_barrier
	s_add_i32 s35, s21, s7
	v_lshl_add_u64 v[220:221], s[58:59], 0, v[184:185]
	s_mov_b32 m0, s35
	ds_read_b128 v[162:165], v215 offset:16384
	ds_read_b128 v[166:169], v215 offset:17408
	ds_read_b128 v[170:173], v215 offset:18432
	ds_read_b128 v[174:177], v215 offset:19456
	ds_read_b128 v[198:201], v215 offset:20480
	ds_read_b128 v[202:205], v215 offset:21504
	ds_read_b128 v[206:209], v215 offset:22528
	ds_read_b128 v[216:219], v215 offset:23552
	global_load_lds_dwordx4 v[220:221], off
	s_add_i32 m0, s35, 0x2000
	s_add_u32 s36, s58, 0x100000
	v_lshl_add_u64 v[222:223], s[58:59], 0, v[188:189]
	s_addc_u32 s37, s59, 0
	s_add_i32 s35, s22, s7
	global_load_lds_dwordx4 v[222:223], off
	v_lshl_add_u64 v[224:225], s[36:37], 0, v[184:185]
	s_mov_b32 m0, s35
	v_lshl_add_u64 v[226:227], s[60:61], 0, v[186:187]
	global_load_lds_dwordx4 v[224:225], off
	v_lshl_add_u64 v[224:225], s[36:37], 0, v[188:189]
	s_add_i32 m0, s35, 0x2000
	s_nop 0
	global_load_lds_dwordx4 v[224:225], off
	v_lshl_add_u64 v[224:225], s[60:61], 0, v[182:183]
	s_mov_b32 m0, s8
	s_nop 0
	global_load_lds_dwordx4 v[224:225], off
	s_mov_b32 m0, s11
	s_nop 0
	global_load_lds_dwordx4 v[226:227], off
	s_waitcnt vmcnt(8)
	s_waitcnt lgkmcnt(0)
	s_barrier
; #define PG8_STAGE(bufoff, gbase, voff) do { _Pragma("unroll") for (int _i = 0; _i < 2; ++_i) \
;         __builtin_amdgcn_global_load_lds((const unsigned*)((const char*)(gbase) + (voff)[_i]), (PG8_LAS unsigned*)(lds + (bufoff) + ldsw + _i * 8192), 16, 0, 0); } while (0)
; #define PG8_LDA(dst, b, h) do { _Pragma("unroll") for (int m = 0; m < 4; ++m) _Pragma("unroll") for (int k = 0; k < 2; ++k) dst[m][k] = *(const PG8_LAS bf16x8*)(lds + PG8_SA(b, h) + aoff + m * 2048 + k * 1024); } while (0)
; #define PG8_LDB(dst, b, h) do { _Pragma("unroll") for (int n = 0; n < 2; ++n) _Pragma("unroll") for (int k = 0; k < 2; ++k) dst[n][k] = *(const PG8_LAS bf16x8*)(lds + PG8_SB(b, h) + boff + n * 2048 + k * 1024); } while (0)
; #define PG8_MMA(ai, bj, At, Bt) do { __builtin_amdgcn_s_setprio(1); _Pragma("unroll") for (int m = 0; m < 4; ++m) _Pragma("unroll") for (int n = 0; n < 2; ++n) _Pragma("unroll") for (int k = 0; k < 2; ++k) \
;         acc[ai][bj][m][n] = mma16(Bt[n][k], At[m][k], acc[ai][bj][m][n]); __builtin_amdgcn_s_setprio(0); } while (0)
; #define PG8_WAIT_V(n) asm volatile("s_waitcnt vmcnt(" #n ")" ::: "memory")
; #define PG8_WAIT_L(n) asm volatile("s_waitcnt lgkmcnt(" #n ")" ::: "memory")
; #define PG8_BAR __builtin_amdgcn_s_barrier()
; #define PG8_SCHED __builtin_amdgcn_sched_barrier(0)
; template <class Epi, class Sched, bool ALIGN_EPI = false, bool SP2 = false>
; __device__ __forceinline__ void gemm_phase(PG8_LAS unsigned char* lds, const Gemm g, const Sched& S, const Epi& E) {
;     ...
;             PG8_WAIT_V(8); PG8_WAIT_L(0); PG8_BAR; PG8_MMA(1, 0, At, B0); PG8_MMA(1, 1, At, B1); PG8_BAR; PG8_SCHED;
;             PG8_LDB(B0, 1, 0); PG8_LDB(B1, 1, 1); PG8_SCHED; PG8_LDA(At, 1, 0); PG8_STAGE(PG8_SA(0, 1), a2 + hstepA, voffA);
;             PG8_WAIT_V(8); PG8_WAIT_L(0); PG8_BAR; PG8_MMA(0, 0, At, B0); PG8_MMA(0, 1, At, B1); PG8_BAR; PG8_SCHED;
	s_setprio 1
	s_waitcnt lgkmcnt(0)
	v_mfma_f32_16x16x32_bf16 v[62:65], v[130:133], v[162:165], 0
	v_mfma_f32_16x16x32_bf16 v[62:65], v[134:137], v[166:169], v[62:65]
	v_mfma_f32_16x16x32_bf16 v[58:61], v[142:145], v[166:169], 0
	v_mfma_f32_16x16x32_bf16 v[58:61], v[138:141], v[162:165], v[58:61]
	v_mfma_f32_16x16x32_bf16 v[42:45], v[138:141], v[170:173], 0
	v_mfma_f32_16x16x32_bf16 v[42:45], v[142:145], v[174:177], v[42:45]
	v_mfma_f32_16x16x32_bf16 v[46:49], v[134:137], v[174:177], 0
	v_mfma_f32_16x16x32_bf16 v[46:49], v[130:133], v[170:173], v[46:49]
	v_mfma_f32_16x16x32_bf16 v[30:33], v[130:133], v[198:201], 0
	v_mfma_f32_16x16x32_bf16 v[30:33], v[134:137], v[202:205], v[30:33]
	v_mfma_f32_16x16x32_bf16 v[26:29], v[142:145], v[202:205], 0
	v_mfma_f32_16x16x32_bf16 v[26:29], v[138:141], v[198:201], v[26:29]
	v_mfma_f32_16x16x32_bf16 v[10:13], v[138:141], v[206:209], 0
	v_mfma_f32_16x16x32_bf16 v[10:13], v[142:145], v[216:219], v[10:13]
	v_mfma_f32_16x16x32_bf16 v[14:17], v[134:137], v[216:219], 0
	v_mfma_f32_16x16x32_bf16 v[14:17], v[130:133], v[206:209], v[14:17]
	s_setprio 0
	s_setprio 1
	v_mfma_f32_16x16x32_bf16 v[6:9], v[146:149], v[206:209], 0
	v_mfma_f32_16x16x32_bf16 v[6:9], v[150:153], v[216:219], v[6:9]
	v_mfma_f32_16x16x32_bf16 v[2:5], v[158:161], v[216:219], 0
	v_mfma_f32_16x16x32_bf16 v[2:5], v[154:157], v[206:209], v[2:5]
	v_mfma_f32_16x16x32_bf16 v[18:21], v[154:157], v[198:201], 0
	v_mfma_f32_16x16x32_bf16 v[18:21], v[158:161], v[202:205], v[18:21]
	v_mfma_f32_16x16x32_bf16 v[22:25], v[150:153], v[202:205], 0
	v_mfma_f32_16x16x32_bf16 v[22:25], v[146:149], v[198:201], v[22:25]
	v_mfma_f32_16x16x32_bf16 v[38:41], v[146:149], v[170:173], 0
	v_mfma_f32_16x16x32_bf16 v[38:41], v[150:153], v[174:177], v[38:41]
	v_mfma_f32_16x16x32_bf16 v[34:37], v[158:161], v[174:177], 0
	v_mfma_f32_16x16x32_bf16 v[34:37], v[154:157], v[170:173], v[34:37]
	v_mfma_f32_16x16x32_bf16 v[50:53], v[154:157], v[162:165], 0
	v_mfma_f32_16x16x32_bf16 v[50:53], v[158:161], v[166:169], v[50:53]
	v_mfma_f32_16x16x32_bf16 v[54:57], v[150:153], v[166:169], 0
	v_mfma_f32_16x16x32_bf16 v[54:57], v[146:149], v[162:165], v[54:57]
	s_setprio 0
	s_barrier
	s_add_i32 s35, 0, 0x18000
	s_add_i32 s43, 0, 0x1c000
	v_add_u32_e32 v142, s35, v212
	v_add_u32_e32 v158, s43, v212
	ds_read_b128 v[130:133], v142
	ds_read_b128 v[134:137], v142 offset:1024
	ds_read_b128 v[138:141], v142 offset:2048
	ds_read_b128 v[142:145], v142 offset:3072
	ds_read_b128 v[146:149], v158
	ds_read_b128 v[150:153], v158 offset:1024
	ds_read_b128 v[154:157], v158 offset:2048
	ds_read_b128 v[158:161], v158 offset:3072
	s_add_u32 s36, s60, 0x100000
	s_addc_u32 s37, s61, 0
	s_mov_b32 m0, s12
	v_lshl_add_u64 v[228:229], s[36:37], 0, v[182:183]
	ds_read_b128 v[162:165], v215 offset:32768
	ds_read_b128 v[166:169], v215 offset:33792
	ds_read_b128 v[170:173], v215 offset:34816
	ds_read_b128 v[174:177], v215 offset:35840
	ds_read_b128 v[198:201], v215 offset:36864
	ds_read_b128 v[202:205], v215 offset:37888
	ds_read_b128 v[206:209], v215 offset:38912
	ds_read_b128 v[216:219], v215 offset:39936
	global_load_lds_dwordx4 v[228:229], off
	v_lshl_add_u64 v[228:229], s[36:37], 0, v[186:187]
	s_mov_b32 m0, s13
	s_nop 0
	global_load_lds_dwordx4 v[228:229], off
	s_waitcnt vmcnt(8)
	s_waitcnt lgkmcnt(0)
	s_barrier
	s_setprio 1
	s_waitcnt lgkmcnt(0)
	v_mfma_f32_16x16x32_bf16 v[126:129], v[130:133], v[162:165], v[126:129]
	v_mfma_f32_16x16x32_bf16 v[126:129], v[134:137], v[166:169], v[126:129]
	v_mfma_f32_16x16x32_bf16 v[122:125], v[142:145], v[166:169], v[122:125]
	v_mfma_f32_16x16x32_bf16 v[122:125], v[138:141], v[162:165], v[122:125]
	v_mfma_f32_16x16x32_bf16 v[106:109], v[138:141], v[170:173], v[106:109]
	v_mfma_f32_16x16x32_bf16 v[106:109], v[142:145], v[174:177], v[106:109]
	v_mfma_f32_16x16x32_bf16 v[110:113], v[134:137], v[174:177], v[110:113]
	v_mfma_f32_16x16x32_bf16 v[110:113], v[130:133], v[170:173], v[110:113]
	v_mfma_f32_16x16x32_bf16 v[94:97], v[130:133], v[198:201], v[94:97]
	v_mfma_f32_16x16x32_bf16 v[94:97], v[134:137], v[202:205], v[94:97]
	v_mfma_f32_16x16x32_bf16 v[90:93], v[142:145], v[202:205], v[90:93]
	v_mfma_f32_16x16x32_bf16 v[90:93], v[138:141], v[198:201], v[90:93]
	v_mfma_f32_16x16x32_bf16 v[74:77], v[138:141], v[206:209], v[74:77]
	v_mfma_f32_16x16x32_bf16 v[74:77], v[142:145], v[216:219], v[74:77]
	v_mfma_f32_16x16x32_bf16 v[78:81], v[134:137], v[216:219], v[78:81]
	v_mfma_f32_16x16x32_bf16 v[78:81], v[130:133], v[206:209], v[78:81]
	s_setprio 0
	s_setprio 1
	v_mfma_f32_16x16x32_bf16 v[70:73], v[146:149], v[206:209], v[70:73]
	v_mfma_f32_16x16x32_bf16 v[70:73], v[150:153], v[216:219], v[70:73]
	v_mfma_f32_16x16x32_bf16 v[66:69], v[158:161], v[216:219], v[66:69]
	v_mfma_f32_16x16x32_bf16 v[66:69], v[154:157], v[206:209], v[66:69]
	v_mfma_f32_16x16x32_bf16 v[82:85], v[154:157], v[198:201], v[82:85]
	v_mfma_f32_16x16x32_bf16 v[82:85], v[158:161], v[202:205], v[82:85]
	v_mfma_f32_16x16x32_bf16 v[86:89], v[150:153], v[202:205], v[86:89]
	v_mfma_f32_16x16x32_bf16 v[86:89], v[146:149], v[198:201], v[86:89]
	v_mfma_f32_16x16x32_bf16 v[102:105], v[146:149], v[170:173], v[102:105]
	v_mfma_f32_16x16x32_bf16 v[102:105], v[150:153], v[174:177], v[102:105]
	v_mfma_f32_16x16x32_bf16 v[98:101], v[158:161], v[174:177], v[98:101]
	v_mfma_f32_16x16x32_bf16 v[98:101], v[154:157], v[170:173], v[98:101]
	v_mfma_f32_16x16x32_bf16 v[114:117], v[154:157], v[162:165], v[114:117]
	v_mfma_f32_16x16x32_bf16 v[114:117], v[158:161], v[166:169], v[114:117]
	v_mfma_f32_16x16x32_bf16 v[118:121], v[150:153], v[166:169], v[118:121]
	v_mfma_f32_16x16x32_bf16 v[118:121], v[146:149], v[162:165], v[118:121]
	s_setprio 0
	s_barrier
; #define PG8_STAGE(bufoff, gbase, voff) do { _Pragma("unroll") for (int _i = 0; _i < 2; ++_i) \
;         __builtin_amdgcn_global_load_lds((const unsigned*)((const char*)(gbase) + (voff)[_i]), (PG8_LAS unsigned*)(lds + (bufoff) + ldsw + _i * 8192), 16, 0, 0); } while (0)
; #define PG8_LDA(dst, b, h) do { _Pragma("unroll") for (int m = 0; m < 4; ++m) _Pragma("unroll") for (int k = 0; k < 2; ++k) dst[m][k] = *(const PG8_LAS bf16x8*)(lds + PG8_SA(b, h) + aoff + m * 2048 + k * 1024); } while (0)
; #define PG8_LDB(dst, b, h) do { _Pragma("unroll") for (int n = 0; n < 2; ++n) _Pragma("unroll") for (int k = 0; k < 2; ++k) dst[n][k] = *(const PG8_LAS bf16x8*)(lds + PG8_SB(b, h) + boff + n * 2048 + k * 1024); } while (0)
; #define PG8_MMA(ai, bj, At, Bt) do { __builtin_amdgcn_s_setprio(1); _Pragma("unroll") for (int m = 0; m < 4; ++m) _Pragma("unroll") for (int n = 0; n < 2; ++n) _Pragma("unroll") for (int k = 0; k < 2; ++k) \
;         acc[ai][bj][m][n] = mma16(Bt[n][k], At[m][k], acc[ai][bj][m][n]); __builtin_amdgcn_s_setprio(0); } while (0)
; #define PG8_WAIT_V(n) asm volatile("s_waitcnt vmcnt(" #n ")" ::: "memory")
; template <class Epi, class Sched, bool ALIGN_EPI = false, bool SP2 = false>
; __device__ __forceinline__ void gemm_phase(PG8_LAS unsigned char* lds, const Gemm g, const Sched& S, const Epi& E) {
;     ...
;         for (int t = 0; t < nt; t += 2) {
;     ...
;             PG8_LDB(B0, 0, 0); PG8_LDB(B1, 0, 1); PG8_SCHED; PG8_LDA(At, 0, 0); PG8_STAGE(PG8_SA(1, 1), a1 + hstepA, voffA);
;             PG8_WAIT_V(8); PG8_WAIT_L(0); PG8_BAR; PG8_MMA(0, 0, At, B0); PG8_MMA(0, 1, At, B1); PG8_BAR; PG8_SCHED;
;             PG8_LDA(At, 0, 1); PG8_STAGE(PG8_SB(0, 0), b2, voffB); PG8_STAGE(PG8_SB(0, 1), b2 + hstepB, voffB); PG8_STAGE(PG8_SA(0, 0), a2, voffA);
;             PG8_WAIT_V(8); PG8_WAIT_L(0); PG8_BAR; PG8_MMA(1, 0, At, B0); PG8_MMA(1, 1, At, B1); PG8_BAR; PG8_SCHED;
;             PG8_LDB(B0, 1, 0); PG8_LDB(B1, 1, 1); PG8_SCHED; PG8_LDA(At, 1, 0); PG8_STAGE(PG8_SA(0, 1), a2 + hstepA, voffA);
;             PG8_WAIT_V(8); PG8_WAIT_L(0); PG8_BAR; PG8_MMA(0, 0, At, B0); PG8_MMA(0, 1, At, B1); PG8_BAR; PG8_SCHED;
;             PG8_LDA(At, 1, 1); PG8_STAGE(PG8_SB(1, 0), b3, voffB); PG8_STAGE(PG8_SB(1, 1), b3 + hstepB, voffB); PG8_STAGE(PG8_SA(1, 0), a3, voffA);
;             PG8_WAIT_V(8); PG8_WAIT_L(0); PG8_BAR; PG8_MMA(1, 0, At, B0); PG8_MMA(1, 1, At, B1); PG8_BAR; PG8_SCHED;
	s_add_i32 s35, s35, s7
	v_lshl_add_u64 v[220:221], v[220:221], 0, s[38:39]
	s_mov_b32 m0, s35
	ds_read_b128 v[162:165], v215 offset:49152
	ds_read_b128 v[166:169], v215 offset:50176
	ds_read_b128 v[170:173], v215 offset:51200
	ds_read_b128 v[174:177], v215 offset:52224
	ds_read_b128 v[198:201], v215 offset:53248
	ds_read_b128 v[202:205], v215 offset:54272
	ds_read_b128 v[206:209], v215 offset:55296
	ds_read_b128 v[216:219], v215 offset:56320
	global_load_lds_dwordx4 v[220:221], off
	s_add_i32 m0, s35, 0x2000
	s_add_u32 s36, s58, 0x100080
	v_lshl_add_u64 v[220:221], v[222:223], 0, s[38:39]
	s_addc_u32 s37, s59, 0
	s_add_i32 s35, s43, s7
	global_load_lds_dwordx4 v[220:221], off
	v_lshl_add_u64 v[220:221], s[36:37], 0, v[184:185]
	s_mov_b32 m0, s35
	s_nop 0
	global_load_lds_dwordx4 v[220:221], off
	v_lshl_add_u64 v[220:221], s[36:37], 0, v[188:189]
	s_add_i32 m0, s35, 0x2000
	s_nop 0
	global_load_lds_dwordx4 v[220:221], off
	v_lshl_add_u64 v[220:221], v[224:225], 0, s[38:39]
	s_mov_b32 m0, s17
	s_nop 0
	global_load_lds_dwordx4 v[220:221], off
	v_lshl_add_u64 v[220:221], v[226:227], 0, s[38:39]
	s_mov_b32 m0, s18
	s_nop 0
	global_load_lds_dwordx4 v[220:221], off
	s_waitcnt vmcnt(8)
	s_waitcnt lgkmcnt(0)
	s_barrier
	s_setprio 1
	s_waitcnt lgkmcnt(0)
	v_mfma_f32_16x16x32_bf16 v[62:65], v[130:133], v[162:165], v[62:65]
	v_mfma_f32_16x16x32_bf16 v[62:65], v[134:137], v[166:169], v[62:65]
	v_mfma_f32_16x16x32_bf16 v[58:61], v[142:145], v[166:169], v[58:61]
	v_mfma_f32_16x16x32_bf16 v[58:61], v[138:141], v[162:165], v[58:61]
	v_mfma_f32_16x16x32_bf16 v[42:45], v[138:141], v[170:173], v[42:45]
	v_mfma_f32_16x16x32_bf16 v[42:45], v[142:145], v[174:177], v[42:45]
	v_mfma_f32_16x16x32_bf16 v[46:49], v[134:137], v[174:177], v[46:49]
	v_mfma_f32_16x16x32_bf16 v[46:49], v[130:133], v[170:173], v[46:49]
	v_mfma_f32_16x16x32_bf16 v[30:33], v[130:133], v[198:201], v[30:33]
	v_mfma_f32_16x16x32_bf16 v[30:33], v[134:137], v[202:205], v[30:33]
	v_mfma_f32_16x16x32_bf16 v[26:29], v[142:145], v[202:205], v[26:29]
	v_mfma_f32_16x16x32_bf16 v[26:29], v[138:141], v[198:201], v[26:29]
	v_mfma_f32_16x16x32_bf16 v[10:13], v[138:141], v[206:209], v[10:13]
	v_mfma_f32_16x16x32_bf16 v[10:13], v[142:145], v[216:219], v[10:13]
	v_mfma_f32_16x16x32_bf16 v[14:17], v[134:137], v[216:219], v[14:17]
	v_mfma_f32_16x16x32_bf16 v[14:17], v[130:133], v[206:209], v[14:17]
	s_setprio 0
	s_setprio 1
	v_mfma_f32_16x16x32_bf16 v[6:9], v[146:149], v[206:209], v[6:9]
	v_mfma_f32_16x16x32_bf16 v[6:9], v[150:153], v[216:219], v[6:9]
	v_mfma_f32_16x16x32_bf16 v[2:5], v[158:161], v[216:219], v[2:5]
	v_mfma_f32_16x16x32_bf16 v[2:5], v[154:157], v[206:209], v[2:5]
	v_mfma_f32_16x16x32_bf16 v[18:21], v[154:157], v[198:201], v[18:21]
	v_mfma_f32_16x16x32_bf16 v[18:21], v[158:161], v[202:205], v[18:21]
	v_mfma_f32_16x16x32_bf16 v[22:25], v[150:153], v[202:205], v[22:25]
	v_mfma_f32_16x16x32_bf16 v[22:25], v[146:149], v[198:201], v[22:25]
	v_mfma_f32_16x16x32_bf16 v[38:41], v[146:149], v[170:173], v[38:41]
	v_mfma_f32_16x16x32_bf16 v[38:41], v[150:153], v[174:177], v[38:41]
	v_mfma_f32_16x16x32_bf16 v[34:37], v[158:161], v[174:177], v[34:37]
	v_mfma_f32_16x16x32_bf16 v[34:37], v[154:157], v[170:173], v[34:37]
	v_mfma_f32_16x16x32_bf16 v[50:53], v[154:157], v[162:165], v[50:53]
	v_mfma_f32_16x16x32_bf16 v[50:53], v[158:161], v[166:169], v[50:53]
	v_mfma_f32_16x16x32_bf16 v[54:57], v[150:153], v[166:169], v[54:57]
	v_mfma_f32_16x16x32_bf16 v[54:57], v[146:149], v[162:165], v[54:57]
	s_setprio 0
	s_barrier
	s_add_i32 s33, s33, 2
	s_add_u32 s56, s56, 0x100
	s_addc_u32 s57, s57, 0
	s_add_u32 s28, s28, 0x100
	s_addc_u32 s29, s29, 0
.LBB0_579:
	ds_read_b128 v[130:133], v1
	ds_read_b128 v[134:137], v1 offset:1024
	ds_read_b128 v[138:141], v1 offset:2048
	ds_read_b128 v[142:145], v1 offset:3072
	ds_read_b128 v[146:149], v214
	ds_read_b128 v[150:153], v214 offset:1024
	ds_read_b128 v[154:157], v214 offset:2048
	ds_read_b128 v[158:161], v214 offset:3072
	s_add_u32 s35, s56, 0xfff00080
	s_addc_u32 s36, s57, -1
	s_cmp_eq_u32 s33, 60
	s_cselect_b32 s61, s24, s36
	s_cselect_b32 s60, s25, s35
	s_cselect_b32 s59, s26, s29
	s_cselect_b32 s58, s27, s28
	v_lshl_add_u64 v[220:221], s[56:57], 0, v[190:191]
	s_add_i32 m0, s8, 0xc000
	ds_read_b128 v[162:165], v215
	ds_read_b128 v[166:169], v215 offset:1024
	ds_read_b128 v[170:173], v215 offset:2048
	ds_read_b128 v[174:177], v215 offset:3072
	ds_read_b128 v[198:201], v215 offset:4096
	ds_read_b128 v[202:205], v215 offset:5120
	ds_read_b128 v[206:209], v215 offset:6144
	ds_read_b128 v[216:219], v215 offset:7168
	global_load_lds_dwordx4 v[220:221], off
	v_lshl_add_u64 v[220:221], s[56:57], 0, v[192:193]
	s_add_i32 m0, s8, 0xe000
	s_nop 0
	global_load_lds_dwordx4 v[220:221], off
	s_waitcnt vmcnt(8)
	s_waitcnt lgkmcnt(0)
	s_barrier
; #define PG8_STAGE(bufoff, gbase, voff) do { _Pragma("unroll") for (int _i = 0; _i < 2; ++_i) \
;         __builtin_amdgcn_global_load_lds((const unsigned*)((const char*)(gbase) + (voff)[_i]), (PG8_LAS unsigned*)(lds + (bufoff) + ldsw + _i * 8192), 16, 0, 0); } while (0)
; #define PG8_LDA(dst, b, h) do { _Pragma("unroll") for (int m = 0; m < 4; ++m) _Pragma("unroll") for (int k = 0; k < 2; ++k) dst[m][k] = *(const PG8_LAS bf16x8*)(lds + PG8_SA(b, h) + aoff + m * 2048 + k * 1024); } while (0)
; #define PG8_LDB(dst, b, h) do { _Pragma("unroll") for (int n = 0; n < 2; ++n) _Pragma("unroll") for (int k = 0; k < 2; ++k) dst[n][k] = *(const PG8_LAS bf16x8*)(lds + PG8_SB(b, h) + boff + n * 2048 + k * 1024); } while (0)
; #define PG8_MMA(ai, bj, At, Bt) do { __builtin_amdgcn_s_setprio(1); _Pragma("unroll") for (int m = 0; m < 4; ++m) _Pragma("unroll") for (int n = 0; n < 2; ++n) _Pragma("unroll") for (int k = 0; k < 2; ++k) \
;         acc[ai][bj][m][n] = mma16(Bt[n][k], At[m][k], acc[ai][bj][m][n]); __builtin_amdgcn_s_setprio(0); } while (0)
; #define PG8_WAIT_V(n) asm volatile("s_waitcnt vmcnt(" #n ")" ::: "memory")
; #define PG8_WAIT_L(n) asm volatile("s_waitcnt lgkmcnt(" #n ")" ::: "memory")
; #define PG8_BAR __builtin_amdgcn_s_barrier()
; #define PG8_SCHED __builtin_amdgcn_sched_barrier(0)
; template <class Epi, class Sched, bool ALIGN_EPI = false, bool SP2 = false>
; __device__ __forceinline__ void gemm_phase(PG8_LAS unsigned char* lds, const Gemm g, const Sched& S, const Epi& E) {
;     ...
;             PG8_WAIT_V(8); PG8_WAIT_L(0); PG8_BAR; PG8_MMA(0, 0, At, B0); PG8_MMA(0, 1, At, B1); PG8_BAR; PG8_SCHED;
;             PG8_LDA(At, 0, 1); PG8_STAGE(PG8_SB(0, 0), b2, voffB); PG8_STAGE(PG8_SB(0, 1), b2 + hstepB, voffB); PG8_STAGE(PG8_SA(0, 0), a2, voffA);
;             PG8_WAIT_V(8); PG8_WAIT_L(0); PG8_BAR; PG8_MMA(1, 0, At, B0); PG8_MMA(1, 1, At, B1); PG8_BAR; PG8_SCHED;
;             PG8_LDB(B0, 1, 0); PG8_LDB(B1, 1, 1); PG8_SCHED; PG8_LDA(At, 1, 0); PG8_STAGE(PG8_SA(0, 1), a2 + hstepA, voffA);
;             PG8_WAIT_V(8); PG8_WAIT_L(0); PG8_BAR; PG8_MMA(0, 0, At, B0); PG8_MMA(0, 1, At, B1); PG8_BAR; PG8_SCHED;
	s_setprio 1
	s_waitcnt lgkmcnt(0)
	v_mfma_f32_16x16x32_bf16 v[126:129], v[130:133], v[162:165], v[126:129]
	v_mfma_f32_16x16x32_bf16 v[126:129], v[134:137], v[166:169], v[126:129]
	v_mfma_f32_16x16x32_bf16 v[122:125], v[142:145], v[166:169], v[122:125]
	v_mfma_f32_16x16x32_bf16 v[122:125], v[138:141], v[162:165], v[122:125]
	v_mfma_f32_16x16x32_bf16 v[106:109], v[138:141], v[170:173], v[106:109]
	v_mfma_f32_16x16x32_bf16 v[106:109], v[142:145], v[174:177], v[106:109]
	v_mfma_f32_16x16x32_bf16 v[110:113], v[134:137], v[174:177], v[110:113]
	v_mfma_f32_16x16x32_bf16 v[110:113], v[130:133], v[170:173], v[110:113]
	v_mfma_f32_16x16x32_bf16 v[94:97], v[130:133], v[198:201], v[94:97]
	v_mfma_f32_16x16x32_bf16 v[94:97], v[134:137], v[202:205], v[94:97]
	v_mfma_f32_16x16x32_bf16 v[90:93], v[142:145], v[202:205], v[90:93]
	v_mfma_f32_16x16x32_bf16 v[90:93], v[138:141], v[198:201], v[90:93]
	v_mfma_f32_16x16x32_bf16 v[74:77], v[138:141], v[206:209], v[74:77]
	v_mfma_f32_16x16x32_bf16 v[74:77], v[142:145], v[216:219], v[74:77]
	v_mfma_f32_16x16x32_bf16 v[78:81], v[134:137], v[216:219], v[78:81]
	v_mfma_f32_16x16x32_bf16 v[78:81], v[130:133], v[206:209], v[78:81]
	s_setprio 0
	s_setprio 1
	v_mfma_f32_16x16x32_bf16 v[70:73], v[146:149], v[206:209], v[70:73]
	v_mfma_f32_16x16x32_bf16 v[70:73], v[150:153], v[216:219], v[70:73]
	v_mfma_f32_16x16x32_bf16 v[66:69], v[158:161], v[216:219], v[66:69]
	v_mfma_f32_16x16x32_bf16 v[66:69], v[154:157], v[206:209], v[66:69]
	v_mfma_f32_16x16x32_bf16 v[82:85], v[154:157], v[198:201], v[82:85]
	v_mfma_f32_16x16x32_bf16 v[82:85], v[158:161], v[202:205], v[82:85]
	v_mfma_f32_16x16x32_bf16 v[86:89], v[150:153], v[202:205], v[86:89]
	v_mfma_f32_16x16x32_bf16 v[86:89], v[146:149], v[198:201], v[86:89]
	v_mfma_f32_16x16x32_bf16 v[102:105], v[146:149], v[170:173], v[102:105]
	v_mfma_f32_16x16x32_bf16 v[102:105], v[150:153], v[174:177], v[102:105]
	v_mfma_f32_16x16x32_bf16 v[98:101], v[158:161], v[174:177], v[98:101]
	v_mfma_f32_16x16x32_bf16 v[98:101], v[154:157], v[170:173], v[98:101]
	v_mfma_f32_16x16x32_bf16 v[114:117], v[154:157], v[162:165], v[114:117]
	v_mfma_f32_16x16x32_bf16 v[114:117], v[158:161], v[166:169], v[114:117]
	v_mfma_f32_16x16x32_bf16 v[118:121], v[150:153], v[166:169], v[118:121]
	v_mfma_f32_16x16x32_bf16 v[118:121], v[146:149], v[162:165], v[118:121]
	s_setprio 0
	s_barrier
	s_add_i32 s35, s21, s7
	v_lshl_add_u64 v[220:221], s[58:59], 0, v[184:185]
	s_mov_b32 m0, s35
	ds_read_b128 v[162:165], v215 offset:16384
	ds_read_b128 v[166:169], v215 offset:17408
	ds_read_b128 v[170:173], v215 offset:18432
	ds_read_b128 v[174:177], v215 offset:19456
	ds_read_b128 v[198:201], v215 offset:20480
	ds_read_b128 v[202:205], v215 offset:21504
	ds_read_b128 v[206:209], v215 offset:22528
	ds_read_b128 v[216:219], v215 offset:23552
	global_load_lds_dwordx4 v[220:221], off
	s_add_i32 m0, s35, 0x2000
	s_add_u32 s36, s58, 0x100000
	v_lshl_add_u64 v[222:223], s[58:59], 0, v[188:189]
	s_addc_u32 s37, s59, 0
	s_add_i32 s35, s22, s7
	global_load_lds_dwordx4 v[222:223], off
	v_lshl_add_u64 v[224:225], s[36:37], 0, v[184:185]
	s_mov_b32 m0, s35
	v_lshl_add_u64 v[226:227], s[60:61], 0, v[186:187]
	global_load_lds_dwordx4 v[224:225], off
	v_lshl_add_u64 v[224:225], s[36:37], 0, v[188:189]
	s_add_i32 m0, s35, 0x2000
	s_nop 0
	global_load_lds_dwordx4 v[224:225], off
	v_lshl_add_u64 v[224:225], s[60:61], 0, v[182:183]
	s_mov_b32 m0, s8
	s_nop 0
	global_load_lds_dwordx4 v[224:225], off
	s_mov_b32 m0, s11
	s_nop 0
	global_load_lds_dwordx4 v[226:227], off
	s_waitcnt vmcnt(8)
	s_waitcnt lgkmcnt(0)
	s_barrier
	s_setprio 1
	s_waitcnt lgkmcnt(0)
	v_mfma_f32_16x16x32_bf16 v[62:65], v[130:133], v[162:165], v[62:65]
	v_mfma_f32_16x16x32_bf16 v[62:65], v[134:137], v[166:169], v[62:65]
	v_mfma_f32_16x16x32_bf16 v[58:61], v[142:145], v[166:169], v[58:61]
	v_mfma_f32_16x16x32_bf16 v[58:61], v[138:141], v[162:165], v[58:61]
	v_mfma_f32_16x16x32_bf16 v[42:45], v[138:141], v[170:173], v[42:45]
	v_mfma_f32_16x16x32_bf16 v[42:45], v[142:145], v[174:177], v[42:45]
	v_mfma_f32_16x16x32_bf16 v[46:49], v[134:137], v[174:177], v[46:49]
	v_mfma_f32_16x16x32_bf16 v[46:49], v[130:133], v[170:173], v[46:49]
	v_mfma_f32_16x16x32_bf16 v[30:33], v[130:133], v[198:201], v[30:33]
	v_mfma_f32_16x16x32_bf16 v[30:33], v[134:137], v[202:205], v[30:33]
	v_mfma_f32_16x16x32_bf16 v[26:29], v[142:145], v[202:205], v[26:29]
	v_mfma_f32_16x16x32_bf16 v[26:29], v[138:141], v[198:201], v[26:29]
	v_mfma_f32_16x16x32_bf16 v[10:13], v[138:141], v[206:209], v[10:13]
	v_mfma_f32_16x16x32_bf16 v[10:13], v[142:145], v[216:219], v[10:13]
	v_mfma_f32_16x16x32_bf16 v[14:17], v[134:137], v[216:219], v[14:17]
	v_mfma_f32_16x16x32_bf16 v[14:17], v[130:133], v[206:209], v[14:17]
	s_setprio 0
	s_setprio 1
	v_mfma_f32_16x16x32_bf16 v[6:9], v[146:149], v[206:209], v[6:9]
	v_mfma_f32_16x16x32_bf16 v[6:9], v[150:153], v[216:219], v[6:9]
	v_mfma_f32_16x16x32_bf16 v[2:5], v[158:161], v[216:219], v[2:5]
	v_mfma_f32_16x16x32_bf16 v[2:5], v[154:157], v[206:209], v[2:5]
	v_mfma_f32_16x16x32_bf16 v[18:21], v[154:157], v[198:201], v[18:21]
	v_mfma_f32_16x16x32_bf16 v[18:21], v[158:161], v[202:205], v[18:21]
	v_mfma_f32_16x16x32_bf16 v[22:25], v[150:153], v[202:205], v[22:25]
	v_mfma_f32_16x16x32_bf16 v[22:25], v[146:149], v[198:201], v[22:25]
	v_mfma_f32_16x16x32_bf16 v[38:41], v[146:149], v[170:173], v[38:41]
	v_mfma_f32_16x16x32_bf16 v[38:41], v[150:153], v[174:177], v[38:41]
	v_mfma_f32_16x16x32_bf16 v[34:37], v[158:161], v[174:177], v[34:37]
	v_mfma_f32_16x16x32_bf16 v[34:37], v[154:157], v[170:173], v[34:37]
	v_mfma_f32_16x16x32_bf16 v[50:53], v[154:157], v[162:165], v[50:53]
	v_mfma_f32_16x16x32_bf16 v[50:53], v[158:161], v[166:169], v[50:53]
	v_mfma_f32_16x16x32_bf16 v[54:57], v[150:153], v[166:169], v[54:57]
	v_mfma_f32_16x16x32_bf16 v[54:57], v[146:149], v[162:165], v[54:57]
	s_setprio 0
	s_barrier
; #define PG8_STAGE(bufoff, gbase, voff) do { _Pragma("unroll") for (int _i = 0; _i < 2; ++_i) \
;         __builtin_amdgcn_global_load_lds((const unsigned*)((const char*)(gbase) + (voff)[_i]), (PG8_LAS unsigned*)(lds + (bufoff) + ldsw + _i * 8192), 16, 0, 0); } while (0)
; #define PG8_LDA(dst, b, h) do { _Pragma("unroll") for (int m = 0; m < 4; ++m) _Pragma("unroll") for (int k = 0; k < 2; ++k) dst[m][k] = *(const PG8_LAS bf16x8*)(lds + PG8_SA(b, h) + aoff + m * 2048 + k * 1024); } while (0)
; #define PG8_LDB(dst, b, h) do { _Pragma("unroll") for (int n = 0; n < 2; ++n) _Pragma("unroll") for (int k = 0; k < 2; ++k) dst[n][k] = *(const PG8_LAS bf16x8*)(lds + PG8_SB(b, h) + boff + n * 2048 + k * 1024); } while (0)
; #define PG8_MMA(ai, bj, At, Bt) do { __builtin_amdgcn_s_setprio(1); _Pragma("unroll") for (int m = 0; m < 4; ++m) _Pragma("unroll") for (int n = 0; n < 2; ++n) _Pragma("unroll") for (int k = 0; k < 2; ++k) \
;         acc[ai][bj][m][n] = mma16(Bt[n][k], At[m][k], acc[ai][bj][m][n]); __builtin_amdgcn_s_setprio(0); } while (0)
; #define PG8_WAIT_V(n) asm volatile("s_waitcnt vmcnt(" #n ")" ::: "memory")
; #define PG8_WAIT_L(n) asm volatile("s_waitcnt lgkmcnt(" #n ")" ::: "memory")
; #define PG8_BAR __builtin_amdgcn_s_barrier()
; #define PG8_SCHED __builtin_amdgcn_sched_barrier(0)
; template <class Epi, class Sched, bool ALIGN_EPI = false, bool SP2 = false>
; __device__ __forceinline__ void gemm_phase(PG8_LAS unsigned char* lds, const Gemm g, const Sched& S, const Epi& E) {
;     ...
;             PG8_LDB(B0, 1, 0); PG8_LDB(B1, 1, 1); PG8_SCHED; PG8_LDA(At, 1, 0); PG8_STAGE(PG8_SA(0, 1), a2 + hstepA, voffA);
;             PG8_WAIT_V(8); PG8_WAIT_L(0); PG8_BAR; PG8_MMA(0, 0, At, B0); PG8_MMA(0, 1, At, B1); PG8_BAR; PG8_SCHED;
	s_add_i32 s35, 0, 0x18000
	s_add_i32 s43, 0, 0x1c000
	v_add_u32_e32 v142, s35, v212
	v_add_u32_e32 v158, s43, v212
	ds_read_b128 v[130:133], v142
	ds_read_b128 v[134:137], v142 offset:1024
	ds_read_b128 v[138:141], v142 offset:2048
	ds_read_b128 v[142:145], v142 offset:3072
	ds_read_b128 v[146:149], v158
	ds_read_b128 v[150:153], v158 offset:1024
	ds_read_b128 v[154:157], v158 offset:2048
	ds_read_b128 v[158:161], v158 offset:3072
	s_add_u32 s36, s60, 0x100000
	s_addc_u32 s37, s61, 0
	s_mov_b32 m0, s12
	v_lshl_add_u64 v[228:229], s[36:37], 0, v[182:183]
	ds_read_b128 v[162:165], v215 offset:32768
	ds_read_b128 v[166:169], v215 offset:33792
	ds_read_b128 v[170:173], v215 offset:34816
	ds_read_b128 v[174:177], v215 offset:35840
	ds_read_b128 v[198:201], v215 offset:36864
	ds_read_b128 v[202:205], v215 offset:37888
	ds_read_b128 v[206:209], v215 offset:38912
	ds_read_b128 v[216:219], v215 offset:39936
	global_load_lds_dwordx4 v[228:229], off
	v_lshl_add_u64 v[228:229], s[36:37], 0, v[186:187]
	s_mov_b32 m0, s13
	s_nop 0
	global_load_lds_dwordx4 v[228:229], off
	s_waitcnt vmcnt(8)
	s_waitcnt lgkmcnt(0)
	s_barrier
	s_setprio 1
	s_waitcnt lgkmcnt(0)
	v_mfma_f32_16x16x32_bf16 v[126:129], v[130:133], v[162:165], v[126:129]
	v_mfma_f32_16x16x32_bf16 v[126:129], v[134:137], v[166:169], v[126:129]
	v_mfma_f32_16x16x32_bf16 v[122:125], v[142:145], v[166:169], v[122:125]
	v_mfma_f32_16x16x32_bf16 v[122:125], v[138:141], v[162:165], v[122:125]
	v_mfma_f32_16x16x32_bf16 v[106:109], v[138:141], v[170:173], v[106:109]
	v_mfma_f32_16x16x32_bf16 v[106:109], v[142:145], v[174:177], v[106:109]
	v_mfma_f32_16x16x32_bf16 v[110:113], v[134:137], v[174:177], v[110:113]
	v_mfma_f32_16x16x32_bf16 v[110:113], v[130:133], v[170:173], v[110:113]
	v_mfma_f32_16x16x32_bf16 v[94:97], v[130:133], v[198:201], v[94:97]
	v_mfma_f32_16x16x32_bf16 v[94:97], v[134:137], v[202:205], v[94:97]
	v_mfma_f32_16x16x32_bf16 v[90:93], v[142:145], v[202:205], v[90:93]
	v_mfma_f32_16x16x32_bf16 v[90:93], v[138:141], v[198:201], v[90:93]
	v_mfma_f32_16x16x32_bf16 v[74:77], v[138:141], v[206:209], v[74:77]
	v_mfma_f32_16x16x32_bf16 v[74:77], v[142:145], v[216:219], v[74:77]
	v_mfma_f32_16x16x32_bf16 v[78:81], v[134:137], v[216:219], v[78:81]
	v_mfma_f32_16x16x32_bf16 v[78:81], v[130:133], v[206:209], v[78:81]
	s_setprio 0
	s_setprio 1
	v_mfma_f32_16x16x32_bf16 v[70:73], v[146:149], v[206:209], v[70:73]
	v_mfma_f32_16x16x32_bf16 v[70:73], v[150:153], v[216:219], v[70:73]
	v_mfma_f32_16x16x32_bf16 v[66:69], v[158:161], v[216:219], v[66:69]
	v_mfma_f32_16x16x32_bf16 v[66:69], v[154:157], v[206:209], v[66:69]
	v_mfma_f32_16x16x32_bf16 v[82:85], v[154:157], v[198:201], v[82:85]
	v_mfma_f32_16x16x32_bf16 v[82:85], v[158:161], v[202:205], v[82:85]
	v_mfma_f32_16x16x32_bf16 v[86:89], v[150:153], v[202:205], v[86:89]
	v_mfma_f32_16x16x32_bf16 v[86:89], v[146:149], v[198:201], v[86:89]
	v_mfma_f32_16x16x32_bf16 v[102:105], v[146:149], v[170:173], v[102:105]
	v_mfma_f32_16x16x32_bf16 v[102:105], v[150:153], v[174:177], v[102:105]
	v_mfma_f32_16x16x32_bf16 v[98:101], v[158:161], v[174:177], v[98:101]
	v_mfma_f32_16x16x32_bf16 v[98:101], v[154:157], v[170:173], v[98:101]
	v_mfma_f32_16x16x32_bf16 v[114:117], v[154:157], v[162:165], v[114:117]
	v_mfma_f32_16x16x32_bf16 v[114:117], v[158:161], v[166:169], v[114:117]
	v_mfma_f32_16x16x32_bf16 v[118:121], v[150:153], v[166:169], v[118:121]
	v_mfma_f32_16x16x32_bf16 v[118:121], v[146:149], v[162:165], v[118:121]
	s_setprio 0
	s_barrier
; #define PG8_STAGE(bufoff, gbase, voff) do { _Pragma("unroll") for (int _i = 0; _i < 2; ++_i) \
;         __builtin_amdgcn_global_load_lds((const unsigned*)((const char*)(gbase) + (voff)[_i]), (PG8_LAS unsigned*)(lds + (bufoff) + ldsw + _i * 8192), 16, 0, 0); } while (0)
; #define PG8_LDA(dst, b, h) do { _Pragma("unroll") for (int m = 0; m < 4; ++m) _Pragma("unroll") for (int k = 0; k < 2; ++k) dst[m][k] = *(const PG8_LAS bf16x8*)(lds + PG8_SA(b, h) + aoff + m * 2048 + k * 1024); } while (0)
; #define PG8_MMA(ai, bj, At, Bt) do { __builtin_amdgcn_s_setprio(1); _Pragma("unroll") for (int m = 0; m < 4; ++m) _Pragma("unroll") for (int n = 0; n < 2; ++n) _Pragma("unroll") for (int k = 0; k < 2; ++k) \
;         acc[ai][bj][m][n] = mma16(Bt[n][k], At[m][k], acc[ai][bj][m][n]); __builtin_amdgcn_s_setprio(0); } while (0)
; #define PG8_WAIT_V(n) asm volatile("s_waitcnt vmcnt(" #n ")" ::: "memory")
; #define PG8_WAIT_L(n) asm volatile("s_waitcnt lgkmcnt(" #n ")" ::: "memory")
; #define PG8_BAR __builtin_amdgcn_s_barrier()
; #define PG8_SCHED __builtin_amdgcn_sched_barrier(0)
; template <class Epi, class Sched, bool ALIGN_EPI = false, bool SP2 = false>
; __device__ __forceinline__ void gemm_phase(PG8_LAS unsigned char* lds, const Gemm g, const Sched& S, const Epi& E) {
;     ...
;         for (int t = 0; t < nt; t += 2) {
;     ...
;             PG8_LDA(At, 1, 1); PG8_STAGE(PG8_SB(1, 0), b3, voffB); PG8_STAGE(PG8_SB(1, 1), b3 + hstepB, voffB); PG8_STAGE(PG8_SA(1, 0), a3, voffA);
;             PG8_WAIT_V(8); PG8_WAIT_L(0); PG8_BAR; PG8_MMA(1, 0, At, B0); PG8_MMA(1, 1, At, B1); PG8_BAR; PG8_SCHED;
	s_add_i32 s35, s35, s7
	v_lshl_add_u64 v[220:221], v[220:221], 0, s[38:39]
	s_mov_b32 m0, s35
	ds_read_b128 v[162:165], v215 offset:49152
	ds_read_b128 v[166:169], v215 offset:50176
	ds_read_b128 v[170:173], v215 offset:51200
	ds_read_b128 v[174:177], v215 offset:52224
	ds_read_b128 v[198:201], v215 offset:53248
	ds_read_b128 v[202:205], v215 offset:54272
	ds_read_b128 v[206:209], v215 offset:55296
	ds_read_b128 v[216:219], v215 offset:56320
	global_load_lds_dwordx4 v[220:221], off
	s_add_i32 m0, s35, 0x2000
	s_add_u32 s36, s58, 0x100080
	v_lshl_add_u64 v[220:221], v[222:223], 0, s[38:39]
	s_addc_u32 s37, s59, 0
	s_add_i32 s35, s43, s7
	global_load_lds_dwordx4 v[220:221], off
	v_lshl_add_u64 v[220:221], s[36:37], 0, v[184:185]
	s_mov_b32 m0, s35
	s_nop 0
	global_load_lds_dwordx4 v[220:221], off
	v_lshl_add_u64 v[220:221], s[36:37], 0, v[188:189]
	s_add_i32 m0, s35, 0x2000
	s_nop 0
	global_load_lds_dwordx4 v[220:221], off
	v_lshl_add_u64 v[220:221], v[224:225], 0, s[38:39]
	s_mov_b32 m0, s17
	s_nop 0
	global_load_lds_dwordx4 v[220:221], off
	v_lshl_add_u64 v[220:221], v[226:227], 0, s[38:39]
	s_mov_b32 m0, s18
	s_nop 0
	global_load_lds_dwordx4 v[220:221], off
	s_waitcnt vmcnt(8)
	s_waitcnt lgkmcnt(0)
	s_barrier
	s_setprio 1
	s_waitcnt lgkmcnt(0)
	v_mfma_f32_16x16x32_bf16 v[62:65], v[130:133], v[162:165], v[62:65]
	v_mfma_f32_16x16x32_bf16 v[62:65], v[134:137], v[166:169], v[62:65]
	v_mfma_f32_16x16x32_bf16 v[58:61], v[142:145], v[166:169], v[58:61]
	v_mfma_f32_16x16x32_bf16 v[58:61], v[138:141], v[162:165], v[58:61]
	v_mfma_f32_16x16x32_bf16 v[42:45], v[138:141], v[170:173], v[42:45]
	v_mfma_f32_16x16x32_bf16 v[42:45], v[142:145], v[174:177], v[42:45]
	v_mfma_f32_16x16x32_bf16 v[46:49], v[134:137], v[174:177], v[46:49]
	v_mfma_f32_16x16x32_bf16 v[46:49], v[130:133], v[170:173], v[46:49]
	v_mfma_f32_16x16x32_bf16 v[30:33], v[130:133], v[198:201], v[30:33]
	v_mfma_f32_16x16x32_bf16 v[30:33], v[134:137], v[202:205], v[30:33]
	v_mfma_f32_16x16x32_bf16 v[26:29], v[142:145], v[202:205], v[26:29]
	v_mfma_f32_16x16x32_bf16 v[26:29], v[138:141], v[198:201], v[26:29]
	v_mfma_f32_16x16x32_bf16 v[10:13], v[138:141], v[206:209], v[10:13]
	v_mfma_f32_16x16x32_bf16 v[10:13], v[142:145], v[216:219], v[10:13]
	v_mfma_f32_16x16x32_bf16 v[14:17], v[134:137], v[216:219], v[14:17]
	v_mfma_f32_16x16x32_bf16 v[14:17], v[130:133], v[206:209], v[14:17]
	s_setprio 0
	s_setprio 1
	v_mfma_f32_16x16x32_bf16 v[6:9], v[146:149], v[206:209], v[6:9]
	v_mfma_f32_16x16x32_bf16 v[6:9], v[150:153], v[216:219], v[6:9]
	v_mfma_f32_16x16x32_bf16 v[2:5], v[158:161], v[216:219], v[2:5]
	v_mfma_f32_16x16x32_bf16 v[2:5], v[154:157], v[206:209], v[2:5]
	v_mfma_f32_16x16x32_bf16 v[18:21], v[154:157], v[198:201], v[18:21]
	v_mfma_f32_16x16x32_bf16 v[18:21], v[158:161], v[202:205], v[18:21]
	v_mfma_f32_16x16x32_bf16 v[22:25], v[150:153], v[202:205], v[22:25]
	v_mfma_f32_16x16x32_bf16 v[22:25], v[146:149], v[198:201], v[22:25]
	v_mfma_f32_16x16x32_bf16 v[38:41], v[146:149], v[170:173], v[38:41]
	v_mfma_f32_16x16x32_bf16 v[38:41], v[150:153], v[174:177], v[38:41]
	v_mfma_f32_16x16x32_bf16 v[34:37], v[158:161], v[174:177], v[34:37]
	v_mfma_f32_16x16x32_bf16 v[34:37], v[154:157], v[170:173], v[34:37]
	v_mfma_f32_16x16x32_bf16 v[50:53], v[154:157], v[162:165], v[50:53]
	v_mfma_f32_16x16x32_bf16 v[50:53], v[158:161], v[166:169], v[50:53]
	v_mfma_f32_16x16x32_bf16 v[54:57], v[150:153], v[166:169], v[54:57]
	v_mfma_f32_16x16x32_bf16 v[54:57], v[146:149], v[162:165], v[54:57]
	s_setprio 0
	s_barrier
	s_add_i32 s33, s33, 2
	s_add_u32 s56, s56, 0x100
	s_addc_u32 s57, s57, 0
	s_add_u32 s28, s28, 0x100
	s_addc_u32 s29, s29, 0
	s_cmp_gt_u32 s33, 61
	s_cbranch_scc0 .LBB0_579
	s_and_b64 vcc, exec, s[40:41]
	s_cbranch_vccz .LBB0_582
	s_barrier

; #define PG8_STAGE(bufoff, gbase, voff) do { _Pragma("unroll") for (int _i = 0; _i < 2; ++_i) \
;         __builtin_amdgcn_global_load_lds((const unsigned*)((const char*)(gbase) + (voff)[_i]), (PG8_LAS unsigned*)(lds + (bufoff) + ldsw + _i * 8192), 16, 0, 0); } while (0)
; #define PG8_LDA(dst, b, h) do { _Pragma("unroll") for (int m = 0; m < 4; ++m) _Pragma("unroll") for (int k = 0; k < 2; ++k) dst[m][k] = *(const PG8_LAS bf16x8*)(lds + PG8_SA(b, h) + aoff + m * 2048 + k * 1024); } while (0)
; #define PG8_LDB(dst, b, h) do { _Pragma("unroll") for (int n = 0; n < 2; ++n) _Pragma("unroll") for (int k = 0; k < 2; ++k) dst[n][k] = *(const PG8_LAS bf16x8*)(lds + PG8_SB(b, h) + boff + n * 2048 + k * 1024); } while (0)
; #define PG8_MMA(ai, bj, At, Bt) do { __builtin_amdgcn_s_setprio(1); _Pragma("unroll") for (int m = 0; m < 4; ++m) _Pragma("unroll") for (int n = 0; n < 2; ++n) _Pragma("unroll") for (int k = 0; k < 2; ++k) \
;         acc[ai][bj][m][n] = mma16(Bt[n][k], At[m][k], acc[ai][bj][m][n]); __builtin_amdgcn_s_setprio(0); } while (0)
; template <class Epi, class Sched, bool ALIGN_EPI = false, bool SP2 = false>
; __device__ __forceinline__ void gemm_phase(PG8_LAS unsigned char* lds, const Gemm g, const Sched& S, const Epi& E) {
;     ...
;         const bool has_next = S.next(ui + 1, nxt);
;         const char* nA = has_next ? PG8_ABASE(nxt) : cA; const char* nB = has_next ? PG8_BBASE(nxt) : cB;
; #pragma unroll 1
;         for (int t = 0; t < nt; t += 2) {
;             const bool last = (t == nt - 2);
;             const char* a1 = cA + (size_t)(t + 1) * kstep;
;             const char* a2 = last ? nA : cA + (size_t)(t + 2) * kstep; const char* b2 = last ? nB : cB + (size_t)(t + 2) * kstep;
;             const char* a3 = a2 + kstep; const char* b3 = b2 + kstep;
;             if (last && has_next) S.a_ready(nxt);
;             if constexpr (SP2) {
;             PG8_LDB(B0, 0, 0); PG8_LDB(B1, 0, 1); PG8_SCHED; PG8_LDA(At, 0, 0); PG8_STAGE(PG8_SA(1, 1), a1 + hstepA, voffA);
;             PG8_WAIT_V(8); PG8_WAIT_L(0); PG8_BAR; PG8_MMA(0, 0, At, B0); PG8_MMA(0, 1, At, B1); PG8_BAR; PG8_SCHED;
;             PG8_LDA(At, 0, 1); PG8_STAGE(PG8_SB(0, 0), b2, voffB); PG8_STAGE(PG8_SB(0, 1), b2 + hstepB, voffB); PG8_STAGE(PG8_SA(0, 0), a2, voffA);
;             PG8_WAIT_V(8); PG8_WAIT_L(0); PG8_BAR; PG8_MMA(1, 0, At, B0); PG8_MMA(1, 1, At, B1); PG8_BAR; PG8_SCHED;
.LBB0_659:
	s_ashr_i32 s55, s54, 31
	s_lshl_b64 s[28:29], s[54:55], 21
	s_add_u32 s60, s70, s28
	s_addc_u32 s61, s71, s29
	s_and_b64 s[0:1], s[0:1], exec
	s_cselect_b32 s27, s61, s65
	s_cselect_b32 s28, s60, s64
	s_add_u32 s0, s66, 0x100080
	s_addc_u32 s1, s67, 0
	s_add_u32 s29, s64, 0x100
	s_addc_u32 s33, s65, 0
	s_mov_b32 s35, -2
	ds_read_b128 v[154:157], v150
	ds_read_b128 v[158:161], v150 offset:1024
	ds_read_b128 v[162:165], v150 offset:2048
	ds_read_b128 v[166:169], v150 offset:3072
	ds_read_b128 v[170:173], v151
	ds_read_b128 v[174:177], v151 offset:1024
	ds_read_b128 v[182:185], v151 offset:2048
	ds_read_b128 v[186:189], v151 offset:3072
	s_add_u32 s36, s0, 0xfff00080
	s_addc_u32 s37, s1, -1
	s_cmp_eq_u32 s35, 60
	s_cselect_b32 s67, s59, s37
	s_cselect_b32 s66, s58, s36
	s_cselect_b32 s65, s27, s33
	s_cselect_b32 s64, s28, s29
	v_lshl_add_u64 v[146:147], s[0:1], 0, v[138:139]
	s_add_i32 m0, s8, 0xc000
	ds_read_b128 v[190:193], v152
	ds_read_b128 v[194:197], v152 offset:1024
	ds_read_b128 v[198:201], v152 offset:2048
	ds_read_b128 v[202:205], v152 offset:3072
	ds_read_b128 v[206:209], v152 offset:4096
	ds_read_b128 v[212:215], v152 offset:5120
	ds_read_b128 v[216:219], v152 offset:6144
	ds_read_b128 v[220:223], v152 offset:7168
	global_load_lds_dwordx4 v[146:147], off
	v_lshl_add_u64 v[146:147], s[0:1], 0, v[140:141]
	s_add_i32 m0, s8, 0xe000
	s_nop 0
	global_load_lds_dwordx4 v[146:147], off
	s_waitcnt vmcnt(8)
	s_waitcnt lgkmcnt(0)
	s_barrier
	s_setprio 1
	s_waitcnt lgkmcnt(0)
	v_mfma_f32_16x16x32_bf16 v[126:129], v[154:157], v[190:193], 0
	v_mfma_f32_16x16x32_bf16 v[126:129], v[158:161], v[194:197], v[126:129]
	v_mfma_f32_16x16x32_bf16 v[122:125], v[166:169], v[194:197], 0
	v_mfma_f32_16x16x32_bf16 v[122:125], v[162:165], v[190:193], v[122:125]
	v_mfma_f32_16x16x32_bf16 v[110:113], v[162:165], v[198:201], 0
	v_mfma_f32_16x16x32_bf16 v[110:113], v[166:169], v[202:205], v[110:113]
	v_mfma_f32_16x16x32_bf16 v[118:121], v[158:161], v[202:205], 0
	v_mfma_f32_16x16x32_bf16 v[118:121], v[154:157], v[198:201], v[118:121]
	v_mfma_f32_16x16x32_bf16 v[102:105], v[154:157], v[206:209], 0
	v_mfma_f32_16x16x32_bf16 v[102:105], v[158:161], v[212:215], v[102:105]
	v_mfma_f32_16x16x32_bf16 v[94:97], v[166:169], v[212:215], 0
	v_mfma_f32_16x16x32_bf16 v[94:97], v[162:165], v[206:209], v[94:97]
	v_mfma_f32_16x16x32_bf16 v[78:81], v[162:165], v[216:219], 0
	v_mfma_f32_16x16x32_bf16 v[78:81], v[166:169], v[220:223], v[78:81]
	v_mfma_f32_16x16x32_bf16 v[86:89], v[158:161], v[220:223], 0
	v_mfma_f32_16x16x32_bf16 v[86:89], v[154:157], v[216:219], v[86:89]
	s_setprio 0
	s_setprio 1
	v_mfma_f32_16x16x32_bf16 v[70:73], v[170:173], v[216:219], 0
	v_mfma_f32_16x16x32_bf16 v[70:73], v[174:177], v[220:223], v[70:73]
	v_mfma_f32_16x16x32_bf16 v[66:69], v[186:189], v[220:223], 0
	v_mfma_f32_16x16x32_bf16 v[66:69], v[182:185], v[216:219], v[66:69]
	v_mfma_f32_16x16x32_bf16 v[74:77], v[182:185], v[206:209], 0
	v_mfma_f32_16x16x32_bf16 v[74:77], v[186:189], v[212:215], v[74:77]
	v_mfma_f32_16x16x32_bf16 v[82:85], v[174:177], v[212:215], 0
	v_mfma_f32_16x16x32_bf16 v[82:85], v[170:173], v[206:209], v[82:85]
	v_mfma_f32_16x16x32_bf16 v[98:101], v[170:173], v[198:201], 0
	v_mfma_f32_16x16x32_bf16 v[98:101], v[174:177], v[202:205], v[98:101]
	v_mfma_f32_16x16x32_bf16 v[90:93], v[186:189], v[202:205], 0
	v_mfma_f32_16x16x32_bf16 v[90:93], v[182:185], v[198:201], v[90:93]
	v_mfma_f32_16x16x32_bf16 v[106:109], v[182:185], v[190:193], 0
	v_mfma_f32_16x16x32_bf16 v[106:109], v[186:189], v[194:197], v[106:109]
	v_mfma_f32_16x16x32_bf16 v[114:117], v[174:177], v[194:197], 0
	v_mfma_f32_16x16x32_bf16 v[114:117], v[170:173], v[190:193], v[114:117]
	s_setprio 0
	s_barrier
	s_add_i32 s36, s20, s7
	v_lshl_add_u64 v[146:147], s[64:65], 0, v[132:133]
	s_mov_b32 m0, s36
	ds_read_b128 v[190:193], v152 offset:16384
	ds_read_b128 v[194:197], v152 offset:17408
	ds_read_b128 v[198:201], v152 offset:18432
	ds_read_b128 v[202:205], v152 offset:19456
	ds_read_b128 v[206:209], v152 offset:20480
	ds_read_b128 v[212:215], v152 offset:21504
	ds_read_b128 v[216:219], v152 offset:22528
	ds_read_b128 v[220:223], v152 offset:23552
	global_load_lds_dwordx4 v[146:147], off
	s_add_i32 m0, s36, 0x2000
	s_add_u32 s36, s64, 0x100000
	v_lshl_add_u64 v[224:225], s[64:65], 0, v[136:137]
	s_addc_u32 s37, s65, 0
	s_add_i32 s46, s21, s7
	global_load_lds_dwordx4 v[224:225], off
	v_lshl_add_u64 v[226:227], s[36:37], 0, v[132:133]
	s_mov_b32 m0, s46
	v_lshl_add_u64 v[228:229], s[66:67], 0, v[134:135]
	global_load_lds_dwordx4 v[226:227], off
	v_lshl_add_u64 v[226:227], s[36:37], 0, v[136:137]
	s_add_i32 m0, s46, 0x2000
	s_nop 0
	global_load_lds_dwordx4 v[226:227], off
	v_lshl_add_u64 v[226:227], s[66:67], 0, v[130:131]
	s_mov_b32 m0, s8
	s_nop 0
	global_load_lds_dwordx4 v[226:227], off
	s_mov_b32 m0, s11
	s_nop 0
	global_load_lds_dwordx4 v[228:229], off
	s_waitcnt vmcnt(8)
	s_waitcnt lgkmcnt(0)
	s_barrier
; #define PG8_STAGE(bufoff, gbase, voff) do { _Pragma("unroll") for (int _i = 0; _i < 2; ++_i) \
;         __builtin_amdgcn_global_load_lds((const unsigned*)((const char*)(gbase) + (voff)[_i]), (PG8_LAS unsigned*)(lds + (bufoff) + ldsw + _i * 8192), 16, 0, 0); } while (0)
; #define PG8_LDA(dst, b, h) do { _Pragma("unroll") for (int m = 0; m < 4; ++m) _Pragma("unroll") for (int k = 0; k < 2; ++k) dst[m][k] = *(const PG8_LAS bf16x8*)(lds + PG8_SA(b, h) + aoff + m * 2048 + k * 1024); } while (0)
; #define PG8_LDB(dst, b, h) do { _Pragma("unroll") for (int n = 0; n < 2; ++n) _Pragma("unroll") for (int k = 0; k < 2; ++k) dst[n][k] = *(const PG8_LAS bf16x8*)(lds + PG8_SB(b, h) + boff + n * 2048 + k * 1024); } while (0)
; #define PG8_MMA(ai, bj, At, Bt) do { __builtin_amdgcn_s_setprio(1); _Pragma("unroll") for (int m = 0; m < 4; ++m) _Pragma("unroll") for (int n = 0; n < 2; ++n) _Pragma("unroll") for (int k = 0; k < 2; ++k) \
;         acc[ai][bj][m][n] = mma16(Bt[n][k], At[m][k], acc[ai][bj][m][n]); __builtin_amdgcn_s_setprio(0); } while (0)
; #define PG8_WAIT_V(n) asm volatile("s_waitcnt vmcnt(" #n ")" ::: "memory")
; #define PG8_WAIT_L(n) asm volatile("s_waitcnt lgkmcnt(" #n ")" ::: "memory")
; #define PG8_BAR __builtin_amdgcn_s_barrier()
; #define PG8_SCHED __builtin_amdgcn_sched_barrier(0)
; template <class Epi, class Sched, bool ALIGN_EPI = false, bool SP2 = false>
; __device__ __forceinline__ void gemm_phase(PG8_LAS unsigned char* lds, const Gemm g, const Sched& S, const Epi& E) {
;     ...
;             PG8_WAIT_V(8); PG8_WAIT_L(0); PG8_BAR; PG8_MMA(1, 0, At, B0); PG8_MMA(1, 1, At, B1); PG8_BAR; PG8_SCHED;
;             PG8_LDB(B0, 1, 0); PG8_LDB(B1, 1, 1); PG8_SCHED; PG8_LDA(At, 1, 0); PG8_STAGE(PG8_SA(0, 1), a2 + hstepA, voffA);
;             PG8_WAIT_V(8); PG8_WAIT_L(0); PG8_BAR; PG8_MMA(0, 0, At, B0); PG8_MMA(0, 1, At, B1); PG8_BAR; PG8_SCHED;
	s_setprio 1
	s_waitcnt lgkmcnt(0)
	v_mfma_f32_16x16x32_bf16 v[62:65], v[154:157], v[190:193], 0
	v_mfma_f32_16x16x32_bf16 v[62:65], v[158:161], v[194:197], v[62:65]
	v_mfma_f32_16x16x32_bf16 v[58:61], v[166:169], v[194:197], 0
	v_mfma_f32_16x16x32_bf16 v[58:61], v[162:165], v[190:193], v[58:61]
	v_mfma_f32_16x16x32_bf16 v[46:49], v[162:165], v[198:201], 0
	v_mfma_f32_16x16x32_bf16 v[46:49], v[166:169], v[202:205], v[46:49]
	v_mfma_f32_16x16x32_bf16 v[54:57], v[158:161], v[202:205], 0
	v_mfma_f32_16x16x32_bf16 v[54:57], v[154:157], v[198:201], v[54:57]
	v_mfma_f32_16x16x32_bf16 v[38:41], v[154:157], v[206:209], 0
	v_mfma_f32_16x16x32_bf16 v[38:41], v[158:161], v[212:215], v[38:41]
	v_mfma_f32_16x16x32_bf16 v[30:33], v[166:169], v[212:215], 0
	v_mfma_f32_16x16x32_bf16 v[30:33], v[162:165], v[206:209], v[30:33]
	v_mfma_f32_16x16x32_bf16 v[14:17], v[162:165], v[216:219], 0
	v_mfma_f32_16x16x32_bf16 v[14:17], v[166:169], v[220:223], v[14:17]
	v_mfma_f32_16x16x32_bf16 v[22:25], v[158:161], v[220:223], 0
	v_mfma_f32_16x16x32_bf16 v[22:25], v[154:157], v[216:219], v[22:25]
	s_setprio 0
	s_setprio 1
	v_mfma_f32_16x16x32_bf16 v[6:9], v[170:173], v[216:219], 0
	v_mfma_f32_16x16x32_bf16 v[6:9], v[174:177], v[220:223], v[6:9]
	v_mfma_f32_16x16x32_bf16 v[2:5], v[186:189], v[220:223], 0
	v_mfma_f32_16x16x32_bf16 v[2:5], v[182:185], v[216:219], v[2:5]
	v_mfma_f32_16x16x32_bf16 v[10:13], v[182:185], v[206:209], 0
	v_mfma_f32_16x16x32_bf16 v[10:13], v[186:189], v[212:215], v[10:13]
	v_mfma_f32_16x16x32_bf16 v[18:21], v[174:177], v[212:215], 0
	v_mfma_f32_16x16x32_bf16 v[18:21], v[170:173], v[206:209], v[18:21]
	v_mfma_f32_16x16x32_bf16 v[34:37], v[170:173], v[198:201], 0
	v_mfma_f32_16x16x32_bf16 v[34:37], v[174:177], v[202:205], v[34:37]
	v_mfma_f32_16x16x32_bf16 v[26:29], v[186:189], v[202:205], 0
	v_mfma_f32_16x16x32_bf16 v[26:29], v[182:185], v[198:201], v[26:29]
	v_mfma_f32_16x16x32_bf16 v[42:45], v[182:185], v[190:193], 0
	v_mfma_f32_16x16x32_bf16 v[42:45], v[186:189], v[194:197], v[42:45]
	v_mfma_f32_16x16x32_bf16 v[50:53], v[174:177], v[194:197], 0
	v_mfma_f32_16x16x32_bf16 v[50:53], v[170:173], v[190:193], v[50:53]
	s_setprio 0
	s_barrier
	s_add_i32 s46, 0, 0x18000
	v_add_u32_e32 v153, s46, v148
	s_add_i32 s47, 0, 0x1c000
	ds_read_b128 v[154:157], v153
	ds_read_b128 v[158:161], v153 offset:1024
	ds_read_b128 v[162:165], v153 offset:2048
	ds_read_b128 v[166:169], v153 offset:3072
	v_add_u32_e32 v153, s47, v148
	ds_read_b128 v[170:173], v153
	ds_read_b128 v[174:177], v153 offset:1024
	ds_read_b128 v[182:185], v153 offset:2048
	ds_read_b128 v[186:189], v153 offset:3072
	s_add_u32 s36, s66, 0x100000
	s_addc_u32 s37, s67, 0
	s_mov_b32 m0, s12
	v_lshl_add_u64 v[230:231], s[36:37], 0, v[130:131]
	ds_read_b128 v[190:193], v152 offset:32768
	ds_read_b128 v[194:197], v152 offset:33792
	ds_read_b128 v[198:201], v152 offset:34816
	ds_read_b128 v[202:205], v152 offset:35840
	ds_read_b128 v[206:209], v152 offset:36864
	ds_read_b128 v[212:215], v152 offset:37888
	ds_read_b128 v[216:219], v152 offset:38912
	ds_read_b128 v[220:223], v152 offset:39936
	global_load_lds_dwordx4 v[230:231], off
	v_lshl_add_u64 v[230:231], s[36:37], 0, v[134:135]
	s_mov_b32 m0, s13
	s_nop 0
	global_load_lds_dwordx4 v[230:231], off
	s_waitcnt vmcnt(8)
	s_waitcnt lgkmcnt(0)
	s_barrier
	s_setprio 1
	s_waitcnt lgkmcnt(0)
	v_mfma_f32_16x16x32_bf16 v[126:129], v[154:157], v[190:193], v[126:129]
	v_mfma_f32_16x16x32_bf16 v[126:129], v[158:161], v[194:197], v[126:129]
	v_mfma_f32_16x16x32_bf16 v[122:125], v[166:169], v[194:197], v[122:125]
	v_mfma_f32_16x16x32_bf16 v[122:125], v[162:165], v[190:193], v[122:125]
	v_mfma_f32_16x16x32_bf16 v[110:113], v[162:165], v[198:201], v[110:113]
	v_mfma_f32_16x16x32_bf16 v[110:113], v[166:169], v[202:205], v[110:113]
	v_mfma_f32_16x16x32_bf16 v[118:121], v[158:161], v[202:205], v[118:121]
	v_mfma_f32_16x16x32_bf16 v[118:121], v[154:157], v[198:201], v[118:121]
	v_mfma_f32_16x16x32_bf16 v[102:105], v[154:157], v[206:209], v[102:105]
	v_mfma_f32_16x16x32_bf16 v[102:105], v[158:161], v[212:215], v[102:105]
	v_mfma_f32_16x16x32_bf16 v[94:97], v[166:169], v[212:215], v[94:97]
	v_mfma_f32_16x16x32_bf16 v[94:97], v[162:165], v[206:209], v[94:97]
	v_mfma_f32_16x16x32_bf16 v[78:81], v[162:165], v[216:219], v[78:81]
	v_mfma_f32_16x16x32_bf16 v[78:81], v[166:169], v[220:223], v[78:81]
	v_mfma_f32_16x16x32_bf16 v[86:89], v[158:161], v[220:223], v[86:89]
	v_mfma_f32_16x16x32_bf16 v[86:89], v[154:157], v[216:219], v[86:89]
	s_setprio 0
	s_setprio 1
	v_mfma_f32_16x16x32_bf16 v[70:73], v[170:173], v[216:219], v[70:73]
	v_mfma_f32_16x16x32_bf16 v[70:73], v[174:177], v[220:223], v[70:73]
	v_mfma_f32_16x16x32_bf16 v[66:69], v[186:189], v[220:223], v[66:69]
	v_mfma_f32_16x16x32_bf16 v[66:69], v[182:185], v[216:219], v[66:69]
	v_mfma_f32_16x16x32_bf16 v[74:77], v[182:185], v[206:209], v[74:77]
	v_mfma_f32_16x16x32_bf16 v[74:77], v[186:189], v[212:215], v[74:77]
	v_mfma_f32_16x16x32_bf16 v[82:85], v[174:177], v[212:215], v[82:85]
	v_mfma_f32_16x16x32_bf16 v[82:85], v[170:173], v[206:209], v[82:85]
	v_mfma_f32_16x16x32_bf16 v[98:101], v[170:173], v[198:201], v[98:101]
	v_mfma_f32_16x16x32_bf16 v[98:101], v[174:177], v[202:205], v[98:101]
	v_mfma_f32_16x16x32_bf16 v[90:93], v[186:189], v[202:205], v[90:93]
	v_mfma_f32_16x16x32_bf16 v[90:93], v[182:185], v[198:201], v[90:93]
	v_mfma_f32_16x16x32_bf16 v[106:109], v[182:185], v[190:193], v[106:109]
	v_mfma_f32_16x16x32_bf16 v[106:109], v[186:189], v[194:197], v[106:109]
	v_mfma_f32_16x16x32_bf16 v[114:117], v[174:177], v[194:197], v[114:117]
	v_mfma_f32_16x16x32_bf16 v[114:117], v[170:173], v[190:193], v[114:117]
	s_setprio 0
	s_barrier
; #define PG8_STAGE(bufoff, gbase, voff) do { _Pragma("unroll") for (int _i = 0; _i < 2; ++_i) \
;         __builtin_amdgcn_global_load_lds((const unsigned*)((const char*)(gbase) + (voff)[_i]), (PG8_LAS unsigned*)(lds + (bufoff) + ldsw + _i * 8192), 16, 0, 0); } while (0)
; #define PG8_LDA(dst, b, h) do { _Pragma("unroll") for (int m = 0; m < 4; ++m) _Pragma("unroll") for (int k = 0; k < 2; ++k) dst[m][k] = *(const PG8_LAS bf16x8*)(lds + PG8_SA(b, h) + aoff + m * 2048 + k * 1024); } while (0)
; #define PG8_LDB(dst, b, h) do { _Pragma("unroll") for (int n = 0; n < 2; ++n) _Pragma("unroll") for (int k = 0; k < 2; ++k) dst[n][k] = *(const PG8_LAS bf16x8*)(lds + PG8_SB(b, h) + boff + n * 2048 + k * 1024); } while (0)
; #define PG8_MMA(ai, bj, At, Bt) do { __builtin_amdgcn_s_setprio(1); _Pragma("unroll") for (int m = 0; m < 4; ++m) _Pragma("unroll") for (int n = 0; n < 2; ++n) _Pragma("unroll") for (int k = 0; k < 2; ++k) \
;         acc[ai][bj][m][n] = mma16(Bt[n][k], At[m][k], acc[ai][bj][m][n]); __builtin_amdgcn_s_setprio(0); } while (0)
; #define PG8_WAIT_V(n) asm volatile("s_waitcnt vmcnt(" #n ")" ::: "memory")
; template <class Epi, class Sched, bool ALIGN_EPI = false, bool SP2 = false>
; __device__ __forceinline__ void gemm_phase(PG8_LAS unsigned char* lds, const Gemm g, const Sched& S, const Epi& E) {
;     ...
;         for (int t = 0; t < nt; t += 2) {
;     ...
;             PG8_LDB(B0, 0, 0); PG8_LDB(B1, 0, 1); PG8_SCHED; PG8_LDA(At, 0, 0); PG8_STAGE(PG8_SA(1, 1), a1 + hstepA, voffA);
;             PG8_WAIT_V(8); PG8_WAIT_L(0); PG8_BAR; PG8_MMA(0, 0, At, B0); PG8_MMA(0, 1, At, B1); PG8_BAR; PG8_SCHED;
;             PG8_LDA(At, 0, 1); PG8_STAGE(PG8_SB(0, 0), b2, voffB); PG8_STAGE(PG8_SB(0, 1), b2 + hstepB, voffB); PG8_STAGE(PG8_SA(0, 0), a2, voffA);
;             PG8_WAIT_V(8); PG8_WAIT_L(0); PG8_BAR; PG8_MMA(1, 0, At, B0); PG8_MMA(1, 1, At, B1); PG8_BAR; PG8_SCHED;
;             PG8_LDB(B0, 1, 0); PG8_LDB(B1, 1, 1); PG8_SCHED; PG8_LDA(At, 1, 0); PG8_STAGE(PG8_SA(0, 1), a2 + hstepA, voffA);
;             PG8_WAIT_V(8); PG8_WAIT_L(0); PG8_BAR; PG8_MMA(0, 0, At, B0); PG8_MMA(0, 1, At, B1); PG8_BAR; PG8_SCHED;
;             PG8_LDA(At, 1, 1); PG8_STAGE(PG8_SB(1, 0), b3, voffB); PG8_STAGE(PG8_SB(1, 1), b3 + hstepB, voffB); PG8_STAGE(PG8_SA(1, 0), a3, voffA);
;             PG8_WAIT_V(8); PG8_WAIT_L(0); PG8_BAR; PG8_MMA(1, 0, At, B0); PG8_MMA(1, 1, At, B1); PG8_BAR; PG8_SCHED;
	s_add_i32 s36, s46, s7
	v_lshl_add_u64 v[146:147], v[146:147], 0, s[40:41]
	s_mov_b32 m0, s36
	ds_read_b128 v[190:193], v152 offset:49152
	ds_read_b128 v[194:197], v152 offset:50176
	ds_read_b128 v[198:201], v152 offset:51200
	ds_read_b128 v[202:205], v152 offset:52224
	ds_read_b128 v[206:209], v152 offset:53248
	ds_read_b128 v[212:215], v152 offset:54272
	ds_read_b128 v[216:219], v152 offset:55296
	ds_read_b128 v[220:223], v152 offset:56320
	global_load_lds_dwordx4 v[146:147], off
	s_add_i32 m0, s36, 0x2000
	s_add_u32 s36, s64, 0x100080
	v_lshl_add_u64 v[146:147], v[224:225], 0, s[40:41]
	s_addc_u32 s37, s65, 0
	s_add_i32 s46, s47, s7
	global_load_lds_dwordx4 v[146:147], off
	v_lshl_add_u64 v[146:147], s[36:37], 0, v[132:133]
	s_mov_b32 m0, s46
	s_nop 0
	global_load_lds_dwordx4 v[146:147], off
	v_lshl_add_u64 v[146:147], s[36:37], 0, v[136:137]
	s_add_i32 m0, s46, 0x2000
	s_nop 0
	global_load_lds_dwordx4 v[146:147], off
	v_lshl_add_u64 v[146:147], v[226:227], 0, s[40:41]
	s_mov_b32 m0, s17
	s_nop 0
	global_load_lds_dwordx4 v[146:147], off
	v_lshl_add_u64 v[146:147], v[228:229], 0, s[40:41]
	s_mov_b32 m0, s18
	s_nop 0
	global_load_lds_dwordx4 v[146:147], off
	s_waitcnt vmcnt(8)
	s_waitcnt lgkmcnt(0)
	s_barrier
	s_setprio 1
	s_waitcnt lgkmcnt(0)
	v_mfma_f32_16x16x32_bf16 v[62:65], v[154:157], v[190:193], v[62:65]
	v_mfma_f32_16x16x32_bf16 v[62:65], v[158:161], v[194:197], v[62:65]
	v_mfma_f32_16x16x32_bf16 v[58:61], v[166:169], v[194:197], v[58:61]
	v_mfma_f32_16x16x32_bf16 v[58:61], v[162:165], v[190:193], v[58:61]
	v_mfma_f32_16x16x32_bf16 v[46:49], v[162:165], v[198:201], v[46:49]
	v_mfma_f32_16x16x32_bf16 v[46:49], v[166:169], v[202:205], v[46:49]
	v_mfma_f32_16x16x32_bf16 v[54:57], v[158:161], v[202:205], v[54:57]
	v_mfma_f32_16x16x32_bf16 v[54:57], v[154:157], v[198:201], v[54:57]
	v_mfma_f32_16x16x32_bf16 v[38:41], v[154:157], v[206:209], v[38:41]
	v_mfma_f32_16x16x32_bf16 v[38:41], v[158:161], v[212:215], v[38:41]
	v_mfma_f32_16x16x32_bf16 v[30:33], v[166:169], v[212:215], v[30:33]
	v_mfma_f32_16x16x32_bf16 v[30:33], v[162:165], v[206:209], v[30:33]
	v_mfma_f32_16x16x32_bf16 v[14:17], v[162:165], v[216:219], v[14:17]
	v_mfma_f32_16x16x32_bf16 v[14:17], v[166:169], v[220:223], v[14:17]
	v_mfma_f32_16x16x32_bf16 v[22:25], v[158:161], v[220:223], v[22:25]
	v_mfma_f32_16x16x32_bf16 v[22:25], v[154:157], v[216:219], v[22:25]
	s_setprio 0
	s_setprio 1
	v_mfma_f32_16x16x32_bf16 v[6:9], v[170:173], v[216:219], v[6:9]
	v_mfma_f32_16x16x32_bf16 v[6:9], v[174:177], v[220:223], v[6:9]
	v_mfma_f32_16x16x32_bf16 v[2:5], v[186:189], v[220:223], v[2:5]
	v_mfma_f32_16x16x32_bf16 v[2:5], v[182:185], v[216:219], v[2:5]
	v_mfma_f32_16x16x32_bf16 v[10:13], v[182:185], v[206:209], v[10:13]
	v_mfma_f32_16x16x32_bf16 v[10:13], v[186:189], v[212:215], v[10:13]
	v_mfma_f32_16x16x32_bf16 v[18:21], v[174:177], v[212:215], v[18:21]
	v_mfma_f32_16x16x32_bf16 v[18:21], v[170:173], v[206:209], v[18:21]
	v_mfma_f32_16x16x32_bf16 v[34:37], v[170:173], v[198:201], v[34:37]
	v_mfma_f32_16x16x32_bf16 v[34:37], v[174:177], v[202:205], v[34:37]
	v_mfma_f32_16x16x32_bf16 v[26:29], v[186:189], v[202:205], v[26:29]
	v_mfma_f32_16x16x32_bf16 v[26:29], v[182:185], v[198:201], v[26:29]
	v_mfma_f32_16x16x32_bf16 v[42:45], v[182:185], v[190:193], v[42:45]
	v_mfma_f32_16x16x32_bf16 v[42:45], v[186:189], v[194:197], v[42:45]
	v_mfma_f32_16x16x32_bf16 v[50:53], v[174:177], v[194:197], v[50:53]
	v_mfma_f32_16x16x32_bf16 v[50:53], v[170:173], v[190:193], v[50:53]
	s_setprio 0
	s_barrier
	s_add_i32 s35, s35, 2
	s_add_u32 s0, s0, 0x100
	s_addc_u32 s1, s1, 0
	s_add_u32 s29, s29, 0x100
	s_addc_u32 s33, s33, 0
.LBB0_660:
	ds_read_b128 v[154:157], v150
	ds_read_b128 v[158:161], v150 offset:1024
	ds_read_b128 v[162:165], v150 offset:2048
	ds_read_b128 v[166:169], v150 offset:3072
	ds_read_b128 v[170:173], v151
	ds_read_b128 v[174:177], v151 offset:1024
	ds_read_b128 v[182:185], v151 offset:2048
	ds_read_b128 v[186:189], v151 offset:3072
	s_add_u32 s36, s0, 0xfff00080
	s_addc_u32 s37, s1, -1
	s_cmp_eq_u32 s35, 60
	s_cselect_b32 s67, s59, s37
	s_cselect_b32 s66, s58, s36
	s_cselect_b32 s65, s27, s33
	s_cselect_b32 s64, s28, s29
	v_lshl_add_u64 v[146:147], s[0:1], 0, v[138:139]
	s_add_i32 m0, s8, 0xc000
	ds_read_b128 v[190:193], v152
	ds_read_b128 v[194:197], v152 offset:1024
	ds_read_b128 v[198:201], v152 offset:2048
	ds_read_b128 v[202:205], v152 offset:3072
	ds_read_b128 v[206:209], v152 offset:4096
	ds_read_b128 v[212:215], v152 offset:5120
	ds_read_b128 v[216:219], v152 offset:6144
	ds_read_b128 v[220:223], v152 offset:7168
	global_load_lds_dwordx4 v[146:147], off
	v_lshl_add_u64 v[146:147], s[0:1], 0, v[140:141]
	s_add_i32 m0, s8, 0xe000
	s_nop 0
	global_load_lds_dwordx4 v[146:147], off
	s_waitcnt vmcnt(8)
	s_waitcnt lgkmcnt(0)
	s_barrier
; #define PG8_STAGE(bufoff, gbase, voff) do { _Pragma("unroll") for (int _i = 0; _i < 2; ++_i) \
;         __builtin_amdgcn_global_load_lds((const unsigned*)((const char*)(gbase) + (voff)[_i]), (PG8_LAS unsigned*)(lds + (bufoff) + ldsw + _i * 8192), 16, 0, 0); } while (0)
; #define PG8_LDA(dst, b, h) do { _Pragma("unroll") for (int m = 0; m < 4; ++m) _Pragma("unroll") for (int k = 0; k < 2; ++k) dst[m][k] = *(const PG8_LAS bf16x8*)(lds + PG8_SA(b, h) + aoff + m * 2048 + k * 1024); } while (0)
; #define PG8_LDB(dst, b, h) do { _Pragma("unroll") for (int n = 0; n < 2; ++n) _Pragma("unroll") for (int k = 0; k < 2; ++k) dst[n][k] = *(const PG8_LAS bf16x8*)(lds + PG8_SB(b, h) + boff + n * 2048 + k * 1024); } while (0)
; #define PG8_MMA(ai, bj, At, Bt) do { __builtin_amdgcn_s_setprio(1); _Pragma("unroll") for (int m = 0; m < 4; ++m) _Pragma("unroll") for (int n = 0; n < 2; ++n) _Pragma("unroll") for (int k = 0; k < 2; ++k) \
;         acc[ai][bj][m][n] = mma16(Bt[n][k], At[m][k], acc[ai][bj][m][n]); __builtin_amdgcn_s_setprio(0); } while (0)
; #define PG8_WAIT_V(n) asm volatile("s_waitcnt vmcnt(" #n ")" ::: "memory")
; #define PG8_WAIT_L(n) asm volatile("s_waitcnt lgkmcnt(" #n ")" ::: "memory")
; #define PG8_BAR __builtin_amdgcn_s_barrier()
; #define PG8_SCHED __builtin_amdgcn_sched_barrier(0)
; template <class Epi, class Sched, bool ALIGN_EPI = false, bool SP2 = false>
; __device__ __forceinline__ void gemm_phase(PG8_LAS unsigned char* lds, const Gemm g, const Sched& S, const Epi& E) {
;     ...
;             PG8_WAIT_V(8); PG8_WAIT_L(0); PG8_BAR; PG8_MMA(0, 0, At, B0); PG8_MMA(0, 1, At, B1); PG8_BAR; PG8_SCHED;
;             PG8_LDA(At, 0, 1); PG8_STAGE(PG8_SB(0, 0), b2, voffB); PG8_STAGE(PG8_SB(0, 1), b2 + hstepB, voffB); PG8_STAGE(PG8_SA(0, 0), a2, voffA);
;             PG8_WAIT_V(8); PG8_WAIT_L(0); PG8_BAR; PG8_MMA(1, 0, At, B0); PG8_MMA(1, 1, At, B1); PG8_BAR; PG8_SCHED;
;             PG8_LDB(B0, 1, 0); PG8_LDB(B1, 1, 1); PG8_SCHED; PG8_LDA(At, 1, 0); PG8_STAGE(PG8_SA(0, 1), a2 + hstepA, voffA);
;             PG8_WAIT_V(8); PG8_WAIT_L(0); PG8_BAR; PG8_MMA(0, 0, At, B0); PG8_MMA(0, 1, At, B1); PG8_BAR; PG8_SCHED;
	s_setprio 1
	s_waitcnt lgkmcnt(0)
	v_mfma_f32_16x16x32_bf16 v[126:129], v[154:157], v[190:193], v[126:129]
	v_mfma_f32_16x16x32_bf16 v[126:129], v[158:161], v[194:197], v[126:129]
	v_mfma_f32_16x16x32_bf16 v[122:125], v[166:169], v[194:197], v[122:125]
	v_mfma_f32_16x16x32_bf16 v[122:125], v[162:165], v[190:193], v[122:125]
	v_mfma_f32_16x16x32_bf16 v[110:113], v[162:165], v[198:201], v[110:113]
	v_mfma_f32_16x16x32_bf16 v[110:113], v[166:169], v[202:205], v[110:113]
	v_mfma_f32_16x16x32_bf16 v[118:121], v[158:161], v[202:205], v[118:121]
	v_mfma_f32_16x16x32_bf16 v[118:121], v[154:157], v[198:201], v[118:121]
	v_mfma_f32_16x16x32_bf16 v[102:105], v[154:157], v[206:209], v[102:105]
	v_mfma_f32_16x16x32_bf16 v[102:105], v[158:161], v[212:215], v[102:105]
	v_mfma_f32_16x16x32_bf16 v[94:97], v[166:169], v[212:215], v[94:97]
	v_mfma_f32_16x16x32_bf16 v[94:97], v[162:165], v[206:209], v[94:97]
	v_mfma_f32_16x16x32_bf16 v[78:81], v[162:165], v[216:219], v[78:81]
	v_mfma_f32_16x16x32_bf16 v[78:81], v[166:169], v[220:223], v[78:81]
	v_mfma_f32_16x16x32_bf16 v[86:89], v[158:161], v[220:223], v[86:89]
	v_mfma_f32_16x16x32_bf16 v[86:89], v[154:157], v[216:219], v[86:89]
	s_setprio 0
	s_setprio 1
	v_mfma_f32_16x16x32_bf16 v[70:73], v[170:173], v[216:219], v[70:73]
	v_mfma_f32_16x16x32_bf16 v[70:73], v[174:177], v[220:223], v[70:73]
	v_mfma_f32_16x16x32_bf16 v[66:69], v[186:189], v[220:223], v[66:69]
	v_mfma_f32_16x16x32_bf16 v[66:69], v[182:185], v[216:219], v[66:69]
	v_mfma_f32_16x16x32_bf16 v[74:77], v[182:185], v[206:209], v[74:77]
	v_mfma_f32_16x16x32_bf16 v[74:77], v[186:189], v[212:215], v[74:77]
	v_mfma_f32_16x16x32_bf16 v[82:85], v[174:177], v[212:215], v[82:85]
	v_mfma_f32_16x16x32_bf16 v[82:85], v[170:173], v[206:209], v[82:85]
	v_mfma_f32_16x16x32_bf16 v[98:101], v[170:173], v[198:201], v[98:101]
	v_mfma_f32_16x16x32_bf16 v[98:101], v[174:177], v[202:205], v[98:101]
	v_mfma_f32_16x16x32_bf16 v[90:93], v[186:189], v[202:205], v[90:93]
	v_mfma_f32_16x16x32_bf16 v[90:93], v[182:185], v[198:201], v[90:93]
	v_mfma_f32_16x16x32_bf16 v[106:109], v[182:185], v[190:193], v[106:109]
	v_mfma_f32_16x16x32_bf16 v[106:109], v[186:189], v[194:197], v[106:109]
	v_mfma_f32_16x16x32_bf16 v[114:117], v[174:177], v[194:197], v[114:117]
	v_mfma_f32_16x16x32_bf16 v[114:117], v[170:173], v[190:193], v[114:117]
	s_setprio 0
	s_barrier
	s_add_i32 s36, s20, s7
	v_lshl_add_u64 v[146:147], s[64:65], 0, v[132:133]
	s_mov_b32 m0, s36
	ds_read_b128 v[190:193], v152 offset:16384
	ds_read_b128 v[194:197], v152 offset:17408
	ds_read_b128 v[198:201], v152 offset:18432
	ds_read_b128 v[202:205], v152 offset:19456
	ds_read_b128 v[206:209], v152 offset:20480
	ds_read_b128 v[212:215], v152 offset:21504
	ds_read_b128 v[216:219], v152 offset:22528
	ds_read_b128 v[220:223], v152 offset:23552
	global_load_lds_dwordx4 v[146:147], off
	s_add_i32 m0, s36, 0x2000
	s_add_u32 s36, s64, 0x100000
	v_lshl_add_u64 v[224:225], s[64:65], 0, v[136:137]
	s_addc_u32 s37, s65, 0
	s_add_i32 s46, s21, s7
	global_load_lds_dwordx4 v[224:225], off
	v_lshl_add_u64 v[226:227], s[36:37], 0, v[132:133]
	s_mov_b32 m0, s46
	v_lshl_add_u64 v[228:229], s[66:67], 0, v[134:135]
	global_load_lds_dwordx4 v[226:227], off
	v_lshl_add_u64 v[226:227], s[36:37], 0, v[136:137]
	s_add_i32 m0, s46, 0x2000
	s_nop 0
	global_load_lds_dwordx4 v[226:227], off
	v_lshl_add_u64 v[226:227], s[66:67], 0, v[130:131]
	s_mov_b32 m0, s8
	s_nop 0
	global_load_lds_dwordx4 v[226:227], off
	s_mov_b32 m0, s11
	s_nop 0
	global_load_lds_dwordx4 v[228:229], off
	s_waitcnt vmcnt(8)
	s_waitcnt lgkmcnt(0)
	s_barrier
	s_setprio 1
	s_waitcnt lgkmcnt(0)
	v_mfma_f32_16x16x32_bf16 v[62:65], v[154:157], v[190:193], v[62:65]
	v_mfma_f32_16x16x32_bf16 v[62:65], v[158:161], v[194:197], v[62:65]
	v_mfma_f32_16x16x32_bf16 v[58:61], v[166:169], v[194:197], v[58:61]
	v_mfma_f32_16x16x32_bf16 v[58:61], v[162:165], v[190:193], v[58:61]
	v_mfma_f32_16x16x32_bf16 v[46:49], v[162:165], v[198:201], v[46:49]
	v_mfma_f32_16x16x32_bf16 v[46:49], v[166:169], v[202:205], v[46:49]
	v_mfma_f32_16x16x32_bf16 v[54:57], v[158:161], v[202:205], v[54:57]
	v_mfma_f32_16x16x32_bf16 v[54:57], v[154:157], v[198:201], v[54:57]
	v_mfma_f32_16x16x32_bf16 v[38:41], v[154:157], v[206:209], v[38:41]
	v_mfma_f32_16x16x32_bf16 v[38:41], v[158:161], v[212:215], v[38:41]
	v_mfma_f32_16x16x32_bf16 v[30:33], v[166:169], v[212:215], v[30:33]
	v_mfma_f32_16x16x32_bf16 v[30:33], v[162:165], v[206:209], v[30:33]
	v_mfma_f32_16x16x32_bf16 v[14:17], v[162:165], v[216:219], v[14:17]
	v_mfma_f32_16x16x32_bf16 v[14:17], v[166:169], v[220:223], v[14:17]
	v_mfma_f32_16x16x32_bf16 v[22:25], v[158:161], v[220:223], v[22:25]
	v_mfma_f32_16x16x32_bf16 v[22:25], v[154:157], v[216:219], v[22:25]
	s_setprio 0
	s_setprio 1
	v_mfma_f32_16x16x32_bf16 v[6:9], v[170:173], v[216:219], v[6:9]
	v_mfma_f32_16x16x32_bf16 v[6:9], v[174:177], v[220:223], v[6:9]
	v_mfma_f32_16x16x32_bf16 v[2:5], v[186:189], v[220:223], v[2:5]
	v_mfma_f32_16x16x32_bf16 v[2:5], v[182:185], v[216:219], v[2:5]
	v_mfma_f32_16x16x32_bf16 v[10:13], v[182:185], v[206:209], v[10:13]
	v_mfma_f32_16x16x32_bf16 v[10:13], v[186:189], v[212:215], v[10:13]
	v_mfma_f32_16x16x32_bf16 v[18:21], v[174:177], v[212:215], v[18:21]
	v_mfma_f32_16x16x32_bf16 v[18:21], v[170:173], v[206:209], v[18:21]
	v_mfma_f32_16x16x32_bf16 v[34:37], v[170:173], v[198:201], v[34:37]
	v_mfma_f32_16x16x32_bf16 v[34:37], v[174:177], v[202:205], v[34:37]
	v_mfma_f32_16x16x32_bf16 v[26:29], v[186:189], v[202:205], v[26:29]
	v_mfma_f32_16x16x32_bf16 v[26:29], v[182:185], v[198:201], v[26:29]
	v_mfma_f32_16x16x32_bf16 v[42:45], v[182:185], v[190:193], v[42:45]
	v_mfma_f32_16x16x32_bf16 v[42:45], v[186:189], v[194:197], v[42:45]
	v_mfma_f32_16x16x32_bf16 v[50:53], v[174:177], v[194:197], v[50:53]
	v_mfma_f32_16x16x32_bf16 v[50:53], v[170:173], v[190:193], v[50:53]
	s_setprio 0
	s_barrier
; #define PG8_STAGE(bufoff, gbase, voff) do { _Pragma("unroll") for (int _i = 0; _i < 2; ++_i) \
;         __builtin_amdgcn_global_load_lds((const unsigned*)((const char*)(gbase) + (voff)[_i]), (PG8_LAS unsigned*)(lds + (bufoff) + ldsw + _i * 8192), 16, 0, 0); } while (0)
; #define PG8_LDA(dst, b, h) do { _Pragma("unroll") for (int m = 0; m < 4; ++m) _Pragma("unroll") for (int k = 0; k < 2; ++k) dst[m][k] = *(const PG8_LAS bf16x8*)(lds + PG8_SA(b, h) + aoff + m * 2048 + k * 1024); } while (0)
; #define PG8_LDB(dst, b, h) do { _Pragma("unroll") for (int n = 0; n < 2; ++n) _Pragma("unroll") for (int k = 0; k < 2; ++k) dst[n][k] = *(const PG8_LAS bf16x8*)(lds + PG8_SB(b, h) + boff + n * 2048 + k * 1024); } while (0)
; #define PG8_MMA(ai, bj, At, Bt) do { __builtin_amdgcn_s_setprio(1); _Pragma("unroll") for (int m = 0; m < 4; ++m) _Pragma("unroll") for (int n = 0; n < 2; ++n) _Pragma("unroll") for (int k = 0; k < 2; ++k) \
;         acc[ai][bj][m][n] = mma16(Bt[n][k], At[m][k], acc[ai][bj][m][n]); __builtin_amdgcn_s_setprio(0); } while (0)
; #define PG8_WAIT_V(n) asm volatile("s_waitcnt vmcnt(" #n ")" ::: "memory")
; #define PG8_WAIT_L(n) asm volatile("s_waitcnt lgkmcnt(" #n ")" ::: "memory")
; #define PG8_BAR __builtin_amdgcn_s_barrier()
; #define PG8_SCHED __builtin_amdgcn_sched_barrier(0)
; template <class Epi, class Sched, bool ALIGN_EPI = false, bool SP2 = false>
; __device__ __forceinline__ void gemm_phase(PG8_LAS unsigned char* lds, const Gemm g, const Sched& S, const Epi& E) {
;     ...
;             PG8_LDB(B0, 1, 0); PG8_LDB(B1, 1, 1); PG8_SCHED; PG8_LDA(At, 1, 0); PG8_STAGE(PG8_SA(0, 1), a2 + hstepA, voffA);
;             PG8_WAIT_V(8); PG8_WAIT_L(0); PG8_BAR; PG8_MMA(0, 0, At, B0); PG8_MMA(0, 1, At, B1); PG8_BAR; PG8_SCHED;
	s_add_i32 s46, 0, 0x18000
	v_add_u32_e32 v153, s46, v148
	s_add_i32 s47, 0, 0x1c000
	ds_read_b128 v[154:157], v153
	ds_read_b128 v[158:161], v153 offset:1024
	ds_read_b128 v[162:165], v153 offset:2048
	ds_read_b128 v[166:169], v153 offset:3072
	v_add_u32_e32 v153, s47, v148
	ds_read_b128 v[170:173], v153
	ds_read_b128 v[174:177], v153 offset:1024
	ds_read_b128 v[182:185], v153 offset:2048
	ds_read_b128 v[186:189], v153 offset:3072
	s_add_u32 s36, s66, 0x100000
	s_addc_u32 s37, s67, 0
	s_mov_b32 m0, s12
	v_lshl_add_u64 v[230:231], s[36:37], 0, v[130:131]
	ds_read_b128 v[190:193], v152 offset:32768
	ds_read_b128 v[194:197], v152 offset:33792
	ds_read_b128 v[198:201], v152 offset:34816
	ds_read_b128 v[202:205], v152 offset:35840
	ds_read_b128 v[206:209], v152 offset:36864
	ds_read_b128 v[212:215], v152 offset:37888
	ds_read_b128 v[216:219], v152 offset:38912
	ds_read_b128 v[220:223], v152 offset:39936
	global_load_lds_dwordx4 v[230:231], off
	v_lshl_add_u64 v[230:231], s[36:37], 0, v[134:135]
	s_mov_b32 m0, s13
	s_nop 0
	global_load_lds_dwordx4 v[230:231], off
	s_waitcnt vmcnt(8)
	s_waitcnt lgkmcnt(0)
	s_barrier
	s_setprio 1
	s_waitcnt lgkmcnt(0)
	v_mfma_f32_16x16x32_bf16 v[126:129], v[154:157], v[190:193], v[126:129]
	v_mfma_f32_16x16x32_bf16 v[126:129], v[158:161], v[194:197], v[126:129]
	v_mfma_f32_16x16x32_bf16 v[122:125], v[166:169], v[194:197], v[122:125]
	v_mfma_f32_16x16x32_bf16 v[122:125], v[162:165], v[190:193], v[122:125]
	v_mfma_f32_16x16x32_bf16 v[110:113], v[162:165], v[198:201], v[110:113]
	v_mfma_f32_16x16x32_bf16 v[110:113], v[166:169], v[202:205], v[110:113]
	v_mfma_f32_16x16x32_bf16 v[118:121], v[158:161], v[202:205], v[118:121]
	v_mfma_f32_16x16x32_bf16 v[118:121], v[154:157], v[198:201], v[118:121]
	v_mfma_f32_16x16x32_bf16 v[102:105], v[154:157], v[206:209], v[102:105]
	v_mfma_f32_16x16x32_bf16 v[102:105], v[158:161], v[212:215], v[102:105]
	v_mfma_f32_16x16x32_bf16 v[94:97], v[166:169], v[212:215], v[94:97]
	v_mfma_f32_16x16x32_bf16 v[94:97], v[162:165], v[206:209], v[94:97]
	v_mfma_f32_16x16x32_bf16 v[78:81], v[162:165], v[216:219], v[78:81]
	v_mfma_f32_16x16x32_bf16 v[78:81], v[166:169], v[220:223], v[78:81]
	v_mfma_f32_16x16x32_bf16 v[86:89], v[158:161], v[220:223], v[86:89]
	v_mfma_f32_16x16x32_bf16 v[86:89], v[154:157], v[216:219], v[86:89]
	s_setprio 0
	s_setprio 1
	v_mfma_f32_16x16x32_bf16 v[70:73], v[170:173], v[216:219], v[70:73]
	v_mfma_f32_16x16x32_bf16 v[70:73], v[174:177], v[220:223], v[70:73]
	v_mfma_f32_16x16x32_bf16 v[66:69], v[186:189], v[220:223], v[66:69]
	v_mfma_f32_16x16x32_bf16 v[66:69], v[182:185], v[216:219], v[66:69]
	v_mfma_f32_16x16x32_bf16 v[74:77], v[182:185], v[206:209], v[74:77]
	v_mfma_f32_16x16x32_bf16 v[74:77], v[186:189], v[212:215], v[74:77]
	v_mfma_f32_16x16x32_bf16 v[82:85], v[174:177], v[212:215], v[82:85]
	v_mfma_f32_16x16x32_bf16 v[82:85], v[170:173], v[206:209], v[82:85]
	v_mfma_f32_16x16x32_bf16 v[98:101], v[170:173], v[198:201], v[98:101]
	v_mfma_f32_16x16x32_bf16 v[98:101], v[174:177], v[202:205], v[98:101]
	v_mfma_f32_16x16x32_bf16 v[90:93], v[186:189], v[202:205], v[90:93]
	v_mfma_f32_16x16x32_bf16 v[90:93], v[182:185], v[198:201], v[90:93]
	v_mfma_f32_16x16x32_bf16 v[106:109], v[182:185], v[190:193], v[106:109]
	v_mfma_f32_16x16x32_bf16 v[106:109], v[186:189], v[194:197], v[106:109]
	v_mfma_f32_16x16x32_bf16 v[114:117], v[174:177], v[194:197], v[114:117]
	v_mfma_f32_16x16x32_bf16 v[114:117], v[170:173], v[190:193], v[114:117]
	s_setprio 0
	s_barrier
; #define PG8_STAGE(bufoff, gbase, voff) do { _Pragma("unroll") for (int _i = 0; _i < 2; ++_i) \
;         __builtin_amdgcn_global_load_lds((const unsigned*)((const char*)(gbase) + (voff)[_i]), (PG8_LAS unsigned*)(lds + (bufoff) + ldsw + _i * 8192), 16, 0, 0); } while (0)
; #define PG8_LDA(dst, b, h) do { _Pragma("unroll") for (int m = 0; m < 4; ++m) _Pragma("unroll") for (int k = 0; k < 2; ++k) dst[m][k] = *(const PG8_LAS bf16x8*)(lds + PG8_SA(b, h) + aoff + m * 2048 + k * 1024); } while (0)
; #define PG8_MMA(ai, bj, At, Bt) do { __builtin_amdgcn_s_setprio(1); _Pragma("unroll") for (int m = 0; m < 4; ++m) _Pragma("unroll") for (int n = 0; n < 2; ++n) _Pragma("unroll") for (int k = 0; k < 2; ++k) \
;         acc[ai][bj][m][n] = mma16(Bt[n][k], At[m][k], acc[ai][bj][m][n]); __builtin_amdgcn_s_setprio(0); } while (0)
; #define PG8_WAIT_V(n) asm volatile("s_waitcnt vmcnt(" #n ")" ::: "memory")
; #define PG8_WAIT_L(n) asm volatile("s_waitcnt lgkmcnt(" #n ")" ::: "memory")
; #define PG8_BAR __builtin_amdgcn_s_barrier()
; #define PG8_SCHED __builtin_amdgcn_sched_barrier(0)
; template <class Epi, class Sched, bool ALIGN_EPI = false, bool SP2 = false>
; __device__ __forceinline__ void gemm_phase(PG8_LAS unsigned char* lds, const Gemm g, const Sched& S, const Epi& E) {
;     ...
;         for (int t = 0; t < nt; t += 2) {
;     ...
;             PG8_LDA(At, 1, 1); PG8_STAGE(PG8_SB(1, 0), b3, voffB); PG8_STAGE(PG8_SB(1, 1), b3 + hstepB, voffB); PG8_STAGE(PG8_SA(1, 0), a3, voffA);
;             PG8_WAIT_V(8); PG8_WAIT_L(0); PG8_BAR; PG8_MMA(1, 0, At, B0); PG8_MMA(1, 1, At, B1); PG8_BAR; PG8_SCHED;
	s_add_i32 s36, s46, s7
	v_lshl_add_u64 v[146:147], v[146:147], 0, s[40:41]
	s_mov_b32 m0, s36
	ds_read_b128 v[190:193], v152 offset:49152
	ds_read_b128 v[194:197], v152 offset:50176
	ds_read_b128 v[198:201], v152 offset:51200
	ds_read_b128 v[202:205], v152 offset:52224
	ds_read_b128 v[206:209], v152 offset:53248
	ds_read_b128 v[212:215], v152 offset:54272
	ds_read_b128 v[216:219], v152 offset:55296
	ds_read_b128 v[220:223], v152 offset:56320
	global_load_lds_dwordx4 v[146:147], off
	s_add_i32 m0, s36, 0x2000
	s_add_u32 s36, s64, 0x100080
	v_lshl_add_u64 v[146:147], v[224:225], 0, s[40:41]
	s_addc_u32 s37, s65, 0
	s_add_i32 s46, s47, s7
	global_load_lds_dwordx4 v[146:147], off
	v_lshl_add_u64 v[146:147], s[36:37], 0, v[132:133]
	s_mov_b32 m0, s46
	s_nop 0
	global_load_lds_dwordx4 v[146:147], off
	v_lshl_add_u64 v[146:147], s[36:37], 0, v[136:137]
	s_add_i32 m0, s46, 0x2000
	s_nop 0
	global_load_lds_dwordx4 v[146:147], off
	v_lshl_add_u64 v[146:147], v[226:227], 0, s[40:41]
	s_mov_b32 m0, s17
	s_nop 0
	global_load_lds_dwordx4 v[146:147], off
	v_lshl_add_u64 v[146:147], v[228:229], 0, s[40:41]
	s_mov_b32 m0, s18
	s_nop 0
	global_load_lds_dwordx4 v[146:147], off
	s_waitcnt vmcnt(8)
	s_waitcnt lgkmcnt(0)
	s_barrier
	s_setprio 1
	s_waitcnt lgkmcnt(0)
	v_mfma_f32_16x16x32_bf16 v[62:65], v[154:157], v[190:193], v[62:65]
	v_mfma_f32_16x16x32_bf16 v[62:65], v[158:161], v[194:197], v[62:65]
	v_mfma_f32_16x16x32_bf16 v[58:61], v[166:169], v[194:197], v[58:61]
	v_mfma_f32_16x16x32_bf16 v[58:61], v[162:165], v[190:193], v[58:61]
	v_mfma_f32_16x16x32_bf16 v[46:49], v[162:165], v[198:201], v[46:49]
	v_mfma_f32_16x16x32_bf16 v[46:49], v[166:169], v[202:205], v[46:49]
	v_mfma_f32_16x16x32_bf16 v[54:57], v[158:161], v[202:205], v[54:57]
	v_mfma_f32_16x16x32_bf16 v[54:57], v[154:157], v[198:201], v[54:57]
	v_mfma_f32_16x16x32_bf16 v[38:41], v[154:157], v[206:209], v[38:41]
	v_mfma_f32_16x16x32_bf16 v[38:41], v[158:161], v[212:215], v[38:41]
	v_mfma_f32_16x16x32_bf16 v[30:33], v[166:169], v[212:215], v[30:33]
	v_mfma_f32_16x16x32_bf16 v[30:33], v[162:165], v[206:209], v[30:33]
	v_mfma_f32_16x16x32_bf16 v[14:17], v[162:165], v[216:219], v[14:17]
	v_mfma_f32_16x16x32_bf16 v[14:17], v[166:169], v[220:223], v[14:17]
	v_mfma_f32_16x16x32_bf16 v[22:25], v[158:161], v[220:223], v[22:25]
	v_mfma_f32_16x16x32_bf16 v[22:25], v[154:157], v[216:219], v[22:25]
	s_setprio 0
	s_setprio 1
	v_mfma_f32_16x16x32_bf16 v[6:9], v[170:173], v[216:219], v[6:9]
	v_mfma_f32_16x16x32_bf16 v[6:9], v[174:177], v[220:223], v[6:9]
	v_mfma_f32_16x16x32_bf16 v[2:5], v[186:189], v[220:223], v[2:5]
	v_mfma_f32_16x16x32_bf16 v[2:5], v[182:185], v[216:219], v[2:5]
	v_mfma_f32_16x16x32_bf16 v[10:13], v[182:185], v[206:209], v[10:13]
	v_mfma_f32_16x16x32_bf16 v[10:13], v[186:189], v[212:215], v[10:13]
	v_mfma_f32_16x16x32_bf16 v[18:21], v[174:177], v[212:215], v[18:21]
	v_mfma_f32_16x16x32_bf16 v[18:21], v[170:173], v[206:209], v[18:21]
	v_mfma_f32_16x16x32_bf16 v[34:37], v[170:173], v[198:201], v[34:37]
	v_mfma_f32_16x16x32_bf16 v[34:37], v[174:177], v[202:205], v[34:37]
	v_mfma_f32_16x16x32_bf16 v[26:29], v[186:189], v[202:205], v[26:29]
	v_mfma_f32_16x16x32_bf16 v[26:29], v[182:185], v[198:201], v[26:29]
	v_mfma_f32_16x16x32_bf16 v[42:45], v[182:185], v[190:193], v[42:45]
	v_mfma_f32_16x16x32_bf16 v[42:45], v[186:189], v[194:197], v[42:45]
	v_mfma_f32_16x16x32_bf16 v[50:53], v[174:177], v[194:197], v[50:53]
	v_mfma_f32_16x16x32_bf16 v[50:53], v[170:173], v[190:193], v[50:53]
	s_setprio 0
	s_barrier
	s_add_i32 s35, s35, 2
	s_add_u32 s0, s0, 0x100
	s_addc_u32 s1, s1, 0
	s_add_u32 s29, s29, 0x100
	s_addc_u32 s33, s33, 0
	s_cmp_gt_u32 s35, 61
	s_cbranch_scc0 .LBB0_660
	s_and_b64 vcc, exec, s[42:43]
	s_cbranch_vccz .LBB0_663
	s_barrier

; #define PG8_STAGE(bufoff, gbase, voff) do { _Pragma("unroll") for (int _i = 0; _i < 2; ++_i) \
;         __builtin_amdgcn_global_load_lds((const unsigned*)((const char*)(gbase) + (voff)[_i]), (PG8_LAS unsigned*)(lds + (bufoff) + ldsw + _i * 8192), 16, 0, 0); } while (0)
; #define PG8_LDA(dst, b, h) do { _Pragma("unroll") for (int m = 0; m < 4; ++m) _Pragma("unroll") for (int k = 0; k < 2; ++k) dst[m][k] = *(const PG8_LAS bf16x8*)(lds + PG8_SA(b, h) + aoff + m * 2048 + k * 1024); } while (0)
; #define PG8_LDB(dst, b, h) do { _Pragma("unroll") for (int n = 0; n < 2; ++n) _Pragma("unroll") for (int k = 0; k < 2; ++k) dst[n][k] = *(const PG8_LAS bf16x8*)(lds + PG8_SB(b, h) + boff + n * 2048 + k * 1024); } while (0)
; #define PG8_MMA(ai, bj, At, Bt) do { __builtin_amdgcn_s_setprio(1); _Pragma("unroll") for (int m = 0; m < 4; ++m) _Pragma("unroll") for (int n = 0; n < 2; ++n) _Pragma("unroll") for (int k = 0; k < 2; ++k) \
;         acc[ai][bj][m][n] = mma16(Bt[n][k], At[m][k], acc[ai][bj][m][n]); __builtin_amdgcn_s_setprio(0); } while (0)
; template <class Epi, class Sched, bool ALIGN_EPI = false, bool SP2 = false>
; __device__ __forceinline__ void gemm_phase(PG8_LAS unsigned char* lds, const Gemm g, const Sched& S, const Epi& E) {
;     ...
;         const bool has_next = S.next(ui + 1, nxt);
;         const char* nA = has_next ? PG8_ABASE(nxt) : cA; const char* nB = has_next ? PG8_BBASE(nxt) : cB;
; #pragma unroll 1
;         for (int t = 0; t < nt; t += 2) {
;             const bool last = (t == nt - 2);
;             const char* a1 = cA + (size_t)(t + 1) * kstep;
;             const char* a2 = last ? nA : cA + (size_t)(t + 2) * kstep; const char* b2 = last ? nB : cB + (size_t)(t + 2) * kstep;
;             const char* a3 = a2 + kstep; const char* b3 = b2 + kstep;
;             if (last && has_next) S.a_ready(nxt);
;             if constexpr (SP2) {
;             PG8_LDB(B0, 0, 0); PG8_LDB(B1, 0, 1); PG8_SCHED; PG8_LDA(At, 0, 0); PG8_STAGE(PG8_SA(1, 1), a1 + hstepA, voffA);
;             PG8_WAIT_V(8); PG8_WAIT_L(0); PG8_BAR; PG8_MMA(0, 0, At, B0); PG8_MMA(0, 1, At, B1); PG8_BAR; PG8_SCHED;
;             PG8_LDA(At, 0, 1); PG8_STAGE(PG8_SB(0, 0), b2, voffB); PG8_STAGE(PG8_SB(0, 1), b2 + hstepB, voffB); PG8_STAGE(PG8_SA(0, 0), a2, voffA);
;             PG8_WAIT_V(8); PG8_WAIT_L(0); PG8_BAR; PG8_MMA(1, 0, At, B0); PG8_MMA(1, 1, At, B1); PG8_BAR; PG8_SCHED;
.LBB0_840:
	s_ashr_i32 s49, s48, 31
	s_lshl_b64 s[50:51], s[48:49], 20
	s_add_u32 s47, s38, s50
	s_addc_u32 s52, s39, s51
	s_ashr_i32 s50, s46, 30
	s_ashr_i32 s51, s50, 31
	s_lshl_b64 s[50:51], s[50:51], 12
	s_add_u32 s50, s47, s50
	s_addc_u32 s51, s52, s51
	s_and_b64 s[52:53], s[4:5], exec
	s_cselect_b32 s62, s51, s57
	s_cselect_b32 s63, s50, s56
	s_ashr_i32 s47, s46, 31
	s_lshl_b64 s[52:53], s[46:47], 20
	s_add_u32 s52, s96, s52
	s_addc_u32 s53, s97, s53
	s_and_b64 s[60:61], s[4:5], exec
	s_cselect_b32 s64, s53, s59
	s_cselect_b32 s65, s52, s58
	s_add_u32 s56, s56, 0x80080
	s_addc_u32 s57, s57, 0
	s_add_u32 s66, s58, 0x100
	s_addc_u32 s67, s59, 0
	s_mov_b32 s68, -2
	ds_read_b128 v[90:93], v173
	ds_read_b128 v[94:97], v173 offset:1024
	ds_read_b128 v[98:101], v173 offset:2048
	ds_read_b128 v[106:109], v173 offset:3072
	ds_read_b128 v[182:185], v174
	ds_read_b128 v[186:189], v174 offset:1024
	ds_read_b128 v[190:193], v174 offset:2048
	ds_read_b128 v[194:197], v174 offset:3072
	s_add_u32 s58, s56, 0xfff80080
	s_addc_u32 s59, s57, -1
	s_cmp_eq_u32 s68, 28
	s_cselect_b32 s61, s62, s59
	s_cselect_b32 s60, s63, s58
	s_cselect_b32 s59, s64, s67
	s_cselect_b32 s58, s65, s66
	v_lshl_add_u64 v[166:167], s[56:57], 0, v[158:159]
	s_add_i32 m0, s12, 0xc000
	ds_read_b128 v[198:201], v175
	ds_read_b128 v[202:205], v175 offset:1024
	ds_read_b128 v[206:209], v175 offset:2048
	ds_read_b128 v[212:215], v175 offset:3072
	ds_read_b128 v[216:219], v175 offset:4096
	ds_read_b128 v[220:223], v175 offset:5120
	ds_read_b128 v[224:227], v175 offset:6144
	ds_read_b128 v[228:231], v175 offset:7168
	global_load_lds_dwordx4 v[166:167], off
	v_lshl_add_u64 v[166:167], s[56:57], 0, v[160:161]
	s_add_i32 m0, s12, 0xe000
	s_nop 0
	global_load_lds_dwordx4 v[166:167], off
	s_waitcnt vmcnt(8)
	s_waitcnt lgkmcnt(0)
	s_barrier
	s_setprio 1
	s_waitcnt lgkmcnt(0)
	v_mfma_i32_16x16x64_i8 v[142:145], v[90:93], v[198:201], 0
	v_mfma_i32_16x16x64_i8 v[142:145], v[94:97], v[202:205], v[142:145]
	v_mfma_i32_16x16x64_i8 v[138:141], v[106:109], v[202:205], 0
	v_mfma_i32_16x16x64_i8 v[138:141], v[98:101], v[198:201], v[138:141]
	v_mfma_i32_16x16x64_i8 v[122:125], v[98:101], v[206:209], 0
	v_mfma_i32_16x16x64_i8 v[122:125], v[106:109], v[212:215], v[122:125]
	v_mfma_i32_16x16x64_i8 v[126:129], v[94:97], v[212:215], 0
	v_mfma_i32_16x16x64_i8 v[126:129], v[90:93], v[206:209], v[126:129]
	v_mfma_i32_16x16x64_i8 v[110:113], v[90:93], v[216:219], 0
	v_mfma_i32_16x16x64_i8 v[110:113], v[94:97], v[220:223], v[110:113]
	v_mfma_i32_16x16x64_i8 v[102:105], v[106:109], v[220:223], 0
	v_mfma_i32_16x16x64_i8 v[102:105], v[98:101], v[216:219], v[102:105]
	v_mfma_i32_16x16x64_i8 v[74:77], v[98:101], v[224:227], 0
	v_mfma_i32_16x16x64_i8 v[74:77], v[106:109], v[228:231], v[74:77]
	v_mfma_i32_16x16x64_i8 v[78:81], v[94:97], v[228:231], 0
	v_mfma_i32_16x16x64_i8 v[78:81], v[90:93], v[224:227], v[78:81]
	s_setprio 0
	s_setprio 1
	v_mfma_i32_16x16x64_i8 v[70:73], v[182:185], v[224:227], 0
	v_mfma_i32_16x16x64_i8 v[70:73], v[186:189], v[228:231], v[70:73]
	v_mfma_i32_16x16x64_i8 v[66:69], v[194:197], v[228:231], 0
	v_mfma_i32_16x16x64_i8 v[66:69], v[190:193], v[224:227], v[66:69]
	v_mfma_i32_16x16x64_i8 v[82:85], v[190:193], v[216:219], 0
	v_mfma_i32_16x16x64_i8 v[82:85], v[194:197], v[220:223], v[82:85]
	v_mfma_i32_16x16x64_i8 v[86:89], v[186:189], v[220:223], 0
	v_mfma_i32_16x16x64_i8 v[86:89], v[182:185], v[216:219], v[86:89]
	v_mfma_i32_16x16x64_i8 v[118:121], v[182:185], v[206:209], 0
	v_mfma_i32_16x16x64_i8 v[118:121], v[186:189], v[212:215], v[118:121]
	v_mfma_i32_16x16x64_i8 v[114:117], v[194:197], v[212:215], 0
	v_mfma_i32_16x16x64_i8 v[114:117], v[190:193], v[206:209], v[114:117]
	v_mfma_i32_16x16x64_i8 v[130:133], v[190:193], v[198:201], 0
	v_mfma_i32_16x16x64_i8 v[130:133], v[194:197], v[202:205], v[130:133]
	v_mfma_i32_16x16x64_i8 v[134:137], v[186:189], v[202:205], 0
	v_mfma_i32_16x16x64_i8 v[134:137], v[182:185], v[198:201], v[134:137]
	s_setprio 0
	s_barrier
	s_add_i32 s69, s27, s6
	v_lshl_add_u64 v[166:167], s[58:59], 0, v[150:151]
	s_mov_b32 m0, s69
	ds_read_b128 v[198:201], v175 offset:16384
	ds_read_b128 v[202:205], v175 offset:17408
	ds_read_b128 v[206:209], v175 offset:18432
	ds_read_b128 v[212:215], v175 offset:19456
	ds_read_b128 v[216:219], v175 offset:20480
	ds_read_b128 v[220:223], v175 offset:21504
	ds_read_b128 v[224:227], v175 offset:22528
	ds_read_b128 v[228:231], v175 offset:23552
	global_load_lds_dwordx4 v[166:167], off
	s_add_i32 m0, s69, 0x2000
	s_add_u32 s70, s58, 0x80000
	v_lshl_add_u64 v[176:177], s[58:59], 0, v[146:147]
	s_addc_u32 s71, s59, 0
	s_add_i32 s69, s28, s6
	global_load_lds_dwordx4 v[176:177], off
	v_lshl_add_u64 v[232:233], s[70:71], 0, v[150:151]
	s_mov_b32 m0, s69
	v_lshl_add_u64 v[234:235], s[60:61], 0, v[148:149]
	global_load_lds_dwordx4 v[232:233], off
	v_lshl_add_u64 v[232:233], s[70:71], 0, v[146:147]
	s_add_i32 m0, s69, 0x2000
	s_nop 0
	global_load_lds_dwordx4 v[232:233], off
	v_lshl_add_u64 v[232:233], s[60:61], 0, v[152:153]
	s_mov_b32 m0, s12
	s_nop 0
	global_load_lds_dwordx4 v[232:233], off
	s_mov_b32 m0, s13
	s_nop 0
	global_load_lds_dwordx4 v[234:235], off
	s_waitcnt vmcnt(8)
	s_waitcnt lgkmcnt(0)
	s_barrier
; #define PG8_STAGE(bufoff, gbase, voff) do { _Pragma("unroll") for (int _i = 0; _i < 2; ++_i) \
;         __builtin_amdgcn_global_load_lds((const unsigned*)((const char*)(gbase) + (voff)[_i]), (PG8_LAS unsigned*)(lds + (bufoff) + ldsw + _i * 8192), 16, 0, 0); } while (0)
; #define PG8_LDA(dst, b, h) do { _Pragma("unroll") for (int m = 0; m < 4; ++m) _Pragma("unroll") for (int k = 0; k < 2; ++k) dst[m][k] = *(const PG8_LAS bf16x8*)(lds + PG8_SA(b, h) + aoff + m * 2048 + k * 1024); } while (0)
; #define PG8_LDB(dst, b, h) do { _Pragma("unroll") for (int n = 0; n < 2; ++n) _Pragma("unroll") for (int k = 0; k < 2; ++k) dst[n][k] = *(const PG8_LAS bf16x8*)(lds + PG8_SB(b, h) + boff + n * 2048 + k * 1024); } while (0)
; #define PG8_MMA(ai, bj, At, Bt) do { __builtin_amdgcn_s_setprio(1); _Pragma("unroll") for (int m = 0; m < 4; ++m) _Pragma("unroll") for (int n = 0; n < 2; ++n) _Pragma("unroll") for (int k = 0; k < 2; ++k) \
;         acc[ai][bj][m][n] = mma16(Bt[n][k], At[m][k], acc[ai][bj][m][n]); __builtin_amdgcn_s_setprio(0); } while (0)
; #define PG8_WAIT_V(n) asm volatile("s_waitcnt vmcnt(" #n ")" ::: "memory")
; #define PG8_WAIT_L(n) asm volatile("s_waitcnt lgkmcnt(" #n ")" ::: "memory")
; #define PG8_BAR __builtin_amdgcn_s_barrier()
; #define PG8_SCHED __builtin_amdgcn_sched_barrier(0)
; template <class Epi, class Sched, bool ALIGN_EPI = false, bool SP2 = false>
; __device__ __forceinline__ void gemm_phase(PG8_LAS unsigned char* lds, const Gemm g, const Sched& S, const Epi& E) {
;     ...
;             PG8_WAIT_V(8); PG8_WAIT_L(0); PG8_BAR; PG8_MMA(1, 0, At, B0); PG8_MMA(1, 1, At, B1); PG8_BAR; PG8_SCHED;
;             PG8_LDB(B0, 1, 0); PG8_LDB(B1, 1, 1); PG8_SCHED; PG8_LDA(At, 1, 0); PG8_STAGE(PG8_SA(0, 1), a2 + hstepA, voffA);
;             PG8_WAIT_V(8); PG8_WAIT_L(0); PG8_BAR; PG8_MMA(0, 0, At, B0); PG8_MMA(0, 1, At, B1); PG8_BAR; PG8_SCHED;
	s_setprio 1
	s_waitcnt lgkmcnt(0)
	v_mfma_i32_16x16x64_i8 v[62:65], v[90:93], v[198:201], 0
	v_mfma_i32_16x16x64_i8 v[62:65], v[94:97], v[202:205], v[62:65]
	v_mfma_i32_16x16x64_i8 v[58:61], v[106:109], v[202:205], 0
	v_mfma_i32_16x16x64_i8 v[58:61], v[98:101], v[198:201], v[58:61]
	v_mfma_i32_16x16x64_i8 v[42:45], v[98:101], v[206:209], 0
	v_mfma_i32_16x16x64_i8 v[42:45], v[106:109], v[212:215], v[42:45]
	v_mfma_i32_16x16x64_i8 v[46:49], v[94:97], v[212:215], 0
	v_mfma_i32_16x16x64_i8 v[46:49], v[90:93], v[206:209], v[46:49]
	v_mfma_i32_16x16x64_i8 v[30:33], v[90:93], v[216:219], 0
	v_mfma_i32_16x16x64_i8 v[30:33], v[94:97], v[220:223], v[30:33]
	v_mfma_i32_16x16x64_i8 v[26:29], v[106:109], v[220:223], 0
	v_mfma_i32_16x16x64_i8 v[26:29], v[98:101], v[216:219], v[26:29]
	v_mfma_i32_16x16x64_i8 v[10:13], v[98:101], v[224:227], 0
	v_mfma_i32_16x16x64_i8 v[10:13], v[106:109], v[228:231], v[10:13]
	v_mfma_i32_16x16x64_i8 v[14:17], v[94:97], v[228:231], 0
	v_mfma_i32_16x16x64_i8 v[14:17], v[90:93], v[224:227], v[14:17]
	s_setprio 0
	s_setprio 1
	v_mfma_i32_16x16x64_i8 v[6:9], v[182:185], v[224:227], 0
	v_mfma_i32_16x16x64_i8 v[6:9], v[186:189], v[228:231], v[6:9]
	v_mfma_i32_16x16x64_i8 v[2:5], v[194:197], v[228:231], 0
	v_mfma_i32_16x16x64_i8 v[2:5], v[190:193], v[224:227], v[2:5]
	v_mfma_i32_16x16x64_i8 v[18:21], v[190:193], v[216:219], 0
	v_mfma_i32_16x16x64_i8 v[18:21], v[194:197], v[220:223], v[18:21]
	v_mfma_i32_16x16x64_i8 v[22:25], v[186:189], v[220:223], 0
	v_mfma_i32_16x16x64_i8 v[22:25], v[182:185], v[216:219], v[22:25]
	v_mfma_i32_16x16x64_i8 v[38:41], v[182:185], v[206:209], 0
	v_mfma_i32_16x16x64_i8 v[38:41], v[186:189], v[212:215], v[38:41]
	v_mfma_i32_16x16x64_i8 v[34:37], v[194:197], v[212:215], 0
	v_mfma_i32_16x16x64_i8 v[34:37], v[190:193], v[206:209], v[34:37]
	v_mfma_i32_16x16x64_i8 v[50:53], v[190:193], v[198:201], 0
	v_mfma_i32_16x16x64_i8 v[50:53], v[194:197], v[202:205], v[50:53]
	v_mfma_i32_16x16x64_i8 v[54:57], v[186:189], v[202:205], 0
	v_mfma_i32_16x16x64_i8 v[54:57], v[182:185], v[198:201], v[54:57]
	s_setprio 0
	s_barrier
	s_add_i32 s69, 0, 0x18000
	s_add_i32 s70, 0, 0x1c000
	v_add_u32_e32 v106, s69, v171
	v_add_u32_e32 v181, s70, v171
	ds_read_b128 v[90:93], v106
	ds_read_b128 v[94:97], v106 offset:1024
	ds_read_b128 v[98:101], v106 offset:2048
	ds_read_b128 v[106:109], v106 offset:3072
	ds_read_b128 v[182:185], v181
	ds_read_b128 v[186:189], v181 offset:1024
	ds_read_b128 v[190:193], v181 offset:2048
	ds_read_b128 v[194:197], v181 offset:3072
	s_add_u32 s60, s60, 0x80000
	s_addc_u32 s61, s61, 0
	s_mov_b32 m0, s16
	v_lshl_add_u64 v[236:237], s[60:61], 0, v[152:153]
	ds_read_b128 v[198:201], v175 offset:32768
	ds_read_b128 v[202:205], v175 offset:33792
	ds_read_b128 v[206:209], v175 offset:34816
	ds_read_b128 v[212:215], v175 offset:35840
	ds_read_b128 v[216:219], v175 offset:36864
	ds_read_b128 v[220:223], v175 offset:37888
	ds_read_b128 v[224:227], v175 offset:38912
	ds_read_b128 v[228:231], v175 offset:39936
	global_load_lds_dwordx4 v[236:237], off
	v_lshl_add_u64 v[236:237], s[60:61], 0, v[148:149]
	s_mov_b32 m0, s17
	s_nop 0
	global_load_lds_dwordx4 v[236:237], off
	s_waitcnt vmcnt(8)
	s_waitcnt lgkmcnt(0)
	s_barrier
	s_setprio 1
	s_waitcnt lgkmcnt(0)
	v_mfma_i32_16x16x64_i8 v[142:145], v[90:93], v[198:201], v[142:145]
	v_mfma_i32_16x16x64_i8 v[142:145], v[94:97], v[202:205], v[142:145]
	v_mfma_i32_16x16x64_i8 v[138:141], v[106:109], v[202:205], v[138:141]
	v_mfma_i32_16x16x64_i8 v[138:141], v[98:101], v[198:201], v[138:141]
	v_mfma_i32_16x16x64_i8 v[122:125], v[98:101], v[206:209], v[122:125]
	v_mfma_i32_16x16x64_i8 v[122:125], v[106:109], v[212:215], v[122:125]
	v_mfma_i32_16x16x64_i8 v[126:129], v[94:97], v[212:215], v[126:129]
	v_mfma_i32_16x16x64_i8 v[126:129], v[90:93], v[206:209], v[126:129]
	v_mfma_i32_16x16x64_i8 v[110:113], v[90:93], v[216:219], v[110:113]
	v_mfma_i32_16x16x64_i8 v[110:113], v[94:97], v[220:223], v[110:113]
	v_mfma_i32_16x16x64_i8 v[102:105], v[106:109], v[220:223], v[102:105]
	v_mfma_i32_16x16x64_i8 v[102:105], v[98:101], v[216:219], v[102:105]
	v_mfma_i32_16x16x64_i8 v[74:77], v[98:101], v[224:227], v[74:77]
	v_mfma_i32_16x16x64_i8 v[74:77], v[106:109], v[228:231], v[74:77]
	v_mfma_i32_16x16x64_i8 v[78:81], v[94:97], v[228:231], v[78:81]
	v_mfma_i32_16x16x64_i8 v[78:81], v[90:93], v[224:227], v[78:81]
	s_setprio 0
	s_setprio 1
	v_mfma_i32_16x16x64_i8 v[70:73], v[182:185], v[224:227], v[70:73]
	v_mfma_i32_16x16x64_i8 v[70:73], v[186:189], v[228:231], v[70:73]
	v_mfma_i32_16x16x64_i8 v[66:69], v[194:197], v[228:231], v[66:69]
	v_mfma_i32_16x16x64_i8 v[66:69], v[190:193], v[224:227], v[66:69]
	v_mfma_i32_16x16x64_i8 v[82:85], v[190:193], v[216:219], v[82:85]
	v_mfma_i32_16x16x64_i8 v[82:85], v[194:197], v[220:223], v[82:85]
	v_mfma_i32_16x16x64_i8 v[86:89], v[186:189], v[220:223], v[86:89]
	v_mfma_i32_16x16x64_i8 v[86:89], v[182:185], v[216:219], v[86:89]
	v_mfma_i32_16x16x64_i8 v[118:121], v[182:185], v[206:209], v[118:121]
	v_mfma_i32_16x16x64_i8 v[118:121], v[186:189], v[212:215], v[118:121]
	v_mfma_i32_16x16x64_i8 v[114:117], v[194:197], v[212:215], v[114:117]
	v_mfma_i32_16x16x64_i8 v[114:117], v[190:193], v[206:209], v[114:117]
	v_mfma_i32_16x16x64_i8 v[130:133], v[190:193], v[198:201], v[130:133]
	v_mfma_i32_16x16x64_i8 v[130:133], v[194:197], v[202:205], v[130:133]
	v_mfma_i32_16x16x64_i8 v[134:137], v[186:189], v[202:205], v[134:137]
	v_mfma_i32_16x16x64_i8 v[134:137], v[182:185], v[198:201], v[134:137]
	s_setprio 0
	s_barrier
; #define PG8_STAGE(bufoff, gbase, voff) do { _Pragma("unroll") for (int _i = 0; _i < 2; ++_i) \
;         __builtin_amdgcn_global_load_lds((const unsigned*)((const char*)(gbase) + (voff)[_i]), (PG8_LAS unsigned*)(lds + (bufoff) + ldsw + _i * 8192), 16, 0, 0); } while (0)
; #define PG8_LDA(dst, b, h) do { _Pragma("unroll") for (int m = 0; m < 4; ++m) _Pragma("unroll") for (int k = 0; k < 2; ++k) dst[m][k] = *(const PG8_LAS bf16x8*)(lds + PG8_SA(b, h) + aoff + m * 2048 + k * 1024); } while (0)
; #define PG8_LDB(dst, b, h) do { _Pragma("unroll") for (int n = 0; n < 2; ++n) _Pragma("unroll") for (int k = 0; k < 2; ++k) dst[n][k] = *(const PG8_LAS bf16x8*)(lds + PG8_SB(b, h) + boff + n * 2048 + k * 1024); } while (0)
; #define PG8_MMA(ai, bj, At, Bt) do { __builtin_amdgcn_s_setprio(1); _Pragma("unroll") for (int m = 0; m < 4; ++m) _Pragma("unroll") for (int n = 0; n < 2; ++n) _Pragma("unroll") for (int k = 0; k < 2; ++k) \
;         acc[ai][bj][m][n] = mma16(Bt[n][k], At[m][k], acc[ai][bj][m][n]); __builtin_amdgcn_s_setprio(0); } while (0)
; #define PG8_WAIT_V(n) asm volatile("s_waitcnt vmcnt(" #n ")" ::: "memory")
; template <class Epi, class Sched, bool ALIGN_EPI = false, bool SP2 = false>
; __device__ __forceinline__ void gemm_phase(PG8_LAS unsigned char* lds, const Gemm g, const Sched& S, const Epi& E) {
;     ...
;         for (int t = 0; t < nt; t += 2) {
;     ...
;             PG8_LDB(B0, 0, 0); PG8_LDB(B1, 0, 1); PG8_SCHED; PG8_LDA(At, 0, 0); PG8_STAGE(PG8_SA(1, 1), a1 + hstepA, voffA);
;             PG8_WAIT_V(8); PG8_WAIT_L(0); PG8_BAR; PG8_MMA(0, 0, At, B0); PG8_MMA(0, 1, At, B1); PG8_BAR; PG8_SCHED;
;             PG8_LDA(At, 0, 1); PG8_STAGE(PG8_SB(0, 0), b2, voffB); PG8_STAGE(PG8_SB(0, 1), b2 + hstepB, voffB); PG8_STAGE(PG8_SA(0, 0), a2, voffA);
;             PG8_WAIT_V(8); PG8_WAIT_L(0); PG8_BAR; PG8_MMA(1, 0, At, B0); PG8_MMA(1, 1, At, B1); PG8_BAR; PG8_SCHED;
;             PG8_LDB(B0, 1, 0); PG8_LDB(B1, 1, 1); PG8_SCHED; PG8_LDA(At, 1, 0); PG8_STAGE(PG8_SA(0, 1), a2 + hstepA, voffA);
;             PG8_WAIT_V(8); PG8_WAIT_L(0); PG8_BAR; PG8_MMA(0, 0, At, B0); PG8_MMA(0, 1, At, B1); PG8_BAR; PG8_SCHED;
;             PG8_LDA(At, 1, 1); PG8_STAGE(PG8_SB(1, 0), b3, voffB); PG8_STAGE(PG8_SB(1, 1), b3 + hstepB, voffB); PG8_STAGE(PG8_SA(1, 0), a3, voffA);
;             PG8_WAIT_V(8); PG8_WAIT_L(0); PG8_BAR; PG8_MMA(1, 0, At, B0); PG8_MMA(1, 1, At, B1); PG8_BAR; PG8_SCHED;
	s_add_i32 s60, s69, s6
	v_lshl_add_u64 v[166:167], v[166:167], 0, s[36:37]
	s_mov_b32 m0, s60
	ds_read_b128 v[198:201], v175 offset:49152
	ds_read_b128 v[202:205], v175 offset:50176
	ds_read_b128 v[206:209], v175 offset:51200
	ds_read_b128 v[212:215], v175 offset:52224
	ds_read_b128 v[216:219], v175 offset:53248
	ds_read_b128 v[220:223], v175 offset:54272
	ds_read_b128 v[224:227], v175 offset:55296
	ds_read_b128 v[228:231], v175 offset:56320
	global_load_lds_dwordx4 v[166:167], off
	s_add_i32 m0, s60, 0x2000
	s_add_u32 s58, s58, 0x80080
	v_lshl_add_u64 v[166:167], v[176:177], 0, s[36:37]
	s_addc_u32 s59, s59, 0
	s_add_i32 s60, s70, s6
	global_load_lds_dwordx4 v[166:167], off
	v_lshl_add_u64 v[166:167], s[58:59], 0, v[150:151]
	s_mov_b32 m0, s60
	s_nop 0
	global_load_lds_dwordx4 v[166:167], off
	v_lshl_add_u64 v[166:167], s[58:59], 0, v[146:147]
	s_add_i32 m0, s60, 0x2000
	s_nop 0
	global_load_lds_dwordx4 v[166:167], off
	v_lshl_add_u64 v[166:167], v[232:233], 0, s[36:37]
	s_mov_b32 m0, s24
	s_nop 0
	global_load_lds_dwordx4 v[166:167], off
	v_lshl_add_u64 v[166:167], v[234:235], 0, s[36:37]
	s_mov_b32 m0, s25
	s_nop 0
	global_load_lds_dwordx4 v[166:167], off
	s_waitcnt vmcnt(8)
	s_waitcnt lgkmcnt(0)
	s_barrier
	s_setprio 1
	s_waitcnt lgkmcnt(0)
	v_mfma_i32_16x16x64_i8 v[62:65], v[90:93], v[198:201], v[62:65]
	v_mfma_i32_16x16x64_i8 v[62:65], v[94:97], v[202:205], v[62:65]
	v_mfma_i32_16x16x64_i8 v[58:61], v[106:109], v[202:205], v[58:61]
	v_mfma_i32_16x16x64_i8 v[58:61], v[98:101], v[198:201], v[58:61]
	v_mfma_i32_16x16x64_i8 v[42:45], v[98:101], v[206:209], v[42:45]
	v_mfma_i32_16x16x64_i8 v[42:45], v[106:109], v[212:215], v[42:45]
	v_mfma_i32_16x16x64_i8 v[46:49], v[94:97], v[212:215], v[46:49]
	v_mfma_i32_16x16x64_i8 v[46:49], v[90:93], v[206:209], v[46:49]
	v_mfma_i32_16x16x64_i8 v[30:33], v[90:93], v[216:219], v[30:33]
	v_mfma_i32_16x16x64_i8 v[30:33], v[94:97], v[220:223], v[30:33]
	v_mfma_i32_16x16x64_i8 v[26:29], v[106:109], v[220:223], v[26:29]
	v_mfma_i32_16x16x64_i8 v[26:29], v[98:101], v[216:219], v[26:29]
	v_mfma_i32_16x16x64_i8 v[10:13], v[98:101], v[224:227], v[10:13]
	v_mfma_i32_16x16x64_i8 v[10:13], v[106:109], v[228:231], v[10:13]
	v_mfma_i32_16x16x64_i8 v[14:17], v[94:97], v[228:231], v[14:17]
	v_mfma_i32_16x16x64_i8 v[14:17], v[90:93], v[224:227], v[14:17]
	s_setprio 0
	s_setprio 1
	v_mfma_i32_16x16x64_i8 v[6:9], v[182:185], v[224:227], v[6:9]
	v_mfma_i32_16x16x64_i8 v[6:9], v[186:189], v[228:231], v[6:9]
	v_mfma_i32_16x16x64_i8 v[2:5], v[194:197], v[228:231], v[2:5]
	v_mfma_i32_16x16x64_i8 v[2:5], v[190:193], v[224:227], v[2:5]
	v_mfma_i32_16x16x64_i8 v[18:21], v[190:193], v[216:219], v[18:21]
	v_mfma_i32_16x16x64_i8 v[18:21], v[194:197], v[220:223], v[18:21]
	v_mfma_i32_16x16x64_i8 v[22:25], v[186:189], v[220:223], v[22:25]
	v_mfma_i32_16x16x64_i8 v[22:25], v[182:185], v[216:219], v[22:25]
	v_mfma_i32_16x16x64_i8 v[38:41], v[182:185], v[206:209], v[38:41]
	v_mfma_i32_16x16x64_i8 v[38:41], v[186:189], v[212:215], v[38:41]
	v_mfma_i32_16x16x64_i8 v[34:37], v[194:197], v[212:215], v[34:37]
	v_mfma_i32_16x16x64_i8 v[34:37], v[190:193], v[206:209], v[34:37]
	v_mfma_i32_16x16x64_i8 v[50:53], v[190:193], v[198:201], v[50:53]
	v_mfma_i32_16x16x64_i8 v[50:53], v[194:197], v[202:205], v[50:53]
	v_mfma_i32_16x16x64_i8 v[54:57], v[186:189], v[202:205], v[54:57]
	v_mfma_i32_16x16x64_i8 v[54:57], v[182:185], v[198:201], v[54:57]
	s_setprio 0
	s_barrier
	s_add_i32 s68, s68, 2
	s_add_u32 s56, s56, 0x100
	s_addc_u32 s57, s57, 0
	s_add_u32 s66, s66, 0x100
	s_addc_u32 s67, s67, 0
.LBB0_841:
	ds_read_b128 v[90:93], v173
	ds_read_b128 v[94:97], v173 offset:1024
	ds_read_b128 v[98:101], v173 offset:2048
	ds_read_b128 v[106:109], v173 offset:3072
	ds_read_b128 v[182:185], v174
	ds_read_b128 v[186:189], v174 offset:1024
	ds_read_b128 v[190:193], v174 offset:2048
	ds_read_b128 v[194:197], v174 offset:3072
	s_add_u32 s58, s56, 0xfff80080
	s_addc_u32 s59, s57, -1
	s_cmp_eq_u32 s68, 28
	s_cselect_b32 s61, s62, s59
	s_cselect_b32 s60, s63, s58
	s_cselect_b32 s59, s64, s67
	s_cselect_b32 s58, s65, s66
	v_lshl_add_u64 v[166:167], s[56:57], 0, v[158:159]
	s_add_i32 m0, s12, 0xc000
	ds_read_b128 v[198:201], v175
	ds_read_b128 v[202:205], v175 offset:1024
	ds_read_b128 v[206:209], v175 offset:2048
	ds_read_b128 v[212:215], v175 offset:3072
	ds_read_b128 v[216:219], v175 offset:4096
	ds_read_b128 v[220:223], v175 offset:5120
	ds_read_b128 v[224:227], v175 offset:6144
	ds_read_b128 v[228:231], v175 offset:7168
	global_load_lds_dwordx4 v[166:167], off
	v_lshl_add_u64 v[166:167], s[56:57], 0, v[160:161]
	s_add_i32 m0, s12, 0xe000
	s_nop 0
	global_load_lds_dwordx4 v[166:167], off
	s_waitcnt vmcnt(8)
	s_waitcnt lgkmcnt(0)
	s_barrier
; #define PG8_STAGE(bufoff, gbase, voff) do { _Pragma("unroll") for (int _i = 0; _i < 2; ++_i) \
;         __builtin_amdgcn_global_load_lds((const unsigned*)((const char*)(gbase) + (voff)[_i]), (PG8_LAS unsigned*)(lds + (bufoff) + ldsw + _i * 8192), 16, 0, 0); } while (0)
; #define PG8_LDA(dst, b, h) do { _Pragma("unroll") for (int m = 0; m < 4; ++m) _Pragma("unroll") for (int k = 0; k < 2; ++k) dst[m][k] = *(const PG8_LAS bf16x8*)(lds + PG8_SA(b, h) + aoff + m * 2048 + k * 1024); } while (0)
; #define PG8_LDB(dst, b, h) do { _Pragma("unroll") for (int n = 0; n < 2; ++n) _Pragma("unroll") for (int k = 0; k < 2; ++k) dst[n][k] = *(const PG8_LAS bf16x8*)(lds + PG8_SB(b, h) + boff + n * 2048 + k * 1024); } while (0)
; #define PG8_MMA(ai, bj, At, Bt) do { __builtin_amdgcn_s_setprio(1); _Pragma("unroll") for (int m = 0; m < 4; ++m) _Pragma("unroll") for (int n = 0; n < 2; ++n) _Pragma("unroll") for (int k = 0; k < 2; ++k) \
;         acc[ai][bj][m][n] = mma16(Bt[n][k], At[m][k], acc[ai][bj][m][n]); __builtin_amdgcn_s_setprio(0); } while (0)
; #define PG8_WAIT_V(n) asm volatile("s_waitcnt vmcnt(" #n ")" ::: "memory")
; #define PG8_WAIT_L(n) asm volatile("s_waitcnt lgkmcnt(" #n ")" ::: "memory")
; #define PG8_BAR __builtin_amdgcn_s_barrier()
; #define PG8_SCHED __builtin_amdgcn_sched_barrier(0)
; template <class Epi, class Sched, bool ALIGN_EPI = false, bool SP2 = false>
; __device__ __forceinline__ void gemm_phase(PG8_LAS unsigned char* lds, const Gemm g, const Sched& S, const Epi& E) {
;     ...
;             PG8_WAIT_V(8); PG8_WAIT_L(0); PG8_BAR; PG8_MMA(0, 0, At, B0); PG8_MMA(0, 1, At, B1); PG8_BAR; PG8_SCHED;
;             PG8_LDA(At, 0, 1); PG8_STAGE(PG8_SB(0, 0), b2, voffB); PG8_STAGE(PG8_SB(0, 1), b2 + hstepB, voffB); PG8_STAGE(PG8_SA(0, 0), a2, voffA);
;             PG8_WAIT_V(8); PG8_WAIT_L(0); PG8_BAR; PG8_MMA(1, 0, At, B0); PG8_MMA(1, 1, At, B1); PG8_BAR; PG8_SCHED;
;             PG8_LDB(B0, 1, 0); PG8_LDB(B1, 1, 1); PG8_SCHED; PG8_LDA(At, 1, 0); PG8_STAGE(PG8_SA(0, 1), a2 + hstepA, voffA);
;             PG8_WAIT_V(8); PG8_WAIT_L(0); PG8_BAR; PG8_MMA(0, 0, At, B0); PG8_MMA(0, 1, At, B1); PG8_BAR; PG8_SCHED;
	s_setprio 1
	s_waitcnt lgkmcnt(0)
	v_mfma_i32_16x16x64_i8 v[142:145], v[90:93], v[198:201], v[142:145]
	v_mfma_i32_16x16x64_i8 v[142:145], v[94:97], v[202:205], v[142:145]
	v_mfma_i32_16x16x64_i8 v[138:141], v[106:109], v[202:205], v[138:141]
	v_mfma_i32_16x16x64_i8 v[138:141], v[98:101], v[198:201], v[138:141]
	v_mfma_i32_16x16x64_i8 v[122:125], v[98:101], v[206:209], v[122:125]
	v_mfma_i32_16x16x64_i8 v[122:125], v[106:109], v[212:215], v[122:125]
	v_mfma_i32_16x16x64_i8 v[126:129], v[94:97], v[212:215], v[126:129]
	v_mfma_i32_16x16x64_i8 v[126:129], v[90:93], v[206:209], v[126:129]
	v_mfma_i32_16x16x64_i8 v[110:113], v[90:93], v[216:219], v[110:113]
	v_mfma_i32_16x16x64_i8 v[110:113], v[94:97], v[220:223], v[110:113]
	v_mfma_i32_16x16x64_i8 v[102:105], v[106:109], v[220:223], v[102:105]
	v_mfma_i32_16x16x64_i8 v[102:105], v[98:101], v[216:219], v[102:105]
	v_mfma_i32_16x16x64_i8 v[74:77], v[98:101], v[224:227], v[74:77]
	v_mfma_i32_16x16x64_i8 v[74:77], v[106:109], v[228:231], v[74:77]
	v_mfma_i32_16x16x64_i8 v[78:81], v[94:97], v[228:231], v[78:81]
	v_mfma_i32_16x16x64_i8 v[78:81], v[90:93], v[224:227], v[78:81]
	s_setprio 0
	s_setprio 1
	v_mfma_i32_16x16x64_i8 v[70:73], v[182:185], v[224:227], v[70:73]
	v_mfma_i32_16x16x64_i8 v[70:73], v[186:189], v[228:231], v[70:73]
	v_mfma_i32_16x16x64_i8 v[66:69], v[194:197], v[228:231], v[66:69]
	v_mfma_i32_16x16x64_i8 v[66:69], v[190:193], v[224:227], v[66:69]
	v_mfma_i32_16x16x64_i8 v[82:85], v[190:193], v[216:219], v[82:85]
	v_mfma_i32_16x16x64_i8 v[82:85], v[194:197], v[220:223], v[82:85]
	v_mfma_i32_16x16x64_i8 v[86:89], v[186:189], v[220:223], v[86:89]
	v_mfma_i32_16x16x64_i8 v[86:89], v[182:185], v[216:219], v[86:89]
	v_mfma_i32_16x16x64_i8 v[118:121], v[182:185], v[206:209], v[118:121]
	v_mfma_i32_16x16x64_i8 v[118:121], v[186:189], v[212:215], v[118:121]
	v_mfma_i32_16x16x64_i8 v[114:117], v[194:197], v[212:215], v[114:117]
	v_mfma_i32_16x16x64_i8 v[114:117], v[190:193], v[206:209], v[114:117]
	v_mfma_i32_16x16x64_i8 v[130:133], v[190:193], v[198:201], v[130:133]
	v_mfma_i32_16x16x64_i8 v[130:133], v[194:197], v[202:205], v[130:133]
	v_mfma_i32_16x16x64_i8 v[134:137], v[186:189], v[202:205], v[134:137]
	v_mfma_i32_16x16x64_i8 v[134:137], v[182:185], v[198:201], v[134:137]
	s_setprio 0
	s_barrier
	s_add_i32 s69, s27, s6
	v_lshl_add_u64 v[166:167], s[58:59], 0, v[150:151]
	s_mov_b32 m0, s69
	ds_read_b128 v[198:201], v175 offset:16384
	ds_read_b128 v[202:205], v175 offset:17408
	ds_read_b128 v[206:209], v175 offset:18432
	ds_read_b128 v[212:215], v175 offset:19456
	ds_read_b128 v[216:219], v175 offset:20480
	ds_read_b128 v[220:223], v175 offset:21504
	ds_read_b128 v[224:227], v175 offset:22528
	ds_read_b128 v[228:231], v175 offset:23552
	global_load_lds_dwordx4 v[166:167], off
	s_add_i32 m0, s69, 0x2000
	s_add_u32 s70, s58, 0x80000
	v_lshl_add_u64 v[176:177], s[58:59], 0, v[146:147]
	s_addc_u32 s71, s59, 0
	s_add_i32 s69, s28, s6
	global_load_lds_dwordx4 v[176:177], off
	v_lshl_add_u64 v[232:233], s[70:71], 0, v[150:151]
	s_mov_b32 m0, s69
	v_lshl_add_u64 v[234:235], s[60:61], 0, v[148:149]
	global_load_lds_dwordx4 v[232:233], off
	v_lshl_add_u64 v[232:233], s[70:71], 0, v[146:147]
	s_add_i32 m0, s69, 0x2000
	s_nop 0
	global_load_lds_dwordx4 v[232:233], off
	v_lshl_add_u64 v[232:233], s[60:61], 0, v[152:153]
	s_mov_b32 m0, s12
	s_nop 0
	global_load_lds_dwordx4 v[232:233], off
	s_mov_b32 m0, s13
	s_nop 0
	global_load_lds_dwordx4 v[234:235], off
	s_waitcnt vmcnt(8)
	s_waitcnt lgkmcnt(0)
	s_barrier
	s_setprio 1
	s_waitcnt lgkmcnt(0)
	v_mfma_i32_16x16x64_i8 v[62:65], v[90:93], v[198:201], v[62:65]
	v_mfma_i32_16x16x64_i8 v[62:65], v[94:97], v[202:205], v[62:65]
	v_mfma_i32_16x16x64_i8 v[58:61], v[106:109], v[202:205], v[58:61]
	v_mfma_i32_16x16x64_i8 v[58:61], v[98:101], v[198:201], v[58:61]
	v_mfma_i32_16x16x64_i8 v[42:45], v[98:101], v[206:209], v[42:45]
	v_mfma_i32_16x16x64_i8 v[42:45], v[106:109], v[212:215], v[42:45]
	v_mfma_i32_16x16x64_i8 v[46:49], v[94:97], v[212:215], v[46:49]
	v_mfma_i32_16x16x64_i8 v[46:49], v[90:93], v[206:209], v[46:49]
	v_mfma_i32_16x16x64_i8 v[30:33], v[90:93], v[216:219], v[30:33]
	v_mfma_i32_16x16x64_i8 v[30:33], v[94:97], v[220:223], v[30:33]
	v_mfma_i32_16x16x64_i8 v[26:29], v[106:109], v[220:223], v[26:29]
	v_mfma_i32_16x16x64_i8 v[26:29], v[98:101], v[216:219], v[26:29]
	v_mfma_i32_16x16x64_i8 v[10:13], v[98:101], v[224:227], v[10:13]
	v_mfma_i32_16x16x64_i8 v[10:13], v[106:109], v[228:231], v[10:13]
	v_mfma_i32_16x16x64_i8 v[14:17], v[94:97], v[228:231], v[14:17]
	v_mfma_i32_16x16x64_i8 v[14:17], v[90:93], v[224:227], v[14:17]
	s_setprio 0
	s_setprio 1
	v_mfma_i32_16x16x64_i8 v[6:9], v[182:185], v[224:227], v[6:9]
	v_mfma_i32_16x16x64_i8 v[6:9], v[186:189], v[228:231], v[6:9]
	v_mfma_i32_16x16x64_i8 v[2:5], v[194:197], v[228:231], v[2:5]
	v_mfma_i32_16x16x64_i8 v[2:5], v[190:193], v[224:227], v[2:5]
	v_mfma_i32_16x16x64_i8 v[18:21], v[190:193], v[216:219], v[18:21]
	v_mfma_i32_16x16x64_i8 v[18:21], v[194:197], v[220:223], v[18:21]
	v_mfma_i32_16x16x64_i8 v[22:25], v[186:189], v[220:223], v[22:25]
	v_mfma_i32_16x16x64_i8 v[22:25], v[182:185], v[216:219], v[22:25]
	v_mfma_i32_16x16x64_i8 v[38:41], v[182:185], v[206:209], v[38:41]
	v_mfma_i32_16x16x64_i8 v[38:41], v[186:189], v[212:215], v[38:41]
	v_mfma_i32_16x16x64_i8 v[34:37], v[194:197], v[212:215], v[34:37]
	v_mfma_i32_16x16x64_i8 v[34:37], v[190:193], v[206:209], v[34:37]
	v_mfma_i32_16x16x64_i8 v[50:53], v[190:193], v[198:201], v[50:53]
	v_mfma_i32_16x16x64_i8 v[50:53], v[194:197], v[202:205], v[50:53]
	v_mfma_i32_16x16x64_i8 v[54:57], v[186:189], v[202:205], v[54:57]
	v_mfma_i32_16x16x64_i8 v[54:57], v[182:185], v[198:201], v[54:57]
	s_setprio 0
	s_barrier
; #define PG8_STAGE(bufoff, gbase, voff) do { _Pragma("unroll") for (int _i = 0; _i < 2; ++_i) \
;         __builtin_amdgcn_global_load_lds((const unsigned*)((const char*)(gbase) + (voff)[_i]), (PG8_LAS unsigned*)(lds + (bufoff) + ldsw + _i * 8192), 16, 0, 0); } while (0)
; #define PG8_LDA(dst, b, h) do { _Pragma("unroll") for (int m = 0; m < 4; ++m) _Pragma("unroll") for (int k = 0; k < 2; ++k) dst[m][k] = *(const PG8_LAS bf16x8*)(lds + PG8_SA(b, h) + aoff + m * 2048 + k * 1024); } while (0)
; #define PG8_LDB(dst, b, h) do { _Pragma("unroll") for (int n = 0; n < 2; ++n) _Pragma("unroll") for (int k = 0; k < 2; ++k) dst[n][k] = *(const PG8_LAS bf16x8*)(lds + PG8_SB(b, h) + boff + n * 2048 + k * 1024); } while (0)
; #define PG8_MMA(ai, bj, At, Bt) do { __builtin_amdgcn_s_setprio(1); _Pragma("unroll") for (int m = 0; m < 4; ++m) _Pragma("unroll") for (int n = 0; n < 2; ++n) _Pragma("unroll") for (int k = 0; k < 2; ++k) \
;         acc[ai][bj][m][n] = mma16(Bt[n][k], At[m][k], acc[ai][bj][m][n]); __builtin_amdgcn_s_setprio(0); } while (0)
; #define PG8_WAIT_V(n) asm volatile("s_waitcnt vmcnt(" #n ")" ::: "memory")
; #define PG8_WAIT_L(n) asm volatile("s_waitcnt lgkmcnt(" #n ")" ::: "memory")
; #define PG8_BAR __builtin_amdgcn_s_barrier()
; #define PG8_SCHED __builtin_amdgcn_sched_barrier(0)
; template <class Epi, class Sched, bool ALIGN_EPI = false, bool SP2 = false>
; __device__ __forceinline__ void gemm_phase(PG8_LAS unsigned char* lds, const Gemm g, const Sched& S, const Epi& E) {
;     ...
;             PG8_LDB(B0, 1, 0); PG8_LDB(B1, 1, 1); PG8_SCHED; PG8_LDA(At, 1, 0); PG8_STAGE(PG8_SA(0, 1), a2 + hstepA, voffA);
;             PG8_WAIT_V(8); PG8_WAIT_L(0); PG8_BAR; PG8_MMA(0, 0, At, B0); PG8_MMA(0, 1, At, B1); PG8_BAR; PG8_SCHED;
	s_add_i32 s69, 0, 0x18000
	s_add_i32 s70, 0, 0x1c000
	v_add_u32_e32 v106, s69, v171
	v_add_u32_e32 v181, s70, v171
	ds_read_b128 v[90:93], v106
	ds_read_b128 v[94:97], v106 offset:1024
	ds_read_b128 v[98:101], v106 offset:2048
	ds_read_b128 v[106:109], v106 offset:3072
	ds_read_b128 v[182:185], v181
	ds_read_b128 v[186:189], v181 offset:1024
	ds_read_b128 v[190:193], v181 offset:2048
	ds_read_b128 v[194:197], v181 offset:3072
	s_add_u32 s60, s60, 0x80000
	s_addc_u32 s61, s61, 0
	s_mov_b32 m0, s16
	v_lshl_add_u64 v[236:237], s[60:61], 0, v[152:153]
	ds_read_b128 v[198:201], v175 offset:32768
	ds_read_b128 v[202:205], v175 offset:33792
	ds_read_b128 v[206:209], v175 offset:34816
	ds_read_b128 v[212:215], v175 offset:35840
	ds_read_b128 v[216:219], v175 offset:36864
	ds_read_b128 v[220:223], v175 offset:37888
	ds_read_b128 v[224:227], v175 offset:38912
	ds_read_b128 v[228:231], v175 offset:39936
	global_load_lds_dwordx4 v[236:237], off
	v_lshl_add_u64 v[236:237], s[60:61], 0, v[148:149]
	s_mov_b32 m0, s17
	s_nop 0
	global_load_lds_dwordx4 v[236:237], off
	s_waitcnt vmcnt(8)
	s_waitcnt lgkmcnt(0)
	s_barrier
	s_setprio 1
	s_waitcnt lgkmcnt(0)
	v_mfma_i32_16x16x64_i8 v[142:145], v[90:93], v[198:201], v[142:145]
	v_mfma_i32_16x16x64_i8 v[142:145], v[94:97], v[202:205], v[142:145]
	v_mfma_i32_16x16x64_i8 v[138:141], v[106:109], v[202:205], v[138:141]
	v_mfma_i32_16x16x64_i8 v[138:141], v[98:101], v[198:201], v[138:141]
	v_mfma_i32_16x16x64_i8 v[122:125], v[98:101], v[206:209], v[122:125]
	v_mfma_i32_16x16x64_i8 v[122:125], v[106:109], v[212:215], v[122:125]
	v_mfma_i32_16x16x64_i8 v[126:129], v[94:97], v[212:215], v[126:129]
	v_mfma_i32_16x16x64_i8 v[126:129], v[90:93], v[206:209], v[126:129]
	v_mfma_i32_16x16x64_i8 v[110:113], v[90:93], v[216:219], v[110:113]
	v_mfma_i32_16x16x64_i8 v[110:113], v[94:97], v[220:223], v[110:113]
	v_mfma_i32_16x16x64_i8 v[102:105], v[106:109], v[220:223], v[102:105]
	v_mfma_i32_16x16x64_i8 v[102:105], v[98:101], v[216:219], v[102:105]
	v_mfma_i32_16x16x64_i8 v[74:77], v[98:101], v[224:227], v[74:77]
	v_mfma_i32_16x16x64_i8 v[74:77], v[106:109], v[228:231], v[74:77]
	v_mfma_i32_16x16x64_i8 v[78:81], v[94:97], v[228:231], v[78:81]
	v_mfma_i32_16x16x64_i8 v[78:81], v[90:93], v[224:227], v[78:81]
	s_setprio 0
	s_setprio 1
	v_mfma_i32_16x16x64_i8 v[70:73], v[182:185], v[224:227], v[70:73]
	v_mfma_i32_16x16x64_i8 v[70:73], v[186:189], v[228:231], v[70:73]
	v_mfma_i32_16x16x64_i8 v[66:69], v[194:197], v[228:231], v[66:69]
	v_mfma_i32_16x16x64_i8 v[66:69], v[190:193], v[224:227], v[66:69]
	v_mfma_i32_16x16x64_i8 v[82:85], v[190:193], v[216:219], v[82:85]
	v_mfma_i32_16x16x64_i8 v[82:85], v[194:197], v[220:223], v[82:85]
	v_mfma_i32_16x16x64_i8 v[86:89], v[186:189], v[220:223], v[86:89]
	v_mfma_i32_16x16x64_i8 v[86:89], v[182:185], v[216:219], v[86:89]
	v_mfma_i32_16x16x64_i8 v[118:121], v[182:185], v[206:209], v[118:121]
	v_mfma_i32_16x16x64_i8 v[118:121], v[186:189], v[212:215], v[118:121]
	v_mfma_i32_16x16x64_i8 v[114:117], v[194:197], v[212:215], v[114:117]
	v_mfma_i32_16x16x64_i8 v[114:117], v[190:193], v[206:209], v[114:117]
	v_mfma_i32_16x16x64_i8 v[130:133], v[190:193], v[198:201], v[130:133]
	v_mfma_i32_16x16x64_i8 v[130:133], v[194:197], v[202:205], v[130:133]
	v_mfma_i32_16x16x64_i8 v[134:137], v[186:189], v[202:205], v[134:137]
	v_mfma_i32_16x16x64_i8 v[134:137], v[182:185], v[198:201], v[134:137]
	s_setprio 0
	s_barrier
; #define PG8_STAGE(bufoff, gbase, voff) do { _Pragma("unroll") for (int _i = 0; _i < 2; ++_i) \
;         __builtin_amdgcn_global_load_lds((const unsigned*)((const char*)(gbase) + (voff)[_i]), (PG8_LAS unsigned*)(lds + (bufoff) + ldsw + _i * 8192), 16, 0, 0); } while (0)
; #define PG8_LDA(dst, b, h) do { _Pragma("unroll") for (int m = 0; m < 4; ++m) _Pragma("unroll") for (int k = 0; k < 2; ++k) dst[m][k] = *(const PG8_LAS bf16x8*)(lds + PG8_SA(b, h) + aoff + m * 2048 + k * 1024); } while (0)
; #define PG8_MMA(ai, bj, At, Bt) do { __builtin_amdgcn_s_setprio(1); _Pragma("unroll") for (int m = 0; m < 4; ++m) _Pragma("unroll") for (int n = 0; n < 2; ++n) _Pragma("unroll") for (int k = 0; k < 2; ++k) \
;         acc[ai][bj][m][n] = mma16(Bt[n][k], At[m][k], acc[ai][bj][m][n]); __builtin_amdgcn_s_setprio(0); } while (0)
; #define PG8_WAIT_V(n) asm volatile("s_waitcnt vmcnt(" #n ")" ::: "memory")
; #define PG8_WAIT_L(n) asm volatile("s_waitcnt lgkmcnt(" #n ")" ::: "memory")
; #define PG8_BAR __builtin_amdgcn_s_barrier()
; #define PG8_SCHED __builtin_amdgcn_sched_barrier(0)
; template <class Epi, class Sched, bool ALIGN_EPI = false, bool SP2 = false>
; __device__ __forceinline__ void gemm_phase(PG8_LAS unsigned char* lds, const Gemm g, const Sched& S, const Epi& E) {
;     ...
;         for (int t = 0; t < nt; t += 2) {
;     ...
;             PG8_LDA(At, 1, 1); PG8_STAGE(PG8_SB(1, 0), b3, voffB); PG8_STAGE(PG8_SB(1, 1), b3 + hstepB, voffB); PG8_STAGE(PG8_SA(1, 0), a3, voffA);
;             PG8_WAIT_V(8); PG8_WAIT_L(0); PG8_BAR; PG8_MMA(1, 0, At, B0); PG8_MMA(1, 1, At, B1); PG8_BAR; PG8_SCHED;
	s_add_i32 s60, s69, s6
	v_lshl_add_u64 v[166:167], v[166:167], 0, s[36:37]
	s_mov_b32 m0, s60
	ds_read_b128 v[198:201], v175 offset:49152
	ds_read_b128 v[202:205], v175 offset:50176
	ds_read_b128 v[206:209], v175 offset:51200
	ds_read_b128 v[212:215], v175 offset:52224
	ds_read_b128 v[216:219], v175 offset:53248
	ds_read_b128 v[220:223], v175 offset:54272
	ds_read_b128 v[224:227], v175 offset:55296
	ds_read_b128 v[228:231], v175 offset:56320
	global_load_lds_dwordx4 v[166:167], off
	s_add_i32 m0, s60, 0x2000
	s_add_u32 s58, s58, 0x80080
	v_lshl_add_u64 v[166:167], v[176:177], 0, s[36:37]
	s_addc_u32 s59, s59, 0
	s_add_i32 s60, s70, s6
	global_load_lds_dwordx4 v[166:167], off
	v_lshl_add_u64 v[166:167], s[58:59], 0, v[150:151]
	s_mov_b32 m0, s60
	s_nop 0
	global_load_lds_dwordx4 v[166:167], off
	v_lshl_add_u64 v[166:167], s[58:59], 0, v[146:147]
	s_add_i32 m0, s60, 0x2000
	s_nop 0
	global_load_lds_dwordx4 v[166:167], off
	v_lshl_add_u64 v[166:167], v[232:233], 0, s[36:37]
	s_mov_b32 m0, s24
	s_nop 0
	global_load_lds_dwordx4 v[166:167], off
	v_lshl_add_u64 v[166:167], v[234:235], 0, s[36:37]
	s_mov_b32 m0, s25
	s_nop 0
	global_load_lds_dwordx4 v[166:167], off
	s_waitcnt vmcnt(8)
	s_waitcnt lgkmcnt(0)
	s_barrier
	s_setprio 1
	s_waitcnt lgkmcnt(0)
	v_mfma_i32_16x16x64_i8 v[62:65], v[90:93], v[198:201], v[62:65]
	v_mfma_i32_16x16x64_i8 v[62:65], v[94:97], v[202:205], v[62:65]
	v_mfma_i32_16x16x64_i8 v[58:61], v[106:109], v[202:205], v[58:61]
	v_mfma_i32_16x16x64_i8 v[58:61], v[98:101], v[198:201], v[58:61]
	v_mfma_i32_16x16x64_i8 v[42:45], v[98:101], v[206:209], v[42:45]
	v_mfma_i32_16x16x64_i8 v[42:45], v[106:109], v[212:215], v[42:45]
	v_mfma_i32_16x16x64_i8 v[46:49], v[94:97], v[212:215], v[46:49]
	v_mfma_i32_16x16x64_i8 v[46:49], v[90:93], v[206:209], v[46:49]
	v_mfma_i32_16x16x64_i8 v[30:33], v[90:93], v[216:219], v[30:33]
	v_mfma_i32_16x16x64_i8 v[30:33], v[94:97], v[220:223], v[30:33]
	v_mfma_i32_16x16x64_i8 v[26:29], v[106:109], v[220:223], v[26:29]
	v_mfma_i32_16x16x64_i8 v[26:29], v[98:101], v[216:219], v[26:29]
	v_mfma_i32_16x16x64_i8 v[10:13], v[98:101], v[224:227], v[10:13]
	v_mfma_i32_16x16x64_i8 v[10:13], v[106:109], v[228:231], v[10:13]
	v_mfma_i32_16x16x64_i8 v[14:17], v[94:97], v[228:231], v[14:17]
	v_mfma_i32_16x16x64_i8 v[14:17], v[90:93], v[224:227], v[14:17]
	s_setprio 0
	s_setprio 1
	v_mfma_i32_16x16x64_i8 v[6:9], v[182:185], v[224:227], v[6:9]
	v_mfma_i32_16x16x64_i8 v[6:9], v[186:189], v[228:231], v[6:9]
	v_mfma_i32_16x16x64_i8 v[2:5], v[194:197], v[228:231], v[2:5]
	v_mfma_i32_16x16x64_i8 v[2:5], v[190:193], v[224:227], v[2:5]
	v_mfma_i32_16x16x64_i8 v[18:21], v[190:193], v[216:219], v[18:21]
	v_mfma_i32_16x16x64_i8 v[18:21], v[194:197], v[220:223], v[18:21]
	v_mfma_i32_16x16x64_i8 v[22:25], v[186:189], v[220:223], v[22:25]
	v_mfma_i32_16x16x64_i8 v[22:25], v[182:185], v[216:219], v[22:25]
	v_mfma_i32_16x16x64_i8 v[38:41], v[182:185], v[206:209], v[38:41]
	v_mfma_i32_16x16x64_i8 v[38:41], v[186:189], v[212:215], v[38:41]
	v_mfma_i32_16x16x64_i8 v[34:37], v[194:197], v[212:215], v[34:37]
	v_mfma_i32_16x16x64_i8 v[34:37], v[190:193], v[206:209], v[34:37]
	v_mfma_i32_16x16x64_i8 v[50:53], v[190:193], v[198:201], v[50:53]
	v_mfma_i32_16x16x64_i8 v[50:53], v[194:197], v[202:205], v[50:53]
	v_mfma_i32_16x16x64_i8 v[54:57], v[186:189], v[202:205], v[54:57]
	v_mfma_i32_16x16x64_i8 v[54:57], v[182:185], v[198:201], v[54:57]
	s_setprio 0
	s_barrier
	s_add_i32 s68, s68, 2
	s_add_u32 s56, s56, 0x100
	s_addc_u32 s57, s57, 0
	s_add_u32 s66, s66, 0x100
	s_addc_u32 s67, s67, 0
	s_cmp_gt_u32 s68, 29
	s_cbranch_scc0 .LBB0_841
	s_and_b64 vcc, exec, s[44:45]
	s_cbranch_vccz .LBB0_844
	s_barrier

; #define PG8_STAGE(bufoff, gbase, voff) do { _Pragma("unroll") for (int _i = 0; _i < 2; ++_i) \
;         __builtin_amdgcn_global_load_lds((const unsigned*)((const char*)(gbase) + (voff)[_i]), (PG8_LAS unsigned*)(lds + (bufoff) + ldsw + _i * 8192), 16, 0, 0); } while (0)
; #define PG8_LDA(dst, b, h) do { _Pragma("unroll") for (int m = 0; m < 4; ++m) _Pragma("unroll") for (int k = 0; k < 2; ++k) dst[m][k] = *(const PG8_LAS bf16x8*)(lds + PG8_SA(b, h) + aoff + m * 2048 + k * 1024); } while (0)
; #define PG8_LDB(dst, b, h) do { _Pragma("unroll") for (int n = 0; n < 2; ++n) _Pragma("unroll") for (int k = 0; k < 2; ++k) dst[n][k] = *(const PG8_LAS bf16x8*)(lds + PG8_SB(b, h) + boff + n * 2048 + k * 1024); } while (0)
; template <class Epi, class Sched, bool ALIGN_EPI = false, bool SP2 = false>
; __device__ __forceinline__ void gemm_phase(PG8_LAS unsigned char* lds, const Gemm g, const Sched& S, const Epi& E) {
;     ...
;         for (int t = 0; t < nt; t += 2) {
;             const bool last = (t == nt - 2);
;             const char* a1 = cA + (size_t)(t + 1) * kstep;
;             const char* a2 = last ? nA : cA + (size_t)(t + 2) * kstep; const char* b2 = last ? nB : cB + (size_t)(t + 2) * kstep;
;             const char* a3 = a2 + kstep; const char* b3 = b2 + kstep;
;             if (last && has_next) S.a_ready(nxt);
;             if constexpr (SP2) {
;             PG8_LDB(B0, 0, 0); PG8_LDB(B1, 0, 1); PG8_SCHED; PG8_LDA(At, 0, 0); PG8_STAGE(PG8_SA(1, 1), a1 + hstepA, voffA);
;             PG8_WAIT_V(8); PG8_WAIT_L(0); PG8_BAR; PG8_MMA(0, 0, At, B0); PG8_MMA(0, 1, At, B1); PG8_BAR; PG8_SCHED;
;             PG8_LDA(At, 0, 1); PG8_STAGE(PG8_SB(0, 0), b2, voffB); PG8_STAGE(PG8_SB(0, 1), b2 + hstepB, voffB); PG8_STAGE(PG8_SA(0, 0), a2, voffA);
;             PG8_WAIT_V(8); PG8_WAIT_L(0); PG8_BAR; PG8_MMA(1, 0, At, B0); PG8_MMA(1, 1, At, B1); PG8_BAR; PG8_SCHED;
;             PG8_LDB(B0, 1, 0); PG8_LDB(B1, 1, 1); PG8_SCHED; PG8_LDA(At, 1, 0); PG8_STAGE(PG8_SA(0, 1), a2 + hstepA, voffA);
;             PG8_WAIT_V(8); PG8_WAIT_L(0); PG8_BAR; PG8_MMA(0, 0, At, B0); PG8_MMA(0, 1, At, B1); PG8_BAR; PG8_SCHED;
;             PG8_LDA(At, 1, 1); PG8_STAGE(PG8_SB(1, 0), b3, voffB); PG8_STAGE(PG8_SB(1, 1), b3 + hstepB, voffB); PG8_STAGE(PG8_SA(1, 0), a3, voffA);
;             PG8_WAIT_V(8); PG8_WAIT_L(0); PG8_BAR; PG8_MMA(1, 0, At, B0); PG8_MMA(1, 1, At, B1); PG8_BAR; PG8_SCHED;
.LBB0_1019:
	s_add_u32 s56, s56, 0x158080
	s_addc_u32 s57, s57, 0
	s_add_u32 s65, s58, 0x100
	s_addc_u32 s66, s59, 0
	s_mov_b32 s67, -2
	ds_read_b128 v[122:125], v172
	ds_read_b128 v[126:129], v172 offset:1024
	ds_read_b128 v[130:133], v172 offset:2048
	ds_read_b128 v[138:141], v172 offset:3072
	ds_read_b128 v[182:185], v173
	ds_read_b128 v[186:189], v173 offset:1024
	ds_read_b128 v[190:193], v173 offset:2048
	ds_read_b128 v[194:197], v173 offset:3072
	s_add_u32 s58, s56, 0xffea8080
	s_addc_u32 s59, s57, -1
	s_cmpk_eq_i32 s67, 0x52
	s_cselect_b32 s61, s1, s59
	s_cselect_b32 s60, s0, s58
	s_cselect_b32 s59, s53, s66
	s_cselect_b32 s58, s52, s65
	v_lshl_add_u64 v[166:167], s[56:57], 0, v[158:159]
	s_add_i32 m0, s9, 0xc000
	ds_read_b128 v[198:201], v174
	ds_read_b128 v[202:205], v174 offset:1024
	ds_read_b128 v[206:209], v174 offset:2048
	ds_read_b128 v[212:215], v174 offset:3072
	ds_read_b128 v[216:219], v174 offset:4096
	ds_read_b128 v[220:223], v174 offset:5120
	ds_read_b128 v[224:227], v174 offset:6144
	ds_read_b128 v[228:231], v174 offset:7168
	global_load_lds_dwordx4 v[166:167], off
	v_lshl_add_u64 v[166:167], s[56:57], 0, v[160:161]
	s_add_i32 m0, s9, 0xe000
	s_nop 0
	global_load_lds_dwordx4 v[166:167], off
	s_waitcnt vmcnt(8)
	s_waitcnt lgkmcnt(0)
	s_barrier
	s_setprio 1
	s_waitcnt lgkmcnt(0)
	v_mfma_i32_16x16x64_i8 v[142:145], v[122:125], v[198:201], 0
	v_mfma_i32_16x16x64_i8 v[142:145], v[126:129], v[202:205], v[142:145]
	v_mfma_i32_16x16x64_i8 v[134:137], v[138:141], v[202:205], 0
	v_mfma_i32_16x16x64_i8 v[134:137], v[130:133], v[198:201], v[134:137]
	v_mfma_i32_16x16x64_i8 v[106:109], v[130:133], v[206:209], 0
	v_mfma_i32_16x16x64_i8 v[106:109], v[138:141], v[212:215], v[106:109]
	v_mfma_i32_16x16x64_i8 v[110:113], v[126:129], v[212:215], 0
	v_mfma_i32_16x16x64_i8 v[110:113], v[122:125], v[206:209], v[110:113]
	v_mfma_i32_16x16x64_i8 v[94:97], v[122:125], v[216:219], 0
	v_mfma_i32_16x16x64_i8 v[94:97], v[126:129], v[220:223], v[94:97]
	v_mfma_i32_16x16x64_i8 v[90:93], v[138:141], v[220:223], 0
	v_mfma_i32_16x16x64_i8 v[90:93], v[130:133], v[216:219], v[90:93]
	v_mfma_i32_16x16x64_i8 v[74:77], v[130:133], v[224:227], 0
	v_mfma_i32_16x16x64_i8 v[74:77], v[138:141], v[228:231], v[74:77]
	v_mfma_i32_16x16x64_i8 v[78:81], v[126:129], v[228:231], 0
	v_mfma_i32_16x16x64_i8 v[78:81], v[122:125], v[224:227], v[78:81]
	s_setprio 0
	s_setprio 1
	v_mfma_i32_16x16x64_i8 v[70:73], v[182:185], v[224:227], 0
	v_mfma_i32_16x16x64_i8 v[70:73], v[186:189], v[228:231], v[70:73]
	v_mfma_i32_16x16x64_i8 v[66:69], v[194:197], v[228:231], 0
	v_mfma_i32_16x16x64_i8 v[66:69], v[190:193], v[224:227], v[66:69]
	v_mfma_i32_16x16x64_i8 v[82:85], v[190:193], v[216:219], 0
	v_mfma_i32_16x16x64_i8 v[82:85], v[194:197], v[220:223], v[82:85]
	v_mfma_i32_16x16x64_i8 v[86:89], v[186:189], v[220:223], 0
	v_mfma_i32_16x16x64_i8 v[86:89], v[182:185], v[216:219], v[86:89]
	v_mfma_i32_16x16x64_i8 v[102:105], v[182:185], v[206:209], 0
	v_mfma_i32_16x16x64_i8 v[102:105], v[186:189], v[212:215], v[102:105]
	v_mfma_i32_16x16x64_i8 v[98:101], v[194:197], v[212:215], 0
	v_mfma_i32_16x16x64_i8 v[98:101], v[190:193], v[206:209], v[98:101]
	v_mfma_i32_16x16x64_i8 v[114:117], v[190:193], v[198:201], 0
	v_mfma_i32_16x16x64_i8 v[114:117], v[194:197], v[202:205], v[114:117]
	v_mfma_i32_16x16x64_i8 v[118:121], v[186:189], v[202:205], 0
	v_mfma_i32_16x16x64_i8 v[118:121], v[182:185], v[198:201], v[118:121]
	s_setprio 0
	s_barrier
	s_add_i32 s68, s29, s7
	v_lshl_add_u64 v[166:167], s[58:59], 0, v[148:149]
	s_mov_b32 m0, s68
	ds_read_b128 v[198:201], v174 offset:16384
	ds_read_b128 v[202:205], v174 offset:17408
	ds_read_b128 v[206:209], v174 offset:18432
	ds_read_b128 v[212:215], v174 offset:19456
	ds_read_b128 v[216:219], v174 offset:20480
	ds_read_b128 v[220:223], v174 offset:21504
	ds_read_b128 v[224:227], v174 offset:22528
	ds_read_b128 v[228:231], v174 offset:23552
	global_load_lds_dwordx4 v[166:167], off
	s_add_i32 m0, s68, 0x2000
	s_add_u32 s68, s58, 0x158000
	v_lshl_add_u64 v[176:177], s[58:59], 0, v[152:153]
	s_addc_u32 s69, s59, 0
	s_add_i32 s70, s33, s7
	global_load_lds_dwordx4 v[176:177], off
	v_lshl_add_u64 v[232:233], s[68:69], 0, v[148:149]
	s_mov_b32 m0, s70
	v_lshl_add_u64 v[234:235], s[60:61], 0, v[150:151]
	global_load_lds_dwordx4 v[232:233], off
	v_lshl_add_u64 v[232:233], s[68:69], 0, v[152:153]
	s_add_i32 m0, s70, 0x2000
	s_nop 0
	global_load_lds_dwordx4 v[232:233], off
	v_lshl_add_u64 v[232:233], s[60:61], 0, v[146:147]
	s_mov_b32 m0, s9
	s_nop 0
	global_load_lds_dwordx4 v[232:233], off
	s_mov_b32 m0, s11
	s_nop 0
	global_load_lds_dwordx4 v[234:235], off
	s_waitcnt vmcnt(8)
	s_waitcnt lgkmcnt(0)
	s_barrier
; #define PG8_STAGE(bufoff, gbase, voff) do { _Pragma("unroll") for (int _i = 0; _i < 2; ++_i) \
;         __builtin_amdgcn_global_load_lds((const unsigned*)((const char*)(gbase) + (voff)[_i]), (PG8_LAS unsigned*)(lds + (bufoff) + ldsw + _i * 8192), 16, 0, 0); } while (0)
; #define PG8_LDA(dst, b, h) do { _Pragma("unroll") for (int m = 0; m < 4; ++m) _Pragma("unroll") for (int k = 0; k < 2; ++k) dst[m][k] = *(const PG8_LAS bf16x8*)(lds + PG8_SA(b, h) + aoff + m * 2048 + k * 1024); } while (0)
; #define PG8_LDB(dst, b, h) do { _Pragma("unroll") for (int n = 0; n < 2; ++n) _Pragma("unroll") for (int k = 0; k < 2; ++k) dst[n][k] = *(const PG8_LAS bf16x8*)(lds + PG8_SB(b, h) + boff + n * 2048 + k * 1024); } while (0)
; #define PG8_MMA(ai, bj, At, Bt) do { __builtin_amdgcn_s_setprio(1); _Pragma("unroll") for (int m = 0; m < 4; ++m) _Pragma("unroll") for (int n = 0; n < 2; ++n) _Pragma("unroll") for (int k = 0; k < 2; ++k) \
;         acc[ai][bj][m][n] = mma16(Bt[n][k], At[m][k], acc[ai][bj][m][n]); __builtin_amdgcn_s_setprio(0); } while (0)
; #define PG8_WAIT_V(n) asm volatile("s_waitcnt vmcnt(" #n ")" ::: "memory")
; template <class Epi, class Sched, bool ALIGN_EPI = false, bool SP2 = false>
; __device__ __forceinline__ void gemm_phase(PG8_LAS unsigned char* lds, const Gemm g, const Sched& S, const Epi& E) {
;     ...
;             PG8_LDB(B0, 0, 0); PG8_LDB(B1, 0, 1); PG8_SCHED; PG8_LDA(At, 0, 0); PG8_STAGE(PG8_SA(1, 1), a1 + hstepA, voffA);
;             PG8_WAIT_V(8); PG8_WAIT_L(0); PG8_BAR; PG8_MMA(0, 0, At, B0); PG8_MMA(0, 1, At, B1); PG8_BAR; PG8_SCHED;
;             PG8_LDA(At, 0, 1); PG8_STAGE(PG8_SB(0, 0), b2, voffB); PG8_STAGE(PG8_SB(0, 1), b2 + hstepB, voffB); PG8_STAGE(PG8_SA(0, 0), a2, voffA);
;             PG8_WAIT_V(8); PG8_WAIT_L(0); PG8_BAR; PG8_MMA(1, 0, At, B0); PG8_MMA(1, 1, At, B1); PG8_BAR; PG8_SCHED;
;             PG8_LDB(B0, 1, 0); PG8_LDB(B1, 1, 1); PG8_SCHED; PG8_LDA(At, 1, 0); PG8_STAGE(PG8_SA(0, 1), a2 + hstepA, voffA);
;             PG8_WAIT_V(8); PG8_WAIT_L(0); PG8_BAR; PG8_MMA(0, 0, At, B0); PG8_MMA(0, 1, At, B1); PG8_BAR; PG8_SCHED;
;             PG8_LDA(At, 1, 1); PG8_STAGE(PG8_SB(1, 0), b3, voffB); PG8_STAGE(PG8_SB(1, 1), b3 + hstepB, voffB); PG8_STAGE(PG8_SA(1, 0), a3, voffA);
;             PG8_WAIT_V(8); PG8_WAIT_L(0); PG8_BAR; PG8_MMA(1, 0, At, B0); PG8_MMA(1, 1, At, B1); PG8_BAR; PG8_SCHED;
	s_setprio 1
	s_waitcnt lgkmcnt(0)
	v_mfma_i32_16x16x64_i8 v[62:65], v[122:125], v[198:201], 0
	v_mfma_i32_16x16x64_i8 v[62:65], v[126:129], v[202:205], v[62:65]
	v_mfma_i32_16x16x64_i8 v[58:61], v[138:141], v[202:205], 0
	v_mfma_i32_16x16x64_i8 v[58:61], v[130:133], v[198:201], v[58:61]
	v_mfma_i32_16x16x64_i8 v[42:45], v[130:133], v[206:209], 0
	v_mfma_i32_16x16x64_i8 v[42:45], v[138:141], v[212:215], v[42:45]
	v_mfma_i32_16x16x64_i8 v[46:49], v[126:129], v[212:215], 0
	v_mfma_i32_16x16x64_i8 v[46:49], v[122:125], v[206:209], v[46:49]
	v_mfma_i32_16x16x64_i8 v[30:33], v[122:125], v[216:219], 0
	v_mfma_i32_16x16x64_i8 v[30:33], v[126:129], v[220:223], v[30:33]
	v_mfma_i32_16x16x64_i8 v[26:29], v[138:141], v[220:223], 0
	v_mfma_i32_16x16x64_i8 v[26:29], v[130:133], v[216:219], v[26:29]
	v_mfma_i32_16x16x64_i8 v[10:13], v[130:133], v[224:227], 0
	v_mfma_i32_16x16x64_i8 v[10:13], v[138:141], v[228:231], v[10:13]
	v_mfma_i32_16x16x64_i8 v[14:17], v[126:129], v[228:231], 0
	v_mfma_i32_16x16x64_i8 v[14:17], v[122:125], v[224:227], v[14:17]
	s_setprio 0
	s_setprio 1
	v_mfma_i32_16x16x64_i8 v[6:9], v[182:185], v[224:227], 0
	v_mfma_i32_16x16x64_i8 v[6:9], v[186:189], v[228:231], v[6:9]
	v_mfma_i32_16x16x64_i8 v[2:5], v[194:197], v[228:231], 0
	v_mfma_i32_16x16x64_i8 v[2:5], v[190:193], v[224:227], v[2:5]
	v_mfma_i32_16x16x64_i8 v[18:21], v[190:193], v[216:219], 0
	v_mfma_i32_16x16x64_i8 v[18:21], v[194:197], v[220:223], v[18:21]
	v_mfma_i32_16x16x64_i8 v[22:25], v[186:189], v[220:223], 0
	v_mfma_i32_16x16x64_i8 v[22:25], v[182:185], v[216:219], v[22:25]
	v_mfma_i32_16x16x64_i8 v[38:41], v[182:185], v[206:209], 0
	v_mfma_i32_16x16x64_i8 v[38:41], v[186:189], v[212:215], v[38:41]
	v_mfma_i32_16x16x64_i8 v[34:37], v[194:197], v[212:215], 0
	v_mfma_i32_16x16x64_i8 v[34:37], v[190:193], v[206:209], v[34:37]
	v_mfma_i32_16x16x64_i8 v[50:53], v[190:193], v[198:201], 0
	v_mfma_i32_16x16x64_i8 v[50:53], v[194:197], v[202:205], v[50:53]
	v_mfma_i32_16x16x64_i8 v[54:57], v[186:189], v[202:205], 0
	v_mfma_i32_16x16x64_i8 v[54:57], v[182:185], v[198:201], v[54:57]
	s_setprio 0
	s_barrier
	s_add_i32 s68, 0, 0x18000
	s_add_i32 s69, 0, 0x1c000
	v_add_u32_e32 v138, s68, v170
	v_add_u32_e32 v175, s69, v170
	ds_read_b128 v[122:125], v138
	ds_read_b128 v[126:129], v138 offset:1024
	ds_read_b128 v[130:133], v138 offset:2048
	ds_read_b128 v[138:141], v138 offset:3072
	ds_read_b128 v[182:185], v175
	ds_read_b128 v[186:189], v175 offset:1024
	ds_read_b128 v[190:193], v175 offset:2048
	ds_read_b128 v[194:197], v175 offset:3072
	s_add_u32 s60, s60, 0x158000
	s_addc_u32 s61, s61, 0
	s_mov_b32 m0, s12
	v_lshl_add_u64 v[236:237], s[60:61], 0, v[146:147]
	ds_read_b128 v[198:201], v174 offset:32768
	ds_read_b128 v[202:205], v174 offset:33792
	ds_read_b128 v[206:209], v174 offset:34816
	ds_read_b128 v[212:215], v174 offset:35840
	ds_read_b128 v[216:219], v174 offset:36864
	ds_read_b128 v[220:223], v174 offset:37888
	ds_read_b128 v[224:227], v174 offset:38912
	ds_read_b128 v[228:231], v174 offset:39936
	global_load_lds_dwordx4 v[236:237], off
	v_lshl_add_u64 v[236:237], s[60:61], 0, v[150:151]
	s_mov_b32 m0, s13
	s_nop 0
	global_load_lds_dwordx4 v[236:237], off
	s_waitcnt vmcnt(8)
	s_waitcnt lgkmcnt(0)
	s_barrier
	s_setprio 1
	s_waitcnt lgkmcnt(0)
	v_mfma_i32_16x16x64_i8 v[142:145], v[122:125], v[198:201], v[142:145]
	v_mfma_i32_16x16x64_i8 v[142:145], v[126:129], v[202:205], v[142:145]
	v_mfma_i32_16x16x64_i8 v[134:137], v[138:141], v[202:205], v[134:137]
	v_mfma_i32_16x16x64_i8 v[134:137], v[130:133], v[198:201], v[134:137]
	v_mfma_i32_16x16x64_i8 v[106:109], v[130:133], v[206:209], v[106:109]
	v_mfma_i32_16x16x64_i8 v[106:109], v[138:141], v[212:215], v[106:109]
	v_mfma_i32_16x16x64_i8 v[110:113], v[126:129], v[212:215], v[110:113]
	v_mfma_i32_16x16x64_i8 v[110:113], v[122:125], v[206:209], v[110:113]
	v_mfma_i32_16x16x64_i8 v[94:97], v[122:125], v[216:219], v[94:97]
	v_mfma_i32_16x16x64_i8 v[94:97], v[126:129], v[220:223], v[94:97]
	v_mfma_i32_16x16x64_i8 v[90:93], v[138:141], v[220:223], v[90:93]
	v_mfma_i32_16x16x64_i8 v[90:93], v[130:133], v[216:219], v[90:93]
	v_mfma_i32_16x16x64_i8 v[74:77], v[130:133], v[224:227], v[74:77]
	v_mfma_i32_16x16x64_i8 v[74:77], v[138:141], v[228:231], v[74:77]
	v_mfma_i32_16x16x64_i8 v[78:81], v[126:129], v[228:231], v[78:81]
	v_mfma_i32_16x16x64_i8 v[78:81], v[122:125], v[224:227], v[78:81]
	s_setprio 0
	s_setprio 1
	v_mfma_i32_16x16x64_i8 v[70:73], v[182:185], v[224:227], v[70:73]
	v_mfma_i32_16x16x64_i8 v[70:73], v[186:189], v[228:231], v[70:73]
	v_mfma_i32_16x16x64_i8 v[66:69], v[194:197], v[228:231], v[66:69]
	v_mfma_i32_16x16x64_i8 v[66:69], v[190:193], v[224:227], v[66:69]
	v_mfma_i32_16x16x64_i8 v[82:85], v[190:193], v[216:219], v[82:85]
	v_mfma_i32_16x16x64_i8 v[82:85], v[194:197], v[220:223], v[82:85]
	v_mfma_i32_16x16x64_i8 v[86:89], v[186:189], v[220:223], v[86:89]
	v_mfma_i32_16x16x64_i8 v[86:89], v[182:185], v[216:219], v[86:89]
	v_mfma_i32_16x16x64_i8 v[102:105], v[182:185], v[206:209], v[102:105]
	v_mfma_i32_16x16x64_i8 v[102:105], v[186:189], v[212:215], v[102:105]
	v_mfma_i32_16x16x64_i8 v[98:101], v[194:197], v[212:215], v[98:101]
	v_mfma_i32_16x16x64_i8 v[98:101], v[190:193], v[206:209], v[98:101]
	v_mfma_i32_16x16x64_i8 v[114:117], v[190:193], v[198:201], v[114:117]
	v_mfma_i32_16x16x64_i8 v[114:117], v[194:197], v[202:205], v[114:117]
	v_mfma_i32_16x16x64_i8 v[118:121], v[186:189], v[202:205], v[118:121]
	v_mfma_i32_16x16x64_i8 v[118:121], v[182:185], v[198:201], v[118:121]
	s_setprio 0
	s_barrier
; #define PG8_STAGE(bufoff, gbase, voff) do { _Pragma("unroll") for (int _i = 0; _i < 2; ++_i) \
;         __builtin_amdgcn_global_load_lds((const unsigned*)((const char*)(gbase) + (voff)[_i]), (PG8_LAS unsigned*)(lds + (bufoff) + ldsw + _i * 8192), 16, 0, 0); } while (0)
; #define PG8_LDA(dst, b, h) do { _Pragma("unroll") for (int m = 0; m < 4; ++m) _Pragma("unroll") for (int k = 0; k < 2; ++k) dst[m][k] = *(const PG8_LAS bf16x8*)(lds + PG8_SA(b, h) + aoff + m * 2048 + k * 1024); } while (0)
; #define PG8_LDB(dst, b, h) do { _Pragma("unroll") for (int n = 0; n < 2; ++n) _Pragma("unroll") for (int k = 0; k < 2; ++k) dst[n][k] = *(const PG8_LAS bf16x8*)(lds + PG8_SB(b, h) + boff + n * 2048 + k * 1024); } while (0)
; #define PG8_WAIT_V(n) asm volatile("s_waitcnt vmcnt(" #n ")" ::: "memory")
; #define PG8_WAIT_L(n) asm volatile("s_waitcnt lgkmcnt(" #n ")" ::: "memory")
; #define PG8_BAR __builtin_amdgcn_s_barrier()
; #define PG8_SCHED __builtin_amdgcn_sched_barrier(0)
; template <class Epi, class Sched, bool ALIGN_EPI = false, bool SP2 = false>
; __device__ __forceinline__ void gemm_phase(PG8_LAS unsigned char* lds, const Gemm g, const Sched& S, const Epi& E) {
;     ...
;             PG8_LDB(B0, 0, 0); PG8_LDB(B1, 0, 1); PG8_SCHED; PG8_LDA(At, 0, 0); PG8_STAGE(PG8_SA(1, 1), a1 + hstepA, voffA);
;             PG8_WAIT_V(8); PG8_WAIT_L(0); PG8_BAR; PG8_MMA(0, 0, At, B0); PG8_MMA(0, 1, At, B1); PG8_BAR; PG8_SCHED;
;             PG8_LDA(At, 0, 1); PG8_STAGE(PG8_SB(0, 0), b2, voffB); PG8_STAGE(PG8_SB(0, 1), b2 + hstepB, voffB); PG8_STAGE(PG8_SA(0, 0), a2, voffA);
;             PG8_WAIT_V(8); PG8_WAIT_L(0); PG8_BAR; PG8_MMA(1, 0, At, B0); PG8_MMA(1, 1, At, B1); PG8_BAR; PG8_SCHED;
;             PG8_LDB(B0, 1, 0); PG8_LDB(B1, 1, 1); PG8_SCHED; PG8_LDA(At, 1, 0); PG8_STAGE(PG8_SA(0, 1), a2 + hstepA, voffA);
;             PG8_WAIT_V(8); PG8_WAIT_L(0); PG8_BAR; PG8_MMA(0, 0, At, B0); PG8_MMA(0, 1, At, B1); PG8_BAR; PG8_SCHED;
;             PG8_LDA(At, 1, 1); PG8_STAGE(PG8_SB(1, 0), b3, voffB); PG8_STAGE(PG8_SB(1, 1), b3 + hstepB, voffB); PG8_STAGE(PG8_SA(1, 0), a3, voffA);
;             PG8_WAIT_V(8); PG8_WAIT_L(0); PG8_BAR; PG8_MMA(1, 0, At, B0); PG8_MMA(1, 1, At, B1); PG8_BAR; PG8_SCHED;
;             } else {
;             PG8_LDB(B0, 0, 0); PG8_SCHED; PG8_LDA(At, 0, 0); PG8_STAGE(PG8_SA(1, 1), a1 + hstepA, voffA);
	s_add_i32 s60, s68, s7
	v_lshl_add_u64 v[166:167], v[166:167], 0, s[24:25]
	s_mov_b32 m0, s60
	ds_read_b128 v[198:201], v174 offset:49152
	ds_read_b128 v[202:205], v174 offset:50176
	ds_read_b128 v[206:209], v174 offset:51200
	ds_read_b128 v[212:215], v174 offset:52224
	ds_read_b128 v[216:219], v174 offset:53248
	ds_read_b128 v[220:223], v174 offset:54272
	ds_read_b128 v[224:227], v174 offset:55296
	ds_read_b128 v[228:231], v174 offset:56320
	global_load_lds_dwordx4 v[166:167], off
	s_add_i32 m0, s60, 0x2000
	s_add_u32 s58, s58, 0x158080
	v_lshl_add_u64 v[166:167], v[176:177], 0, s[24:25]
	s_addc_u32 s59, s59, 0
	s_add_i32 s60, s69, s7
	global_load_lds_dwordx4 v[166:167], off
	v_lshl_add_u64 v[166:167], s[58:59], 0, v[148:149]
	s_mov_b32 m0, s60
	s_nop 0
	global_load_lds_dwordx4 v[166:167], off
	v_lshl_add_u64 v[166:167], s[58:59], 0, v[152:153]
	s_add_i32 m0, s60, 0x2000
	s_nop 0
	global_load_lds_dwordx4 v[166:167], off
	v_lshl_add_u64 v[166:167], v[232:233], 0, s[24:25]
	s_mov_b32 m0, s26
	s_nop 0
	global_load_lds_dwordx4 v[166:167], off
	v_lshl_add_u64 v[166:167], v[234:235], 0, s[24:25]
	s_mov_b32 m0, s27
	s_nop 0
	global_load_lds_dwordx4 v[166:167], off
	s_waitcnt vmcnt(8)
	s_waitcnt lgkmcnt(0)
	s_barrier
	s_setprio 1
	s_waitcnt lgkmcnt(0)
	v_mfma_i32_16x16x64_i8 v[62:65], v[122:125], v[198:201], v[62:65]
	v_mfma_i32_16x16x64_i8 v[62:65], v[126:129], v[202:205], v[62:65]
	v_mfma_i32_16x16x64_i8 v[58:61], v[138:141], v[202:205], v[58:61]
	v_mfma_i32_16x16x64_i8 v[58:61], v[130:133], v[198:201], v[58:61]
	v_mfma_i32_16x16x64_i8 v[42:45], v[130:133], v[206:209], v[42:45]
	v_mfma_i32_16x16x64_i8 v[42:45], v[138:141], v[212:215], v[42:45]
	v_mfma_i32_16x16x64_i8 v[46:49], v[126:129], v[212:215], v[46:49]
	v_mfma_i32_16x16x64_i8 v[46:49], v[122:125], v[206:209], v[46:49]
	v_mfma_i32_16x16x64_i8 v[30:33], v[122:125], v[216:219], v[30:33]
	v_mfma_i32_16x16x64_i8 v[30:33], v[126:129], v[220:223], v[30:33]
	v_mfma_i32_16x16x64_i8 v[26:29], v[138:141], v[220:223], v[26:29]
	v_mfma_i32_16x16x64_i8 v[26:29], v[130:133], v[216:219], v[26:29]
	v_mfma_i32_16x16x64_i8 v[10:13], v[130:133], v[224:227], v[10:13]
	v_mfma_i32_16x16x64_i8 v[10:13], v[138:141], v[228:231], v[10:13]
	v_mfma_i32_16x16x64_i8 v[14:17], v[126:129], v[228:231], v[14:17]
	v_mfma_i32_16x16x64_i8 v[14:17], v[122:125], v[224:227], v[14:17]
	s_setprio 0
	s_setprio 1
	v_mfma_i32_16x16x64_i8 v[6:9], v[182:185], v[224:227], v[6:9]
	v_mfma_i32_16x16x64_i8 v[6:9], v[186:189], v[228:231], v[6:9]
	v_mfma_i32_16x16x64_i8 v[2:5], v[194:197], v[228:231], v[2:5]
	v_mfma_i32_16x16x64_i8 v[2:5], v[190:193], v[224:227], v[2:5]
	v_mfma_i32_16x16x64_i8 v[18:21], v[190:193], v[216:219], v[18:21]
	v_mfma_i32_16x16x64_i8 v[18:21], v[194:197], v[220:223], v[18:21]
	v_mfma_i32_16x16x64_i8 v[22:25], v[186:189], v[220:223], v[22:25]
	v_mfma_i32_16x16x64_i8 v[22:25], v[182:185], v[216:219], v[22:25]
	v_mfma_i32_16x16x64_i8 v[38:41], v[182:185], v[206:209], v[38:41]
	v_mfma_i32_16x16x64_i8 v[38:41], v[186:189], v[212:215], v[38:41]
	v_mfma_i32_16x16x64_i8 v[34:37], v[194:197], v[212:215], v[34:37]
	v_mfma_i32_16x16x64_i8 v[34:37], v[190:193], v[206:209], v[34:37]
	v_mfma_i32_16x16x64_i8 v[50:53], v[190:193], v[198:201], v[50:53]
	v_mfma_i32_16x16x64_i8 v[50:53], v[194:197], v[202:205], v[50:53]
	v_mfma_i32_16x16x64_i8 v[54:57], v[186:189], v[202:205], v[54:57]
	v_mfma_i32_16x16x64_i8 v[54:57], v[182:185], v[198:201], v[54:57]
	s_setprio 0
	s_barrier
	s_add_i32 s67, s67, 2
	s_add_u32 s56, s56, 0x100
	s_addc_u32 s57, s57, 0
	s_add_u32 s65, s65, 0x100
	s_addc_u32 s66, s66, 0
.LBB0_1020:
	ds_read_b128 v[122:125], v172
	ds_read_b128 v[126:129], v172 offset:1024
	ds_read_b128 v[130:133], v172 offset:2048
	ds_read_b128 v[138:141], v172 offset:3072
	ds_read_b128 v[182:185], v173
	ds_read_b128 v[186:189], v173 offset:1024
	ds_read_b128 v[190:193], v173 offset:2048
	ds_read_b128 v[194:197], v173 offset:3072
	s_add_u32 s58, s56, 0xffea8080
	s_addc_u32 s59, s57, -1
	s_cmpk_eq_i32 s67, 0x52
	s_cselect_b32 s61, s1, s59
	s_cselect_b32 s60, s0, s58
	s_cselect_b32 s59, s53, s66
	s_cselect_b32 s58, s52, s65
	v_lshl_add_u64 v[166:167], s[56:57], 0, v[158:159]
	s_add_i32 m0, s9, 0xc000
	ds_read_b128 v[198:201], v174
	ds_read_b128 v[202:205], v174 offset:1024
	ds_read_b128 v[206:209], v174 offset:2048
	ds_read_b128 v[212:215], v174 offset:3072
	ds_read_b128 v[216:219], v174 offset:4096
	ds_read_b128 v[220:223], v174 offset:5120
	ds_read_b128 v[224:227], v174 offset:6144
	ds_read_b128 v[228:231], v174 offset:7168
	global_load_lds_dwordx4 v[166:167], off
	v_lshl_add_u64 v[166:167], s[56:57], 0, v[160:161]
	s_add_i32 m0, s9, 0xe000
	s_nop 0
	global_load_lds_dwordx4 v[166:167], off
	s_waitcnt vmcnt(8)
	s_waitcnt lgkmcnt(0)
	s_barrier
; #define PG8_STAGE(bufoff, gbase, voff) do { _Pragma("unroll") for (int _i = 0; _i < 2; ++_i) \
;         __builtin_amdgcn_global_load_lds((const unsigned*)((const char*)(gbase) + (voff)[_i]), (PG8_LAS unsigned*)(lds + (bufoff) + ldsw + _i * 8192), 16, 0, 0); } while (0)
; #define PG8_LDA(dst, b, h) do { _Pragma("unroll") for (int m = 0; m < 4; ++m) _Pragma("unroll") for (int k = 0; k < 2; ++k) dst[m][k] = *(const PG8_LAS bf16x8*)(lds + PG8_SA(b, h) + aoff + m * 2048 + k * 1024); } while (0)
; #define PG8_LDB(dst, b, h) do { _Pragma("unroll") for (int n = 0; n < 2; ++n) _Pragma("unroll") for (int k = 0; k < 2; ++k) dst[n][k] = *(const PG8_LAS bf16x8*)(lds + PG8_SB(b, h) + boff + n * 2048 + k * 1024); } while (0)
; #define PG8_MMA(ai, bj, At, Bt) do { __builtin_amdgcn_s_setprio(1); _Pragma("unroll") for (int m = 0; m < 4; ++m) _Pragma("unroll") for (int n = 0; n < 2; ++n) _Pragma("unroll") for (int k = 0; k < 2; ++k) \
;         acc[ai][bj][m][n] = mma16(Bt[n][k], At[m][k], acc[ai][bj][m][n]); __builtin_amdgcn_s_setprio(0); } while (0)
; #define PG8_WAIT_V(n) asm volatile("s_waitcnt vmcnt(" #n ")" ::: "memory")
; template <class Epi, class Sched, bool ALIGN_EPI = false, bool SP2 = false>
; __device__ __forceinline__ void gemm_phase(PG8_LAS unsigned char* lds, const Gemm g, const Sched& S, const Epi& E) {
;     ...
;             PG8_LDB(B0, 0, 0); PG8_LDB(B1, 0, 1); PG8_SCHED; PG8_LDA(At, 0, 0); PG8_STAGE(PG8_SA(1, 1), a1 + hstepA, voffA);
;             PG8_WAIT_V(8); PG8_WAIT_L(0); PG8_BAR; PG8_MMA(0, 0, At, B0); PG8_MMA(0, 1, At, B1); PG8_BAR; PG8_SCHED;
;             PG8_LDA(At, 0, 1); PG8_STAGE(PG8_SB(0, 0), b2, voffB); PG8_STAGE(PG8_SB(0, 1), b2 + hstepB, voffB); PG8_STAGE(PG8_SA(0, 0), a2, voffA);
;             PG8_WAIT_V(8); PG8_WAIT_L(0); PG8_BAR; PG8_MMA(1, 0, At, B0); PG8_MMA(1, 1, At, B1); PG8_BAR; PG8_SCHED;
;             PG8_LDB(B0, 1, 0); PG8_LDB(B1, 1, 1); PG8_SCHED; PG8_LDA(At, 1, 0); PG8_STAGE(PG8_SA(0, 1), a2 + hstepA, voffA);
;             PG8_WAIT_V(8); PG8_WAIT_L(0); PG8_BAR; PG8_MMA(0, 0, At, B0); PG8_MMA(0, 1, At, B1); PG8_BAR; PG8_SCHED;
;             PG8_LDA(At, 1, 1); PG8_STAGE(PG8_SB(1, 0), b3, voffB); PG8_STAGE(PG8_SB(1, 1), b3 + hstepB, voffB); PG8_STAGE(PG8_SA(1, 0), a3, voffA);
;             PG8_WAIT_V(8); PG8_WAIT_L(0); PG8_BAR; PG8_MMA(1, 0, At, B0); PG8_MMA(1, 1, At, B1); PG8_BAR; PG8_SCHED;
	s_setprio 1
	s_waitcnt lgkmcnt(0)
	v_mfma_i32_16x16x64_i8 v[142:145], v[122:125], v[198:201], v[142:145]
	v_mfma_i32_16x16x64_i8 v[142:145], v[126:129], v[202:205], v[142:145]
	v_mfma_i32_16x16x64_i8 v[134:137], v[138:141], v[202:205], v[134:137]
	v_mfma_i32_16x16x64_i8 v[134:137], v[130:133], v[198:201], v[134:137]
	v_mfma_i32_16x16x64_i8 v[106:109], v[130:133], v[206:209], v[106:109]
	v_mfma_i32_16x16x64_i8 v[106:109], v[138:141], v[212:215], v[106:109]
	v_mfma_i32_16x16x64_i8 v[110:113], v[126:129], v[212:215], v[110:113]
	v_mfma_i32_16x16x64_i8 v[110:113], v[122:125], v[206:209], v[110:113]
	v_mfma_i32_16x16x64_i8 v[94:97], v[122:125], v[216:219], v[94:97]
	v_mfma_i32_16x16x64_i8 v[94:97], v[126:129], v[220:223], v[94:97]
	v_mfma_i32_16x16x64_i8 v[90:93], v[138:141], v[220:223], v[90:93]
	v_mfma_i32_16x16x64_i8 v[90:93], v[130:133], v[216:219], v[90:93]
	v_mfma_i32_16x16x64_i8 v[74:77], v[130:133], v[224:227], v[74:77]
	v_mfma_i32_16x16x64_i8 v[74:77], v[138:141], v[228:231], v[74:77]
	v_mfma_i32_16x16x64_i8 v[78:81], v[126:129], v[228:231], v[78:81]
	v_mfma_i32_16x16x64_i8 v[78:81], v[122:125], v[224:227], v[78:81]
	s_setprio 0
	s_setprio 1
	v_mfma_i32_16x16x64_i8 v[70:73], v[182:185], v[224:227], v[70:73]
	v_mfma_i32_16x16x64_i8 v[70:73], v[186:189], v[228:231], v[70:73]
	v_mfma_i32_16x16x64_i8 v[66:69], v[194:197], v[228:231], v[66:69]
	v_mfma_i32_16x16x64_i8 v[66:69], v[190:193], v[224:227], v[66:69]
	v_mfma_i32_16x16x64_i8 v[82:85], v[190:193], v[216:219], v[82:85]
	v_mfma_i32_16x16x64_i8 v[82:85], v[194:197], v[220:223], v[82:85]
	v_mfma_i32_16x16x64_i8 v[86:89], v[186:189], v[220:223], v[86:89]
	v_mfma_i32_16x16x64_i8 v[86:89], v[182:185], v[216:219], v[86:89]
	v_mfma_i32_16x16x64_i8 v[102:105], v[182:185], v[206:209], v[102:105]
	v_mfma_i32_16x16x64_i8 v[102:105], v[186:189], v[212:215], v[102:105]
	v_mfma_i32_16x16x64_i8 v[98:101], v[194:197], v[212:215], v[98:101]
	v_mfma_i32_16x16x64_i8 v[98:101], v[190:193], v[206:209], v[98:101]
	v_mfma_i32_16x16x64_i8 v[114:117], v[190:193], v[198:201], v[114:117]
	v_mfma_i32_16x16x64_i8 v[114:117], v[194:197], v[202:205], v[114:117]
	v_mfma_i32_16x16x64_i8 v[118:121], v[186:189], v[202:205], v[118:121]
	v_mfma_i32_16x16x64_i8 v[118:121], v[182:185], v[198:201], v[118:121]
	s_setprio 0
	s_barrier
	s_add_i32 s68, s29, s7
	v_lshl_add_u64 v[166:167], s[58:59], 0, v[148:149]
	s_mov_b32 m0, s68
	ds_read_b128 v[198:201], v174 offset:16384
	ds_read_b128 v[202:205], v174 offset:17408
	ds_read_b128 v[206:209], v174 offset:18432
	ds_read_b128 v[212:215], v174 offset:19456
	ds_read_b128 v[216:219], v174 offset:20480
	ds_read_b128 v[220:223], v174 offset:21504
	ds_read_b128 v[224:227], v174 offset:22528
	ds_read_b128 v[228:231], v174 offset:23552
	global_load_lds_dwordx4 v[166:167], off
	s_add_i32 m0, s68, 0x2000
	s_add_u32 s68, s58, 0x158000
	v_lshl_add_u64 v[176:177], s[58:59], 0, v[152:153]
	s_addc_u32 s69, s59, 0
	s_add_i32 s70, s33, s7
	global_load_lds_dwordx4 v[176:177], off
	v_lshl_add_u64 v[232:233], s[68:69], 0, v[148:149]
	s_mov_b32 m0, s70
	v_lshl_add_u64 v[234:235], s[60:61], 0, v[150:151]
	global_load_lds_dwordx4 v[232:233], off
	v_lshl_add_u64 v[232:233], s[68:69], 0, v[152:153]
	s_add_i32 m0, s70, 0x2000
	s_nop 0
	global_load_lds_dwordx4 v[232:233], off
	v_lshl_add_u64 v[232:233], s[60:61], 0, v[146:147]
	s_mov_b32 m0, s9
	s_nop 0
	global_load_lds_dwordx4 v[232:233], off
	s_mov_b32 m0, s11
	s_nop 0
	global_load_lds_dwordx4 v[234:235], off
	s_waitcnt vmcnt(8)
	s_waitcnt lgkmcnt(0)
	s_barrier
	s_setprio 1
	s_waitcnt lgkmcnt(0)
	v_mfma_i32_16x16x64_i8 v[62:65], v[122:125], v[198:201], v[62:65]
	v_mfma_i32_16x16x64_i8 v[62:65], v[126:129], v[202:205], v[62:65]
	v_mfma_i32_16x16x64_i8 v[58:61], v[138:141], v[202:205], v[58:61]
	v_mfma_i32_16x16x64_i8 v[58:61], v[130:133], v[198:201], v[58:61]
	v_mfma_i32_16x16x64_i8 v[42:45], v[130:133], v[206:209], v[42:45]
	v_mfma_i32_16x16x64_i8 v[42:45], v[138:141], v[212:215], v[42:45]
	v_mfma_i32_16x16x64_i8 v[46:49], v[126:129], v[212:215], v[46:49]
	v_mfma_i32_16x16x64_i8 v[46:49], v[122:125], v[206:209], v[46:49]
	v_mfma_i32_16x16x64_i8 v[30:33], v[122:125], v[216:219], v[30:33]
	v_mfma_i32_16x16x64_i8 v[30:33], v[126:129], v[220:223], v[30:33]
	v_mfma_i32_16x16x64_i8 v[26:29], v[138:141], v[220:223], v[26:29]
	v_mfma_i32_16x16x64_i8 v[26:29], v[130:133], v[216:219], v[26:29]
	v_mfma_i32_16x16x64_i8 v[10:13], v[130:133], v[224:227], v[10:13]
	v_mfma_i32_16x16x64_i8 v[10:13], v[138:141], v[228:231], v[10:13]
	v_mfma_i32_16x16x64_i8 v[14:17], v[126:129], v[228:231], v[14:17]
	v_mfma_i32_16x16x64_i8 v[14:17], v[122:125], v[224:227], v[14:17]
	s_setprio 0
	s_setprio 1
	v_mfma_i32_16x16x64_i8 v[6:9], v[182:185], v[224:227], v[6:9]
	v_mfma_i32_16x16x64_i8 v[6:9], v[186:189], v[228:231], v[6:9]
	v_mfma_i32_16x16x64_i8 v[2:5], v[194:197], v[228:231], v[2:5]
	v_mfma_i32_16x16x64_i8 v[2:5], v[190:193], v[224:227], v[2:5]
	v_mfma_i32_16x16x64_i8 v[18:21], v[190:193], v[216:219], v[18:21]
	v_mfma_i32_16x16x64_i8 v[18:21], v[194:197], v[220:223], v[18:21]
	v_mfma_i32_16x16x64_i8 v[22:25], v[186:189], v[220:223], v[22:25]
	v_mfma_i32_16x16x64_i8 v[22:25], v[182:185], v[216:219], v[22:25]
	v_mfma_i32_16x16x64_i8 v[38:41], v[182:185], v[206:209], v[38:41]
	v_mfma_i32_16x16x64_i8 v[38:41], v[186:189], v[212:215], v[38:41]
	v_mfma_i32_16x16x64_i8 v[34:37], v[194:197], v[212:215], v[34:37]
	v_mfma_i32_16x16x64_i8 v[34:37], v[190:193], v[206:209], v[34:37]
	v_mfma_i32_16x16x64_i8 v[50:53], v[190:193], v[198:201], v[50:53]
	v_mfma_i32_16x16x64_i8 v[50:53], v[194:197], v[202:205], v[50:53]
	v_mfma_i32_16x16x64_i8 v[54:57], v[186:189], v[202:205], v[54:57]
	v_mfma_i32_16x16x64_i8 v[54:57], v[182:185], v[198:201], v[54:57]
	s_setprio 0
	s_barrier
; #define PG8_STAGE(bufoff, gbase, voff) do { _Pragma("unroll") for (int _i = 0; _i < 2; ++_i) \
;         __builtin_amdgcn_global_load_lds((const unsigned*)((const char*)(gbase) + (voff)[_i]), (PG8_LAS unsigned*)(lds + (bufoff) + ldsw + _i * 8192), 16, 0, 0); } while (0)
; #define PG8_LDA(dst, b, h) do { _Pragma("unroll") for (int m = 0; m < 4; ++m) _Pragma("unroll") for (int k = 0; k < 2; ++k) dst[m][k] = *(const PG8_LAS bf16x8*)(lds + PG8_SA(b, h) + aoff + m * 2048 + k * 1024); } while (0)
; #define PG8_LDB(dst, b, h) do { _Pragma("unroll") for (int n = 0; n < 2; ++n) _Pragma("unroll") for (int k = 0; k < 2; ++k) dst[n][k] = *(const PG8_LAS bf16x8*)(lds + PG8_SB(b, h) + boff + n * 2048 + k * 1024); } while (0)
; #define PG8_MMA(ai, bj, At, Bt) do { __builtin_amdgcn_s_setprio(1); _Pragma("unroll") for (int m = 0; m < 4; ++m) _Pragma("unroll") for (int n = 0; n < 2; ++n) _Pragma("unroll") for (int k = 0; k < 2; ++k) \
;         acc[ai][bj][m][n] = mma16(Bt[n][k], At[m][k], acc[ai][bj][m][n]); __builtin_amdgcn_s_setprio(0); } while (0)
; #define PG8_WAIT_V(n) asm volatile("s_waitcnt vmcnt(" #n ")" ::: "memory")
; #define PG8_WAIT_L(n) asm volatile("s_waitcnt lgkmcnt(" #n ")" ::: "memory")
; #define PG8_BAR __builtin_amdgcn_s_barrier()
; #define PG8_SCHED __builtin_amdgcn_sched_barrier(0)
; template <class Epi, class Sched, bool ALIGN_EPI = false, bool SP2 = false>
; __device__ __forceinline__ void gemm_phase(PG8_LAS unsigned char* lds, const Gemm g, const Sched& S, const Epi& E) {
;     ...
;             PG8_LDB(B0, 1, 0); PG8_LDB(B1, 1, 1); PG8_SCHED; PG8_LDA(At, 1, 0); PG8_STAGE(PG8_SA(0, 1), a2 + hstepA, voffA);
;             PG8_WAIT_V(8); PG8_WAIT_L(0); PG8_BAR; PG8_MMA(0, 0, At, B0); PG8_MMA(0, 1, At, B1); PG8_BAR; PG8_SCHED;
	s_add_i32 s68, 0, 0x18000
	s_add_i32 s69, 0, 0x1c000
	v_add_u32_e32 v138, s68, v170
	v_add_u32_e32 v175, s69, v170
	ds_read_b128 v[122:125], v138
	ds_read_b128 v[126:129], v138 offset:1024
	ds_read_b128 v[130:133], v138 offset:2048
	ds_read_b128 v[138:141], v138 offset:3072
	ds_read_b128 v[182:185], v175
	ds_read_b128 v[186:189], v175 offset:1024
	ds_read_b128 v[190:193], v175 offset:2048
	ds_read_b128 v[194:197], v175 offset:3072
	s_add_u32 s60, s60, 0x158000
	s_addc_u32 s61, s61, 0
	s_mov_b32 m0, s12
	v_lshl_add_u64 v[236:237], s[60:61], 0, v[146:147]
	ds_read_b128 v[198:201], v174 offset:32768
	ds_read_b128 v[202:205], v174 offset:33792
	ds_read_b128 v[206:209], v174 offset:34816
	ds_read_b128 v[212:215], v174 offset:35840
	ds_read_b128 v[216:219], v174 offset:36864
	ds_read_b128 v[220:223], v174 offset:37888
	ds_read_b128 v[224:227], v174 offset:38912
	ds_read_b128 v[228:231], v174 offset:39936
	global_load_lds_dwordx4 v[236:237], off
	v_lshl_add_u64 v[236:237], s[60:61], 0, v[150:151]
	s_mov_b32 m0, s13
	s_nop 0
	global_load_lds_dwordx4 v[236:237], off
	s_waitcnt vmcnt(8)
	s_waitcnt lgkmcnt(0)
	s_barrier
	s_setprio 1
	s_waitcnt lgkmcnt(0)
	v_mfma_i32_16x16x64_i8 v[142:145], v[122:125], v[198:201], v[142:145]
	v_mfma_i32_16x16x64_i8 v[142:145], v[126:129], v[202:205], v[142:145]
	v_mfma_i32_16x16x64_i8 v[134:137], v[138:141], v[202:205], v[134:137]
	v_mfma_i32_16x16x64_i8 v[134:137], v[130:133], v[198:201], v[134:137]
	v_mfma_i32_16x16x64_i8 v[106:109], v[130:133], v[206:209], v[106:109]
	v_mfma_i32_16x16x64_i8 v[106:109], v[138:141], v[212:215], v[106:109]
	v_mfma_i32_16x16x64_i8 v[110:113], v[126:129], v[212:215], v[110:113]
	v_mfma_i32_16x16x64_i8 v[110:113], v[122:125], v[206:209], v[110:113]
	v_mfma_i32_16x16x64_i8 v[94:97], v[122:125], v[216:219], v[94:97]
	v_mfma_i32_16x16x64_i8 v[94:97], v[126:129], v[220:223], v[94:97]
	v_mfma_i32_16x16x64_i8 v[90:93], v[138:141], v[220:223], v[90:93]
	v_mfma_i32_16x16x64_i8 v[90:93], v[130:133], v[216:219], v[90:93]
	v_mfma_i32_16x16x64_i8 v[74:77], v[130:133], v[224:227], v[74:77]
	v_mfma_i32_16x16x64_i8 v[74:77], v[138:141], v[228:231], v[74:77]
	v_mfma_i32_16x16x64_i8 v[78:81], v[126:129], v[228:231], v[78:81]
	v_mfma_i32_16x16x64_i8 v[78:81], v[122:125], v[224:227], v[78:81]
	s_setprio 0
	s_setprio 1
	v_mfma_i32_16x16x64_i8 v[70:73], v[182:185], v[224:227], v[70:73]
	v_mfma_i32_16x16x64_i8 v[70:73], v[186:189], v[228:231], v[70:73]
	v_mfma_i32_16x16x64_i8 v[66:69], v[194:197], v[228:231], v[66:69]
	v_mfma_i32_16x16x64_i8 v[66:69], v[190:193], v[224:227], v[66:69]
	v_mfma_i32_16x16x64_i8 v[82:85], v[190:193], v[216:219], v[82:85]
	v_mfma_i32_16x16x64_i8 v[82:85], v[194:197], v[220:223], v[82:85]
	v_mfma_i32_16x16x64_i8 v[86:89], v[186:189], v[220:223], v[86:89]
	v_mfma_i32_16x16x64_i8 v[86:89], v[182:185], v[216:219], v[86:89]
	v_mfma_i32_16x16x64_i8 v[102:105], v[182:185], v[206:209], v[102:105]
	v_mfma_i32_16x16x64_i8 v[102:105], v[186:189], v[212:215], v[102:105]
	v_mfma_i32_16x16x64_i8 v[98:101], v[194:197], v[212:215], v[98:101]
	v_mfma_i32_16x16x64_i8 v[98:101], v[190:193], v[206:209], v[98:101]
	v_mfma_i32_16x16x64_i8 v[114:117], v[190:193], v[198:201], v[114:117]
	v_mfma_i32_16x16x64_i8 v[114:117], v[194:197], v[202:205], v[114:117]
	v_mfma_i32_16x16x64_i8 v[118:121], v[186:189], v[202:205], v[118:121]
	v_mfma_i32_16x16x64_i8 v[118:121], v[182:185], v[198:201], v[118:121]
	s_setprio 0
	s_barrier
; #define PG8_STAGE(bufoff, gbase, voff) do { _Pragma("unroll") for (int _i = 0; _i < 2; ++_i) \
;         __builtin_amdgcn_global_load_lds((const unsigned*)((const char*)(gbase) + (voff)[_i]), (PG8_LAS unsigned*)(lds + (bufoff) + ldsw + _i * 8192), 16, 0, 0); } while (0)
; #define PG8_LDA(dst, b, h) do { _Pragma("unroll") for (int m = 0; m < 4; ++m) _Pragma("unroll") for (int k = 0; k < 2; ++k) dst[m][k] = *(const PG8_LAS bf16x8*)(lds + PG8_SA(b, h) + aoff + m * 2048 + k * 1024); } while (0)
; #define PG8_MMA(ai, bj, At, Bt) do { __builtin_amdgcn_s_setprio(1); _Pragma("unroll") for (int m = 0; m < 4; ++m) _Pragma("unroll") for (int n = 0; n < 2; ++n) _Pragma("unroll") for (int k = 0; k < 2; ++k) \
;         acc[ai][bj][m][n] = mma16(Bt[n][k], At[m][k], acc[ai][bj][m][n]); __builtin_amdgcn_s_setprio(0); } while (0)
; #define PG8_WAIT_V(n) asm volatile("s_waitcnt vmcnt(" #n ")" ::: "memory")
; #define PG8_WAIT_L(n) asm volatile("s_waitcnt lgkmcnt(" #n ")" ::: "memory")
; #define PG8_BAR __builtin_amdgcn_s_barrier()
; #define PG8_SCHED __builtin_amdgcn_sched_barrier(0)
; template <class Epi, class Sched, bool ALIGN_EPI = false, bool SP2 = false>
; __device__ __forceinline__ void gemm_phase(PG8_LAS unsigned char* lds, const Gemm g, const Sched& S, const Epi& E) {
;     ...
;             PG8_LDA(At, 1, 1); PG8_STAGE(PG8_SB(1, 0), b3, voffB); PG8_STAGE(PG8_SB(1, 1), b3 + hstepB, voffB); PG8_STAGE(PG8_SA(1, 0), a3, voffA);
;             PG8_WAIT_V(8); PG8_WAIT_L(0); PG8_BAR; PG8_MMA(1, 0, At, B0); PG8_MMA(1, 1, At, B1); PG8_BAR; PG8_SCHED;
;     ...
;         if constexpr (ALIGN_EPI) { if (wr == 0) PG8_BAR; }
	s_add_i32 s60, s68, s7
	v_lshl_add_u64 v[166:167], v[166:167], 0, s[24:25]
	s_mov_b32 m0, s60
	ds_read_b128 v[198:201], v174 offset:49152
	ds_read_b128 v[202:205], v174 offset:50176
	ds_read_b128 v[206:209], v174 offset:51200
	ds_read_b128 v[212:215], v174 offset:52224
	ds_read_b128 v[216:219], v174 offset:53248
	ds_read_b128 v[220:223], v174 offset:54272
	ds_read_b128 v[224:227], v174 offset:55296
	ds_read_b128 v[228:231], v174 offset:56320
	global_load_lds_dwordx4 v[166:167], off
	s_add_i32 m0, s60, 0x2000
	s_add_u32 s58, s58, 0x158080
	v_lshl_add_u64 v[166:167], v[176:177], 0, s[24:25]
	s_addc_u32 s59, s59, 0
	s_add_i32 s60, s69, s7
	global_load_lds_dwordx4 v[166:167], off
	v_lshl_add_u64 v[166:167], s[58:59], 0, v[148:149]
	s_mov_b32 m0, s60
	s_nop 0
	global_load_lds_dwordx4 v[166:167], off
	v_lshl_add_u64 v[166:167], s[58:59], 0, v[152:153]
	s_add_i32 m0, s60, 0x2000
	s_nop 0
	global_load_lds_dwordx4 v[166:167], off
	v_lshl_add_u64 v[166:167], v[232:233], 0, s[24:25]
	s_mov_b32 m0, s26
	s_nop 0
	global_load_lds_dwordx4 v[166:167], off
	v_lshl_add_u64 v[166:167], v[234:235], 0, s[24:25]
	s_mov_b32 m0, s27
	s_nop 0
	global_load_lds_dwordx4 v[166:167], off
	s_waitcnt vmcnt(8)
	s_waitcnt lgkmcnt(0)
	s_barrier
	s_setprio 1
	s_waitcnt lgkmcnt(0)
	v_mfma_i32_16x16x64_i8 v[62:65], v[122:125], v[198:201], v[62:65]
	v_mfma_i32_16x16x64_i8 v[62:65], v[126:129], v[202:205], v[62:65]
	v_mfma_i32_16x16x64_i8 v[58:61], v[138:141], v[202:205], v[58:61]
	v_mfma_i32_16x16x64_i8 v[58:61], v[130:133], v[198:201], v[58:61]
	v_mfma_i32_16x16x64_i8 v[42:45], v[130:133], v[206:209], v[42:45]
	v_mfma_i32_16x16x64_i8 v[42:45], v[138:141], v[212:215], v[42:45]
	v_mfma_i32_16x16x64_i8 v[46:49], v[126:129], v[212:215], v[46:49]
	v_mfma_i32_16x16x64_i8 v[46:49], v[122:125], v[206:209], v[46:49]
	v_mfma_i32_16x16x64_i8 v[30:33], v[122:125], v[216:219], v[30:33]
	v_mfma_i32_16x16x64_i8 v[30:33], v[126:129], v[220:223], v[30:33]
	v_mfma_i32_16x16x64_i8 v[26:29], v[138:141], v[220:223], v[26:29]
	v_mfma_i32_16x16x64_i8 v[26:29], v[130:133], v[216:219], v[26:29]
	v_mfma_i32_16x16x64_i8 v[10:13], v[130:133], v[224:227], v[10:13]
	v_mfma_i32_16x16x64_i8 v[10:13], v[138:141], v[228:231], v[10:13]
	v_mfma_i32_16x16x64_i8 v[14:17], v[126:129], v[228:231], v[14:17]
	v_mfma_i32_16x16x64_i8 v[14:17], v[122:125], v[224:227], v[14:17]
	s_setprio 0
	s_setprio 1
	v_mfma_i32_16x16x64_i8 v[6:9], v[182:185], v[224:227], v[6:9]
	v_mfma_i32_16x16x64_i8 v[6:9], v[186:189], v[228:231], v[6:9]
	v_mfma_i32_16x16x64_i8 v[2:5], v[194:197], v[228:231], v[2:5]
	v_mfma_i32_16x16x64_i8 v[2:5], v[190:193], v[224:227], v[2:5]
	v_mfma_i32_16x16x64_i8 v[18:21], v[190:193], v[216:219], v[18:21]
	v_mfma_i32_16x16x64_i8 v[18:21], v[194:197], v[220:223], v[18:21]
	v_mfma_i32_16x16x64_i8 v[22:25], v[186:189], v[220:223], v[22:25]
	v_mfma_i32_16x16x64_i8 v[22:25], v[182:185], v[216:219], v[22:25]
	v_mfma_i32_16x16x64_i8 v[38:41], v[182:185], v[206:209], v[38:41]
	v_mfma_i32_16x16x64_i8 v[38:41], v[186:189], v[212:215], v[38:41]
	v_mfma_i32_16x16x64_i8 v[34:37], v[194:197], v[212:215], v[34:37]
	v_mfma_i32_16x16x64_i8 v[34:37], v[190:193], v[206:209], v[34:37]
	v_mfma_i32_16x16x64_i8 v[50:53], v[190:193], v[198:201], v[50:53]
	v_mfma_i32_16x16x64_i8 v[50:53], v[194:197], v[202:205], v[50:53]
	v_mfma_i32_16x16x64_i8 v[54:57], v[186:189], v[202:205], v[54:57]
	v_mfma_i32_16x16x64_i8 v[54:57], v[182:185], v[198:201], v[54:57]
	s_setprio 0
	s_barrier
	s_add_i32 s67, s67, 2
	s_add_u32 s56, s56, 0x100
	s_addc_u32 s57, s57, 0
	s_add_u32 s65, s65, 0x100
	s_addc_u32 s66, s66, 0
	s_cmpk_gt_u32 s67, 0x53
	s_cbranch_scc0 .LBB0_1020
	s_and_b64 vcc, exec, s[36:37]
	s_cbranch_vccz .LBB0_1023
	s_barrier

; #define PG8_STAGE(bufoff, gbase, voff) do { _Pragma("unroll") for (int _i = 0; _i < 2; ++_i) \
;         __builtin_amdgcn_global_load_lds((const unsigned*)((const char*)(gbase) + (voff)[_i]), (PG8_LAS unsigned*)(lds + (bufoff) + ldsw + _i * 8192), 16, 0, 0); } while (0)
; #define PG8_LDA(dst, b, h) do { _Pragma("unroll") for (int m = 0; m < 4; ++m) _Pragma("unroll") for (int k = 0; k < 2; ++k) dst[m][k] = *(const PG8_LAS bf16x8*)(lds + PG8_SA(b, h) + aoff + m * 2048 + k * 1024); } while (0)
; #define PG8_LDB(dst, b, h) do { _Pragma("unroll") for (int n = 0; n < 2; ++n) _Pragma("unroll") for (int k = 0; k < 2; ++k) dst[n][k] = *(const PG8_LAS bf16x8*)(lds + PG8_SB(b, h) + boff + n * 2048 + k * 1024); } while (0)
; template <class Epi, class Sched, bool ALIGN_EPI = false, bool SP2 = false>
; __device__ __forceinline__ void gemm_phase(PG8_LAS unsigned char* lds, const Gemm g, const Sched& S, const Epi& E) {
;     ...
;         for (int t = 0; t < nt; t += 2) {
;             const bool last = (t == nt - 2);
;             const char* a1 = cA + (size_t)(t + 1) * kstep;
;             const char* a2 = last ? nA : cA + (size_t)(t + 2) * kstep; const char* b2 = last ? nB : cB + (size_t)(t + 2) * kstep;
;             const char* a3 = a2 + kstep; const char* b3 = b2 + kstep;
;             if (last && has_next) S.a_ready(nxt);
;             if constexpr (SP2) {
;             PG8_LDB(B0, 0, 0); PG8_LDB(B1, 0, 1); PG8_SCHED; PG8_LDA(At, 0, 0); PG8_STAGE(PG8_SA(1, 1), a1 + hstepA, voffA);
;             PG8_WAIT_V(8); PG8_WAIT_L(0); PG8_BAR; PG8_MMA(0, 0, At, B0); PG8_MMA(0, 1, At, B1); PG8_BAR; PG8_SCHED;
;             PG8_LDA(At, 0, 1); PG8_STAGE(PG8_SB(0, 0), b2, voffB); PG8_STAGE(PG8_SB(0, 1), b2 + hstepB, voffB); PG8_STAGE(PG8_SA(0, 0), a2, voffA);
;             PG8_WAIT_V(8); PG8_WAIT_L(0); PG8_BAR; PG8_MMA(1, 0, At, B0); PG8_MMA(1, 1, At, B1); PG8_BAR; PG8_SCHED;
;             PG8_LDB(B0, 1, 0); PG8_LDB(B1, 1, 1); PG8_SCHED; PG8_LDA(At, 1, 0); PG8_STAGE(PG8_SA(0, 1), a2 + hstepA, voffA);
;             PG8_WAIT_V(8); PG8_WAIT_L(0); PG8_BAR; PG8_MMA(0, 0, At, B0); PG8_MMA(0, 1, At, B1); PG8_BAR; PG8_SCHED;
;             PG8_LDA(At, 1, 1); PG8_STAGE(PG8_SB(1, 0), b3, voffB); PG8_STAGE(PG8_SB(1, 1), b3 + hstepB, voffB); PG8_STAGE(PG8_SA(1, 0), a3, voffA);
;             PG8_WAIT_V(8); PG8_WAIT_L(0); PG8_BAR; PG8_MMA(1, 0, At, B0); PG8_MMA(1, 1, At, B1); PG8_BAR; PG8_SCHED;
.LBB0_1036:
	s_add_u32 s50, s50, 0x158080
	s_addc_u32 s51, s51, 0
	s_add_u32 s45, s8, 0x100
	s_addc_u32 s70, s9, 0
	s_mov_b32 s71, -2
	ds_read_b128 v[118:121], v167
	ds_read_b128 v[126:129], v167 offset:1024
	ds_read_b128 v[130:133], v167 offset:2048
	ds_read_b128 v[134:137], v167 offset:3072
	ds_read_b128 v[172:175], v168
	ds_read_b128 v[182:185], v168 offset:1024
	ds_read_b128 v[186:189], v168 offset:2048
	ds_read_b128 v[190:193], v168 offset:3072
	s_add_u32 s52, s50, 0xffea8080
	s_addc_u32 s53, s51, -1
	s_cmpk_eq_i32 s71, 0x52
	s_cselect_b32 s55, s47, s53
	s_cselect_b32 s54, s46, s52
	s_cselect_b32 s53, s9, s70
	s_cselect_b32 s52, s8, s45
	s_mov_b32 m0, s35
	v_lshl_add_u64 v[162:163], s[50:51], 0, v[158:159]
	ds_read_b128 v[194:197], v169
	ds_read_b128 v[198:201], v169 offset:1024
	ds_read_b128 v[202:205], v169 offset:2048
	ds_read_b128 v[206:209], v169 offset:3072
	ds_read_b128 v[212:215], v169 offset:4096
	ds_read_b128 v[216:219], v169 offset:5120
	ds_read_b128 v[220:223], v169 offset:6144
	ds_read_b128 v[224:227], v169 offset:7168
	global_load_lds_dwordx4 v[162:163], off
	v_lshl_add_u64 v[162:163], s[50:51], 0, v[160:161]
	s_mov_b32 m0, s56
	s_nop 0
	global_load_lds_dwordx4 v[162:163], off
	s_waitcnt vmcnt(8)
	s_waitcnt lgkmcnt(0)
	s_barrier
	s_setprio 1
	s_waitcnt lgkmcnt(0)
	v_mfma_i32_16x16x64_i8 v[142:145], v[118:121], v[194:197], 0
	v_mfma_i32_16x16x64_i8 v[142:145], v[126:129], v[198:201], v[142:145]
	v_mfma_i32_16x16x64_i8 v[138:141], v[134:137], v[198:201], 0
	v_mfma_i32_16x16x64_i8 v[138:141], v[130:133], v[194:197], v[138:141]
	v_mfma_i32_16x16x64_i8 v[106:109], v[130:133], v[202:205], 0
	v_mfma_i32_16x16x64_i8 v[106:109], v[134:137], v[206:209], v[106:109]
	v_mfma_i32_16x16x64_i8 v[110:113], v[126:129], v[206:209], 0
	v_mfma_i32_16x16x64_i8 v[110:113], v[118:121], v[202:205], v[110:113]
	v_mfma_i32_16x16x64_i8 v[94:97], v[118:121], v[212:215], 0
	v_mfma_i32_16x16x64_i8 v[94:97], v[126:129], v[216:219], v[94:97]
	v_mfma_i32_16x16x64_i8 v[90:93], v[134:137], v[216:219], 0
	v_mfma_i32_16x16x64_i8 v[90:93], v[130:133], v[212:215], v[90:93]
	v_mfma_i32_16x16x64_i8 v[74:77], v[130:133], v[220:223], 0
	v_mfma_i32_16x16x64_i8 v[74:77], v[134:137], v[224:227], v[74:77]
	v_mfma_i32_16x16x64_i8 v[78:81], v[126:129], v[224:227], 0
	v_mfma_i32_16x16x64_i8 v[78:81], v[118:121], v[220:223], v[78:81]
	s_setprio 0
	s_setprio 1
	v_mfma_i32_16x16x64_i8 v[70:73], v[172:175], v[220:223], 0
	v_mfma_i32_16x16x64_i8 v[70:73], v[182:185], v[224:227], v[70:73]
	v_mfma_i32_16x16x64_i8 v[66:69], v[190:193], v[224:227], 0
	v_mfma_i32_16x16x64_i8 v[66:69], v[186:189], v[220:223], v[66:69]
	v_mfma_i32_16x16x64_i8 v[82:85], v[186:189], v[212:215], 0
	v_mfma_i32_16x16x64_i8 v[82:85], v[190:193], v[216:219], v[82:85]
	v_mfma_i32_16x16x64_i8 v[86:89], v[182:185], v[216:219], 0
	v_mfma_i32_16x16x64_i8 v[86:89], v[172:175], v[212:215], v[86:89]
	v_mfma_i32_16x16x64_i8 v[102:105], v[172:175], v[202:205], 0
	v_mfma_i32_16x16x64_i8 v[102:105], v[182:185], v[206:209], v[102:105]
	v_mfma_i32_16x16x64_i8 v[98:101], v[190:193], v[206:209], 0
	v_mfma_i32_16x16x64_i8 v[98:101], v[186:189], v[202:205], v[98:101]
	v_mfma_i32_16x16x64_i8 v[114:117], v[186:189], v[194:197], 0
	v_mfma_i32_16x16x64_i8 v[114:117], v[190:193], v[198:201], v[114:117]
	v_mfma_i32_16x16x64_i8 v[122:125], v[182:185], v[198:201], 0
	v_mfma_i32_16x16x64_i8 v[122:125], v[172:175], v[194:197], v[122:125]
	s_setprio 0
	s_barrier
	s_mov_b32 m0, s57
	v_lshl_add_u64 v[162:163], s[52:53], 0, v[150:151]
	s_add_u32 s74, s52, 0x158000
	ds_read_b128 v[194:197], v169 offset:16384
	ds_read_b128 v[198:201], v169 offset:17408
	ds_read_b128 v[202:205], v169 offset:18432
	ds_read_b128 v[206:209], v169 offset:19456
	ds_read_b128 v[212:215], v169 offset:20480
	ds_read_b128 v[216:219], v169 offset:21504
	ds_read_b128 v[220:223], v169 offset:22528
	ds_read_b128 v[224:227], v169 offset:23552
	global_load_lds_dwordx4 v[162:163], off
	v_lshl_add_u64 v[176:177], s[52:53], 0, v[146:147]
	s_mov_b32 m0, s58
	s_addc_u32 s75, s53, 0
	global_load_lds_dwordx4 v[176:177], off
	v_lshl_add_u64 v[228:229], s[74:75], 0, v[150:151]
	s_mov_b32 m0, s63
	v_lshl_add_u64 v[230:231], s[54:55], 0, v[148:149]
	global_load_lds_dwordx4 v[228:229], off
	v_lshl_add_u64 v[228:229], s[74:75], 0, v[146:147]
	s_mov_b32 m0, s64
	s_nop 0
	global_load_lds_dwordx4 v[228:229], off
	v_lshl_add_u64 v[228:229], s[54:55], 0, v[152:153]
	s_mov_b32 m0, s5
	s_nop 0
	global_load_lds_dwordx4 v[228:229], off
	s_mov_b32 m0, s6
	s_nop 0
	global_load_lds_dwordx4 v[230:231], off
	s_waitcnt vmcnt(8)
	s_waitcnt lgkmcnt(0)
	s_barrier
	s_setprio 1
	s_waitcnt lgkmcnt(0)
	v_mfma_i32_16x16x64_i8 v[62:65], v[118:121], v[194:197], 0
	v_mfma_i32_16x16x64_i8 v[62:65], v[126:129], v[198:201], v[62:65]
	v_mfma_i32_16x16x64_i8 v[58:61], v[134:137], v[198:201], 0
	v_mfma_i32_16x16x64_i8 v[58:61], v[130:133], v[194:197], v[58:61]
	v_mfma_i32_16x16x64_i8 v[42:45], v[130:133], v[202:205], 0
	v_mfma_i32_16x16x64_i8 v[42:45], v[134:137], v[206:209], v[42:45]
	v_mfma_i32_16x16x64_i8 v[46:49], v[126:129], v[206:209], 0
	v_mfma_i32_16x16x64_i8 v[46:49], v[118:121], v[202:205], v[46:49]
	v_mfma_i32_16x16x64_i8 v[30:33], v[118:121], v[212:215], 0
	v_mfma_i32_16x16x64_i8 v[30:33], v[126:129], v[216:219], v[30:33]
	v_mfma_i32_16x16x64_i8 v[26:29], v[134:137], v[216:219], 0
	v_mfma_i32_16x16x64_i8 v[26:29], v[130:133], v[212:215], v[26:29]
	v_mfma_i32_16x16x64_i8 v[10:13], v[130:133], v[220:223], 0
	v_mfma_i32_16x16x64_i8 v[10:13], v[134:137], v[224:227], v[10:13]
	v_mfma_i32_16x16x64_i8 v[14:17], v[126:129], v[224:227], 0
	v_mfma_i32_16x16x64_i8 v[14:17], v[118:121], v[220:223], v[14:17]
	s_setprio 0
	s_setprio 1
	v_mfma_i32_16x16x64_i8 v[6:9], v[172:175], v[220:223], 0
	v_mfma_i32_16x16x64_i8 v[6:9], v[182:185], v[224:227], v[6:9]
	v_mfma_i32_16x16x64_i8 v[2:5], v[190:193], v[224:227], 0
	v_mfma_i32_16x16x64_i8 v[2:5], v[186:189], v[220:223], v[2:5]
	v_mfma_i32_16x16x64_i8 v[18:21], v[186:189], v[212:215], 0
	v_mfma_i32_16x16x64_i8 v[18:21], v[190:193], v[216:219], v[18:21]
	v_mfma_i32_16x16x64_i8 v[22:25], v[182:185], v[216:219], 0
	v_mfma_i32_16x16x64_i8 v[22:25], v[172:175], v[212:215], v[22:25]
	v_mfma_i32_16x16x64_i8 v[38:41], v[172:175], v[202:205], 0
	v_mfma_i32_16x16x64_i8 v[38:41], v[182:185], v[206:209], v[38:41]
	v_mfma_i32_16x16x64_i8 v[34:37], v[190:193], v[206:209], 0
	v_mfma_i32_16x16x64_i8 v[34:37], v[186:189], v[202:205], v[34:37]
	v_mfma_i32_16x16x64_i8 v[50:53], v[186:189], v[194:197], 0
	v_mfma_i32_16x16x64_i8 v[50:53], v[190:193], v[198:201], v[50:53]
	v_mfma_i32_16x16x64_i8 v[54:57], v[182:185], v[198:201], 0
	v_mfma_i32_16x16x64_i8 v[54:57], v[172:175], v[194:197], v[54:57]
	s_setprio 0
	s_barrier
; #define PG8_STAGE(bufoff, gbase, voff) do { _Pragma("unroll") for (int _i = 0; _i < 2; ++_i) \
;         __builtin_amdgcn_global_load_lds((const unsigned*)((const char*)(gbase) + (voff)[_i]), (PG8_LAS unsigned*)(lds + (bufoff) + ldsw + _i * 8192), 16, 0, 0); } while (0)
; #define PG8_LDA(dst, b, h) do { _Pragma("unroll") for (int m = 0; m < 4; ++m) _Pragma("unroll") for (int k = 0; k < 2; ++k) dst[m][k] = *(const PG8_LAS bf16x8*)(lds + PG8_SA(b, h) + aoff + m * 2048 + k * 1024); } while (0)
; #define PG8_LDB(dst, b, h) do { _Pragma("unroll") for (int n = 0; n < 2; ++n) _Pragma("unroll") for (int k = 0; k < 2; ++k) dst[n][k] = *(const PG8_LAS bf16x8*)(lds + PG8_SB(b, h) + boff + n * 2048 + k * 1024); } while (0)
; #define PG8_MMA(ai, bj, At, Bt) do { __builtin_amdgcn_s_setprio(1); _Pragma("unroll") for (int m = 0; m < 4; ++m) _Pragma("unroll") for (int n = 0; n < 2; ++n) _Pragma("unroll") for (int k = 0; k < 2; ++k) \
;         acc[ai][bj][m][n] = mma16(Bt[n][k], At[m][k], acc[ai][bj][m][n]); __builtin_amdgcn_s_setprio(0); } while (0)
; #define PG8_WAIT_V(n) asm volatile("s_waitcnt vmcnt(" #n ")" ::: "memory")
; #define PG8_WAIT_L(n) asm volatile("s_waitcnt lgkmcnt(" #n ")" ::: "memory")
; #define PG8_BAR __builtin_amdgcn_s_barrier()
; #define PG8_SCHED __builtin_amdgcn_sched_barrier(0)
; template <class Epi, class Sched, bool ALIGN_EPI = false, bool SP2 = false>
; __device__ __forceinline__ void gemm_phase(PG8_LAS unsigned char* lds, const Gemm g, const Sched& S, const Epi& E) {
;     ...
;             PG8_LDB(B0, 1, 0); PG8_LDB(B1, 1, 1); PG8_SCHED; PG8_LDA(At, 1, 0); PG8_STAGE(PG8_SA(0, 1), a2 + hstepA, voffA);
;             PG8_WAIT_V(8); PG8_WAIT_L(0); PG8_BAR; PG8_MMA(0, 0, At, B0); PG8_MMA(0, 1, At, B1); PG8_BAR; PG8_SCHED;
;             PG8_LDA(At, 1, 1); PG8_STAGE(PG8_SB(1, 0), b3, voffB); PG8_STAGE(PG8_SB(1, 1), b3 + hstepB, voffB); PG8_STAGE(PG8_SA(1, 0), a3, voffA);
;             PG8_WAIT_V(8); PG8_WAIT_L(0); PG8_BAR; PG8_MMA(1, 0, At, B0); PG8_MMA(1, 1, At, B1); PG8_BAR; PG8_SCHED;
	ds_read_b128 v[118:121], v170
	ds_read_b128 v[126:129], v170 offset:1024
	ds_read_b128 v[130:133], v170 offset:2048
	ds_read_b128 v[134:137], v170 offset:3072
	ds_read_b128 v[172:175], v171
	ds_read_b128 v[182:185], v171 offset:1024
	ds_read_b128 v[186:189], v171 offset:2048
	ds_read_b128 v[190:193], v171 offset:3072
	s_add_u32 s54, s54, 0x158000
	s_addc_u32 s55, s55, 0
	s_mov_b32 m0, s7
	v_lshl_add_u64 v[232:233], s[54:55], 0, v[152:153]
	ds_read_b128 v[194:197], v169 offset:32768
	ds_read_b128 v[198:201], v169 offset:33792
	ds_read_b128 v[202:205], v169 offset:34816
	ds_read_b128 v[206:209], v169 offset:35840
	ds_read_b128 v[212:215], v169 offset:36864
	ds_read_b128 v[216:219], v169 offset:37888
	ds_read_b128 v[220:223], v169 offset:38912
	ds_read_b128 v[224:227], v169 offset:39936
	global_load_lds_dwordx4 v[232:233], off
	v_lshl_add_u64 v[232:233], s[54:55], 0, v[148:149]
	s_mov_b32 m0, s11
	s_nop 0
	global_load_lds_dwordx4 v[232:233], off
	s_waitcnt vmcnt(8)
	s_waitcnt lgkmcnt(0)
	s_barrier
	s_setprio 1
	s_waitcnt lgkmcnt(0)
	v_mfma_i32_16x16x64_i8 v[142:145], v[118:121], v[194:197], v[142:145]
	v_mfma_i32_16x16x64_i8 v[142:145], v[126:129], v[198:201], v[142:145]
	v_mfma_i32_16x16x64_i8 v[138:141], v[134:137], v[198:201], v[138:141]
	v_mfma_i32_16x16x64_i8 v[138:141], v[130:133], v[194:197], v[138:141]
	v_mfma_i32_16x16x64_i8 v[106:109], v[130:133], v[202:205], v[106:109]
	v_mfma_i32_16x16x64_i8 v[106:109], v[134:137], v[206:209], v[106:109]
	v_mfma_i32_16x16x64_i8 v[110:113], v[126:129], v[206:209], v[110:113]
	v_mfma_i32_16x16x64_i8 v[110:113], v[118:121], v[202:205], v[110:113]
	v_mfma_i32_16x16x64_i8 v[94:97], v[118:121], v[212:215], v[94:97]
	v_mfma_i32_16x16x64_i8 v[94:97], v[126:129], v[216:219], v[94:97]
	v_mfma_i32_16x16x64_i8 v[90:93], v[134:137], v[216:219], v[90:93]
	v_mfma_i32_16x16x64_i8 v[90:93], v[130:133], v[212:215], v[90:93]
	v_mfma_i32_16x16x64_i8 v[74:77], v[130:133], v[220:223], v[74:77]
	v_mfma_i32_16x16x64_i8 v[74:77], v[134:137], v[224:227], v[74:77]
	v_mfma_i32_16x16x64_i8 v[78:81], v[126:129], v[224:227], v[78:81]
	v_mfma_i32_16x16x64_i8 v[78:81], v[118:121], v[220:223], v[78:81]
	s_setprio 0
	s_setprio 1
	v_mfma_i32_16x16x64_i8 v[70:73], v[172:175], v[220:223], v[70:73]
	v_mfma_i32_16x16x64_i8 v[70:73], v[182:185], v[224:227], v[70:73]
	v_mfma_i32_16x16x64_i8 v[66:69], v[190:193], v[224:227], v[66:69]
	v_mfma_i32_16x16x64_i8 v[66:69], v[186:189], v[220:223], v[66:69]
	v_mfma_i32_16x16x64_i8 v[82:85], v[186:189], v[212:215], v[82:85]
	v_mfma_i32_16x16x64_i8 v[82:85], v[190:193], v[216:219], v[82:85]
	v_mfma_i32_16x16x64_i8 v[86:89], v[182:185], v[216:219], v[86:89]
	v_mfma_i32_16x16x64_i8 v[86:89], v[172:175], v[212:215], v[86:89]
	v_mfma_i32_16x16x64_i8 v[102:105], v[172:175], v[202:205], v[102:105]
	v_mfma_i32_16x16x64_i8 v[102:105], v[182:185], v[206:209], v[102:105]
	v_mfma_i32_16x16x64_i8 v[98:101], v[190:193], v[206:209], v[98:101]
	v_mfma_i32_16x16x64_i8 v[98:101], v[186:189], v[202:205], v[98:101]
	v_mfma_i32_16x16x64_i8 v[114:117], v[186:189], v[194:197], v[114:117]
	v_mfma_i32_16x16x64_i8 v[114:117], v[190:193], v[198:201], v[114:117]
	v_mfma_i32_16x16x64_i8 v[122:125], v[182:185], v[198:201], v[122:125]
	v_mfma_i32_16x16x64_i8 v[122:125], v[172:175], v[194:197], v[122:125]
	s_setprio 0
	s_barrier
	s_mov_b32 m0, s65
	v_lshl_add_u64 v[162:163], v[162:163], 0, s[22:23]
	s_add_u32 s52, s52, 0x158080
	ds_read_b128 v[194:197], v169 offset:49152
	ds_read_b128 v[198:201], v169 offset:50176
	ds_read_b128 v[202:205], v169 offset:51200
	ds_read_b128 v[206:209], v169 offset:52224
	ds_read_b128 v[212:215], v169 offset:53248
	ds_read_b128 v[216:219], v169 offset:54272
	ds_read_b128 v[220:223], v169 offset:55296
	ds_read_b128 v[224:227], v169 offset:56320
	global_load_lds_dwordx4 v[162:163], off
	v_lshl_add_u64 v[162:163], v[176:177], 0, s[22:23]
	s_mov_b32 m0, s66
	s_addc_u32 s53, s53, 0
	global_load_lds_dwordx4 v[162:163], off
	v_lshl_add_u64 v[162:163], s[52:53], 0, v[150:151]
	s_mov_b32 m0, s67
	s_nop 0
	global_load_lds_dwordx4 v[162:163], off
	v_lshl_add_u64 v[162:163], s[52:53], 0, v[146:147]
	s_mov_b32 m0, s68
	s_nop 0
	global_load_lds_dwordx4 v[162:163], off
	v_lshl_add_u64 v[162:163], v[228:229], 0, s[22:23]
	s_mov_b32 m0, s26
	s_nop 0
	global_load_lds_dwordx4 v[162:163], off
	v_lshl_add_u64 v[162:163], v[230:231], 0, s[22:23]
	s_mov_b32 m0, s27
	s_nop 0
	global_load_lds_dwordx4 v[162:163], off
	s_waitcnt vmcnt(8)
	s_waitcnt lgkmcnt(0)
	s_barrier
	s_setprio 1
	s_waitcnt lgkmcnt(0)
	v_mfma_i32_16x16x64_i8 v[62:65], v[118:121], v[194:197], v[62:65]
	v_mfma_i32_16x16x64_i8 v[62:65], v[126:129], v[198:201], v[62:65]
	v_mfma_i32_16x16x64_i8 v[58:61], v[134:137], v[198:201], v[58:61]
	v_mfma_i32_16x16x64_i8 v[58:61], v[130:133], v[194:197], v[58:61]
	v_mfma_i32_16x16x64_i8 v[42:45], v[130:133], v[202:205], v[42:45]
	v_mfma_i32_16x16x64_i8 v[42:45], v[134:137], v[206:209], v[42:45]
	v_mfma_i32_16x16x64_i8 v[46:49], v[126:129], v[206:209], v[46:49]
	v_mfma_i32_16x16x64_i8 v[46:49], v[118:121], v[202:205], v[46:49]
	v_mfma_i32_16x16x64_i8 v[30:33], v[118:121], v[212:215], v[30:33]
	v_mfma_i32_16x16x64_i8 v[30:33], v[126:129], v[216:219], v[30:33]
	v_mfma_i32_16x16x64_i8 v[26:29], v[134:137], v[216:219], v[26:29]
	v_mfma_i32_16x16x64_i8 v[26:29], v[130:133], v[212:215], v[26:29]
	v_mfma_i32_16x16x64_i8 v[10:13], v[130:133], v[220:223], v[10:13]
	v_mfma_i32_16x16x64_i8 v[10:13], v[134:137], v[224:227], v[10:13]
	v_mfma_i32_16x16x64_i8 v[14:17], v[126:129], v[224:227], v[14:17]
	v_mfma_i32_16x16x64_i8 v[14:17], v[118:121], v[220:223], v[14:17]
	s_setprio 0
	s_setprio 1
	v_mfma_i32_16x16x64_i8 v[6:9], v[172:175], v[220:223], v[6:9]
	v_mfma_i32_16x16x64_i8 v[6:9], v[182:185], v[224:227], v[6:9]
	v_mfma_i32_16x16x64_i8 v[2:5], v[190:193], v[224:227], v[2:5]
	v_mfma_i32_16x16x64_i8 v[2:5], v[186:189], v[220:223], v[2:5]
	v_mfma_i32_16x16x64_i8 v[18:21], v[186:189], v[212:215], v[18:21]
	v_mfma_i32_16x16x64_i8 v[18:21], v[190:193], v[216:219], v[18:21]
	v_mfma_i32_16x16x64_i8 v[22:25], v[182:185], v[216:219], v[22:25]
	v_mfma_i32_16x16x64_i8 v[22:25], v[172:175], v[212:215], v[22:25]
	v_mfma_i32_16x16x64_i8 v[38:41], v[172:175], v[202:205], v[38:41]
	v_mfma_i32_16x16x64_i8 v[38:41], v[182:185], v[206:209], v[38:41]
	v_mfma_i32_16x16x64_i8 v[34:37], v[190:193], v[206:209], v[34:37]
	v_mfma_i32_16x16x64_i8 v[34:37], v[186:189], v[202:205], v[34:37]
	v_mfma_i32_16x16x64_i8 v[50:53], v[186:189], v[194:197], v[50:53]
	v_mfma_i32_16x16x64_i8 v[50:53], v[190:193], v[198:201], v[50:53]
	v_mfma_i32_16x16x64_i8 v[54:57], v[182:185], v[198:201], v[54:57]
	v_mfma_i32_16x16x64_i8 v[54:57], v[172:175], v[194:197], v[54:57]
	s_setprio 0
	s_barrier
	s_add_i32 s71, s71, 2
	s_add_u32 s50, s50, 0x100
	s_addc_u32 s51, s51, 0
	s_add_u32 s45, s45, 0x100
	s_addc_u32 s70, s70, 0
; #define PG8_STAGE(bufoff, gbase, voff) do { _Pragma("unroll") for (int _i = 0; _i < 2; ++_i) \
;         __builtin_amdgcn_global_load_lds((const unsigned*)((const char*)(gbase) + (voff)[_i]), (PG8_LAS unsigned*)(lds + (bufoff) + ldsw + _i * 8192), 16, 0, 0); } while (0)
; #define PG8_LDA(dst, b, h) do { _Pragma("unroll") for (int m = 0; m < 4; ++m) _Pragma("unroll") for (int k = 0; k < 2; ++k) dst[m][k] = *(const PG8_LAS bf16x8*)(lds + PG8_SA(b, h) + aoff + m * 2048 + k * 1024); } while (0)
; #define PG8_LDB(dst, b, h) do { _Pragma("unroll") for (int n = 0; n < 2; ++n) _Pragma("unroll") for (int k = 0; k < 2; ++k) dst[n][k] = *(const PG8_LAS bf16x8*)(lds + PG8_SB(b, h) + boff + n * 2048 + k * 1024); } while (0)
; #define PG8_MMA(ai, bj, At, Bt) do { __builtin_amdgcn_s_setprio(1); _Pragma("unroll") for (int m = 0; m < 4; ++m) _Pragma("unroll") for (int n = 0; n < 2; ++n) _Pragma("unroll") for (int k = 0; k < 2; ++k) \
;         acc[ai][bj][m][n] = mma16(Bt[n][k], At[m][k], acc[ai][bj][m][n]); __builtin_amdgcn_s_setprio(0); } while (0)
; #define PG8_WAIT_V(n) asm volatile("s_waitcnt vmcnt(" #n ")" ::: "memory")
; #define PG8_WAIT_L(n) asm volatile("s_waitcnt lgkmcnt(" #n ")" ::: "memory")
; #define PG8_BAR __builtin_amdgcn_s_barrier()
; #define PG8_SCHED __builtin_amdgcn_sched_barrier(0)
; template <class Epi, class Sched, bool ALIGN_EPI = false, bool SP2 = false>
; __device__ __forceinline__ void gemm_phase(PG8_LAS unsigned char* lds, const Gemm g, const Sched& S, const Epi& E) {
;     ...
;             PG8_LDB(B0, 0, 0); PG8_LDB(B1, 0, 1); PG8_SCHED; PG8_LDA(At, 0, 0); PG8_STAGE(PG8_SA(1, 1), a1 + hstepA, voffA);
;             PG8_WAIT_V(8); PG8_WAIT_L(0); PG8_BAR; PG8_MMA(0, 0, At, B0); PG8_MMA(0, 1, At, B1); PG8_BAR; PG8_SCHED;
;             PG8_LDA(At, 0, 1); PG8_STAGE(PG8_SB(0, 0), b2, voffB); PG8_STAGE(PG8_SB(0, 1), b2 + hstepB, voffB); PG8_STAGE(PG8_SA(0, 0), a2, voffA);
;             PG8_WAIT_V(8); PG8_WAIT_L(0); PG8_BAR; PG8_MMA(1, 0, At, B0); PG8_MMA(1, 1, At, B1); PG8_BAR; PG8_SCHED;
.LBB0_1037:
	ds_read_b128 v[118:121], v167
	ds_read_b128 v[126:129], v167 offset:1024
	ds_read_b128 v[130:133], v167 offset:2048
	ds_read_b128 v[134:137], v167 offset:3072
	ds_read_b128 v[172:175], v168
	ds_read_b128 v[182:185], v168 offset:1024
	ds_read_b128 v[186:189], v168 offset:2048
	ds_read_b128 v[190:193], v168 offset:3072
	s_add_u32 s52, s50, 0xffea8080
	s_addc_u32 s53, s51, -1
	s_cmpk_eq_i32 s71, 0x52
	s_cselect_b32 s55, s47, s53
	s_cselect_b32 s54, s46, s52
	s_cselect_b32 s53, s9, s70
	s_cselect_b32 s52, s8, s45
	s_mov_b32 m0, s35
	v_lshl_add_u64 v[162:163], s[50:51], 0, v[158:159]
	ds_read_b128 v[194:197], v169
	ds_read_b128 v[198:201], v169 offset:1024
	ds_read_b128 v[202:205], v169 offset:2048
	ds_read_b128 v[206:209], v169 offset:3072
	ds_read_b128 v[212:215], v169 offset:4096
	ds_read_b128 v[216:219], v169 offset:5120
	ds_read_b128 v[220:223], v169 offset:6144
	ds_read_b128 v[224:227], v169 offset:7168
	global_load_lds_dwordx4 v[162:163], off
	v_lshl_add_u64 v[162:163], s[50:51], 0, v[160:161]
	s_mov_b32 m0, s56
	s_nop 0
	global_load_lds_dwordx4 v[162:163], off
	s_waitcnt vmcnt(8)
	s_waitcnt lgkmcnt(0)
	s_barrier
	s_setprio 1
	s_waitcnt lgkmcnt(0)
	v_mfma_i32_16x16x64_i8 v[142:145], v[118:121], v[194:197], v[142:145]
	v_mfma_i32_16x16x64_i8 v[142:145], v[126:129], v[198:201], v[142:145]
	v_mfma_i32_16x16x64_i8 v[138:141], v[134:137], v[198:201], v[138:141]
	v_mfma_i32_16x16x64_i8 v[138:141], v[130:133], v[194:197], v[138:141]
	v_mfma_i32_16x16x64_i8 v[106:109], v[130:133], v[202:205], v[106:109]
	v_mfma_i32_16x16x64_i8 v[106:109], v[134:137], v[206:209], v[106:109]
	v_mfma_i32_16x16x64_i8 v[110:113], v[126:129], v[206:209], v[110:113]
	v_mfma_i32_16x16x64_i8 v[110:113], v[118:121], v[202:205], v[110:113]
	v_mfma_i32_16x16x64_i8 v[94:97], v[118:121], v[212:215], v[94:97]
	v_mfma_i32_16x16x64_i8 v[94:97], v[126:129], v[216:219], v[94:97]
	v_mfma_i32_16x16x64_i8 v[90:93], v[134:137], v[216:219], v[90:93]
	v_mfma_i32_16x16x64_i8 v[90:93], v[130:133], v[212:215], v[90:93]
	v_mfma_i32_16x16x64_i8 v[74:77], v[130:133], v[220:223], v[74:77]
	v_mfma_i32_16x16x64_i8 v[74:77], v[134:137], v[224:227], v[74:77]
	v_mfma_i32_16x16x64_i8 v[78:81], v[126:129], v[224:227], v[78:81]
	v_mfma_i32_16x16x64_i8 v[78:81], v[118:121], v[220:223], v[78:81]
	s_setprio 0
	s_setprio 1
	v_mfma_i32_16x16x64_i8 v[70:73], v[172:175], v[220:223], v[70:73]
	v_mfma_i32_16x16x64_i8 v[70:73], v[182:185], v[224:227], v[70:73]
	v_mfma_i32_16x16x64_i8 v[66:69], v[190:193], v[224:227], v[66:69]
	v_mfma_i32_16x16x64_i8 v[66:69], v[186:189], v[220:223], v[66:69]
	v_mfma_i32_16x16x64_i8 v[82:85], v[186:189], v[212:215], v[82:85]
	v_mfma_i32_16x16x64_i8 v[82:85], v[190:193], v[216:219], v[82:85]
	v_mfma_i32_16x16x64_i8 v[86:89], v[182:185], v[216:219], v[86:89]
	v_mfma_i32_16x16x64_i8 v[86:89], v[172:175], v[212:215], v[86:89]
	v_mfma_i32_16x16x64_i8 v[102:105], v[172:175], v[202:205], v[102:105]
	v_mfma_i32_16x16x64_i8 v[102:105], v[182:185], v[206:209], v[102:105]
	v_mfma_i32_16x16x64_i8 v[98:101], v[190:193], v[206:209], v[98:101]
	v_mfma_i32_16x16x64_i8 v[98:101], v[186:189], v[202:205], v[98:101]
	v_mfma_i32_16x16x64_i8 v[114:117], v[186:189], v[194:197], v[114:117]
	v_mfma_i32_16x16x64_i8 v[114:117], v[190:193], v[198:201], v[114:117]
	v_mfma_i32_16x16x64_i8 v[122:125], v[182:185], v[198:201], v[122:125]
	v_mfma_i32_16x16x64_i8 v[122:125], v[172:175], v[194:197], v[122:125]
	s_setprio 0
	s_barrier
	s_mov_b32 m0, s57
	v_lshl_add_u64 v[162:163], s[52:53], 0, v[150:151]
	s_add_u32 s74, s52, 0x158000
	ds_read_b128 v[194:197], v169 offset:16384
	ds_read_b128 v[198:201], v169 offset:17408
	ds_read_b128 v[202:205], v169 offset:18432
	ds_read_b128 v[206:209], v169 offset:19456
	ds_read_b128 v[212:215], v169 offset:20480
	ds_read_b128 v[216:219], v169 offset:21504
	ds_read_b128 v[220:223], v169 offset:22528
	ds_read_b128 v[224:227], v169 offset:23552
	global_load_lds_dwordx4 v[162:163], off
	v_lshl_add_u64 v[176:177], s[52:53], 0, v[146:147]
	s_mov_b32 m0, s58
	s_addc_u32 s75, s53, 0
	global_load_lds_dwordx4 v[176:177], off
	v_lshl_add_u64 v[228:229], s[74:75], 0, v[150:151]
	s_mov_b32 m0, s63
	v_lshl_add_u64 v[230:231], s[54:55], 0, v[148:149]
	global_load_lds_dwordx4 v[228:229], off
	v_lshl_add_u64 v[228:229], s[74:75], 0, v[146:147]
	s_mov_b32 m0, s64
	s_nop 0
	global_load_lds_dwordx4 v[228:229], off
	v_lshl_add_u64 v[228:229], s[54:55], 0, v[152:153]
	s_mov_b32 m0, s5
	s_nop 0
	global_load_lds_dwordx4 v[228:229], off
	s_mov_b32 m0, s6
	s_nop 0
	global_load_lds_dwordx4 v[230:231], off
	s_waitcnt vmcnt(8)
	s_waitcnt lgkmcnt(0)
	s_barrier
; #define PG8_STAGE(bufoff, gbase, voff) do { _Pragma("unroll") for (int _i = 0; _i < 2; ++_i) \
;         __builtin_amdgcn_global_load_lds((const unsigned*)((const char*)(gbase) + (voff)[_i]), (PG8_LAS unsigned*)(lds + (bufoff) + ldsw + _i * 8192), 16, 0, 0); } while (0)
; #define PG8_LDA(dst, b, h) do { _Pragma("unroll") for (int m = 0; m < 4; ++m) _Pragma("unroll") for (int k = 0; k < 2; ++k) dst[m][k] = *(const PG8_LAS bf16x8*)(lds + PG8_SA(b, h) + aoff + m * 2048 + k * 1024); } while (0)
; #define PG8_LDB(dst, b, h) do { _Pragma("unroll") for (int n = 0; n < 2; ++n) _Pragma("unroll") for (int k = 0; k < 2; ++k) dst[n][k] = *(const PG8_LAS bf16x8*)(lds + PG8_SB(b, h) + boff + n * 2048 + k * 1024); } while (0)
; #define PG8_MMA(ai, bj, At, Bt) do { __builtin_amdgcn_s_setprio(1); _Pragma("unroll") for (int m = 0; m < 4; ++m) _Pragma("unroll") for (int n = 0; n < 2; ++n) _Pragma("unroll") for (int k = 0; k < 2; ++k) \
;         acc[ai][bj][m][n] = mma16(Bt[n][k], At[m][k], acc[ai][bj][m][n]); __builtin_amdgcn_s_setprio(0); } while (0)
; #define PG8_WAIT_V(n) asm volatile("s_waitcnt vmcnt(" #n ")" ::: "memory")
; #define PG8_WAIT_L(n) asm volatile("s_waitcnt lgkmcnt(" #n ")" ::: "memory")
; #define PG8_BAR __builtin_amdgcn_s_barrier()
; #define PG8_SCHED __builtin_amdgcn_sched_barrier(0)
; template <class Epi, class Sched, bool ALIGN_EPI = false, bool SP2 = false>
; __device__ __forceinline__ void gemm_phase(PG8_LAS unsigned char* lds, const Gemm g, const Sched& S, const Epi& E) {
;     ...
;             PG8_WAIT_V(8); PG8_WAIT_L(0); PG8_BAR; PG8_MMA(1, 0, At, B0); PG8_MMA(1, 1, At, B1); PG8_BAR; PG8_SCHED;
;             PG8_LDB(B0, 1, 0); PG8_LDB(B1, 1, 1); PG8_SCHED; PG8_LDA(At, 1, 0); PG8_STAGE(PG8_SA(0, 1), a2 + hstepA, voffA);
;             PG8_WAIT_V(8); PG8_WAIT_L(0); PG8_BAR; PG8_MMA(0, 0, At, B0); PG8_MMA(0, 1, At, B1); PG8_BAR; PG8_SCHED;
	s_setprio 1
	s_waitcnt lgkmcnt(0)
	v_mfma_i32_16x16x64_i8 v[62:65], v[118:121], v[194:197], v[62:65]
	v_mfma_i32_16x16x64_i8 v[62:65], v[126:129], v[198:201], v[62:65]
	v_mfma_i32_16x16x64_i8 v[58:61], v[134:137], v[198:201], v[58:61]
	v_mfma_i32_16x16x64_i8 v[58:61], v[130:133], v[194:197], v[58:61]
	v_mfma_i32_16x16x64_i8 v[42:45], v[130:133], v[202:205], v[42:45]
	v_mfma_i32_16x16x64_i8 v[42:45], v[134:137], v[206:209], v[42:45]
	v_mfma_i32_16x16x64_i8 v[46:49], v[126:129], v[206:209], v[46:49]
	v_mfma_i32_16x16x64_i8 v[46:49], v[118:121], v[202:205], v[46:49]
	v_mfma_i32_16x16x64_i8 v[30:33], v[118:121], v[212:215], v[30:33]
	v_mfma_i32_16x16x64_i8 v[30:33], v[126:129], v[216:219], v[30:33]
	v_mfma_i32_16x16x64_i8 v[26:29], v[134:137], v[216:219], v[26:29]
	v_mfma_i32_16x16x64_i8 v[26:29], v[130:133], v[212:215], v[26:29]
	v_mfma_i32_16x16x64_i8 v[10:13], v[130:133], v[220:223], v[10:13]
	v_mfma_i32_16x16x64_i8 v[10:13], v[134:137], v[224:227], v[10:13]
	v_mfma_i32_16x16x64_i8 v[14:17], v[126:129], v[224:227], v[14:17]
	v_mfma_i32_16x16x64_i8 v[14:17], v[118:121], v[220:223], v[14:17]
	s_setprio 0
	s_setprio 1
	v_mfma_i32_16x16x64_i8 v[6:9], v[172:175], v[220:223], v[6:9]
	v_mfma_i32_16x16x64_i8 v[6:9], v[182:185], v[224:227], v[6:9]
	v_mfma_i32_16x16x64_i8 v[2:5], v[190:193], v[224:227], v[2:5]
	v_mfma_i32_16x16x64_i8 v[2:5], v[186:189], v[220:223], v[2:5]
	v_mfma_i32_16x16x64_i8 v[18:21], v[186:189], v[212:215], v[18:21]
	v_mfma_i32_16x16x64_i8 v[18:21], v[190:193], v[216:219], v[18:21]
	v_mfma_i32_16x16x64_i8 v[22:25], v[182:185], v[216:219], v[22:25]
	v_mfma_i32_16x16x64_i8 v[22:25], v[172:175], v[212:215], v[22:25]
	v_mfma_i32_16x16x64_i8 v[38:41], v[172:175], v[202:205], v[38:41]
	v_mfma_i32_16x16x64_i8 v[38:41], v[182:185], v[206:209], v[38:41]
	v_mfma_i32_16x16x64_i8 v[34:37], v[190:193], v[206:209], v[34:37]
	v_mfma_i32_16x16x64_i8 v[34:37], v[186:189], v[202:205], v[34:37]
	v_mfma_i32_16x16x64_i8 v[50:53], v[186:189], v[194:197], v[50:53]
	v_mfma_i32_16x16x64_i8 v[50:53], v[190:193], v[198:201], v[50:53]
	v_mfma_i32_16x16x64_i8 v[54:57], v[182:185], v[198:201], v[54:57]
	v_mfma_i32_16x16x64_i8 v[54:57], v[172:175], v[194:197], v[54:57]
	s_setprio 0
	s_barrier
	ds_read_b128 v[118:121], v170
	ds_read_b128 v[126:129], v170 offset:1024
	ds_read_b128 v[130:133], v170 offset:2048
	ds_read_b128 v[134:137], v170 offset:3072
	ds_read_b128 v[172:175], v171
	ds_read_b128 v[182:185], v171 offset:1024
	ds_read_b128 v[186:189], v171 offset:2048
	ds_read_b128 v[190:193], v171 offset:3072
	s_add_u32 s54, s54, 0x158000
	s_addc_u32 s55, s55, 0
	s_mov_b32 m0, s7
	v_lshl_add_u64 v[232:233], s[54:55], 0, v[152:153]
	ds_read_b128 v[194:197], v169 offset:32768
	ds_read_b128 v[198:201], v169 offset:33792
	ds_read_b128 v[202:205], v169 offset:34816
	ds_read_b128 v[206:209], v169 offset:35840
	ds_read_b128 v[212:215], v169 offset:36864
	ds_read_b128 v[216:219], v169 offset:37888
	ds_read_b128 v[220:223], v169 offset:38912
	ds_read_b128 v[224:227], v169 offset:39936
	global_load_lds_dwordx4 v[232:233], off
	v_lshl_add_u64 v[232:233], s[54:55], 0, v[148:149]
	s_mov_b32 m0, s11
	s_nop 0
	global_load_lds_dwordx4 v[232:233], off
	s_waitcnt vmcnt(8)
	s_waitcnt lgkmcnt(0)
	s_barrier
	s_setprio 1
	s_waitcnt lgkmcnt(0)
	v_mfma_i32_16x16x64_i8 v[142:145], v[118:121], v[194:197], v[142:145]
	v_mfma_i32_16x16x64_i8 v[142:145], v[126:129], v[198:201], v[142:145]
	v_mfma_i32_16x16x64_i8 v[138:141], v[134:137], v[198:201], v[138:141]
	v_mfma_i32_16x16x64_i8 v[138:141], v[130:133], v[194:197], v[138:141]
	v_mfma_i32_16x16x64_i8 v[106:109], v[130:133], v[202:205], v[106:109]
	v_mfma_i32_16x16x64_i8 v[106:109], v[134:137], v[206:209], v[106:109]
	v_mfma_i32_16x16x64_i8 v[110:113], v[126:129], v[206:209], v[110:113]
	v_mfma_i32_16x16x64_i8 v[110:113], v[118:121], v[202:205], v[110:113]
	v_mfma_i32_16x16x64_i8 v[94:97], v[118:121], v[212:215], v[94:97]
	v_mfma_i32_16x16x64_i8 v[94:97], v[126:129], v[216:219], v[94:97]
	v_mfma_i32_16x16x64_i8 v[90:93], v[134:137], v[216:219], v[90:93]
	v_mfma_i32_16x16x64_i8 v[90:93], v[130:133], v[212:215], v[90:93]
	v_mfma_i32_16x16x64_i8 v[74:77], v[130:133], v[220:223], v[74:77]
	v_mfma_i32_16x16x64_i8 v[74:77], v[134:137], v[224:227], v[74:77]
	v_mfma_i32_16x16x64_i8 v[78:81], v[126:129], v[224:227], v[78:81]
	v_mfma_i32_16x16x64_i8 v[78:81], v[118:121], v[220:223], v[78:81]
	s_setprio 0
	s_setprio 1
	v_mfma_i32_16x16x64_i8 v[70:73], v[172:175], v[220:223], v[70:73]
	v_mfma_i32_16x16x64_i8 v[70:73], v[182:185], v[224:227], v[70:73]
	v_mfma_i32_16x16x64_i8 v[66:69], v[190:193], v[224:227], v[66:69]
	v_mfma_i32_16x16x64_i8 v[66:69], v[186:189], v[220:223], v[66:69]
	v_mfma_i32_16x16x64_i8 v[82:85], v[186:189], v[212:215], v[82:85]
	v_mfma_i32_16x16x64_i8 v[82:85], v[190:193], v[216:219], v[82:85]
	v_mfma_i32_16x16x64_i8 v[86:89], v[182:185], v[216:219], v[86:89]
	v_mfma_i32_16x16x64_i8 v[86:89], v[172:175], v[212:215], v[86:89]
	v_mfma_i32_16x16x64_i8 v[102:105], v[172:175], v[202:205], v[102:105]
	v_mfma_i32_16x16x64_i8 v[102:105], v[182:185], v[206:209], v[102:105]
	v_mfma_i32_16x16x64_i8 v[98:101], v[190:193], v[206:209], v[98:101]
	v_mfma_i32_16x16x64_i8 v[98:101], v[186:189], v[202:205], v[98:101]
	v_mfma_i32_16x16x64_i8 v[114:117], v[186:189], v[194:197], v[114:117]
	v_mfma_i32_16x16x64_i8 v[114:117], v[190:193], v[198:201], v[114:117]
	v_mfma_i32_16x16x64_i8 v[122:125], v[182:185], v[198:201], v[122:125]
	v_mfma_i32_16x16x64_i8 v[122:125], v[172:175], v[194:197], v[122:125]
	s_setprio 0
	s_barrier
; #define PG8_STAGE(bufoff, gbase, voff) do { _Pragma("unroll") for (int _i = 0; _i < 2; ++_i) \
;         __builtin_amdgcn_global_load_lds((const unsigned*)((const char*)(gbase) + (voff)[_i]), (PG8_LAS unsigned*)(lds + (bufoff) + ldsw + _i * 8192), 16, 0, 0); } while (0)
; #define PG8_LDA(dst, b, h) do { _Pragma("unroll") for (int m = 0; m < 4; ++m) _Pragma("unroll") for (int k = 0; k < 2; ++k) dst[m][k] = *(const PG8_LAS bf16x8*)(lds + PG8_SA(b, h) + aoff + m * 2048 + k * 1024); } while (0)
; #define PG8_MMA(ai, bj, At, Bt) do { __builtin_amdgcn_s_setprio(1); _Pragma("unroll") for (int m = 0; m < 4; ++m) _Pragma("unroll") for (int n = 0; n < 2; ++n) _Pragma("unroll") for (int k = 0; k < 2; ++k) \
;         acc[ai][bj][m][n] = mma16(Bt[n][k], At[m][k], acc[ai][bj][m][n]); __builtin_amdgcn_s_setprio(0); } while (0)
; #define PG8_WAIT_V(n) asm volatile("s_waitcnt vmcnt(" #n ")" ::: "memory")
; #define PG8_WAIT_L(n) asm volatile("s_waitcnt lgkmcnt(" #n ")" ::: "memory")
; #define PG8_BAR __builtin_amdgcn_s_barrier()
; #define PG8_SCHED __builtin_amdgcn_sched_barrier(0)
; template <class Epi, class Sched, bool ALIGN_EPI = false, bool SP2 = false>
; __device__ __forceinline__ void gemm_phase(PG8_LAS unsigned char* lds, const Gemm g, const Sched& S, const Epi& E) {
;     ...
;             PG8_LDA(At, 1, 1); PG8_STAGE(PG8_SB(1, 0), b3, voffB); PG8_STAGE(PG8_SB(1, 1), b3 + hstepB, voffB); PG8_STAGE(PG8_SA(1, 0), a3, voffA);
;             PG8_WAIT_V(8); PG8_WAIT_L(0); PG8_BAR; PG8_MMA(1, 0, At, B0); PG8_MMA(1, 1, At, B1); PG8_BAR; PG8_SCHED;
;     ...
;         if constexpr (ALIGN_EPI) { if (wr == 0) PG8_BAR; }
	s_mov_b32 m0, s65
	v_lshl_add_u64 v[162:163], v[162:163], 0, s[22:23]
	s_add_u32 s52, s52, 0x158080
	ds_read_b128 v[194:197], v169 offset:49152
	ds_read_b128 v[198:201], v169 offset:50176
	ds_read_b128 v[202:205], v169 offset:51200
	ds_read_b128 v[206:209], v169 offset:52224
	ds_read_b128 v[212:215], v169 offset:53248
	ds_read_b128 v[216:219], v169 offset:54272
	ds_read_b128 v[220:223], v169 offset:55296
	ds_read_b128 v[224:227], v169 offset:56320
	global_load_lds_dwordx4 v[162:163], off
	v_lshl_add_u64 v[162:163], v[176:177], 0, s[22:23]
	s_mov_b32 m0, s66
	s_addc_u32 s53, s53, 0
	global_load_lds_dwordx4 v[162:163], off
	v_lshl_add_u64 v[162:163], s[52:53], 0, v[150:151]
	s_mov_b32 m0, s67
	s_nop 0
	global_load_lds_dwordx4 v[162:163], off
	v_lshl_add_u64 v[162:163], s[52:53], 0, v[146:147]
	s_mov_b32 m0, s68
	s_nop 0
	global_load_lds_dwordx4 v[162:163], off
	v_lshl_add_u64 v[162:163], v[228:229], 0, s[22:23]
	s_mov_b32 m0, s26
	s_nop 0
	global_load_lds_dwordx4 v[162:163], off
	v_lshl_add_u64 v[162:163], v[230:231], 0, s[22:23]
	s_mov_b32 m0, s27
	s_nop 0
	global_load_lds_dwordx4 v[162:163], off
	s_waitcnt vmcnt(8)
	s_waitcnt lgkmcnt(0)
	s_barrier
	s_setprio 1
	s_waitcnt lgkmcnt(0)
	v_mfma_i32_16x16x64_i8 v[62:65], v[118:121], v[194:197], v[62:65]
	v_mfma_i32_16x16x64_i8 v[62:65], v[126:129], v[198:201], v[62:65]
	v_mfma_i32_16x16x64_i8 v[58:61], v[134:137], v[198:201], v[58:61]
	v_mfma_i32_16x16x64_i8 v[58:61], v[130:133], v[194:197], v[58:61]
	v_mfma_i32_16x16x64_i8 v[42:45], v[130:133], v[202:205], v[42:45]
	v_mfma_i32_16x16x64_i8 v[42:45], v[134:137], v[206:209], v[42:45]
	v_mfma_i32_16x16x64_i8 v[46:49], v[126:129], v[206:209], v[46:49]
	v_mfma_i32_16x16x64_i8 v[46:49], v[118:121], v[202:205], v[46:49]
	v_mfma_i32_16x16x64_i8 v[30:33], v[118:121], v[212:215], v[30:33]
	v_mfma_i32_16x16x64_i8 v[30:33], v[126:129], v[216:219], v[30:33]
	v_mfma_i32_16x16x64_i8 v[26:29], v[134:137], v[216:219], v[26:29]
	v_mfma_i32_16x16x64_i8 v[26:29], v[130:133], v[212:215], v[26:29]
	v_mfma_i32_16x16x64_i8 v[10:13], v[130:133], v[220:223], v[10:13]
	v_mfma_i32_16x16x64_i8 v[10:13], v[134:137], v[224:227], v[10:13]
	v_mfma_i32_16x16x64_i8 v[14:17], v[126:129], v[224:227], v[14:17]
	v_mfma_i32_16x16x64_i8 v[14:17], v[118:121], v[220:223], v[14:17]
	s_setprio 0
	s_setprio 1
	v_mfma_i32_16x16x64_i8 v[6:9], v[172:175], v[220:223], v[6:9]
	v_mfma_i32_16x16x64_i8 v[6:9], v[182:185], v[224:227], v[6:9]
	v_mfma_i32_16x16x64_i8 v[2:5], v[190:193], v[224:227], v[2:5]
	v_mfma_i32_16x16x64_i8 v[2:5], v[186:189], v[220:223], v[2:5]
	v_mfma_i32_16x16x64_i8 v[18:21], v[186:189], v[212:215], v[18:21]
	v_mfma_i32_16x16x64_i8 v[18:21], v[190:193], v[216:219], v[18:21]
	v_mfma_i32_16x16x64_i8 v[22:25], v[182:185], v[216:219], v[22:25]
	v_mfma_i32_16x16x64_i8 v[22:25], v[172:175], v[212:215], v[22:25]
	v_mfma_i32_16x16x64_i8 v[38:41], v[172:175], v[202:205], v[38:41]
	v_mfma_i32_16x16x64_i8 v[38:41], v[182:185], v[206:209], v[38:41]
	v_mfma_i32_16x16x64_i8 v[34:37], v[190:193], v[206:209], v[34:37]
	v_mfma_i32_16x16x64_i8 v[34:37], v[186:189], v[202:205], v[34:37]
	v_mfma_i32_16x16x64_i8 v[50:53], v[186:189], v[194:197], v[50:53]
	v_mfma_i32_16x16x64_i8 v[50:53], v[190:193], v[198:201], v[50:53]
	v_mfma_i32_16x16x64_i8 v[54:57], v[182:185], v[198:201], v[54:57]
	v_mfma_i32_16x16x64_i8 v[54:57], v[172:175], v[194:197], v[54:57]
	s_setprio 0
	s_barrier
	s_add_i32 s71, s71, 2
	s_add_u32 s50, s50, 0x100
	s_addc_u32 s51, s51, 0
	s_add_u32 s45, s45, 0x100
	s_addc_u32 s70, s70, 0
	s_cmpk_gt_u32 s71, 0x53
	s_cbranch_scc0 .LBB0_1037
	s_and_b64 vcc, exec, s[24:25]
	s_cbranch_vccz .LBB0_1040
	s_barrier
